# write-through (sc1) on the six GEMM epilogues' output stores
# baseline (speedup 1.0000x reference)
; __device__ __forceinline__ unsigned cvt_pk_bf16(float lo, float hi) { unsigned r; asm volatile("v_cvt_pk_bf16_f32 %0, %1, %2" : "=v"(r) : "v"(lo), "v"(hi)); return r; }
;     __device__ __forceinline__ void operator()(const f32x4 (&acc)[2][2][4][2], const Unit& u, int wr, int wc, int fr, int fq) const {
;         const int row0 = u.pm * BM + wr * 64 + fr, col0 = u.pn * BM + wc * 32 + 8 * fq;
; #pragma unroll
;         for (int ai = 0; ai < 2; ++ai)
; #pragma unroll
;             for (int m = 0; m < 4; ++m) { const int row = row0 + ai * HALF + m * 16; const float rs = ACT == 1 ? ss[row] : 1.0f;
;                 bf16_t* rowp = O + (size_t)row * ldc + col0;
; #pragma unroll
;                 for (int bj = 0; bj < 2; ++bj) { f32x4 v0 = acc[ai][bj][m][0] * rs, v1 = acc[ai][bj][m][1] * rs;
;                     if (ACT == 1) {
; #pragma unroll
;                         for (int e = 0; e < 4; ++e) { const float a0 = fmaxf(v0[e], 0.f), a1 = fmaxf(v1[e], 0.f); v0[e] = a0 * a0; v1[e] = a1 * a1; } }
;                     u32x4 w; w.x = cvt_pk_bf16(v0[0], v0[1]); w.y = cvt_pk_bf16(v0[2], v0[3]); w.z = cvt_pk_bf16(v1[0], v1[1]); w.w = cvt_pk_bf16(v1[2], v1[3]);
;                     *(u32x4*)(rowp + bj * HALF) = w; } }
.LBB0_179:
	v_lshl_or_b32 v146, s48, 8, v151
	v_lshl_add_u32 v155, s24, 8, v149
	v_ashrrev_i32_e32 v147, 31, v146
	v_mov_b64_e32 v[144:145], s[74:75]
	v_mad_i64_i32 v[156:157], s[26:27], v155, s47, v[144:145]
	v_lshlrev_b64 v[146:147], 1, v[146:147]
	v_lshl_add_u64 v[156:157], v[156:157], 0, v[146:147]
	v_cvt_pk_bf16_f32 v124, v124, v125
	v_cvt_pk_bf16_f32 v125, v126, v127
	v_cvt_pk_bf16_f32 v126, v120, v121
	v_cvt_pk_bf16_f32 v127, v122, v123
	global_store_dwordx4 v[156:157], v[124:127], off sc1
	v_cvt_pk_bf16_f32 v112, v112, v113
	v_cvt_pk_bf16_f32 v113, v114, v115
	v_cvt_pk_bf16_f32 v114, v104, v105
	v_or_b32_e32 v104, 16, v155
	v_mad_i64_i32 v[104:105], s[26:27], v104, s47, v[144:145]
	v_cvt_pk_bf16_f32 v115, v106, v107
	global_store_dwordx4 v[156:157], v[112:115], off offset:256 sc1
	s_andn2_b64 vcc, exec, s[4:5]
	s_mov_b64 s[4:5], -1
	v_lshl_add_u64 v[112:113], v[104:105], 0, v[146:147]
	v_cvt_pk_bf16_f32 v104, v116, v117
	v_cvt_pk_bf16_f32 v105, v118, v119
	v_cvt_pk_bf16_f32 v106, v108, v109
	v_cvt_pk_bf16_f32 v107, v110, v111
	global_store_dwordx4 v[112:113], v[104:107], off sc1
	v_cvt_pk_bf16_f32 v96, v96, v97
	v_cvt_pk_bf16_f32 v97, v98, v99
	v_cvt_pk_bf16_f32 v98, v88, v89
	v_or_b32_e32 v88, 32, v155
	v_mad_i64_i32 v[88:89], s[26:27], v88, s47, v[144:145]
	v_cvt_pk_bf16_f32 v99, v90, v91
	global_store_dwordx4 v[112:113], v[96:99], off offset:256 sc1
	s_nop 1
	v_lshl_add_u64 v[96:97], v[88:89], 0, v[146:147]
	v_cvt_pk_bf16_f32 v88, v100, v101
	v_cvt_pk_bf16_f32 v89, v102, v103
	v_cvt_pk_bf16_f32 v90, v92, v93
	v_cvt_pk_bf16_f32 v91, v94, v95
	global_store_dwordx4 v[96:97], v[88:91], off sc1
	v_cvt_pk_bf16_f32 v80, v80, v81
	v_cvt_pk_bf16_f32 v81, v82, v83
	v_cvt_pk_bf16_f32 v82, v72, v73
	v_or_b32_e32 v72, 48, v155
	v_mad_i64_i32 v[72:73], s[26:27], v72, s47, v[144:145]
	v_cvt_pk_bf16_f32 v83, v74, v75
	global_store_dwordx4 v[96:97], v[80:83], off offset:256 sc1
	s_nop 1
	v_lshl_add_u64 v[80:81], v[72:73], 0, v[146:147]
	v_cvt_pk_bf16_f32 v72, v84, v85
	v_cvt_pk_bf16_f32 v73, v86, v87
	v_cvt_pk_bf16_f32 v74, v76, v77
	v_cvt_pk_bf16_f32 v75, v78, v79
	global_store_dwordx4 v[80:81], v[72:75], off sc1
	v_cvt_pk_bf16_f32 v68, v68, v69
	v_cvt_pk_bf16_f32 v69, v70, v71
	v_cvt_pk_bf16_f32 v70, v64, v65
	v_add_u32_e32 v64, 0x80, v155
	v_mad_i64_i32 v[64:65], s[26:27], v64, s47, v[144:145]
	v_lshl_add_u64 v[64:65], v[64:65], 0, v[146:147]
	v_cvt_pk_bf16_f32 v71, v66, v67
	global_store_dwordx4 v[80:81], v[68:71], off offset:256 sc1
	v_cvt_pk_bf16_f32 v60, v60, v61
	v_cvt_pk_bf16_f32 v61, v62, v63
	v_cvt_pk_bf16_f32 v62, v56, v57
	v_cvt_pk_bf16_f32 v63, v58, v59
	global_store_dwordx4 v[64:65], v[60:63], off sc1
	v_cvt_pk_bf16_f32 v48, v48, v49
	v_cvt_pk_bf16_f32 v49, v50, v51
	v_cvt_pk_bf16_f32 v50, v40, v41
	v_add_u32_e32 v40, 0x90, v155
	v_mad_i64_i32 v[40:41], s[26:27], v40, s47, v[144:145]
	v_cvt_pk_bf16_f32 v51, v42, v43
	global_store_dwordx4 v[64:65], v[48:51], off offset:256 sc1
	s_nop 1
	v_lshl_add_u64 v[48:49], v[40:41], 0, v[146:147]
	v_cvt_pk_bf16_f32 v40, v52, v53
	v_cvt_pk_bf16_f32 v41, v54, v55
	v_cvt_pk_bf16_f32 v42, v44, v45
	v_cvt_pk_bf16_f32 v43, v46, v47
	global_store_dwordx4 v[48:49], v[40:43], off sc1
	v_cvt_pk_bf16_f32 v32, v32, v33
	v_cvt_pk_bf16_f32 v33, v34, v35
	v_cvt_pk_bf16_f32 v34, v24, v25
	v_add_u32_e32 v24, 0xa0, v155
	v_mad_i64_i32 v[24:25], s[26:27], v24, s47, v[144:145]
	v_cvt_pk_bf16_f32 v35, v26, v27
	global_store_dwordx4 v[48:49], v[32:35], off offset:256 sc1
	s_nop 1
	v_lshl_add_u64 v[32:33], v[24:25], 0, v[146:147]
	v_cvt_pk_bf16_f32 v24, v36, v37
	v_cvt_pk_bf16_f32 v25, v38, v39
	v_cvt_pk_bf16_f32 v26, v28, v29
	v_cvt_pk_bf16_f32 v27, v30, v31
	global_store_dwordx4 v[32:33], v[24:27], off sc1
	v_cvt_pk_bf16_f32 v16, v16, v17
	v_cvt_pk_bf16_f32 v17, v18, v19
	v_cvt_pk_bf16_f32 v18, v8, v9
	v_add_u32_e32 v8, 0xb0, v155
	v_mad_i64_i32 v[8:9], s[26:27], v8, s47, v[144:145]
	v_cvt_pk_bf16_f32 v19, v10, v11
	global_store_dwordx4 v[32:33], v[16:19], off offset:256 sc1
	s_nop 1
	v_lshl_add_u64 v[16:17], v[8:9], 0, v[146:147]
	v_cvt_pk_bf16_f32 v8, v20, v21
	v_cvt_pk_bf16_f32 v9, v22, v23
	v_cvt_pk_bf16_f32 v10, v12, v13
	v_cvt_pk_bf16_f32 v11, v14, v15
	global_store_dwordx4 v[16:17], v[8:11], off sc1
	v_cvt_pk_bf16_f32 v4, v4, v5
	v_cvt_pk_bf16_f32 v5, v6, v7
	v_cvt_pk_bf16_f32 v6, v0, v1
	v_cvt_pk_bf16_f32 v7, v2, v3
	global_store_dwordx4 v[16:17], v[4:7], off offset:256 sc1
	s_cbranch_vccnz .LBB0_168
	s_andn2_b64 vcc, exec, s[6:7]
	s_cbranch_vccnz .LBB0_167
	s_barrier
	s_branch .LBB0_167

; __device__ __forceinline__ unsigned cvt_pk_bf16(float lo, float hi) { unsigned r; asm volatile("v_cvt_pk_bf16_f32 %0, %1, %2" : "=v"(r) : "v"(lo), "v"(hi)); return r; }
; __device__ __forceinline__ float sigmoidf_(float x) { return 1.f / (1.f + __expf(-x)); }
; __device__ __forceinline__ void unpack8(const u32x4& w, float (&f)[8]) { f[0] = bflo(w.x); f[1] = bfhi(w.x); f[2] = bflo(w.y); f[3] = bfhi(w.y); f[4] = bflo(w.z); f[5] = bfhi(w.z); f[6] = bflo(w.w); f[7] = bfhi(w.w); }
;     __device__ __forceinline__ void operator()(const f32x4 (&acc)[2][2][4][2], const Unit& u, int wr, int wc, int fr, int fq) const {
;     ...
;         for (int ai = 0; ai < 2; ++ai) { u32x4 gw[4][2];
; #pragma unroll
;             for (int m = 0; m < 4; ++m)
; #pragma unroll
;                 for (int bj = 0; bj < 2; ++bj) gw[m][bj] = *(const u32x4*)(gate + (size_t)(row0 + ai * HALF + m * 16) * ldg + col0 + bj * HALF);
; #pragma unroll
;             for (int m = 0; m < 4; ++m)
; #pragma unroll
;                 for (int bj = 0; bj < 2; ++bj) { float g[8]; unpack8(gw[m][bj], g); const f32x4 a0 = acc[ai][bj][m][0], a1 = acc[ai][bj][m][1]; float o[8];
; #pragma unroll
;                     for (int e = 0; e < 4; ++e) { o[e] = a0[e] * sigmoidf_(g[e]); o[4 + e] = a1[e] * sigmoidf_(g[4 + e]); }
;                     *(u32x4*)(T + (size_t)(row0 + ai * HALF + m * 16) * DM + col0 + bj * HALF) = (u32x4){cvt_pk_bf16(o[0], o[1]), cvt_pk_bf16(o[2], o[3]), cvt_pk_bf16(o[4], o[5]), cvt_pk_bf16(o[6], o[7])}; } }
.LBB0_672:
	v_lshl_or_b32 v104, s43, 8, v199
	v_ashrrev_i32_e32 v105, 31, v104
	v_lshlrev_b64 v[164:165], 1, v[104:105]
	v_lshl_add_u32 v166, s42, 8, v185
	v_lshl_add_u64 v[168:169], s[16:17], 0, v[164:165]
	v_mad_i64_i32 v[104:105], s[0:1], v166, s39, v[168:169]
	global_load_dwordx4 v[204:207], v[104:105], off nt
	v_or_b32_e32 v174, 16, v166
	v_or_b32_e32 v172, 32, v166
	v_or_b32_e32 v170, 48, v166
	v_mad_i64_i32 v[106:107], s[0:1], v174, s39, v[168:169]
	v_mad_i64_i32 v[116:117], s[0:1], v172, s39, v[168:169]
	v_mad_i64_i32 v[210:211], s[0:1], v170, s39, v[168:169]
	global_load_dwordx4 v[152:155], v[104:105], off offset:256 nt
	global_load_dwordx4 v[148:151], v[106:107], off nt
	global_load_dwordx4 v[144:147], v[106:107], off offset:256 nt
	global_load_dwordx4 v[140:143], v[116:117], off nt
	global_load_dwordx4 v[128:131], v[116:117], off offset:256 nt
	s_nop 0
	global_load_dwordx4 v[116:119], v[210:211], off nt
	global_load_dwordx4 v[104:107], v[210:211], off offset:256 nt
	v_ashrrev_i32_e32 v167, 31, v166
	v_lshlrev_b64 v[208:209], 12, v[166:167]
	v_ashrrev_i32_e32 v175, 31, v174
	v_ashrrev_i32_e32 v173, 31, v172
	v_ashrrev_i32_e32 v171, 31, v170
	s_waitcnt vmcnt(0)
	v_lshlrev_b32_e32 v167, 16, v204
	v_lshlrev_b32_e32 v210, 16, v206
	v_mul_f32_e32 v167, 0xbfb8aa3b, v167
	v_and_b32_e32 v203, 0xffff0000, v204
	v_mul_f32_e32 v210, 0xbfb8aa3b, v210
	v_exp_f32_e32 v167, v167
	v_mul_f32_e32 v203, 0xbfb8aa3b, v203
	v_exp_f32_e32 v210, v210
	v_exp_f32_e32 v203, v203
	v_add_f32_e32 v167, 1.0, v167
	v_and_b32_e32 v206, 0xffff0000, v206
	v_add_f32_e32 v210, 1.0, v210
	v_div_scale_f32 v212, s[0:1], v167, v167, 1.0
	v_mul_f32_e32 v206, 0xbfb8aa3b, v206
	v_add_f32_e32 v203, 1.0, v203
	v_div_scale_f32 v214, s[0:1], v210, v210, 1.0
	v_rcp_f32_e32 v220, v212
	v_exp_f32_e32 v206, v206
	v_div_scale_f32 v216, s[6:7], v203, v203, 1.0
	v_rcp_f32_e32 v221, v214
	v_rcp_f32_e32 v224, v216
	v_fma_f32 v226, -v212, v220, 1.0
	v_add_f32_e32 v206, 1.0, v206
	v_div_scale_f32 v213, vcc, 1.0, v167, 1.0
	v_fma_f32 v227, -v214, v221, 1.0
	v_fmac_f32_e32 v220, v226, v220
	v_div_scale_f32 v215, s[0:1], 1.0, v210, 1.0
	v_div_scale_f32 v218, s[8:9], v206, v206, 1.0
	v_fma_f32 v228, -v216, v224, 1.0
	v_fmac_f32_e32 v221, v227, v221
	v_mul_f32_e32 v226, v213, v220
	v_lshlrev_b32_e32 v204, 16, v205
	v_div_scale_f32 v217, s[6:7], 1.0, v203, 1.0
	v_rcp_f32_e32 v225, v218
	v_fmac_f32_e32 v224, v228, v224
	v_mul_f32_e32 v227, v215, v221
	v_fma_f32 v230, -v212, v226, v213
	v_mul_f32_e32 v204, 0xbfb8aa3b, v204
	v_mul_f32_e32 v228, v217, v224
	v_fma_f32 v231, -v214, v227, v215
	v_fmac_f32_e32 v226, v230, v220
	v_exp_f32_e32 v204, v204
	v_fma_f32 v232, -v216, v228, v217
	v_fmac_f32_e32 v227, v231, v221
	v_fma_f32 v212, -v212, v226, v213
	v_fmac_f32_e32 v228, v232, v224
	v_fma_f32 v213, -v214, v227, v215
	v_div_fmas_f32 v212, v212, v220, v226
	s_mov_b64 vcc, s[0:1]
	v_fma_f32 v229, -v218, v225, 1.0
	v_fma_f32 v214, -v216, v228, v217
	v_div_fixup_f32 v167, v212, v167, 1.0
	v_div_fmas_f32 v212, v213, v221, v227
	s_mov_b64 vcc, s[6:7]
	v_div_scale_f32 v219, s[8:9], 1.0, v206, 1.0
	v_fmac_f32_e32 v225, v229, v225
	v_mul_f32_e32 v136, v136, v167
	v_div_fixup_f32 v167, v212, v210, 1.0
	v_div_fmas_f32 v210, v214, v224, v228
	v_add_f32_e32 v204, 1.0, v204
	v_mul_f32_e32 v229, v219, v225
	v_mul_f32_e32 v167, v132, v167
	v_div_fixup_f32 v132, v210, v203, 1.0
	v_fma_f32 v233, -v218, v229, v219
	v_mul_f32_e32 v132, v137, v132
	v_div_scale_f32 v137, s[0:1], v204, v204, 1.0
	v_fmac_f32_e32 v229, v233, v225
	v_rcp_f32_e32 v203, v137
	v_fma_f32 v215, -v218, v229, v219
	s_mov_b64 vcc, s[8:9]
	v_div_fmas_f32 v210, v215, v225, v229
	v_lshlrev_b32_e32 v211, 16, v207
	v_div_fixup_f32 v206, v210, v206, 1.0
	v_mul_f32_e32 v206, v133, v206
	v_fma_f32 v133, -v137, v203, 1.0
	v_mul_f32_e32 v211, 0xbfb8aa3b, v211
	v_fmac_f32_e32 v203, v133, v203
	v_div_scale_f32 v133, vcc, 1.0, v204, 1.0
	v_exp_f32_e32 v211, v211
	v_mul_f32_e32 v210, v133, v203
	v_fma_f32 v212, -v137, v210, v133
	v_fmac_f32_e32 v210, v212, v203
	v_fma_f32 v133, -v137, v210, v133
	v_add_f32_e32 v137, 1.0, v211
	v_div_scale_f32 v211, s[0:1], v137, v137, 1.0
	v_rcp_f32_e32 v212, v211
	v_and_b32_e32 v205, 0xffff0000, v205
	v_div_fmas_f32 v133, v133, v203, v210
	v_div_fixup_f32 v133, v133, v204, 1.0
	v_mul_f32_e32 v204, 0xbfb8aa3b, v205
	v_exp_f32_e32 v204, v204
	v_mul_f32_e32 v133, v138, v133
	v_fma_f32 v138, -v211, v212, 1.0
	v_fmac_f32_e32 v212, v138, v212
	v_div_scale_f32 v138, vcc, 1.0, v137, 1.0
	v_mul_f32_e32 v203, v138, v212
	v_fma_f32 v205, -v211, v203, v138
	v_add_f32_e32 v204, 1.0, v204
	v_fmac_f32_e32 v203, v205, v212
	v_div_scale_f32 v205, s[0:1], v204, v204, 1.0
	v_rcp_f32_e32 v210, v205
	v_fma_f32 v138, -v211, v203, v138
	v_and_b32_e32 v207, 0xffff0000, v207
	v_div_fmas_f32 v138, v138, v212, v203
	v_div_fixup_f32 v137, v138, v137, 1.0
	v_mul_f32_e32 v203, 0xbfb8aa3b, v207
	v_mul_f32_e32 v137, v134, v137
	v_fma_f32 v134, -v205, v210, 1.0
	v_exp_f32_e32 v203, v203
	v_fmac_f32_e32 v210, v134, v210
	v_div_scale_f32 v134, vcc, 1.0, v204, 1.0
	v_mul_f32_e32 v138, v134, v210
	v_fma_f32 v207, -v205, v138, v134
	v_fmac_f32_e32 v138, v207, v210
	v_add_f32_e32 v203, 1.0, v203
	v_fma_f32 v134, -v205, v138, v134
	v_div_scale_f32 v205, s[0:1], v203, v203, 1.0
	v_rcp_f32_e32 v207, v205
	v_div_fmas_f32 v134, v134, v210, v138
	v_div_fixup_f32 v134, v134, v204, 1.0
	v_mul_f32_e32 v134, v139, v134
	v_fma_f32 v138, -v205, v207, 1.0
	v_fmac_f32_e32 v207, v138, v207
	v_div_scale_f32 v138, vcc, 1.0, v203, 1.0
	v_mul_f32_e32 v139, v138, v207
	v_fma_f32 v204, -v205, v139, v138
	v_fmac_f32_e32 v139, v204, v207
	v_fma_f32 v138, -v205, v139, v138
; __device__ __forceinline__ unsigned cvt_pk_bf16(float lo, float hi) { unsigned r; asm volatile("v_cvt_pk_bf16_f32 %0, %1, %2" : "=v"(r) : "v"(lo), "v"(hi)); return r; }
; __device__ __forceinline__ float sigmoidf_(float x) { return 1.f / (1.f + __expf(-x)); }
; __device__ __forceinline__ void unpack8(const u32x4& w, float (&f)[8]) { f[0] = bflo(w.x); f[1] = bfhi(w.x); f[2] = bflo(w.y); f[3] = bfhi(w.y); f[4] = bflo(w.z); f[5] = bfhi(w.z); f[6] = bflo(w.w); f[7] = bfhi(w.w); }
;     __device__ __forceinline__ void operator()(const f32x4 (&acc)[2][2][4][2], const Unit& u, int wr, int wc, int fr, int fq) const {
;     ...
;             for (int m = 0; m < 4; ++m)
; #pragma unroll
;                 for (int bj = 0; bj < 2; ++bj) { float g[8]; unpack8(gw[m][bj], g); const f32x4 a0 = acc[ai][bj][m][0], a1 = acc[ai][bj][m][1]; float o[8];
; #pragma unroll
;                     for (int e = 0; e < 4; ++e) { o[e] = a0[e] * sigmoidf_(g[e]); o[4 + e] = a1[e] * sigmoidf_(g[4 + e]); }
;                     *(u32x4*)(T + (size_t)(row0 + ai * HALF + m * 16) * DM + col0 + bj * HALF) = (u32x4){cvt_pk_bf16(o[0], o[1]), cvt_pk_bf16(o[2], o[3]), cvt_pk_bf16(o[4], o[5]), cvt_pk_bf16(o[6], o[7])}; } }
	v_div_fmas_f32 v138, v138, v207, v139
	v_div_fixup_f32 v138, v138, v203, 1.0
	v_mul_f32_e32 v135, v135, v138
	v_cvt_pk_bf16_f32 v132, v136, v132
	v_cvt_pk_bf16_f32 v133, v133, v134
	v_cvt_pk_bf16_f32 v134, v167, v206
	v_cvt_pk_bf16_f32 v135, v137, v135
	v_lshl_add_u64 v[136:137], s[84:85], 0, v[208:209]
	v_lshl_add_u64 v[136:137], v[136:137], 0, v[164:165]
	global_store_dwordx4 v[136:137], v[132:135], off sc1
	v_lshlrev_b32_e32 v138, 16, v154
	v_mul_f32_e32 v138, 0xbfb8aa3b, v138
	v_lshlrev_b32_e32 v132, 16, v152
	v_mul_f32_e32 v132, 0xbfb8aa3b, v132
	v_exp_f32_e32 v132, v132
	v_and_b32_e32 v133, 0xffff0000, v152
	v_exp_f32_e32 v138, v138
	v_mul_f32_e32 v133, 0xbfb8aa3b, v133
	v_add_f32_e32 v132, 1.0, v132
	v_div_scale_f32 v139, s[0:1], v132, v132, 1.0
	v_rcp_f32_e32 v152, v139
	v_add_f32_e32 v138, 1.0, v138
	v_exp_f32_e32 v133, v133
	v_lshlrev_b32_e32 v134, 16, v153
	v_fma_f32 v167, -v139, v152, 1.0
	v_fmac_f32_e32 v152, v167, v152
	v_div_scale_f32 v167, vcc, 1.0, v132, 1.0
	v_mul_f32_e32 v203, v167, v152
	v_fma_f32 v204, -v139, v203, v167
	v_fmac_f32_e32 v203, v204, v152
	v_fma_f32 v139, -v139, v203, v167
	v_div_scale_f32 v167, s[0:1], v138, v138, 1.0
	v_rcp_f32_e32 v204, v167
	v_div_fmas_f32 v139, v139, v152, v203
	v_div_fixup_f32 v132, v139, v132, 1.0
	v_mul_f32_e32 v124, v124, v132
	v_fma_f32 v132, -v167, v204, 1.0
	v_fmac_f32_e32 v204, v132, v204
	v_div_scale_f32 v132, vcc, 1.0, v138, 1.0
	v_mul_f32_e32 v139, v132, v204
	v_fma_f32 v152, -v167, v139, v132
	v_add_f32_e32 v133, 1.0, v133
	v_fmac_f32_e32 v139, v152, v204
	v_div_scale_f32 v152, s[0:1], v133, v133, 1.0
	v_fma_f32 v132, -v167, v139, v132
	v_rcp_f32_e32 v167, v152
	v_and_b32_e32 v135, 0xffff0000, v153
	v_and_b32_e32 v153, 0xffff0000, v154
	v_div_fmas_f32 v132, v132, v204, v139
	v_div_fixup_f32 v132, v132, v138, 1.0
	v_mul_f32_e32 v139, 0xbfb8aa3b, v153
	v_mul_f32_e32 v132, v120, v132
	v_fma_f32 v120, -v152, v167, 1.0
	v_exp_f32_e32 v139, v139
	v_fmac_f32_e32 v167, v120, v167
	v_div_scale_f32 v120, vcc, 1.0, v133, 1.0
	v_mul_f32_e32 v138, v120, v167
	v_fma_f32 v153, -v152, v138, v120
	v_fmac_f32_e32 v138, v153, v167
	v_add_f32_e32 v139, 1.0, v139
	v_fma_f32 v120, -v152, v138, v120
	v_div_scale_f32 v152, s[0:1], v139, v139, 1.0
	v_rcp_f32_e32 v153, v152
	v_div_fmas_f32 v120, v120, v167, v138
	v_mul_f32_e32 v134, 0xbfb8aa3b, v134
	v_div_fixup_f32 v120, v120, v133, 1.0
	v_exp_f32_e32 v134, v134
	v_mul_f32_e32 v120, v125, v120
	v_fma_f32 v125, -v152, v153, 1.0
	v_fmac_f32_e32 v153, v125, v153
	v_div_scale_f32 v125, vcc, 1.0, v139, 1.0
	v_mul_f32_e32 v133, v125, v153
	v_fma_f32 v138, -v152, v133, v125
	v_add_f32_e32 v134, 1.0, v134
	v_fmac_f32_e32 v133, v138, v153
	v_div_scale_f32 v138, s[0:1], v134, v134, 1.0
	v_fma_f32 v125, -v152, v133, v125
	v_rcp_f32_e32 v152, v138
	v_div_fmas_f32 v125, v125, v153, v133
	v_lshlrev_b32_e32 v154, 16, v155
	v_div_fixup_f32 v125, v125, v139, 1.0
	v_mul_f32_e32 v125, v121, v125
	v_fma_f32 v121, -v138, v152, 1.0
	v_mul_f32_e32 v139, 0xbfb8aa3b, v154
	v_fmac_f32_e32 v152, v121, v152
	v_div_scale_f32 v121, vcc, 1.0, v134, 1.0
	v_exp_f32_e32 v139, v139
	v_mul_f32_e32 v133, v121, v152
	v_fma_f32 v153, -v138, v133, v121
	v_fmac_f32_e32 v133, v153, v152
	v_fma_f32 v121, -v138, v133, v121
	v_add_f32_e32 v138, 1.0, v139
	v_div_scale_f32 v139, s[0:1], v138, v138, 1.0
	v_rcp_f32_e32 v153, v139
	v_div_fmas_f32 v121, v121, v152, v133
	v_div_fixup_f32 v121, v121, v134, 1.0
	v_mul_f32_e32 v134, 0xbfb8aa3b, v135
	v_exp_f32_e32 v134, v134
	v_mul_f32_e32 v121, v126, v121
	v_fma_f32 v126, -v139, v153, 1.0
	v_fmac_f32_e32 v153, v126, v153
	v_div_scale_f32 v126, vcc, 1.0, v138, 1.0
	v_mul_f32_e32 v133, v126, v153
	v_fma_f32 v135, -v139, v133, v126
	v_add_f32_e32 v134, 1.0, v134
	v_fmac_f32_e32 v133, v135, v153
	v_div_scale_f32 v135, s[0:1], v134, v134, 1.0
	v_fma_f32 v126, -v139, v133, v126
	v_rcp_f32_e32 v139, v135
	v_div_fmas_f32 v126, v126, v153, v133
	v_and_b32_e32 v155, 0xffff0000, v155
	v_div_fixup_f32 v126, v126, v138, 1.0
	v_mul_f32_e32 v126, v122, v126
	v_fma_f32 v122, -v135, v139, 1.0
	v_mul_f32_e32 v138, 0xbfb8aa3b, v155
	v_fmac_f32_e32 v139, v122, v139
	v_div_scale_f32 v122, vcc, 1.0, v134, 1.0
	v_exp_f32_e32 v138, v138
	v_mul_f32_e32 v133, v122, v139
	v_fma_f32 v152, -v135, v133, v122
	v_fmac_f32_e32 v133, v152, v139
	v_fma_f32 v122, -v135, v133, v122
	v_add_f32_e32 v135, 1.0, v138
	v_div_scale_f32 v138, s[0:1], v135, v135, 1.0
	v_rcp_f32_e32 v152, v138
	v_div_fmas_f32 v122, v122, v139, v133
	v_div_fixup_f32 v122, v122, v134, 1.0
	v_mul_f32_e32 v122, v127, v122
	v_fma_f32 v127, -v138, v152, 1.0
	v_fmac_f32_e32 v152, v127, v152
	v_div_scale_f32 v127, vcc, 1.0, v135, 1.0
	v_mul_f32_e32 v133, v127, v152
	v_fma_f32 v134, -v138, v133, v127
	v_fmac_f32_e32 v133, v134, v152
	v_fma_f32 v127, -v138, v133, v127
	v_div_fmas_f32 v127, v127, v152, v133
	v_div_fixup_f32 v127, v127, v135, 1.0
	v_mul_f32_e32 v123, v123, v127
	v_cvt_pk_bf16_f32 v120, v124, v120
	v_cvt_pk_bf16_f32 v121, v121, v122
	v_cvt_pk_bf16_f32 v122, v132, v125
	v_cvt_pk_bf16_f32 v123, v126, v123
	global_store_dwordx4 v[136:137], v[120:123], off offset:256 sc1
	v_lshlrev_b32_e32 v126, 16, v150
	v_mul_f32_e32 v126, 0xbfb8aa3b, v126
	v_lshlrev_b32_e32 v122, 16, v148
	v_mul_f32_e32 v122, 0xbfb8aa3b, v122
	v_exp_f32_e32 v122, v122
	v_exp_f32_e32 v126, v126
	v_and_b32_e32 v123, 0xffff0000, v148
	v_mul_f32_e32 v123, 0xbfb8aa3b, v123
	v_add_f32_e32 v122, 1.0, v122
	v_div_scale_f32 v127, s[0:1], v122, v122, 1.0
	v_rcp_f32_e32 v132, v127
	v_add_f32_e32 v126, 1.0, v126
	v_exp_f32_e32 v123, v123
	v_and_b32_e32 v133, 0xffff0000, v150
	v_fma_f32 v136, -v127, v132, 1.0
	v_fmac_f32_e32 v132, v136, v132
; __device__ __forceinline__ unsigned cvt_pk_bf16(float lo, float hi) { unsigned r; asm volatile("v_cvt_pk_bf16_f32 %0, %1, %2" : "=v"(r) : "v"(lo), "v"(hi)); return r; }
; __device__ __forceinline__ float sigmoidf_(float x) { return 1.f / (1.f + __expf(-x)); }
; __device__ __forceinline__ void unpack8(const u32x4& w, float (&f)[8]) { f[0] = bflo(w.x); f[1] = bfhi(w.x); f[2] = bflo(w.y); f[3] = bfhi(w.y); f[4] = bflo(w.z); f[5] = bfhi(w.z); f[6] = bflo(w.w); f[7] = bfhi(w.w); }
;     __device__ __forceinline__ void operator()(const f32x4 (&acc)[2][2][4][2], const Unit& u, int wr, int wc, int fr, int fq) const {
;     ...
;             for (int m = 0; m < 4; ++m)
; #pragma unroll
;                 for (int bj = 0; bj < 2; ++bj) { float g[8]; unpack8(gw[m][bj], g); const f32x4 a0 = acc[ai][bj][m][0], a1 = acc[ai][bj][m][1]; float o[8];
; #pragma unroll
;                     for (int e = 0; e < 4; ++e) { o[e] = a0[e] * sigmoidf_(g[e]); o[4 + e] = a1[e] * sigmoidf_(g[4 + e]); }
;                     *(u32x4*)(T + (size_t)(row0 + ai * HALF + m * 16) * DM + col0 + bj * HALF) = (u32x4){cvt_pk_bf16(o[0], o[1]), cvt_pk_bf16(o[2], o[3]), cvt_pk_bf16(o[4], o[5]), cvt_pk_bf16(o[6], o[7])}; } }
	v_div_scale_f32 v136, vcc, 1.0, v122, 1.0
	v_mul_f32_e32 v137, v136, v132
	v_fma_f32 v138, -v127, v137, v136
	v_fmac_f32_e32 v137, v138, v132
	v_fma_f32 v127, -v127, v137, v136
	v_div_scale_f32 v136, s[0:1], v126, v126, 1.0
	v_rcp_f32_e32 v138, v136
	v_div_fmas_f32 v127, v127, v132, v137
	v_div_fixup_f32 v122, v127, v122, 1.0
	v_mul_f32_e32 v112, v112, v122
	v_fma_f32 v122, -v136, v138, 1.0
	v_fmac_f32_e32 v138, v122, v138
	v_div_scale_f32 v122, vcc, 1.0, v126, 1.0
	v_mul_f32_e32 v127, v122, v138
	v_fma_f32 v132, -v136, v127, v122
	v_add_f32_e32 v123, 1.0, v123
	v_fmac_f32_e32 v127, v132, v138
	v_div_scale_f32 v132, s[0:1], v123, v123, 1.0
	v_fma_f32 v122, -v136, v127, v122
	v_rcp_f32_e32 v136, v132
	v_div_fmas_f32 v122, v122, v138, v127
	v_div_fixup_f32 v122, v122, v126, 1.0
	v_mul_f32_e32 v127, 0xbfb8aa3b, v133
	v_mul_f32_e32 v122, v108, v122
	v_fma_f32 v108, -v132, v136, 1.0
	v_exp_f32_e32 v127, v127
	v_fmac_f32_e32 v136, v108, v136
	v_div_scale_f32 v108, vcc, 1.0, v123, 1.0
	v_mul_f32_e32 v126, v108, v136
	v_fma_f32 v133, -v132, v126, v108
	v_fmac_f32_e32 v126, v133, v136
	v_add_f32_e32 v127, 1.0, v127
	v_fma_f32 v108, -v132, v126, v108
	v_div_scale_f32 v132, s[0:1], v127, v127, 1.0
	v_rcp_f32_e32 v133, v132
	v_lshlrev_b32_e32 v124, 16, v149
	v_div_fmas_f32 v108, v108, v136, v126
	v_mul_f32_e32 v124, 0xbfb8aa3b, v124
	v_div_fixup_f32 v108, v108, v123, 1.0
	v_exp_f32_e32 v124, v124
	v_mul_f32_e32 v108, v113, v108
	v_fma_f32 v113, -v132, v133, 1.0
	v_fmac_f32_e32 v133, v113, v133
	v_div_scale_f32 v113, vcc, 1.0, v127, 1.0
	v_mul_f32_e32 v123, v113, v133
	v_fma_f32 v126, -v132, v123, v113
	v_add_f32_e32 v124, 1.0, v124
	v_fmac_f32_e32 v123, v126, v133
	v_div_scale_f32 v126, s[0:1], v124, v124, 1.0
	v_fma_f32 v113, -v132, v123, v113
	v_rcp_f32_e32 v132, v126
	v_div_fmas_f32 v113, v113, v133, v123
	v_lshlrev_b32_e32 v134, 16, v151
	v_div_fixup_f32 v113, v113, v127, 1.0
	v_mul_f32_e32 v113, v109, v113
	v_fma_f32 v109, -v126, v132, 1.0
	v_mul_f32_e32 v127, 0xbfb8aa3b, v134
	v_fmac_f32_e32 v132, v109, v132
	v_div_scale_f32 v109, vcc, 1.0, v124, 1.0
	v_exp_f32_e32 v127, v127
	v_mul_f32_e32 v123, v109, v132
	v_fma_f32 v133, -v126, v123, v109
	v_fmac_f32_e32 v123, v133, v132
	v_fma_f32 v109, -v126, v123, v109
	v_add_f32_e32 v126, 1.0, v127
	v_div_scale_f32 v127, s[0:1], v126, v126, 1.0
	v_rcp_f32_e32 v133, v127
	v_and_b32_e32 v125, 0xffff0000, v149
	v_div_fmas_f32 v109, v109, v132, v123
	v_div_fixup_f32 v109, v109, v124, 1.0
	v_mul_f32_e32 v124, 0xbfb8aa3b, v125
	v_exp_f32_e32 v124, v124
	v_mul_f32_e32 v109, v114, v109
	v_fma_f32 v114, -v127, v133, 1.0
	v_fmac_f32_e32 v133, v114, v133
	v_div_scale_f32 v114, vcc, 1.0, v126, 1.0
	v_mul_f32_e32 v123, v114, v133
	v_fma_f32 v125, -v127, v123, v114
	v_add_f32_e32 v124, 1.0, v124
	v_fmac_f32_e32 v123, v125, v133
	v_div_scale_f32 v125, s[0:1], v124, v124, 1.0
	v_fma_f32 v114, -v127, v123, v114
	v_rcp_f32_e32 v127, v125
	v_div_fmas_f32 v114, v114, v133, v123
	v_and_b32_e32 v135, 0xffff0000, v151
	v_div_fixup_f32 v114, v114, v126, 1.0
	v_mul_f32_e32 v114, v110, v114
	v_fma_f32 v110, -v125, v127, 1.0
	v_mul_f32_e32 v126, 0xbfb8aa3b, v135
	v_fmac_f32_e32 v127, v110, v127
	v_div_scale_f32 v110, vcc, 1.0, v124, 1.0
	v_exp_f32_e32 v126, v126
	v_mul_f32_e32 v123, v110, v127
	v_fma_f32 v132, -v125, v123, v110
	v_fmac_f32_e32 v123, v132, v127
	v_fma_f32 v110, -v125, v123, v110
	v_add_f32_e32 v125, 1.0, v126
	v_div_scale_f32 v126, s[0:1], v125, v125, 1.0
	v_rcp_f32_e32 v132, v126
	v_div_fmas_f32 v110, v110, v127, v123
	v_div_fixup_f32 v110, v110, v124, 1.0
	v_mul_f32_e32 v110, v115, v110
	v_fma_f32 v115, -v126, v132, 1.0
	v_fmac_f32_e32 v132, v115, v132
	v_div_scale_f32 v115, vcc, 1.0, v125, 1.0
	v_mul_f32_e32 v123, v115, v132
	v_fma_f32 v124, -v126, v123, v115
	v_fmac_f32_e32 v123, v124, v132
	v_fma_f32 v115, -v126, v123, v115
	v_lshlrev_b64 v[120:121], 12, v[174:175]
	v_div_fmas_f32 v115, v115, v132, v123
	v_div_fixup_f32 v115, v115, v125, 1.0
	v_cvt_pk_bf16_f32 v108, v112, v108
	v_cvt_pk_bf16_f32 v109, v109, v110
	v_cvt_pk_bf16_f32 v110, v122, v113
	v_lshl_add_u64 v[112:113], s[84:85], 0, v[120:121]
	v_mul_f32_e32 v111, v111, v115
	v_lshl_add_u64 v[112:113], v[112:113], 0, v[164:165]
	v_cvt_pk_bf16_f32 v111, v114, v111
	global_store_dwordx4 v[112:113], v[108:111], off sc1
	v_lshlrev_b32_e32 v114, 16, v146
	v_mul_f32_e32 v114, 0xbfb8aa3b, v114
	v_lshlrev_b32_e32 v108, 16, v144
	v_mul_f32_e32 v108, 0xbfb8aa3b, v108
	v_exp_f32_e32 v108, v108
	v_exp_f32_e32 v114, v114
	v_and_b32_e32 v109, 0xffff0000, v144
	v_mul_f32_e32 v109, 0xbfb8aa3b, v109
	v_add_f32_e32 v108, 1.0, v108
	v_div_scale_f32 v115, s[0:1], v108, v108, 1.0
	v_rcp_f32_e32 v120, v115
	v_add_f32_e32 v114, 1.0, v114
	v_exp_f32_e32 v109, v109
	v_and_b32_e32 v121, 0xffff0000, v146
	v_fma_f32 v124, -v115, v120, 1.0
	v_fmac_f32_e32 v120, v124, v120
	v_div_scale_f32 v124, vcc, 1.0, v108, 1.0
	v_mul_f32_e32 v125, v124, v120
	v_fma_f32 v126, -v115, v125, v124
	v_fmac_f32_e32 v125, v126, v120
	v_fma_f32 v115, -v115, v125, v124
	v_div_scale_f32 v124, s[0:1], v114, v114, 1.0
	v_rcp_f32_e32 v126, v124
	v_div_fmas_f32 v115, v115, v120, v125
	v_div_fixup_f32 v108, v115, v108, 1.0
	v_mul_f32_e32 v100, v100, v108
	v_fma_f32 v108, -v124, v126, 1.0
	v_fmac_f32_e32 v126, v108, v126
	v_div_scale_f32 v108, vcc, 1.0, v114, 1.0
	v_mul_f32_e32 v115, v108, v126
	v_fma_f32 v120, -v124, v115, v108
	v_add_f32_e32 v109, 1.0, v109
	v_fmac_f32_e32 v115, v120, v126
	v_div_scale_f32 v120, s[0:1], v109, v109, 1.0
	v_fma_f32 v108, -v124, v115, v108
	v_rcp_f32_e32 v124, v120
	v_div_fmas_f32 v108, v108, v126, v115
	v_div_fixup_f32 v108, v108, v114, 1.0
	v_mul_f32_e32 v115, 0xbfb8aa3b, v121
; __device__ __forceinline__ unsigned cvt_pk_bf16(float lo, float hi) { unsigned r; asm volatile("v_cvt_pk_bf16_f32 %0, %1, %2" : "=v"(r) : "v"(lo), "v"(hi)); return r; }
; __device__ __forceinline__ float sigmoidf_(float x) { return 1.f / (1.f + __expf(-x)); }
; __device__ __forceinline__ void unpack8(const u32x4& w, float (&f)[8]) { f[0] = bflo(w.x); f[1] = bfhi(w.x); f[2] = bflo(w.y); f[3] = bfhi(w.y); f[4] = bflo(w.z); f[5] = bfhi(w.z); f[6] = bflo(w.w); f[7] = bfhi(w.w); }
;     __device__ __forceinline__ void operator()(const f32x4 (&acc)[2][2][4][2], const Unit& u, int wr, int wc, int fr, int fq) const {
;     ...
;                 for (int bj = 0; bj < 2; ++bj) { float g[8]; unpack8(gw[m][bj], g); const f32x4 a0 = acc[ai][bj][m][0], a1 = acc[ai][bj][m][1]; float o[8];
; #pragma unroll
;                     for (int e = 0; e < 4; ++e) { o[e] = a0[e] * sigmoidf_(g[e]); o[4 + e] = a1[e] * sigmoidf_(g[4 + e]); }
;                     *(u32x4*)(T + (size_t)(row0 + ai * HALF + m * 16) * DM + col0 + bj * HALF) = (u32x4){cvt_pk_bf16(o[0], o[1]), cvt_pk_bf16(o[2], o[3]), cvt_pk_bf16(o[4], o[5]), cvt_pk_bf16(o[6], o[7])}; } }
	v_mul_f32_e32 v108, v96, v108
	v_fma_f32 v96, -v120, v124, 1.0
	v_exp_f32_e32 v115, v115
	v_fmac_f32_e32 v124, v96, v124
	v_div_scale_f32 v96, vcc, 1.0, v109, 1.0
	v_mul_f32_e32 v114, v96, v124
	v_fma_f32 v121, -v120, v114, v96
	v_fmac_f32_e32 v114, v121, v124
	v_add_f32_e32 v115, 1.0, v115
	v_fma_f32 v96, -v120, v114, v96
	v_div_scale_f32 v120, s[0:1], v115, v115, 1.0
	v_rcp_f32_e32 v121, v120
	v_lshlrev_b32_e32 v110, 16, v145
	v_div_fmas_f32 v96, v96, v124, v114
	v_mul_f32_e32 v110, 0xbfb8aa3b, v110
	v_div_fixup_f32 v96, v96, v109, 1.0
	v_exp_f32_e32 v110, v110
	v_mul_f32_e32 v96, v101, v96
	v_fma_f32 v101, -v120, v121, 1.0
	v_fmac_f32_e32 v121, v101, v121
	v_div_scale_f32 v101, vcc, 1.0, v115, 1.0
	v_mul_f32_e32 v109, v101, v121
	v_fma_f32 v114, -v120, v109, v101
	v_add_f32_e32 v110, 1.0, v110
	v_fmac_f32_e32 v109, v114, v121
	v_div_scale_f32 v114, s[0:1], v110, v110, 1.0
	v_fma_f32 v101, -v120, v109, v101
	v_rcp_f32_e32 v120, v114
	v_div_fmas_f32 v101, v101, v121, v109
	v_lshlrev_b32_e32 v122, 16, v147
	v_div_fixup_f32 v101, v101, v115, 1.0
	v_mul_f32_e32 v101, v97, v101
	v_fma_f32 v97, -v114, v120, 1.0
	v_mul_f32_e32 v115, 0xbfb8aa3b, v122
	v_fmac_f32_e32 v120, v97, v120
	v_div_scale_f32 v97, vcc, 1.0, v110, 1.0
	v_exp_f32_e32 v115, v115
	v_mul_f32_e32 v109, v97, v120
	v_fma_f32 v121, -v114, v109, v97
	v_fmac_f32_e32 v109, v121, v120
	v_fma_f32 v97, -v114, v109, v97
	v_add_f32_e32 v114, 1.0, v115
	v_div_scale_f32 v115, s[0:1], v114, v114, 1.0
	v_rcp_f32_e32 v121, v115
	v_and_b32_e32 v111, 0xffff0000, v145
	v_div_fmas_f32 v97, v97, v120, v109
	v_div_fixup_f32 v97, v97, v110, 1.0
	v_mul_f32_e32 v110, 0xbfb8aa3b, v111
	v_exp_f32_e32 v110, v110
	v_mul_f32_e32 v97, v102, v97
	v_fma_f32 v102, -v115, v121, 1.0
	v_fmac_f32_e32 v121, v102, v121
	v_div_scale_f32 v102, vcc, 1.0, v114, 1.0
	v_mul_f32_e32 v109, v102, v121
	v_fma_f32 v111, -v115, v109, v102
	v_add_f32_e32 v110, 1.0, v110
	v_fmac_f32_e32 v109, v111, v121
	v_div_scale_f32 v111, s[0:1], v110, v110, 1.0
	v_fma_f32 v102, -v115, v109, v102
	v_rcp_f32_e32 v115, v111
	v_div_fmas_f32 v102, v102, v121, v109
	v_and_b32_e32 v123, 0xffff0000, v147
	v_div_fixup_f32 v102, v102, v114, 1.0
	v_mul_f32_e32 v102, v98, v102
	v_fma_f32 v98, -v111, v115, 1.0
	v_mul_f32_e32 v114, 0xbfb8aa3b, v123
	v_fmac_f32_e32 v115, v98, v115
	v_div_scale_f32 v98, vcc, 1.0, v110, 1.0
	v_exp_f32_e32 v114, v114
	v_mul_f32_e32 v109, v98, v115
	v_fma_f32 v120, -v111, v109, v98
	v_fmac_f32_e32 v109, v120, v115
	v_fma_f32 v98, -v111, v109, v98
	v_add_f32_e32 v111, 1.0, v114
	v_div_scale_f32 v114, s[0:1], v111, v111, 1.0
	v_rcp_f32_e32 v120, v114
	v_div_fmas_f32 v98, v98, v115, v109
	v_div_fixup_f32 v98, v98, v110, 1.0
	v_mul_f32_e32 v98, v103, v98
	v_fma_f32 v103, -v114, v120, 1.0
	v_fmac_f32_e32 v120, v103, v120
	v_div_scale_f32 v103, vcc, 1.0, v111, 1.0
	v_mul_f32_e32 v109, v103, v120
	v_fma_f32 v110, -v114, v109, v103
	v_fmac_f32_e32 v109, v110, v120
	v_fma_f32 v103, -v114, v109, v103
	v_div_fmas_f32 v103, v103, v120, v109
	v_div_fixup_f32 v103, v103, v111, 1.0
	v_mul_f32_e32 v99, v99, v103
	v_cvt_pk_bf16_f32 v96, v100, v96
	v_cvt_pk_bf16_f32 v97, v97, v98
	v_cvt_pk_bf16_f32 v98, v108, v101
	v_cvt_pk_bf16_f32 v99, v102, v99
	global_store_dwordx4 v[112:113], v[96:99], off offset:256 sc1
	v_lshlrev_b32_e32 v102, 16, v142
	v_mul_f32_e32 v102, 0xbfb8aa3b, v102
	v_lshlrev_b32_e32 v98, 16, v140
	v_mul_f32_e32 v98, 0xbfb8aa3b, v98
	v_exp_f32_e32 v98, v98
	v_exp_f32_e32 v102, v102
	v_and_b32_e32 v99, 0xffff0000, v140
	v_mul_f32_e32 v99, 0xbfb8aa3b, v99
	v_add_f32_e32 v98, 1.0, v98
	v_div_scale_f32 v103, s[0:1], v98, v98, 1.0
	v_rcp_f32_e32 v108, v103
	v_add_f32_e32 v102, 1.0, v102
	v_exp_f32_e32 v99, v99
	v_and_b32_e32 v109, 0xffff0000, v142
	v_fma_f32 v112, -v103, v108, 1.0
	v_fmac_f32_e32 v108, v112, v108
	v_div_scale_f32 v112, vcc, 1.0, v98, 1.0
	v_mul_f32_e32 v113, v112, v108
	v_fma_f32 v114, -v103, v113, v112
	v_fmac_f32_e32 v113, v114, v108
	v_fma_f32 v103, -v103, v113, v112
	v_div_scale_f32 v112, s[0:1], v102, v102, 1.0
	v_rcp_f32_e32 v114, v112
	v_div_fmas_f32 v103, v103, v108, v113
	v_div_fixup_f32 v98, v103, v98, 1.0
	v_mul_f32_e32 v92, v92, v98
	v_fma_f32 v98, -v112, v114, 1.0
	v_fmac_f32_e32 v114, v98, v114
	v_div_scale_f32 v98, vcc, 1.0, v102, 1.0
	v_mul_f32_e32 v103, v98, v114
	v_fma_f32 v108, -v112, v103, v98
	v_add_f32_e32 v99, 1.0, v99
	v_fmac_f32_e32 v103, v108, v114
	v_div_scale_f32 v108, s[0:1], v99, v99, 1.0
	v_fma_f32 v98, -v112, v103, v98
	v_rcp_f32_e32 v112, v108
	v_div_fmas_f32 v98, v98, v114, v103
	v_div_fixup_f32 v98, v98, v102, 1.0
	v_mul_f32_e32 v103, 0xbfb8aa3b, v109
	v_mul_f32_e32 v98, v88, v98
	v_fma_f32 v88, -v108, v112, 1.0
	v_exp_f32_e32 v103, v103
	v_fmac_f32_e32 v112, v88, v112
	v_div_scale_f32 v88, vcc, 1.0, v99, 1.0
	v_mul_f32_e32 v102, v88, v112
	v_fma_f32 v109, -v108, v102, v88
	v_fmac_f32_e32 v102, v109, v112
	v_add_f32_e32 v103, 1.0, v103
	v_fma_f32 v88, -v108, v102, v88
	v_div_scale_f32 v108, s[0:1], v103, v103, 1.0
	v_rcp_f32_e32 v109, v108
	v_lshlrev_b32_e32 v100, 16, v141
	v_div_fmas_f32 v88, v88, v112, v102
	v_mul_f32_e32 v100, 0xbfb8aa3b, v100
	v_div_fixup_f32 v88, v88, v99, 1.0
	v_exp_f32_e32 v100, v100
	v_mul_f32_e32 v88, v93, v88
	v_fma_f32 v93, -v108, v109, 1.0
	v_fmac_f32_e32 v109, v93, v109
	v_div_scale_f32 v93, vcc, 1.0, v103, 1.0
	v_mul_f32_e32 v99, v93, v109
	v_fma_f32 v102, -v108, v99, v93
	v_add_f32_e32 v100, 1.0, v100
	v_fmac_f32_e32 v99, v102, v109
	v_div_scale_f32 v102, s[0:1], v100, v100, 1.0
	v_fma_f32 v93, -v108, v99, v93
	v_rcp_f32_e32 v108, v102
	v_div_fmas_f32 v93, v93, v109, v99
	v_lshlrev_b32_e32 v110, 16, v143
	v_div_fixup_f32 v93, v93, v103, 1.0
; __device__ __forceinline__ unsigned cvt_pk_bf16(float lo, float hi) { unsigned r; asm volatile("v_cvt_pk_bf16_f32 %0, %1, %2" : "=v"(r) : "v"(lo), "v"(hi)); return r; }
; __device__ __forceinline__ float sigmoidf_(float x) { return 1.f / (1.f + __expf(-x)); }
; __device__ __forceinline__ void unpack8(const u32x4& w, float (&f)[8]) { f[0] = bflo(w.x); f[1] = bfhi(w.x); f[2] = bflo(w.y); f[3] = bfhi(w.y); f[4] = bflo(w.z); f[5] = bfhi(w.z); f[6] = bflo(w.w); f[7] = bfhi(w.w); }
;     __device__ __forceinline__ void operator()(const f32x4 (&acc)[2][2][4][2], const Unit& u, int wr, int wc, int fr, int fq) const {
;     ...
;                 for (int bj = 0; bj < 2; ++bj) { float g[8]; unpack8(gw[m][bj], g); const f32x4 a0 = acc[ai][bj][m][0], a1 = acc[ai][bj][m][1]; float o[8];
; #pragma unroll
;                     for (int e = 0; e < 4; ++e) { o[e] = a0[e] * sigmoidf_(g[e]); o[4 + e] = a1[e] * sigmoidf_(g[4 + e]); }
;                     *(u32x4*)(T + (size_t)(row0 + ai * HALF + m * 16) * DM + col0 + bj * HALF) = (u32x4){cvt_pk_bf16(o[0], o[1]), cvt_pk_bf16(o[2], o[3]), cvt_pk_bf16(o[4], o[5]), cvt_pk_bf16(o[6], o[7])}; } }
	v_mul_f32_e32 v93, v89, v93
	v_fma_f32 v89, -v102, v108, 1.0
	v_mul_f32_e32 v103, 0xbfb8aa3b, v110
	v_fmac_f32_e32 v108, v89, v108
	v_div_scale_f32 v89, vcc, 1.0, v100, 1.0
	v_exp_f32_e32 v103, v103
	v_mul_f32_e32 v99, v89, v108
	v_fma_f32 v109, -v102, v99, v89
	v_fmac_f32_e32 v99, v109, v108
	v_fma_f32 v89, -v102, v99, v89
	v_add_f32_e32 v102, 1.0, v103
	v_div_scale_f32 v103, s[0:1], v102, v102, 1.0
	v_rcp_f32_e32 v109, v103
	v_and_b32_e32 v101, 0xffff0000, v141
	v_div_fmas_f32 v89, v89, v108, v99
	v_div_fixup_f32 v89, v89, v100, 1.0
	v_mul_f32_e32 v100, 0xbfb8aa3b, v101
	v_exp_f32_e32 v100, v100
	v_mul_f32_e32 v89, v94, v89
	v_fma_f32 v94, -v103, v109, 1.0
	v_fmac_f32_e32 v109, v94, v109
	v_div_scale_f32 v94, vcc, 1.0, v102, 1.0
	v_mul_f32_e32 v99, v94, v109
	v_fma_f32 v101, -v103, v99, v94
	v_add_f32_e32 v100, 1.0, v100
	v_fmac_f32_e32 v99, v101, v109
	v_div_scale_f32 v101, s[0:1], v100, v100, 1.0
	v_fma_f32 v94, -v103, v99, v94
	v_rcp_f32_e32 v103, v101
	v_div_fmas_f32 v94, v94, v109, v99
	v_and_b32_e32 v111, 0xffff0000, v143
	v_div_fixup_f32 v94, v94, v102, 1.0
	v_mul_f32_e32 v94, v90, v94
	v_fma_f32 v90, -v101, v103, 1.0
	v_mul_f32_e32 v102, 0xbfb8aa3b, v111
	v_fmac_f32_e32 v103, v90, v103
	v_div_scale_f32 v90, vcc, 1.0, v100, 1.0
	v_exp_f32_e32 v102, v102
	v_mul_f32_e32 v99, v90, v103
	v_fma_f32 v108, -v101, v99, v90
	v_fmac_f32_e32 v99, v108, v103
	v_fma_f32 v90, -v101, v99, v90
	v_add_f32_e32 v101, 1.0, v102
	v_div_scale_f32 v102, s[0:1], v101, v101, 1.0
	v_rcp_f32_e32 v108, v102
	v_div_fmas_f32 v90, v90, v103, v99
	v_div_fixup_f32 v90, v90, v100, 1.0
	v_mul_f32_e32 v90, v95, v90
	v_fma_f32 v95, -v102, v108, 1.0
	v_fmac_f32_e32 v108, v95, v108
	v_div_scale_f32 v95, vcc, 1.0, v101, 1.0
	v_mul_f32_e32 v99, v95, v108
	v_fma_f32 v100, -v102, v99, v95
	v_fmac_f32_e32 v99, v100, v108
	v_fma_f32 v95, -v102, v99, v95
	v_lshlrev_b64 v[96:97], 12, v[172:173]
	v_div_fmas_f32 v95, v95, v108, v99
	v_div_fixup_f32 v95, v95, v101, 1.0
	v_cvt_pk_bf16_f32 v88, v92, v88
	v_cvt_pk_bf16_f32 v89, v89, v90
	v_cvt_pk_bf16_f32 v90, v98, v93
	v_lshl_add_u64 v[92:93], s[84:85], 0, v[96:97]
	v_mul_f32_e32 v91, v91, v95
	v_lshl_add_u64 v[92:93], v[92:93], 0, v[164:165]
	v_cvt_pk_bf16_f32 v91, v94, v91
	global_store_dwordx4 v[92:93], v[88:91], off sc1
	v_lshlrev_b32_e32 v94, 16, v130
	v_mul_f32_e32 v94, 0xbfb8aa3b, v94
	v_lshlrev_b32_e32 v88, 16, v128
	v_mul_f32_e32 v88, 0xbfb8aa3b, v88
	v_exp_f32_e32 v88, v88
	v_exp_f32_e32 v94, v94
	v_and_b32_e32 v89, 0xffff0000, v128
	v_mul_f32_e32 v89, 0xbfb8aa3b, v89
	v_add_f32_e32 v88, 1.0, v88
	v_div_scale_f32 v95, s[0:1], v88, v88, 1.0
	v_rcp_f32_e32 v96, v95
	v_add_f32_e32 v94, 1.0, v94
	v_exp_f32_e32 v89, v89
	v_and_b32_e32 v97, 0xffff0000, v130
	v_fma_f32 v100, -v95, v96, 1.0
	v_fmac_f32_e32 v96, v100, v96
	v_div_scale_f32 v100, vcc, 1.0, v88, 1.0
	v_mul_f32_e32 v101, v100, v96
	v_fma_f32 v102, -v95, v101, v100
	v_fmac_f32_e32 v101, v102, v96
	v_fma_f32 v95, -v95, v101, v100
	v_div_scale_f32 v100, s[0:1], v94, v94, 1.0
	v_rcp_f32_e32 v102, v100
	v_div_fmas_f32 v95, v95, v96, v101
	v_div_fixup_f32 v88, v95, v88, 1.0
	v_mul_f32_e32 v84, v84, v88
	v_fma_f32 v88, -v100, v102, 1.0
	v_fmac_f32_e32 v102, v88, v102
	v_div_scale_f32 v88, vcc, 1.0, v94, 1.0
	v_mul_f32_e32 v95, v88, v102
	v_fma_f32 v96, -v100, v95, v88
	v_add_f32_e32 v89, 1.0, v89
	v_fmac_f32_e32 v95, v96, v102
	v_div_scale_f32 v96, s[0:1], v89, v89, 1.0
	v_fma_f32 v88, -v100, v95, v88
	v_rcp_f32_e32 v100, v96
	v_div_fmas_f32 v88, v88, v102, v95
	v_div_fixup_f32 v88, v88, v94, 1.0
	v_mul_f32_e32 v95, 0xbfb8aa3b, v97
	v_mul_f32_e32 v88, v80, v88
	v_fma_f32 v80, -v96, v100, 1.0
	v_exp_f32_e32 v95, v95
	v_fmac_f32_e32 v100, v80, v100
	v_div_scale_f32 v80, vcc, 1.0, v89, 1.0
	v_mul_f32_e32 v94, v80, v100
	v_fma_f32 v97, -v96, v94, v80
	v_fmac_f32_e32 v94, v97, v100
	v_add_f32_e32 v95, 1.0, v95
	v_fma_f32 v80, -v96, v94, v80
	v_div_scale_f32 v96, s[0:1], v95, v95, 1.0
	v_rcp_f32_e32 v97, v96
	v_lshlrev_b32_e32 v90, 16, v129
	v_div_fmas_f32 v80, v80, v100, v94
	v_mul_f32_e32 v90, 0xbfb8aa3b, v90
	v_div_fixup_f32 v80, v80, v89, 1.0
	v_exp_f32_e32 v90, v90
	v_mul_f32_e32 v80, v85, v80
	v_fma_f32 v85, -v96, v97, 1.0
	v_fmac_f32_e32 v97, v85, v97
	v_div_scale_f32 v85, vcc, 1.0, v95, 1.0
	v_mul_f32_e32 v89, v85, v97
	v_fma_f32 v94, -v96, v89, v85
	v_add_f32_e32 v90, 1.0, v90
	v_fmac_f32_e32 v89, v94, v97
	v_div_scale_f32 v94, s[0:1], v90, v90, 1.0
	v_fma_f32 v85, -v96, v89, v85
	v_rcp_f32_e32 v96, v94
	v_div_fmas_f32 v85, v85, v97, v89
	v_lshlrev_b32_e32 v98, 16, v131
	v_div_fixup_f32 v85, v85, v95, 1.0
	v_mul_f32_e32 v85, v81, v85
	v_fma_f32 v81, -v94, v96, 1.0
	v_mul_f32_e32 v95, 0xbfb8aa3b, v98
	v_fmac_f32_e32 v96, v81, v96
	v_div_scale_f32 v81, vcc, 1.0, v90, 1.0
	v_exp_f32_e32 v95, v95
	v_mul_f32_e32 v89, v81, v96
	v_fma_f32 v97, -v94, v89, v81
	v_fmac_f32_e32 v89, v97, v96
	v_fma_f32 v81, -v94, v89, v81
	v_add_f32_e32 v94, 1.0, v95
	v_div_scale_f32 v95, s[0:1], v94, v94, 1.0
	v_rcp_f32_e32 v97, v95
	v_and_b32_e32 v91, 0xffff0000, v129
	v_div_fmas_f32 v81, v81, v96, v89
	v_div_fixup_f32 v81, v81, v90, 1.0
	v_mul_f32_e32 v90, 0xbfb8aa3b, v91
	v_exp_f32_e32 v90, v90
	v_mul_f32_e32 v81, v86, v81
	v_fma_f32 v86, -v95, v97, 1.0
	v_fmac_f32_e32 v97, v86, v97
	v_div_scale_f32 v86, vcc, 1.0, v94, 1.0
	v_mul_f32_e32 v89, v86, v97
	v_fma_f32 v91, -v95, v89, v86
	v_add_f32_e32 v90, 1.0, v90
	v_fmac_f32_e32 v89, v91, v97
	v_div_scale_f32 v91, s[0:1], v90, v90, 1.0
	v_fma_f32 v86, -v95, v89, v86
	v_rcp_f32_e32 v95, v91
	v_div_fmas_f32 v86, v86, v97, v89
	v_and_b32_e32 v99, 0xffff0000, v131
	v_div_fixup_f32 v86, v86, v94, 1.0
	v_mul_f32_e32 v86, v82, v86
	v_fma_f32 v82, -v91, v95, 1.0
; __device__ __forceinline__ unsigned cvt_pk_bf16(float lo, float hi) { unsigned r; asm volatile("v_cvt_pk_bf16_f32 %0, %1, %2" : "=v"(r) : "v"(lo), "v"(hi)); return r; }
; __device__ __forceinline__ float sigmoidf_(float x) { return 1.f / (1.f + __expf(-x)); }
; __device__ __forceinline__ void unpack8(const u32x4& w, float (&f)[8]) { f[0] = bflo(w.x); f[1] = bfhi(w.x); f[2] = bflo(w.y); f[3] = bfhi(w.y); f[4] = bflo(w.z); f[5] = bfhi(w.z); f[6] = bflo(w.w); f[7] = bfhi(w.w); }
;     __device__ __forceinline__ void operator()(const f32x4 (&acc)[2][2][4][2], const Unit& u, int wr, int wc, int fr, int fq) const {
;     ...
;                 for (int bj = 0; bj < 2; ++bj) { float g[8]; unpack8(gw[m][bj], g); const f32x4 a0 = acc[ai][bj][m][0], a1 = acc[ai][bj][m][1]; float o[8];
; #pragma unroll
;                     for (int e = 0; e < 4; ++e) { o[e] = a0[e] * sigmoidf_(g[e]); o[4 + e] = a1[e] * sigmoidf_(g[4 + e]); }
;                     *(u32x4*)(T + (size_t)(row0 + ai * HALF + m * 16) * DM + col0 + bj * HALF) = (u32x4){cvt_pk_bf16(o[0], o[1]), cvt_pk_bf16(o[2], o[3]), cvt_pk_bf16(o[4], o[5]), cvt_pk_bf16(o[6], o[7])}; } }
	v_mul_f32_e32 v94, 0xbfb8aa3b, v99
	v_fmac_f32_e32 v95, v82, v95
	v_div_scale_f32 v82, vcc, 1.0, v90, 1.0
	v_exp_f32_e32 v94, v94
	v_mul_f32_e32 v89, v82, v95
	v_fma_f32 v96, -v91, v89, v82
	v_fmac_f32_e32 v89, v96, v95
	v_fma_f32 v82, -v91, v89, v82
	v_add_f32_e32 v91, 1.0, v94
	v_div_scale_f32 v94, s[0:1], v91, v91, 1.0
	v_rcp_f32_e32 v96, v94
	v_div_fmas_f32 v82, v82, v95, v89
	v_div_fixup_f32 v82, v82, v90, 1.0
	v_mul_f32_e32 v82, v87, v82
	v_fma_f32 v87, -v94, v96, 1.0
	v_fmac_f32_e32 v96, v87, v96
	v_div_scale_f32 v87, vcc, 1.0, v91, 1.0
	v_mul_f32_e32 v89, v87, v96
	v_fma_f32 v90, -v94, v89, v87
	v_fmac_f32_e32 v89, v90, v96
	v_fma_f32 v87, -v94, v89, v87
	v_div_fmas_f32 v87, v87, v96, v89
	v_div_fixup_f32 v87, v87, v91, 1.0
	v_mul_f32_e32 v83, v83, v87
	v_cvt_pk_bf16_f32 v80, v84, v80
	v_cvt_pk_bf16_f32 v81, v81, v82
	v_cvt_pk_bf16_f32 v82, v88, v85
	v_cvt_pk_bf16_f32 v83, v86, v83
	global_store_dwordx4 v[92:93], v[80:83], off offset:256 sc1
	v_lshlrev_b32_e32 v86, 16, v118
	v_mul_f32_e32 v86, 0xbfb8aa3b, v86
	v_lshlrev_b32_e32 v82, 16, v116
	v_mul_f32_e32 v82, 0xbfb8aa3b, v82
	v_exp_f32_e32 v82, v82
	v_exp_f32_e32 v86, v86
	v_and_b32_e32 v83, 0xffff0000, v116
	v_mul_f32_e32 v83, 0xbfb8aa3b, v83
	v_add_f32_e32 v82, 1.0, v82
	v_div_scale_f32 v87, s[0:1], v82, v82, 1.0
	v_rcp_f32_e32 v88, v87
	v_add_f32_e32 v86, 1.0, v86
	v_exp_f32_e32 v83, v83
	v_and_b32_e32 v89, 0xffff0000, v118
	v_fma_f32 v92, -v87, v88, 1.0
	v_fmac_f32_e32 v88, v92, v88
	v_div_scale_f32 v92, vcc, 1.0, v82, 1.0
	v_mul_f32_e32 v93, v92, v88
	v_fma_f32 v94, -v87, v93, v92
	v_fmac_f32_e32 v93, v94, v88
	v_fma_f32 v87, -v87, v93, v92
	v_div_scale_f32 v92, s[0:1], v86, v86, 1.0
	v_rcp_f32_e32 v94, v92
	v_div_fmas_f32 v87, v87, v88, v93
	v_div_fixup_f32 v82, v87, v82, 1.0
	v_mul_f32_e32 v76, v76, v82
	v_fma_f32 v82, -v92, v94, 1.0
	v_fmac_f32_e32 v94, v82, v94
	v_div_scale_f32 v82, vcc, 1.0, v86, 1.0
	v_mul_f32_e32 v87, v82, v94
	v_fma_f32 v88, -v92, v87, v82
	v_add_f32_e32 v83, 1.0, v83
	v_fmac_f32_e32 v87, v88, v94
	v_div_scale_f32 v88, s[0:1], v83, v83, 1.0
	v_fma_f32 v82, -v92, v87, v82
	v_rcp_f32_e32 v92, v88
	v_div_fmas_f32 v82, v82, v94, v87
	v_div_fixup_f32 v82, v82, v86, 1.0
	v_mul_f32_e32 v87, 0xbfb8aa3b, v89
	v_mul_f32_e32 v82, v72, v82
	v_fma_f32 v72, -v88, v92, 1.0
	v_exp_f32_e32 v87, v87
	v_fmac_f32_e32 v92, v72, v92
	v_div_scale_f32 v72, vcc, 1.0, v83, 1.0
	v_mul_f32_e32 v86, v72, v92
	v_fma_f32 v89, -v88, v86, v72
	v_fmac_f32_e32 v86, v89, v92
	v_add_f32_e32 v87, 1.0, v87
	v_fma_f32 v72, -v88, v86, v72
	v_div_scale_f32 v88, s[0:1], v87, v87, 1.0
	v_rcp_f32_e32 v89, v88
	v_lshlrev_b32_e32 v84, 16, v117
	v_div_fmas_f32 v72, v72, v92, v86
	v_mul_f32_e32 v84, 0xbfb8aa3b, v84
	v_div_fixup_f32 v72, v72, v83, 1.0
	v_exp_f32_e32 v84, v84
	v_mul_f32_e32 v72, v77, v72
	v_fma_f32 v77, -v88, v89, 1.0
	v_fmac_f32_e32 v89, v77, v89
	v_div_scale_f32 v77, vcc, 1.0, v87, 1.0
	v_mul_f32_e32 v83, v77, v89
	v_fma_f32 v86, -v88, v83, v77
	v_add_f32_e32 v84, 1.0, v84
	v_fmac_f32_e32 v83, v86, v89
	v_div_scale_f32 v86, s[0:1], v84, v84, 1.0
	v_fma_f32 v77, -v88, v83, v77
	v_rcp_f32_e32 v88, v86
	v_div_fmas_f32 v77, v77, v89, v83
	v_lshlrev_b32_e32 v90, 16, v119
	v_div_fixup_f32 v77, v77, v87, 1.0
	v_mul_f32_e32 v77, v73, v77
	v_fma_f32 v73, -v86, v88, 1.0
	v_mul_f32_e32 v87, 0xbfb8aa3b, v90
	v_fmac_f32_e32 v88, v73, v88
	v_div_scale_f32 v73, vcc, 1.0, v84, 1.0
	v_exp_f32_e32 v87, v87
	v_mul_f32_e32 v83, v73, v88
	v_fma_f32 v89, -v86, v83, v73
	v_fmac_f32_e32 v83, v89, v88
	v_fma_f32 v73, -v86, v83, v73
	v_add_f32_e32 v86, 1.0, v87
	v_div_scale_f32 v87, s[0:1], v86, v86, 1.0
	v_rcp_f32_e32 v89, v87
	v_and_b32_e32 v85, 0xffff0000, v117
	v_div_fmas_f32 v73, v73, v88, v83
	v_div_fixup_f32 v73, v73, v84, 1.0
	v_mul_f32_e32 v84, 0xbfb8aa3b, v85
	v_exp_f32_e32 v84, v84
	v_mul_f32_e32 v73, v78, v73
	v_fma_f32 v78, -v87, v89, 1.0
	v_fmac_f32_e32 v89, v78, v89
	v_div_scale_f32 v78, vcc, 1.0, v86, 1.0
	v_mul_f32_e32 v83, v78, v89
	v_fma_f32 v85, -v87, v83, v78
	v_add_f32_e32 v84, 1.0, v84
	v_fmac_f32_e32 v83, v85, v89
	v_div_scale_f32 v85, s[0:1], v84, v84, 1.0
	v_fma_f32 v78, -v87, v83, v78
	v_rcp_f32_e32 v87, v85
	v_div_fmas_f32 v78, v78, v89, v83
	v_and_b32_e32 v91, 0xffff0000, v119
	v_div_fixup_f32 v78, v78, v86, 1.0
	v_mul_f32_e32 v78, v74, v78
	v_fma_f32 v74, -v85, v87, 1.0
	v_mul_f32_e32 v86, 0xbfb8aa3b, v91
	v_fmac_f32_e32 v87, v74, v87
	v_div_scale_f32 v74, vcc, 1.0, v84, 1.0
	v_exp_f32_e32 v86, v86
	v_mul_f32_e32 v83, v74, v87
	v_fma_f32 v88, -v85, v83, v74
	v_fmac_f32_e32 v83, v88, v87
	v_fma_f32 v74, -v85, v83, v74
	v_add_f32_e32 v85, 1.0, v86
	v_div_scale_f32 v86, s[0:1], v85, v85, 1.0
	v_rcp_f32_e32 v88, v86
	v_div_fmas_f32 v74, v74, v87, v83
	v_div_fixup_f32 v74, v74, v84, 1.0
	v_mul_f32_e32 v74, v79, v74
	v_fma_f32 v79, -v86, v88, 1.0
	v_fmac_f32_e32 v88, v79, v88
	v_div_scale_f32 v79, vcc, 1.0, v85, 1.0
	v_mul_f32_e32 v83, v79, v88
	v_fma_f32 v84, -v86, v83, v79
	v_fmac_f32_e32 v83, v84, v88
	v_fma_f32 v79, -v86, v83, v79
	v_lshlrev_b64 v[80:81], 12, v[170:171]
	v_div_fmas_f32 v79, v79, v88, v83
	v_div_fixup_f32 v79, v79, v85, 1.0
	v_cvt_pk_bf16_f32 v72, v76, v72
	v_cvt_pk_bf16_f32 v73, v73, v74
	v_cvt_pk_bf16_f32 v74, v82, v77
	v_lshl_add_u64 v[76:77], s[84:85], 0, v[80:81]
	v_mul_f32_e32 v75, v75, v79
	v_lshl_add_u64 v[76:77], v[76:77], 0, v[164:165]
	v_cvt_pk_bf16_f32 v75, v78, v75
	global_store_dwordx4 v[76:77], v[72:75], off sc1
	v_lshlrev_b32_e32 v78, 16, v106
	v_mul_f32_e32 v78, 0xbfb8aa3b, v78
	v_lshlrev_b32_e32 v72, 16, v104
	v_mul_f32_e32 v72, 0xbfb8aa3b, v72
	v_exp_f32_e32 v72, v72
	v_exp_f32_e32 v78, v78
	v_and_b32_e32 v73, 0xffff0000, v104
; __device__ __forceinline__ unsigned cvt_pk_bf16(float lo, float hi) { unsigned r; asm volatile("v_cvt_pk_bf16_f32 %0, %1, %2" : "=v"(r) : "v"(lo), "v"(hi)); return r; }
; __device__ __forceinline__ float sigmoidf_(float x) { return 1.f / (1.f + __expf(-x)); }
; __device__ __forceinline__ void unpack8(const u32x4& w, float (&f)[8]) { f[0] = bflo(w.x); f[1] = bfhi(w.x); f[2] = bflo(w.y); f[3] = bfhi(w.y); f[4] = bflo(w.z); f[5] = bfhi(w.z); f[6] = bflo(w.w); f[7] = bfhi(w.w); }
;     __device__ __forceinline__ void operator()(const f32x4 (&acc)[2][2][4][2], const Unit& u, int wr, int wc, int fr, int fq) const {
;     ...
;                 for (int bj = 0; bj < 2; ++bj) gw[m][bj] = *(const u32x4*)(gate + (size_t)(row0 + ai * HALF + m * 16) * ldg + col0 + bj * HALF);
; #pragma unroll
;             for (int m = 0; m < 4; ++m)
; #pragma unroll
;                 for (int bj = 0; bj < 2; ++bj) { float g[8]; unpack8(gw[m][bj], g); const f32x4 a0 = acc[ai][bj][m][0], a1 = acc[ai][bj][m][1]; float o[8];
; #pragma unroll
;                     for (int e = 0; e < 4; ++e) { o[e] = a0[e] * sigmoidf_(g[e]); o[4 + e] = a1[e] * sigmoidf_(g[4 + e]); }
;                     *(u32x4*)(T + (size_t)(row0 + ai * HALF + m * 16) * DM + col0 + bj * HALF) = (u32x4){cvt_pk_bf16(o[0], o[1]), cvt_pk_bf16(o[2], o[3]), cvt_pk_bf16(o[4], o[5]), cvt_pk_bf16(o[6], o[7])}; } }
	v_mul_f32_e32 v73, 0xbfb8aa3b, v73
	v_add_f32_e32 v72, 1.0, v72
	v_div_scale_f32 v79, s[0:1], v72, v72, 1.0
	v_rcp_f32_e32 v80, v79
	v_add_f32_e32 v78, 1.0, v78
	v_exp_f32_e32 v73, v73
	v_and_b32_e32 v81, 0xffff0000, v106
	v_fma_f32 v84, -v79, v80, 1.0
	v_fmac_f32_e32 v80, v84, v80
	v_div_scale_f32 v84, vcc, 1.0, v72, 1.0
	v_mul_f32_e32 v85, v84, v80
	v_fma_f32 v86, -v79, v85, v84
	v_fmac_f32_e32 v85, v86, v80
	v_fma_f32 v79, -v79, v85, v84
	v_div_scale_f32 v84, s[0:1], v78, v78, 1.0
	v_rcp_f32_e32 v86, v84
	v_div_fmas_f32 v79, v79, v80, v85
	v_div_fixup_f32 v72, v79, v72, 1.0
	v_mul_f32_e32 v68, v68, v72
	v_fma_f32 v72, -v84, v86, 1.0
	v_fmac_f32_e32 v86, v72, v86
	v_div_scale_f32 v72, vcc, 1.0, v78, 1.0
	v_mul_f32_e32 v79, v72, v86
	v_fma_f32 v80, -v84, v79, v72
	v_add_f32_e32 v73, 1.0, v73
	v_fmac_f32_e32 v79, v80, v86
	v_div_scale_f32 v80, s[0:1], v73, v73, 1.0
	v_fma_f32 v72, -v84, v79, v72
	v_rcp_f32_e32 v84, v80
	v_div_fmas_f32 v72, v72, v86, v79
	v_div_fixup_f32 v72, v72, v78, 1.0
	v_mul_f32_e32 v79, 0xbfb8aa3b, v81
	v_mul_f32_e32 v72, v64, v72
	v_fma_f32 v64, -v80, v84, 1.0
	v_exp_f32_e32 v79, v79
	v_fmac_f32_e32 v84, v64, v84
	v_div_scale_f32 v64, vcc, 1.0, v73, 1.0
	v_mul_f32_e32 v78, v64, v84
	v_fma_f32 v81, -v80, v78, v64
	v_fmac_f32_e32 v78, v81, v84
	v_add_f32_e32 v79, 1.0, v79
	v_fma_f32 v64, -v80, v78, v64
	v_div_scale_f32 v80, s[0:1], v79, v79, 1.0
	v_rcp_f32_e32 v81, v80
	v_lshlrev_b32_e32 v74, 16, v105
	v_div_fmas_f32 v64, v64, v84, v78
	v_mul_f32_e32 v74, 0xbfb8aa3b, v74
	v_div_fixup_f32 v64, v64, v73, 1.0
	v_exp_f32_e32 v74, v74
	v_mul_f32_e32 v64, v69, v64
	v_fma_f32 v69, -v80, v81, 1.0
	v_fmac_f32_e32 v81, v69, v81
	v_div_scale_f32 v69, vcc, 1.0, v79, 1.0
	v_mul_f32_e32 v73, v69, v81
	v_fma_f32 v78, -v80, v73, v69
	v_add_f32_e32 v74, 1.0, v74
	v_fmac_f32_e32 v73, v78, v81
	v_div_scale_f32 v78, s[0:1], v74, v74, 1.0
	v_fma_f32 v69, -v80, v73, v69
	v_rcp_f32_e32 v80, v78
	v_div_fmas_f32 v69, v69, v81, v73
	v_lshlrev_b32_e32 v82, 16, v107
	v_div_fixup_f32 v69, v69, v79, 1.0
	v_mul_f32_e32 v69, v65, v69
	v_fma_f32 v65, -v78, v80, 1.0
	v_mul_f32_e32 v79, 0xbfb8aa3b, v82
	v_fmac_f32_e32 v80, v65, v80
	v_div_scale_f32 v65, vcc, 1.0, v74, 1.0
	v_exp_f32_e32 v79, v79
	v_mul_f32_e32 v73, v65, v80
	v_fma_f32 v81, -v78, v73, v65
	v_fmac_f32_e32 v73, v81, v80
	v_fma_f32 v65, -v78, v73, v65
	v_add_f32_e32 v78, 1.0, v79
	v_div_scale_f32 v79, s[0:1], v78, v78, 1.0
	v_rcp_f32_e32 v81, v79
	v_and_b32_e32 v75, 0xffff0000, v105
	v_div_fmas_f32 v65, v65, v80, v73
	v_div_fixup_f32 v65, v65, v74, 1.0
	v_mul_f32_e32 v74, 0xbfb8aa3b, v75
	v_exp_f32_e32 v74, v74
	v_mul_f32_e32 v65, v70, v65
	v_fma_f32 v70, -v79, v81, 1.0
	v_fmac_f32_e32 v81, v70, v81
	v_div_scale_f32 v70, vcc, 1.0, v78, 1.0
	v_mul_f32_e32 v73, v70, v81
	v_fma_f32 v75, -v79, v73, v70
	v_add_f32_e32 v74, 1.0, v74
	v_fmac_f32_e32 v73, v75, v81
	v_div_scale_f32 v75, s[0:1], v74, v74, 1.0
	v_fma_f32 v70, -v79, v73, v70
	v_rcp_f32_e32 v79, v75
	v_div_fmas_f32 v70, v70, v81, v73
	v_and_b32_e32 v83, 0xffff0000, v107
	v_div_fixup_f32 v70, v70, v78, 1.0
	v_mul_f32_e32 v70, v66, v70
	v_fma_f32 v66, -v75, v79, 1.0
	v_mul_f32_e32 v78, 0xbfb8aa3b, v83
	v_fmac_f32_e32 v79, v66, v79
	v_div_scale_f32 v66, vcc, 1.0, v74, 1.0
	v_exp_f32_e32 v78, v78
	v_mul_f32_e32 v73, v66, v79
	v_fma_f32 v80, -v75, v73, v66
	v_fmac_f32_e32 v73, v80, v79
	v_fma_f32 v66, -v75, v73, v66
	v_add_f32_e32 v75, 1.0, v78
	v_div_scale_f32 v78, s[0:1], v75, v75, 1.0
	v_rcp_f32_e32 v80, v78
	v_div_fmas_f32 v66, v66, v79, v73
	v_div_fixup_f32 v66, v66, v74, 1.0
	v_mul_f32_e32 v66, v71, v66
	v_fma_f32 v71, -v78, v80, 1.0
	v_fmac_f32_e32 v80, v71, v80
	v_div_scale_f32 v71, vcc, 1.0, v75, 1.0
	v_mul_f32_e32 v73, v71, v80
	v_fma_f32 v74, -v78, v73, v71
	v_fmac_f32_e32 v73, v74, v80
	v_fma_f32 v71, -v78, v73, v71
	v_div_fmas_f32 v71, v71, v80, v73
	v_div_fixup_f32 v71, v71, v75, 1.0
	v_mul_f32_e32 v67, v67, v71
	v_cvt_pk_bf16_f32 v64, v68, v64
	v_cvt_pk_bf16_f32 v65, v65, v66
	v_add_u32_e32 v102, 0x80, v166
	v_cvt_pk_bf16_f32 v66, v72, v69
	v_cvt_pk_bf16_f32 v67, v70, v67
	global_store_dwordx4 v[76:77], v[64:67], off offset:256 sc1
	v_add_u32_e32 v96, 0x90, v166
	v_add_u32_e32 v94, 0xa0, v166
	v_mad_i64_i32 v[64:65], s[0:1], v102, s39, v[168:169]
	global_load_dwordx4 v[98:101], v[64:65], off nt
	global_load_dwordx4 v[88:91], v[64:65], off offset:256 nt
	v_mad_i64_i32 v[64:65], s[0:1], v96, s39, v[168:169]
	v_ashrrev_i32_e32 v103, 31, v102
	global_load_dwordx4 v[84:87], v[64:65], off nt
	global_load_dwordx4 v[80:83], v[64:65], off offset:256 nt
	v_mad_i64_i32 v[64:65], s[0:1], v94, s39, v[168:169]
	v_add_u32_e32 v92, 0xb0, v166
	global_load_dwordx4 v[76:79], v[64:65], off nt
	global_load_dwordx4 v[72:75], v[64:65], off offset:256 nt
	v_mad_i64_i32 v[64:65], s[0:1], v92, s39, v[168:169]
	v_lshlrev_b64 v[102:103], 12, v[102:103]
	global_load_dwordx4 v[68:71], v[64:65], off nt
	s_nop 0
	global_load_dwordx4 v[64:67], v[64:65], off offset:256 nt
	v_ashrrev_i32_e32 v97, 31, v96
	v_ashrrev_i32_e32 v95, 31, v94
	v_ashrrev_i32_e32 v93, 31, v92
	s_waitcnt vmcnt(7)
; __device__ __forceinline__ unsigned cvt_pk_bf16(float lo, float hi) { unsigned r; asm volatile("v_cvt_pk_bf16_f32 %0, %1, %2" : "=v"(r) : "v"(lo), "v"(hi)); return r; }
; __device__ __forceinline__ float sigmoidf_(float x) { return 1.f / (1.f + __expf(-x)); }
; __device__ __forceinline__ void unpack8(const u32x4& w, float (&f)[8]) { f[0] = bflo(w.x); f[1] = bfhi(w.x); f[2] = bflo(w.y); f[3] = bfhi(w.y); f[4] = bflo(w.z); f[5] = bfhi(w.z); f[6] = bflo(w.w); f[7] = bfhi(w.w); }
;     __device__ __forceinline__ void operator()(const f32x4 (&acc)[2][2][4][2], const Unit& u, int wr, int wc, int fr, int fq) const {
;     ...
;                 for (int bj = 0; bj < 2; ++bj) { float g[8]; unpack8(gw[m][bj], g); const f32x4 a0 = acc[ai][bj][m][0], a1 = acc[ai][bj][m][1]; float o[8];
; #pragma unroll
;                     for (int e = 0; e < 4; ++e) { o[e] = a0[e] * sigmoidf_(g[e]); o[4 + e] = a1[e] * sigmoidf_(g[4 + e]); }
;                     *(u32x4*)(T + (size_t)(row0 + ai * HALF + m * 16) * DM + col0 + bj * HALF) = (u32x4){cvt_pk_bf16(o[0], o[1]), cvt_pk_bf16(o[2], o[3]), cvt_pk_bf16(o[4], o[5]), cvt_pk_bf16(o[6], o[7])}; } }
	v_lshlrev_b32_e32 v104, 16, v98
	v_mul_f32_e32 v104, 0xbfb8aa3b, v104
	v_exp_f32_e32 v104, v104
	v_lshlrev_b32_e32 v106, 16, v100
	v_mul_f32_e32 v106, 0xbfb8aa3b, v106
	v_exp_f32_e32 v106, v106
	v_add_f32_e32 v104, 1.0, v104
	v_div_scale_f32 v107, s[0:1], v104, v104, 1.0
	v_rcp_f32_e32 v108, v107
	v_add_f32_e32 v106, 1.0, v106
	v_and_b32_e32 v98, 0xffff0000, v98
	v_mul_f32_e32 v98, 0xbfb8aa3b, v98
	v_fma_f32 v110, -v107, v108, 1.0
	v_fmac_f32_e32 v108, v110, v108
	v_div_scale_f32 v110, vcc, 1.0, v104, 1.0
	v_mul_f32_e32 v111, v110, v108
	v_fma_f32 v112, -v107, v111, v110
	v_fmac_f32_e32 v111, v112, v108
	v_fma_f32 v107, -v107, v111, v110
	v_div_scale_f32 v110, s[0:1], v106, v106, 1.0
	v_rcp_f32_e32 v112, v110
	v_div_fmas_f32 v107, v107, v108, v111
	v_div_fixup_f32 v104, v107, v104, 1.0
	v_exp_f32_e32 v98, v98
	v_mul_f32_e32 v60, v60, v104
	v_fma_f32 v104, -v110, v112, 1.0
	v_fmac_f32_e32 v112, v104, v112
	v_div_scale_f32 v104, vcc, 1.0, v106, 1.0
	v_mul_f32_e32 v107, v104, v112
	v_fma_f32 v108, -v110, v107, v104
	v_add_f32_e32 v98, 1.0, v98
	v_fmac_f32_e32 v107, v108, v112
	v_div_scale_f32 v108, s[0:1], v98, v98, 1.0
	v_fma_f32 v104, -v110, v107, v104
	v_rcp_f32_e32 v110, v108
	v_and_b32_e32 v100, 0xffff0000, v100
	v_div_fmas_f32 v104, v104, v112, v107
	v_mul_f32_e32 v100, 0xbfb8aa3b, v100
	v_div_fixup_f32 v104, v104, v106, 1.0
	v_exp_f32_e32 v100, v100
	v_mul_f32_e32 v104, v56, v104
	v_fma_f32 v56, -v108, v110, 1.0
	v_fmac_f32_e32 v110, v56, v110
	v_div_scale_f32 v56, vcc, 1.0, v98, 1.0
	v_mul_f32_e32 v106, v56, v110
	v_fma_f32 v107, -v108, v106, v56
	v_add_f32_e32 v100, 1.0, v100
	v_fmac_f32_e32 v106, v107, v110
	v_div_scale_f32 v107, s[0:1], v100, v100, 1.0
	v_fma_f32 v56, -v108, v106, v56
	v_rcp_f32_e32 v108, v107
	v_lshlrev_b32_e32 v105, 16, v99
	v_div_fmas_f32 v56, v56, v110, v106
	v_mul_f32_e32 v105, 0xbfb8aa3b, v105
	v_div_fixup_f32 v56, v56, v98, 1.0
	v_exp_f32_e32 v105, v105
	v_mul_f32_e32 v56, v61, v56
	v_fma_f32 v61, -v107, v108, 1.0
	v_fmac_f32_e32 v108, v61, v108
	v_div_scale_f32 v61, vcc, 1.0, v100, 1.0
	v_mul_f32_e32 v98, v61, v108
	v_fma_f32 v106, -v107, v98, v61
	v_add_f32_e32 v105, 1.0, v105
	v_fmac_f32_e32 v98, v106, v108
	v_div_scale_f32 v106, s[0:1], v105, v105, 1.0
	v_fma_f32 v61, -v107, v98, v61
	v_rcp_f32_e32 v107, v106
	v_lshlrev_b32_e32 v109, 16, v101
	v_div_fmas_f32 v61, v61, v108, v98
	v_div_fixup_f32 v61, v61, v100, 1.0
	v_mul_f32_e32 v100, 0xbfb8aa3b, v109
	v_mul_f32_e32 v61, v57, v61
	v_fma_f32 v57, -v106, v107, 1.0
	v_exp_f32_e32 v100, v100
	v_fmac_f32_e32 v107, v57, v107
	v_div_scale_f32 v57, vcc, 1.0, v105, 1.0
	v_mul_f32_e32 v98, v57, v107
	v_fma_f32 v108, -v106, v98, v57
	v_fmac_f32_e32 v98, v108, v107
	v_add_f32_e32 v100, 1.0, v100
	v_fma_f32 v57, -v106, v98, v57
	v_div_scale_f32 v106, s[0:1], v100, v100, 1.0
	v_rcp_f32_e32 v108, v106
	v_and_b32_e32 v99, 0xffff0000, v99
	v_div_fmas_f32 v57, v57, v107, v98
	v_mul_f32_e32 v99, 0xbfb8aa3b, v99
	v_div_fixup_f32 v57, v57, v105, 1.0
	v_exp_f32_e32 v99, v99
	v_mul_f32_e32 v57, v62, v57
	v_fma_f32 v62, -v106, v108, 1.0
	v_fmac_f32_e32 v108, v62, v108
	v_div_scale_f32 v62, vcc, 1.0, v100, 1.0
	v_mul_f32_e32 v98, v62, v108
	v_fma_f32 v105, -v106, v98, v62
	v_add_f32_e32 v99, 1.0, v99
	v_fmac_f32_e32 v98, v105, v108
	v_div_scale_f32 v105, s[0:1], v99, v99, 1.0
	v_fma_f32 v62, -v106, v98, v62
	v_rcp_f32_e32 v106, v105
	v_and_b32_e32 v101, 0xffff0000, v101
	v_div_fmas_f32 v62, v62, v108, v98
	v_div_fixup_f32 v62, v62, v100, 1.0
	v_mul_f32_e32 v100, 0xbfb8aa3b, v101
	v_exp_f32_e32 v100, v100
	v_mul_f32_e32 v62, v58, v62
	v_fma_f32 v58, -v105, v106, 1.0
	v_fmac_f32_e32 v106, v58, v106
	v_div_scale_f32 v58, vcc, 1.0, v99, 1.0
	v_mul_f32_e32 v98, v58, v106
	v_fma_f32 v101, -v105, v98, v58
	v_add_f32_e32 v100, 1.0, v100
	v_fmac_f32_e32 v98, v101, v106
	v_div_scale_f32 v101, s[0:1], v100, v100, 1.0
	v_fma_f32 v58, -v105, v98, v58
	v_rcp_f32_e32 v105, v101
	v_div_fmas_f32 v58, v58, v106, v98
	v_div_fixup_f32 v58, v58, v99, 1.0
	v_mul_f32_e32 v58, v63, v58
	v_fma_f32 v63, -v101, v105, 1.0
	v_fmac_f32_e32 v105, v63, v105
	v_div_scale_f32 v63, vcc, 1.0, v100, 1.0
	v_mul_f32_e32 v98, v63, v105
	v_fma_f32 v99, -v101, v98, v63
	v_fmac_f32_e32 v98, v99, v105
	v_fma_f32 v63, -v101, v98, v63
	v_div_fmas_f32 v63, v63, v105, v98
	v_div_fixup_f32 v63, v63, v100, 1.0
	v_cvt_pk_bf16_f32 v56, v60, v56
	v_cvt_pk_bf16_f32 v57, v57, v58
	v_cvt_pk_bf16_f32 v58, v104, v61
	v_lshl_add_u64 v[60:61], s[84:85], 0, v[102:103]
	v_mul_f32_e32 v59, v59, v63
	v_lshl_add_u64 v[60:61], v[60:61], 0, v[164:165]
	v_cvt_pk_bf16_f32 v59, v62, v59
	global_store_dwordx4 v[60:61], v[56:59], off sc1
	s_waitcnt vmcnt(7)
; __device__ __forceinline__ unsigned cvt_pk_bf16(float lo, float hi) { unsigned r; asm volatile("v_cvt_pk_bf16_f32 %0, %1, %2" : "=v"(r) : "v"(lo), "v"(hi)); return r; }
; __device__ __forceinline__ float sigmoidf_(float x) { return 1.f / (1.f + __expf(-x)); }
; __device__ __forceinline__ void unpack8(const u32x4& w, float (&f)[8]) { f[0] = bflo(w.x); f[1] = bfhi(w.x); f[2] = bflo(w.y); f[3] = bfhi(w.y); f[4] = bflo(w.z); f[5] = bfhi(w.z); f[6] = bflo(w.w); f[7] = bfhi(w.w); }
;     __device__ __forceinline__ void operator()(const f32x4 (&acc)[2][2][4][2], const Unit& u, int wr, int wc, int fr, int fq) const {
;     ...
;                 for (int bj = 0; bj < 2; ++bj) { float g[8]; unpack8(gw[m][bj], g); const f32x4 a0 = acc[ai][bj][m][0], a1 = acc[ai][bj][m][1]; float o[8];
; #pragma unroll
;                     for (int e = 0; e < 4; ++e) { o[e] = a0[e] * sigmoidf_(g[e]); o[4 + e] = a1[e] * sigmoidf_(g[4 + e]); }
;                     *(u32x4*)(T + (size_t)(row0 + ai * HALF + m * 16) * DM + col0 + bj * HALF) = (u32x4){cvt_pk_bf16(o[0], o[1]), cvt_pk_bf16(o[2], o[3]), cvt_pk_bf16(o[4], o[5]), cvt_pk_bf16(o[6], o[7])}; } }
	v_lshlrev_b32_e32 v62, 16, v90
	v_mul_f32_e32 v62, 0xbfb8aa3b, v62
	v_lshlrev_b32_e32 v56, 16, v88
	v_mul_f32_e32 v56, 0xbfb8aa3b, v56
	v_exp_f32_e32 v56, v56
	v_and_b32_e32 v57, 0xffff0000, v88
	v_exp_f32_e32 v62, v62
	v_mul_f32_e32 v57, 0xbfb8aa3b, v57
	v_add_f32_e32 v56, 1.0, v56
	v_div_scale_f32 v63, s[0:1], v56, v56, 1.0
	v_rcp_f32_e32 v88, v63
	v_add_f32_e32 v62, 1.0, v62
	v_exp_f32_e32 v57, v57
	v_lshlrev_b32_e32 v58, 16, v89
	v_fma_f32 v98, -v63, v88, 1.0
	v_fmac_f32_e32 v88, v98, v88
	v_div_scale_f32 v98, vcc, 1.0, v56, 1.0
	v_mul_f32_e32 v99, v98, v88
	v_fma_f32 v100, -v63, v99, v98
	v_fmac_f32_e32 v99, v100, v88
	v_fma_f32 v63, -v63, v99, v98
	v_div_scale_f32 v98, s[0:1], v62, v62, 1.0
	v_rcp_f32_e32 v100, v98
	v_div_fmas_f32 v63, v63, v88, v99
	v_div_fixup_f32 v56, v63, v56, 1.0
	v_mul_f32_e32 v52, v52, v56
	v_fma_f32 v56, -v98, v100, 1.0
	v_fmac_f32_e32 v100, v56, v100
	v_div_scale_f32 v56, vcc, 1.0, v62, 1.0
	v_mul_f32_e32 v63, v56, v100
	v_fma_f32 v88, -v98, v63, v56
	v_add_f32_e32 v57, 1.0, v57
	v_fmac_f32_e32 v63, v88, v100
	v_div_scale_f32 v88, s[0:1], v57, v57, 1.0
	v_fma_f32 v56, -v98, v63, v56
	v_rcp_f32_e32 v98, v88
	v_and_b32_e32 v59, 0xffff0000, v89
	v_and_b32_e32 v89, 0xffff0000, v90
	v_div_fmas_f32 v56, v56, v100, v63
	v_div_fixup_f32 v56, v56, v62, 1.0
	v_mul_f32_e32 v63, 0xbfb8aa3b, v89
	v_mul_f32_e32 v56, v48, v56
	v_fma_f32 v48, -v88, v98, 1.0
	v_exp_f32_e32 v63, v63
	v_fmac_f32_e32 v98, v48, v98
	v_div_scale_f32 v48, vcc, 1.0, v57, 1.0
	v_mul_f32_e32 v62, v48, v98
	v_fma_f32 v89, -v88, v62, v48
	v_fmac_f32_e32 v62, v89, v98
	v_add_f32_e32 v63, 1.0, v63
	v_fma_f32 v48, -v88, v62, v48
	v_div_scale_f32 v88, s[0:1], v63, v63, 1.0
	v_rcp_f32_e32 v89, v88
	v_div_fmas_f32 v48, v48, v98, v62
	v_mul_f32_e32 v58, 0xbfb8aa3b, v58
	v_div_fixup_f32 v48, v48, v57, 1.0
	v_exp_f32_e32 v58, v58
	v_mul_f32_e32 v48, v53, v48
	v_fma_f32 v53, -v88, v89, 1.0
	v_fmac_f32_e32 v89, v53, v89
	v_div_scale_f32 v53, vcc, 1.0, v63, 1.0
	v_mul_f32_e32 v57, v53, v89
	v_fma_f32 v62, -v88, v57, v53
	v_add_f32_e32 v58, 1.0, v58
	v_fmac_f32_e32 v57, v62, v89
	v_div_scale_f32 v62, s[0:1], v58, v58, 1.0
	v_fma_f32 v53, -v88, v57, v53
	v_rcp_f32_e32 v88, v62
	v_div_fmas_f32 v53, v53, v89, v57
	v_lshlrev_b32_e32 v90, 16, v91
	v_div_fixup_f32 v53, v53, v63, 1.0
	v_mul_f32_e32 v53, v49, v53
	v_fma_f32 v49, -v62, v88, 1.0
	v_mul_f32_e32 v63, 0xbfb8aa3b, v90
	v_fmac_f32_e32 v88, v49, v88
	v_div_scale_f32 v49, vcc, 1.0, v58, 1.0
	v_exp_f32_e32 v63, v63
	v_mul_f32_e32 v57, v49, v88
	v_fma_f32 v89, -v62, v57, v49
	v_fmac_f32_e32 v57, v89, v88
	v_fma_f32 v49, -v62, v57, v49
	v_add_f32_e32 v62, 1.0, v63
	v_div_scale_f32 v63, s[0:1], v62, v62, 1.0
	v_rcp_f32_e32 v89, v63
	v_div_fmas_f32 v49, v49, v88, v57
	v_div_fixup_f32 v49, v49, v58, 1.0
	v_mul_f32_e32 v58, 0xbfb8aa3b, v59
	v_exp_f32_e32 v58, v58
	v_mul_f32_e32 v49, v54, v49
	v_fma_f32 v54, -v63, v89, 1.0
	v_fmac_f32_e32 v89, v54, v89
	v_div_scale_f32 v54, vcc, 1.0, v62, 1.0
	v_mul_f32_e32 v57, v54, v89
	v_fma_f32 v59, -v63, v57, v54
	v_add_f32_e32 v58, 1.0, v58
	v_fmac_f32_e32 v57, v59, v89
	v_div_scale_f32 v59, s[0:1], v58, v58, 1.0
	v_fma_f32 v54, -v63, v57, v54
	v_rcp_f32_e32 v63, v59
	v_div_fmas_f32 v54, v54, v89, v57
	v_and_b32_e32 v91, 0xffff0000, v91
	v_div_fixup_f32 v54, v54, v62, 1.0
	v_mul_f32_e32 v54, v50, v54
	v_fma_f32 v50, -v59, v63, 1.0
	v_mul_f32_e32 v62, 0xbfb8aa3b, v91
	v_fmac_f32_e32 v63, v50, v63
	v_div_scale_f32 v50, vcc, 1.0, v58, 1.0
	v_exp_f32_e32 v62, v62
	v_mul_f32_e32 v57, v50, v63
	v_fma_f32 v88, -v59, v57, v50
	v_fmac_f32_e32 v57, v88, v63
	v_fma_f32 v50, -v59, v57, v50
	v_add_f32_e32 v59, 1.0, v62
	v_div_scale_f32 v62, s[0:1], v59, v59, 1.0
	v_rcp_f32_e32 v88, v62
	v_div_fmas_f32 v50, v50, v63, v57
	v_div_fixup_f32 v50, v50, v58, 1.0
	v_mul_f32_e32 v50, v55, v50
	v_fma_f32 v55, -v62, v88, 1.0
	v_fmac_f32_e32 v88, v55, v88
	v_div_scale_f32 v55, vcc, 1.0, v59, 1.0
	v_mul_f32_e32 v57, v55, v88
	v_fma_f32 v58, -v62, v57, v55
	v_fmac_f32_e32 v57, v58, v88
	v_fma_f32 v55, -v62, v57, v55
	v_div_fmas_f32 v55, v55, v88, v57
	v_div_fixup_f32 v55, v55, v59, 1.0
	v_mul_f32_e32 v51, v51, v55
	v_cvt_pk_bf16_f32 v48, v52, v48
	v_cvt_pk_bf16_f32 v49, v49, v50
	v_cvt_pk_bf16_f32 v50, v56, v53
	v_cvt_pk_bf16_f32 v51, v54, v51
	global_store_dwordx4 v[60:61], v[48:51], off offset:256 sc1
	s_waitcnt vmcnt(7)
; __device__ __forceinline__ unsigned cvt_pk_bf16(float lo, float hi) { unsigned r; asm volatile("v_cvt_pk_bf16_f32 %0, %1, %2" : "=v"(r) : "v"(lo), "v"(hi)); return r; }
; __device__ __forceinline__ float sigmoidf_(float x) { return 1.f / (1.f + __expf(-x)); }
; __device__ __forceinline__ void unpack8(const u32x4& w, float (&f)[8]) { f[0] = bflo(w.x); f[1] = bfhi(w.x); f[2] = bflo(w.y); f[3] = bfhi(w.y); f[4] = bflo(w.z); f[5] = bfhi(w.z); f[6] = bflo(w.w); f[7] = bfhi(w.w); }
;     __device__ __forceinline__ void operator()(const f32x4 (&acc)[2][2][4][2], const Unit& u, int wr, int wc, int fr, int fq) const {
;     ...
;                 for (int bj = 0; bj < 2; ++bj) { float g[8]; unpack8(gw[m][bj], g); const f32x4 a0 = acc[ai][bj][m][0], a1 = acc[ai][bj][m][1]; float o[8];
; #pragma unroll
;                     for (int e = 0; e < 4; ++e) { o[e] = a0[e] * sigmoidf_(g[e]); o[4 + e] = a1[e] * sigmoidf_(g[4 + e]); }
;                     *(u32x4*)(T + (size_t)(row0 + ai * HALF + m * 16) * DM + col0 + bj * HALF) = (u32x4){cvt_pk_bf16(o[0], o[1]), cvt_pk_bf16(o[2], o[3]), cvt_pk_bf16(o[4], o[5]), cvt_pk_bf16(o[6], o[7])}; } }
	v_lshlrev_b32_e32 v54, 16, v86
	v_mul_f32_e32 v54, 0xbfb8aa3b, v54
	v_lshlrev_b32_e32 v50, 16, v84
	v_mul_f32_e32 v50, 0xbfb8aa3b, v50
	v_exp_f32_e32 v50, v50
	v_exp_f32_e32 v54, v54
	v_and_b32_e32 v51, 0xffff0000, v84
	v_mul_f32_e32 v51, 0xbfb8aa3b, v51
	v_add_f32_e32 v50, 1.0, v50
	v_div_scale_f32 v55, s[0:1], v50, v50, 1.0
	v_rcp_f32_e32 v56, v55
	v_add_f32_e32 v54, 1.0, v54
	v_exp_f32_e32 v51, v51
	v_and_b32_e32 v57, 0xffff0000, v86
	v_fma_f32 v60, -v55, v56, 1.0
	v_fmac_f32_e32 v56, v60, v56
	v_div_scale_f32 v60, vcc, 1.0, v50, 1.0
	v_mul_f32_e32 v61, v60, v56
	v_fma_f32 v62, -v55, v61, v60
	v_fmac_f32_e32 v61, v62, v56
	v_fma_f32 v55, -v55, v61, v60
	v_div_scale_f32 v60, s[0:1], v54, v54, 1.0
	v_rcp_f32_e32 v62, v60
	v_div_fmas_f32 v55, v55, v56, v61
	v_div_fixup_f32 v50, v55, v50, 1.0
	v_mul_f32_e32 v44, v44, v50
	v_fma_f32 v50, -v60, v62, 1.0
	v_fmac_f32_e32 v62, v50, v62
	v_div_scale_f32 v50, vcc, 1.0, v54, 1.0
	v_mul_f32_e32 v55, v50, v62
	v_fma_f32 v56, -v60, v55, v50
	v_add_f32_e32 v51, 1.0, v51
	v_fmac_f32_e32 v55, v56, v62
	v_div_scale_f32 v56, s[0:1], v51, v51, 1.0
	v_fma_f32 v50, -v60, v55, v50
	v_rcp_f32_e32 v60, v56
	v_div_fmas_f32 v50, v50, v62, v55
	v_div_fixup_f32 v50, v50, v54, 1.0
	v_mul_f32_e32 v55, 0xbfb8aa3b, v57
	v_mul_f32_e32 v50, v40, v50
	v_fma_f32 v40, -v56, v60, 1.0
	v_exp_f32_e32 v55, v55
	v_fmac_f32_e32 v60, v40, v60
	v_div_scale_f32 v40, vcc, 1.0, v51, 1.0
	v_mul_f32_e32 v54, v40, v60
	v_fma_f32 v57, -v56, v54, v40
	v_fmac_f32_e32 v54, v57, v60
	v_add_f32_e32 v55, 1.0, v55
	v_fma_f32 v40, -v56, v54, v40
	v_div_scale_f32 v56, s[0:1], v55, v55, 1.0
	v_rcp_f32_e32 v57, v56
	v_lshlrev_b32_e32 v52, 16, v85
	v_div_fmas_f32 v40, v40, v60, v54
	v_mul_f32_e32 v52, 0xbfb8aa3b, v52
	v_div_fixup_f32 v40, v40, v51, 1.0
	v_exp_f32_e32 v52, v52
	v_mul_f32_e32 v40, v45, v40
	v_fma_f32 v45, -v56, v57, 1.0
	v_fmac_f32_e32 v57, v45, v57
	v_div_scale_f32 v45, vcc, 1.0, v55, 1.0
	v_mul_f32_e32 v51, v45, v57
	v_fma_f32 v54, -v56, v51, v45
	v_add_f32_e32 v52, 1.0, v52
	v_fmac_f32_e32 v51, v54, v57
	v_div_scale_f32 v54, s[0:1], v52, v52, 1.0
	v_fma_f32 v45, -v56, v51, v45
	v_rcp_f32_e32 v56, v54
	v_div_fmas_f32 v45, v45, v57, v51
	v_lshlrev_b32_e32 v58, 16, v87
	v_div_fixup_f32 v45, v45, v55, 1.0
	v_mul_f32_e32 v45, v41, v45
	v_fma_f32 v41, -v54, v56, 1.0
	v_mul_f32_e32 v55, 0xbfb8aa3b, v58
	v_fmac_f32_e32 v56, v41, v56
	v_div_scale_f32 v41, vcc, 1.0, v52, 1.0
	v_exp_f32_e32 v55, v55
	v_mul_f32_e32 v51, v41, v56
	v_fma_f32 v57, -v54, v51, v41
	v_fmac_f32_e32 v51, v57, v56
	v_fma_f32 v41, -v54, v51, v41
	v_add_f32_e32 v54, 1.0, v55
	v_div_scale_f32 v55, s[0:1], v54, v54, 1.0
	v_rcp_f32_e32 v57, v55
	v_and_b32_e32 v53, 0xffff0000, v85
	v_div_fmas_f32 v41, v41, v56, v51
	v_div_fixup_f32 v41, v41, v52, 1.0
	v_mul_f32_e32 v52, 0xbfb8aa3b, v53
	v_exp_f32_e32 v52, v52
	v_mul_f32_e32 v41, v46, v41
	v_fma_f32 v46, -v55, v57, 1.0
	v_fmac_f32_e32 v57, v46, v57
	v_div_scale_f32 v46, vcc, 1.0, v54, 1.0
	v_mul_f32_e32 v51, v46, v57
	v_fma_f32 v53, -v55, v51, v46
	v_add_f32_e32 v52, 1.0, v52
	v_fmac_f32_e32 v51, v53, v57
	v_div_scale_f32 v53, s[0:1], v52, v52, 1.0
	v_fma_f32 v46, -v55, v51, v46
	v_rcp_f32_e32 v55, v53
	v_div_fmas_f32 v46, v46, v57, v51
	v_and_b32_e32 v59, 0xffff0000, v87
	v_div_fixup_f32 v46, v46, v54, 1.0
	v_mul_f32_e32 v46, v42, v46
	v_fma_f32 v42, -v53, v55, 1.0
	v_mul_f32_e32 v54, 0xbfb8aa3b, v59
	v_fmac_f32_e32 v55, v42, v55
	v_div_scale_f32 v42, vcc, 1.0, v52, 1.0
	v_exp_f32_e32 v54, v54
	v_mul_f32_e32 v51, v42, v55
	v_fma_f32 v56, -v53, v51, v42
	v_fmac_f32_e32 v51, v56, v55
	v_fma_f32 v42, -v53, v51, v42
	v_add_f32_e32 v53, 1.0, v54
	v_div_scale_f32 v54, s[0:1], v53, v53, 1.0
	v_rcp_f32_e32 v56, v54
	v_div_fmas_f32 v42, v42, v55, v51
	v_div_fixup_f32 v42, v42, v52, 1.0
	v_mul_f32_e32 v42, v47, v42
	v_fma_f32 v47, -v54, v56, 1.0
	v_fmac_f32_e32 v56, v47, v56
	v_div_scale_f32 v47, vcc, 1.0, v53, 1.0
	v_mul_f32_e32 v51, v47, v56
	v_fma_f32 v52, -v54, v51, v47
	v_fmac_f32_e32 v51, v52, v56
	v_fma_f32 v47, -v54, v51, v47
	v_lshlrev_b64 v[48:49], 12, v[96:97]
	v_div_fmas_f32 v47, v47, v56, v51
	v_div_fixup_f32 v47, v47, v53, 1.0
	v_cvt_pk_bf16_f32 v40, v44, v40
	v_cvt_pk_bf16_f32 v41, v41, v42
	v_cvt_pk_bf16_f32 v42, v50, v45
	v_lshl_add_u64 v[44:45], s[84:85], 0, v[48:49]
	v_mul_f32_e32 v43, v43, v47
	v_lshl_add_u64 v[44:45], v[44:45], 0, v[164:165]
	v_cvt_pk_bf16_f32 v43, v46, v43
	global_store_dwordx4 v[44:45], v[40:43], off sc1
	s_waitcnt vmcnt(7)
; __device__ __forceinline__ unsigned cvt_pk_bf16(float lo, float hi) { unsigned r; asm volatile("v_cvt_pk_bf16_f32 %0, %1, %2" : "=v"(r) : "v"(lo), "v"(hi)); return r; }
; __device__ __forceinline__ float sigmoidf_(float x) { return 1.f / (1.f + __expf(-x)); }
; __device__ __forceinline__ void unpack8(const u32x4& w, float (&f)[8]) { f[0] = bflo(w.x); f[1] = bfhi(w.x); f[2] = bflo(w.y); f[3] = bfhi(w.y); f[4] = bflo(w.z); f[5] = bfhi(w.z); f[6] = bflo(w.w); f[7] = bfhi(w.w); }
;     __device__ __forceinline__ void operator()(const f32x4 (&acc)[2][2][4][2], const Unit& u, int wr, int wc, int fr, int fq) const {
;     ...
;                 for (int bj = 0; bj < 2; ++bj) { float g[8]; unpack8(gw[m][bj], g); const f32x4 a0 = acc[ai][bj][m][0], a1 = acc[ai][bj][m][1]; float o[8];
; #pragma unroll
;                     for (int e = 0; e < 4; ++e) { o[e] = a0[e] * sigmoidf_(g[e]); o[4 + e] = a1[e] * sigmoidf_(g[4 + e]); }
;                     *(u32x4*)(T + (size_t)(row0 + ai * HALF + m * 16) * DM + col0 + bj * HALF) = (u32x4){cvt_pk_bf16(o[0], o[1]), cvt_pk_bf16(o[2], o[3]), cvt_pk_bf16(o[4], o[5]), cvt_pk_bf16(o[6], o[7])}; } }
	v_lshlrev_b32_e32 v46, 16, v82
	v_mul_f32_e32 v46, 0xbfb8aa3b, v46
	v_lshlrev_b32_e32 v40, 16, v80
	v_mul_f32_e32 v40, 0xbfb8aa3b, v40
	v_exp_f32_e32 v40, v40
	v_exp_f32_e32 v46, v46
	v_and_b32_e32 v41, 0xffff0000, v80
	v_mul_f32_e32 v41, 0xbfb8aa3b, v41
	v_add_f32_e32 v40, 1.0, v40
	v_div_scale_f32 v47, s[0:1], v40, v40, 1.0
	v_rcp_f32_e32 v48, v47
	v_add_f32_e32 v46, 1.0, v46
	v_exp_f32_e32 v41, v41
	v_and_b32_e32 v49, 0xffff0000, v82
	v_fma_f32 v52, -v47, v48, 1.0
	v_fmac_f32_e32 v48, v52, v48
	v_div_scale_f32 v52, vcc, 1.0, v40, 1.0
	v_mul_f32_e32 v53, v52, v48
	v_fma_f32 v54, -v47, v53, v52
	v_fmac_f32_e32 v53, v54, v48
	v_fma_f32 v47, -v47, v53, v52
	v_div_scale_f32 v52, s[0:1], v46, v46, 1.0
	v_rcp_f32_e32 v54, v52
	v_div_fmas_f32 v47, v47, v48, v53
	v_div_fixup_f32 v40, v47, v40, 1.0
	v_mul_f32_e32 v36, v36, v40
	v_fma_f32 v40, -v52, v54, 1.0
	v_fmac_f32_e32 v54, v40, v54
	v_div_scale_f32 v40, vcc, 1.0, v46, 1.0
	v_mul_f32_e32 v47, v40, v54
	v_fma_f32 v48, -v52, v47, v40
	v_add_f32_e32 v41, 1.0, v41
	v_fmac_f32_e32 v47, v48, v54
	v_div_scale_f32 v48, s[0:1], v41, v41, 1.0
	v_fma_f32 v40, -v52, v47, v40
	v_rcp_f32_e32 v52, v48
	v_div_fmas_f32 v40, v40, v54, v47
	v_div_fixup_f32 v40, v40, v46, 1.0
	v_mul_f32_e32 v47, 0xbfb8aa3b, v49
	v_mul_f32_e32 v40, v32, v40
	v_fma_f32 v32, -v48, v52, 1.0
	v_exp_f32_e32 v47, v47
	v_fmac_f32_e32 v52, v32, v52
	v_div_scale_f32 v32, vcc, 1.0, v41, 1.0
	v_mul_f32_e32 v46, v32, v52
	v_fma_f32 v49, -v48, v46, v32
	v_fmac_f32_e32 v46, v49, v52
	v_add_f32_e32 v47, 1.0, v47
	v_fma_f32 v32, -v48, v46, v32
	v_div_scale_f32 v48, s[0:1], v47, v47, 1.0
	v_rcp_f32_e32 v49, v48
	v_lshlrev_b32_e32 v42, 16, v81
	v_div_fmas_f32 v32, v32, v52, v46
	v_mul_f32_e32 v42, 0xbfb8aa3b, v42
	v_div_fixup_f32 v32, v32, v41, 1.0
	v_exp_f32_e32 v42, v42
	v_mul_f32_e32 v32, v37, v32
	v_fma_f32 v37, -v48, v49, 1.0
	v_fmac_f32_e32 v49, v37, v49
	v_div_scale_f32 v37, vcc, 1.0, v47, 1.0
	v_mul_f32_e32 v41, v37, v49
	v_fma_f32 v46, -v48, v41, v37
	v_add_f32_e32 v42, 1.0, v42
	v_fmac_f32_e32 v41, v46, v49
	v_div_scale_f32 v46, s[0:1], v42, v42, 1.0
	v_fma_f32 v37, -v48, v41, v37
	v_rcp_f32_e32 v48, v46
	v_div_fmas_f32 v37, v37, v49, v41
	v_lshlrev_b32_e32 v50, 16, v83
	v_div_fixup_f32 v37, v37, v47, 1.0
	v_mul_f32_e32 v37, v33, v37
	v_fma_f32 v33, -v46, v48, 1.0
	v_mul_f32_e32 v47, 0xbfb8aa3b, v50
	v_fmac_f32_e32 v48, v33, v48
	v_div_scale_f32 v33, vcc, 1.0, v42, 1.0
	v_exp_f32_e32 v47, v47
	v_mul_f32_e32 v41, v33, v48
	v_fma_f32 v49, -v46, v41, v33
	v_fmac_f32_e32 v41, v49, v48
	v_fma_f32 v33, -v46, v41, v33
	v_add_f32_e32 v46, 1.0, v47
	v_div_scale_f32 v47, s[0:1], v46, v46, 1.0
	v_rcp_f32_e32 v49, v47
	v_and_b32_e32 v43, 0xffff0000, v81
	v_div_fmas_f32 v33, v33, v48, v41
	v_div_fixup_f32 v33, v33, v42, 1.0
	v_mul_f32_e32 v42, 0xbfb8aa3b, v43
	v_exp_f32_e32 v42, v42
	v_mul_f32_e32 v33, v38, v33
	v_fma_f32 v38, -v47, v49, 1.0
	v_fmac_f32_e32 v49, v38, v49
	v_div_scale_f32 v38, vcc, 1.0, v46, 1.0
	v_mul_f32_e32 v41, v38, v49
	v_fma_f32 v43, -v47, v41, v38
	v_add_f32_e32 v42, 1.0, v42
	v_fmac_f32_e32 v41, v43, v49
	v_div_scale_f32 v43, s[0:1], v42, v42, 1.0
	v_fma_f32 v38, -v47, v41, v38
	v_rcp_f32_e32 v47, v43
	v_div_fmas_f32 v38, v38, v49, v41
	v_and_b32_e32 v51, 0xffff0000, v83
	v_div_fixup_f32 v38, v38, v46, 1.0
	v_mul_f32_e32 v38, v34, v38
	v_fma_f32 v34, -v43, v47, 1.0
	v_mul_f32_e32 v46, 0xbfb8aa3b, v51
	v_fmac_f32_e32 v47, v34, v47
	v_div_scale_f32 v34, vcc, 1.0, v42, 1.0
	v_exp_f32_e32 v46, v46
	v_mul_f32_e32 v41, v34, v47
	v_fma_f32 v48, -v43, v41, v34
	v_fmac_f32_e32 v41, v48, v47
	v_fma_f32 v34, -v43, v41, v34
	v_add_f32_e32 v43, 1.0, v46
	v_div_scale_f32 v46, s[0:1], v43, v43, 1.0
	v_rcp_f32_e32 v48, v46
	v_div_fmas_f32 v34, v34, v47, v41
	v_div_fixup_f32 v34, v34, v42, 1.0
	v_mul_f32_e32 v34, v39, v34
	v_fma_f32 v39, -v46, v48, 1.0
	v_fmac_f32_e32 v48, v39, v48
	v_div_scale_f32 v39, vcc, 1.0, v43, 1.0
	v_mul_f32_e32 v41, v39, v48
	v_fma_f32 v42, -v46, v41, v39
	v_fmac_f32_e32 v41, v42, v48
	v_fma_f32 v39, -v46, v41, v39
	v_div_fmas_f32 v39, v39, v48, v41
	v_div_fixup_f32 v39, v39, v43, 1.0
	v_mul_f32_e32 v35, v35, v39
	v_cvt_pk_bf16_f32 v32, v36, v32
	v_cvt_pk_bf16_f32 v33, v33, v34
	v_cvt_pk_bf16_f32 v34, v40, v37
	v_cvt_pk_bf16_f32 v35, v38, v35
	global_store_dwordx4 v[44:45], v[32:35], off offset:256 sc1
	s_waitcnt vmcnt(7)
; __device__ __forceinline__ unsigned cvt_pk_bf16(float lo, float hi) { unsigned r; asm volatile("v_cvt_pk_bf16_f32 %0, %1, %2" : "=v"(r) : "v"(lo), "v"(hi)); return r; }
; __device__ __forceinline__ float sigmoidf_(float x) { return 1.f / (1.f + __expf(-x)); }
; __device__ __forceinline__ void unpack8(const u32x4& w, float (&f)[8]) { f[0] = bflo(w.x); f[1] = bfhi(w.x); f[2] = bflo(w.y); f[3] = bfhi(w.y); f[4] = bflo(w.z); f[5] = bfhi(w.z); f[6] = bflo(w.w); f[7] = bfhi(w.w); }
;     __device__ __forceinline__ void operator()(const f32x4 (&acc)[2][2][4][2], const Unit& u, int wr, int wc, int fr, int fq) const {
;     ...
;                 for (int bj = 0; bj < 2; ++bj) { float g[8]; unpack8(gw[m][bj], g); const f32x4 a0 = acc[ai][bj][m][0], a1 = acc[ai][bj][m][1]; float o[8];
; #pragma unroll
;                     for (int e = 0; e < 4; ++e) { o[e] = a0[e] * sigmoidf_(g[e]); o[4 + e] = a1[e] * sigmoidf_(g[4 + e]); }
;                     *(u32x4*)(T + (size_t)(row0 + ai * HALF + m * 16) * DM + col0 + bj * HALF) = (u32x4){cvt_pk_bf16(o[0], o[1]), cvt_pk_bf16(o[2], o[3]), cvt_pk_bf16(o[4], o[5]), cvt_pk_bf16(o[6], o[7])}; } }
	v_lshlrev_b32_e32 v38, 16, v78
	v_mul_f32_e32 v38, 0xbfb8aa3b, v38
	v_lshlrev_b32_e32 v34, 16, v76
	v_mul_f32_e32 v34, 0xbfb8aa3b, v34
	v_exp_f32_e32 v34, v34
	v_exp_f32_e32 v38, v38
	v_and_b32_e32 v35, 0xffff0000, v76
	v_mul_f32_e32 v35, 0xbfb8aa3b, v35
	v_add_f32_e32 v34, 1.0, v34
	v_div_scale_f32 v39, s[0:1], v34, v34, 1.0
	v_rcp_f32_e32 v40, v39
	v_add_f32_e32 v38, 1.0, v38
	v_exp_f32_e32 v35, v35
	v_and_b32_e32 v41, 0xffff0000, v78
	v_fma_f32 v44, -v39, v40, 1.0
	v_fmac_f32_e32 v40, v44, v40
	v_div_scale_f32 v44, vcc, 1.0, v34, 1.0
	v_mul_f32_e32 v45, v44, v40
	v_fma_f32 v46, -v39, v45, v44
	v_fmac_f32_e32 v45, v46, v40
	v_fma_f32 v39, -v39, v45, v44
	v_div_scale_f32 v44, s[0:1], v38, v38, 1.0
	v_rcp_f32_e32 v46, v44
	v_div_fmas_f32 v39, v39, v40, v45
	v_div_fixup_f32 v34, v39, v34, 1.0
	v_mul_f32_e32 v28, v28, v34
	v_fma_f32 v34, -v44, v46, 1.0
	v_fmac_f32_e32 v46, v34, v46
	v_div_scale_f32 v34, vcc, 1.0, v38, 1.0
	v_mul_f32_e32 v39, v34, v46
	v_fma_f32 v40, -v44, v39, v34
	v_add_f32_e32 v35, 1.0, v35
	v_fmac_f32_e32 v39, v40, v46
	v_div_scale_f32 v40, s[0:1], v35, v35, 1.0
	v_fma_f32 v34, -v44, v39, v34
	v_rcp_f32_e32 v44, v40
	v_div_fmas_f32 v34, v34, v46, v39
	v_div_fixup_f32 v34, v34, v38, 1.0
	v_mul_f32_e32 v39, 0xbfb8aa3b, v41
	v_mul_f32_e32 v34, v24, v34
	v_fma_f32 v24, -v40, v44, 1.0
	v_exp_f32_e32 v39, v39
	v_fmac_f32_e32 v44, v24, v44
	v_div_scale_f32 v24, vcc, 1.0, v35, 1.0
	v_mul_f32_e32 v38, v24, v44
	v_fma_f32 v41, -v40, v38, v24
	v_fmac_f32_e32 v38, v41, v44
	v_add_f32_e32 v39, 1.0, v39
	v_fma_f32 v24, -v40, v38, v24
	v_div_scale_f32 v40, s[0:1], v39, v39, 1.0
	v_rcp_f32_e32 v41, v40
	v_lshlrev_b32_e32 v36, 16, v77
	v_div_fmas_f32 v24, v24, v44, v38
	v_mul_f32_e32 v36, 0xbfb8aa3b, v36
	v_div_fixup_f32 v24, v24, v35, 1.0
	v_exp_f32_e32 v36, v36
	v_mul_f32_e32 v24, v29, v24
	v_fma_f32 v29, -v40, v41, 1.0
	v_fmac_f32_e32 v41, v29, v41
	v_div_scale_f32 v29, vcc, 1.0, v39, 1.0
	v_mul_f32_e32 v35, v29, v41
	v_fma_f32 v38, -v40, v35, v29
	v_add_f32_e32 v36, 1.0, v36
	v_fmac_f32_e32 v35, v38, v41
	v_div_scale_f32 v38, s[0:1], v36, v36, 1.0
	v_fma_f32 v29, -v40, v35, v29
	v_rcp_f32_e32 v40, v38
	v_div_fmas_f32 v29, v29, v41, v35
	v_lshlrev_b32_e32 v42, 16, v79
	v_div_fixup_f32 v29, v29, v39, 1.0
	v_mul_f32_e32 v29, v25, v29
	v_fma_f32 v25, -v38, v40, 1.0
	v_mul_f32_e32 v39, 0xbfb8aa3b, v42
	v_fmac_f32_e32 v40, v25, v40
	v_div_scale_f32 v25, vcc, 1.0, v36, 1.0
	v_exp_f32_e32 v39, v39
	v_mul_f32_e32 v35, v25, v40
	v_fma_f32 v41, -v38, v35, v25
	v_fmac_f32_e32 v35, v41, v40
	v_fma_f32 v25, -v38, v35, v25
	v_add_f32_e32 v38, 1.0, v39
	v_div_scale_f32 v39, s[0:1], v38, v38, 1.0
	v_rcp_f32_e32 v41, v39
	v_and_b32_e32 v37, 0xffff0000, v77
	v_div_fmas_f32 v25, v25, v40, v35
	v_div_fixup_f32 v25, v25, v36, 1.0
	v_mul_f32_e32 v36, 0xbfb8aa3b, v37
	v_exp_f32_e32 v36, v36
	v_mul_f32_e32 v25, v30, v25
	v_fma_f32 v30, -v39, v41, 1.0
	v_fmac_f32_e32 v41, v30, v41
	v_div_scale_f32 v30, vcc, 1.0, v38, 1.0
	v_mul_f32_e32 v35, v30, v41
	v_fma_f32 v37, -v39, v35, v30
	v_add_f32_e32 v36, 1.0, v36
	v_fmac_f32_e32 v35, v37, v41
	v_div_scale_f32 v37, s[0:1], v36, v36, 1.0
	v_fma_f32 v30, -v39, v35, v30
	v_rcp_f32_e32 v39, v37
	v_div_fmas_f32 v30, v30, v41, v35
	v_and_b32_e32 v43, 0xffff0000, v79
	v_div_fixup_f32 v30, v30, v38, 1.0
	v_mul_f32_e32 v30, v26, v30
	v_fma_f32 v26, -v37, v39, 1.0
	v_mul_f32_e32 v38, 0xbfb8aa3b, v43
	v_fmac_f32_e32 v39, v26, v39
	v_div_scale_f32 v26, vcc, 1.0, v36, 1.0
	v_exp_f32_e32 v38, v38
	v_mul_f32_e32 v35, v26, v39
	v_fma_f32 v40, -v37, v35, v26
	v_fmac_f32_e32 v35, v40, v39
	v_fma_f32 v26, -v37, v35, v26
	v_add_f32_e32 v37, 1.0, v38
	v_div_scale_f32 v38, s[0:1], v37, v37, 1.0
	v_rcp_f32_e32 v40, v38
	v_div_fmas_f32 v26, v26, v39, v35
	v_div_fixup_f32 v26, v26, v36, 1.0
	v_mul_f32_e32 v26, v31, v26
	v_fma_f32 v31, -v38, v40, 1.0
	v_fmac_f32_e32 v40, v31, v40
	v_div_scale_f32 v31, vcc, 1.0, v37, 1.0
	v_mul_f32_e32 v35, v31, v40
	v_fma_f32 v36, -v38, v35, v31
	v_fmac_f32_e32 v35, v36, v40
	v_fma_f32 v31, -v38, v35, v31
	v_lshlrev_b64 v[32:33], 12, v[94:95]
	v_div_fmas_f32 v31, v31, v40, v35
	v_div_fixup_f32 v31, v31, v37, 1.0
	v_cvt_pk_bf16_f32 v24, v28, v24
	v_cvt_pk_bf16_f32 v25, v25, v26
	v_cvt_pk_bf16_f32 v26, v34, v29
	v_lshl_add_u64 v[28:29], s[84:85], 0, v[32:33]
	v_mul_f32_e32 v27, v27, v31
	v_lshl_add_u64 v[28:29], v[28:29], 0, v[164:165]
	v_cvt_pk_bf16_f32 v27, v30, v27
	global_store_dwordx4 v[28:29], v[24:27], off sc1
	s_waitcnt vmcnt(7)
; __device__ __forceinline__ unsigned cvt_pk_bf16(float lo, float hi) { unsigned r; asm volatile("v_cvt_pk_bf16_f32 %0, %1, %2" : "=v"(r) : "v"(lo), "v"(hi)); return r; }
; __device__ __forceinline__ float sigmoidf_(float x) { return 1.f / (1.f + __expf(-x)); }
; __device__ __forceinline__ void unpack8(const u32x4& w, float (&f)[8]) { f[0] = bflo(w.x); f[1] = bfhi(w.x); f[2] = bflo(w.y); f[3] = bfhi(w.y); f[4] = bflo(w.z); f[5] = bfhi(w.z); f[6] = bflo(w.w); f[7] = bfhi(w.w); }
;     __device__ __forceinline__ void operator()(const f32x4 (&acc)[2][2][4][2], const Unit& u, int wr, int wc, int fr, int fq) const {
;     ...
;                 for (int bj = 0; bj < 2; ++bj) { float g[8]; unpack8(gw[m][bj], g); const f32x4 a0 = acc[ai][bj][m][0], a1 = acc[ai][bj][m][1]; float o[8];
; #pragma unroll
;                     for (int e = 0; e < 4; ++e) { o[e] = a0[e] * sigmoidf_(g[e]); o[4 + e] = a1[e] * sigmoidf_(g[4 + e]); }
;                     *(u32x4*)(T + (size_t)(row0 + ai * HALF + m * 16) * DM + col0 + bj * HALF) = (u32x4){cvt_pk_bf16(o[0], o[1]), cvt_pk_bf16(o[2], o[3]), cvt_pk_bf16(o[4], o[5]), cvt_pk_bf16(o[6], o[7])}; } }
	v_lshlrev_b32_e32 v30, 16, v74
	v_mul_f32_e32 v30, 0xbfb8aa3b, v30
	v_lshlrev_b32_e32 v24, 16, v72
	v_mul_f32_e32 v24, 0xbfb8aa3b, v24
	v_exp_f32_e32 v24, v24
	v_exp_f32_e32 v30, v30
	v_and_b32_e32 v25, 0xffff0000, v72
	v_mul_f32_e32 v25, 0xbfb8aa3b, v25
	v_add_f32_e32 v24, 1.0, v24
	v_div_scale_f32 v31, s[0:1], v24, v24, 1.0
	v_rcp_f32_e32 v32, v31
	v_add_f32_e32 v30, 1.0, v30
	v_exp_f32_e32 v25, v25
	v_and_b32_e32 v33, 0xffff0000, v74
	v_fma_f32 v36, -v31, v32, 1.0
	v_fmac_f32_e32 v32, v36, v32
	v_div_scale_f32 v36, vcc, 1.0, v24, 1.0
	v_mul_f32_e32 v37, v36, v32
	v_fma_f32 v38, -v31, v37, v36
	v_fmac_f32_e32 v37, v38, v32
	v_fma_f32 v31, -v31, v37, v36
	v_div_scale_f32 v36, s[0:1], v30, v30, 1.0
	v_rcp_f32_e32 v38, v36
	v_div_fmas_f32 v31, v31, v32, v37
	v_div_fixup_f32 v24, v31, v24, 1.0
	v_mul_f32_e32 v20, v20, v24
	v_fma_f32 v24, -v36, v38, 1.0
	v_fmac_f32_e32 v38, v24, v38
	v_div_scale_f32 v24, vcc, 1.0, v30, 1.0
	v_mul_f32_e32 v31, v24, v38
	v_fma_f32 v32, -v36, v31, v24
	v_add_f32_e32 v25, 1.0, v25
	v_fmac_f32_e32 v31, v32, v38
	v_div_scale_f32 v32, s[0:1], v25, v25, 1.0
	v_fma_f32 v24, -v36, v31, v24
	v_rcp_f32_e32 v36, v32
	v_div_fmas_f32 v24, v24, v38, v31
	v_div_fixup_f32 v24, v24, v30, 1.0
	v_mul_f32_e32 v31, 0xbfb8aa3b, v33
	v_mul_f32_e32 v24, v16, v24
	v_fma_f32 v16, -v32, v36, 1.0
	v_exp_f32_e32 v31, v31
	v_fmac_f32_e32 v36, v16, v36
	v_div_scale_f32 v16, vcc, 1.0, v25, 1.0
	v_mul_f32_e32 v30, v16, v36
	v_fma_f32 v33, -v32, v30, v16
	v_fmac_f32_e32 v30, v33, v36
	v_add_f32_e32 v31, 1.0, v31
	v_fma_f32 v16, -v32, v30, v16
	v_div_scale_f32 v32, s[0:1], v31, v31, 1.0
	v_rcp_f32_e32 v33, v32
	v_lshlrev_b32_e32 v26, 16, v73
	v_div_fmas_f32 v16, v16, v36, v30
	v_mul_f32_e32 v26, 0xbfb8aa3b, v26
	v_div_fixup_f32 v16, v16, v25, 1.0
	v_exp_f32_e32 v26, v26
	v_mul_f32_e32 v16, v21, v16
	v_fma_f32 v21, -v32, v33, 1.0
	v_fmac_f32_e32 v33, v21, v33
	v_div_scale_f32 v21, vcc, 1.0, v31, 1.0
	v_mul_f32_e32 v25, v21, v33
	v_fma_f32 v30, -v32, v25, v21
	v_add_f32_e32 v26, 1.0, v26
	v_fmac_f32_e32 v25, v30, v33
	v_div_scale_f32 v30, s[0:1], v26, v26, 1.0
	v_fma_f32 v21, -v32, v25, v21
	v_rcp_f32_e32 v32, v30
	v_div_fmas_f32 v21, v21, v33, v25
	v_lshlrev_b32_e32 v34, 16, v75
	v_div_fixup_f32 v21, v21, v31, 1.0
	v_mul_f32_e32 v21, v17, v21
	v_fma_f32 v17, -v30, v32, 1.0
	v_mul_f32_e32 v31, 0xbfb8aa3b, v34
	v_fmac_f32_e32 v32, v17, v32
	v_div_scale_f32 v17, vcc, 1.0, v26, 1.0
	v_exp_f32_e32 v31, v31
	v_mul_f32_e32 v25, v17, v32
	v_fma_f32 v33, -v30, v25, v17
	v_fmac_f32_e32 v25, v33, v32
	v_fma_f32 v17, -v30, v25, v17
	v_add_f32_e32 v30, 1.0, v31
	v_div_scale_f32 v31, s[0:1], v30, v30, 1.0
	v_rcp_f32_e32 v33, v31
	v_and_b32_e32 v27, 0xffff0000, v73
	v_div_fmas_f32 v17, v17, v32, v25
	v_div_fixup_f32 v17, v17, v26, 1.0
	v_mul_f32_e32 v26, 0xbfb8aa3b, v27
	v_exp_f32_e32 v26, v26
	v_mul_f32_e32 v17, v22, v17
	v_fma_f32 v22, -v31, v33, 1.0
	v_fmac_f32_e32 v33, v22, v33
	v_div_scale_f32 v22, vcc, 1.0, v30, 1.0
	v_mul_f32_e32 v25, v22, v33
	v_fma_f32 v27, -v31, v25, v22
	v_add_f32_e32 v26, 1.0, v26
	v_fmac_f32_e32 v25, v27, v33
	v_div_scale_f32 v27, s[0:1], v26, v26, 1.0
	v_fma_f32 v22, -v31, v25, v22
	v_rcp_f32_e32 v31, v27
	v_div_fmas_f32 v22, v22, v33, v25
	v_and_b32_e32 v35, 0xffff0000, v75
	v_div_fixup_f32 v22, v22, v30, 1.0
	v_mul_f32_e32 v22, v18, v22
	v_fma_f32 v18, -v27, v31, 1.0
	v_mul_f32_e32 v30, 0xbfb8aa3b, v35
	v_fmac_f32_e32 v31, v18, v31
	v_div_scale_f32 v18, vcc, 1.0, v26, 1.0
	v_exp_f32_e32 v30, v30
	v_mul_f32_e32 v25, v18, v31
	v_fma_f32 v32, -v27, v25, v18
	v_fmac_f32_e32 v25, v32, v31
	v_fma_f32 v18, -v27, v25, v18
	v_add_f32_e32 v27, 1.0, v30
	v_div_scale_f32 v30, s[0:1], v27, v27, 1.0
	v_rcp_f32_e32 v32, v30
	v_div_fmas_f32 v18, v18, v31, v25
	v_div_fixup_f32 v18, v18, v26, 1.0
	v_mul_f32_e32 v18, v23, v18
	v_fma_f32 v23, -v30, v32, 1.0
	v_fmac_f32_e32 v32, v23, v32
	v_div_scale_f32 v23, vcc, 1.0, v27, 1.0
	v_mul_f32_e32 v25, v23, v32
	v_fma_f32 v26, -v30, v25, v23
	v_fmac_f32_e32 v25, v26, v32
	v_fma_f32 v23, -v30, v25, v23
	v_div_fmas_f32 v23, v23, v32, v25
	v_div_fixup_f32 v23, v23, v27, 1.0
	v_mul_f32_e32 v19, v19, v23
	v_cvt_pk_bf16_f32 v16, v20, v16
	v_cvt_pk_bf16_f32 v17, v17, v18
	v_cvt_pk_bf16_f32 v18, v24, v21
	v_cvt_pk_bf16_f32 v19, v22, v19
	global_store_dwordx4 v[28:29], v[16:19], off offset:256 sc1
	s_waitcnt vmcnt(7)
; __device__ __forceinline__ unsigned cvt_pk_bf16(float lo, float hi) { unsigned r; asm volatile("v_cvt_pk_bf16_f32 %0, %1, %2" : "=v"(r) : "v"(lo), "v"(hi)); return r; }
; __device__ __forceinline__ float sigmoidf_(float x) { return 1.f / (1.f + __expf(-x)); }
; __device__ __forceinline__ void unpack8(const u32x4& w, float (&f)[8]) { f[0] = bflo(w.x); f[1] = bfhi(w.x); f[2] = bflo(w.y); f[3] = bfhi(w.y); f[4] = bflo(w.z); f[5] = bfhi(w.z); f[6] = bflo(w.w); f[7] = bfhi(w.w); }
;     __device__ __forceinline__ void operator()(const f32x4 (&acc)[2][2][4][2], const Unit& u, int wr, int wc, int fr, int fq) const {
;     ...
;                 for (int bj = 0; bj < 2; ++bj) { float g[8]; unpack8(gw[m][bj], g); const f32x4 a0 = acc[ai][bj][m][0], a1 = acc[ai][bj][m][1]; float o[8];
; #pragma unroll
;                     for (int e = 0; e < 4; ++e) { o[e] = a0[e] * sigmoidf_(g[e]); o[4 + e] = a1[e] * sigmoidf_(g[4 + e]); }
;                     *(u32x4*)(T + (size_t)(row0 + ai * HALF + m * 16) * DM + col0 + bj * HALF) = (u32x4){cvt_pk_bf16(o[0], o[1]), cvt_pk_bf16(o[2], o[3]), cvt_pk_bf16(o[4], o[5]), cvt_pk_bf16(o[6], o[7])}; } }
	v_lshlrev_b32_e32 v22, 16, v70
	v_mul_f32_e32 v22, 0xbfb8aa3b, v22
	v_lshlrev_b32_e32 v18, 16, v68
	v_mul_f32_e32 v18, 0xbfb8aa3b, v18
	v_exp_f32_e32 v18, v18
	v_exp_f32_e32 v22, v22
	v_and_b32_e32 v19, 0xffff0000, v68
	v_mul_f32_e32 v19, 0xbfb8aa3b, v19
	v_add_f32_e32 v18, 1.0, v18
	v_div_scale_f32 v23, s[0:1], v18, v18, 1.0
	v_rcp_f32_e32 v24, v23
	v_add_f32_e32 v22, 1.0, v22
	v_exp_f32_e32 v19, v19
	v_and_b32_e32 v25, 0xffff0000, v70
	v_fma_f32 v28, -v23, v24, 1.0
	v_fmac_f32_e32 v24, v28, v24
	v_div_scale_f32 v28, vcc, 1.0, v18, 1.0
	v_mul_f32_e32 v29, v28, v24
	v_fma_f32 v30, -v23, v29, v28
	v_fmac_f32_e32 v29, v30, v24
	v_fma_f32 v23, -v23, v29, v28
	v_div_scale_f32 v28, s[0:1], v22, v22, 1.0
	v_rcp_f32_e32 v30, v28
	v_div_fmas_f32 v23, v23, v24, v29
	v_div_fixup_f32 v18, v23, v18, 1.0
	v_mul_f32_e32 v12, v12, v18
	v_fma_f32 v18, -v28, v30, 1.0
	v_fmac_f32_e32 v30, v18, v30
	v_div_scale_f32 v18, vcc, 1.0, v22, 1.0
	v_mul_f32_e32 v23, v18, v30
	v_fma_f32 v24, -v28, v23, v18
	v_add_f32_e32 v19, 1.0, v19
	v_fmac_f32_e32 v23, v24, v30
	v_div_scale_f32 v24, s[0:1], v19, v19, 1.0
	v_fma_f32 v18, -v28, v23, v18
	v_rcp_f32_e32 v28, v24
	v_div_fmas_f32 v18, v18, v30, v23
	v_div_fixup_f32 v18, v18, v22, 1.0
	v_mul_f32_e32 v23, 0xbfb8aa3b, v25
	v_mul_f32_e32 v18, v8, v18
	v_fma_f32 v8, -v24, v28, 1.0
	v_exp_f32_e32 v23, v23
	v_fmac_f32_e32 v28, v8, v28
	v_div_scale_f32 v8, vcc, 1.0, v19, 1.0
	v_mul_f32_e32 v22, v8, v28
	v_fma_f32 v25, -v24, v22, v8
	v_fmac_f32_e32 v22, v25, v28
	v_add_f32_e32 v23, 1.0, v23
	v_fma_f32 v8, -v24, v22, v8
	v_div_scale_f32 v24, s[0:1], v23, v23, 1.0
	v_rcp_f32_e32 v25, v24
	v_lshlrev_b32_e32 v20, 16, v69
	v_div_fmas_f32 v8, v8, v28, v22
	v_mul_f32_e32 v20, 0xbfb8aa3b, v20
	v_div_fixup_f32 v8, v8, v19, 1.0
	v_exp_f32_e32 v20, v20
	v_mul_f32_e32 v8, v13, v8
	v_fma_f32 v13, -v24, v25, 1.0
	v_fmac_f32_e32 v25, v13, v25
	v_div_scale_f32 v13, vcc, 1.0, v23, 1.0
	v_mul_f32_e32 v19, v13, v25
	v_fma_f32 v22, -v24, v19, v13
	v_add_f32_e32 v20, 1.0, v20
	v_fmac_f32_e32 v19, v22, v25
	v_div_scale_f32 v22, s[0:1], v20, v20, 1.0
	v_fma_f32 v13, -v24, v19, v13
	v_rcp_f32_e32 v24, v22
	v_div_fmas_f32 v13, v13, v25, v19
	v_lshlrev_b32_e32 v26, 16, v71
	v_div_fixup_f32 v13, v13, v23, 1.0
	v_mul_f32_e32 v13, v9, v13
	v_fma_f32 v9, -v22, v24, 1.0
	v_mul_f32_e32 v23, 0xbfb8aa3b, v26
	v_fmac_f32_e32 v24, v9, v24
	v_div_scale_f32 v9, vcc, 1.0, v20, 1.0
	v_exp_f32_e32 v23, v23
	v_mul_f32_e32 v19, v9, v24
	v_fma_f32 v25, -v22, v19, v9
	v_fmac_f32_e32 v19, v25, v24
	v_fma_f32 v9, -v22, v19, v9
	v_add_f32_e32 v22, 1.0, v23
	v_div_scale_f32 v23, s[0:1], v22, v22, 1.0
	v_rcp_f32_e32 v25, v23
	v_and_b32_e32 v21, 0xffff0000, v69
	v_div_fmas_f32 v9, v9, v24, v19
	v_div_fixup_f32 v9, v9, v20, 1.0
	v_mul_f32_e32 v20, 0xbfb8aa3b, v21
	v_exp_f32_e32 v20, v20
	v_mul_f32_e32 v9, v14, v9
	v_fma_f32 v14, -v23, v25, 1.0
	v_fmac_f32_e32 v25, v14, v25
	v_div_scale_f32 v14, vcc, 1.0, v22, 1.0
	v_mul_f32_e32 v19, v14, v25
	v_fma_f32 v21, -v23, v19, v14
	v_add_f32_e32 v20, 1.0, v20
	v_fmac_f32_e32 v19, v21, v25
	v_div_scale_f32 v21, s[0:1], v20, v20, 1.0
	v_fma_f32 v14, -v23, v19, v14
	v_rcp_f32_e32 v23, v21
	v_div_fmas_f32 v14, v14, v25, v19
	v_and_b32_e32 v27, 0xffff0000, v71
	v_div_fixup_f32 v14, v14, v22, 1.0
	v_mul_f32_e32 v14, v10, v14
	v_fma_f32 v10, -v21, v23, 1.0
	v_mul_f32_e32 v22, 0xbfb8aa3b, v27
	v_fmac_f32_e32 v23, v10, v23
	v_div_scale_f32 v10, vcc, 1.0, v20, 1.0
	v_exp_f32_e32 v22, v22
	v_mul_f32_e32 v19, v10, v23
	v_fma_f32 v24, -v21, v19, v10
	v_fmac_f32_e32 v19, v24, v23
	v_fma_f32 v10, -v21, v19, v10
	v_add_f32_e32 v21, 1.0, v22
	v_div_scale_f32 v22, s[0:1], v21, v21, 1.0
	v_rcp_f32_e32 v24, v22
	v_div_fmas_f32 v10, v10, v23, v19
	v_div_fixup_f32 v10, v10, v20, 1.0
	v_mul_f32_e32 v10, v15, v10
	v_fma_f32 v15, -v22, v24, 1.0
	v_fmac_f32_e32 v24, v15, v24
	v_div_scale_f32 v15, vcc, 1.0, v21, 1.0
	v_mul_f32_e32 v19, v15, v24
	v_fma_f32 v20, -v22, v19, v15
	v_fmac_f32_e32 v19, v20, v24
	v_fma_f32 v15, -v22, v19, v15
	v_lshlrev_b64 v[16:17], 12, v[92:93]
	v_div_fmas_f32 v15, v15, v24, v19
	v_div_fixup_f32 v15, v15, v21, 1.0
	v_cvt_pk_bf16_f32 v8, v12, v8
	v_cvt_pk_bf16_f32 v9, v9, v10
	v_cvt_pk_bf16_f32 v10, v18, v13
	v_lshl_add_u64 v[12:13], s[84:85], 0, v[16:17]
	v_mul_f32_e32 v11, v11, v15
	v_lshl_add_u64 v[12:13], v[12:13], 0, v[164:165]
	v_cvt_pk_bf16_f32 v11, v14, v11
	global_store_dwordx4 v[12:13], v[8:11], off sc1
	s_waitcnt vmcnt(7)
; __device__ __forceinline__ unsigned cvt_pk_bf16(float lo, float hi) { unsigned r; asm volatile("v_cvt_pk_bf16_f32 %0, %1, %2" : "=v"(r) : "v"(lo), "v"(hi)); return r; }
; __device__ __forceinline__ float sigmoidf_(float x) { return 1.f / (1.f + __expf(-x)); }
; #define PG8_BAR __builtin_amdgcn_s_barrier()
; __device__ __forceinline__ void unpack8(const u32x4& w, float (&f)[8]) { f[0] = bflo(w.x); f[1] = bfhi(w.x); f[2] = bflo(w.y); f[3] = bfhi(w.y); f[4] = bflo(w.z); f[5] = bfhi(w.z); f[6] = bflo(w.w); f[7] = bfhi(w.w); }
; template <class Epi, class Sched>
; __device__ __forceinline__ void gemm_phase(LAS unsigned char* lds, const Gemm g, const Sched& S, const Epi& E) {
;     ...
;         if (wr == 0) PG8_BAR;
;         E(acc, cur, wr, wc, fr, fq);
;         if (!has_next) break;
; #pragma unroll
;         for (int a = 0; a < 2; ++a)
; #pragma unroll
;             for (int b = 0; b < 2; ++b)
; #pragma unroll
;                 for (int m = 0; m < 4; ++m)
; #pragma unroll
;                     for (int n = 0; n < 2; ++n) acc[a][b][m][n] = (f32x4){0.f, 0.f, 0.f, 0.f};
;         cur = nxt; cA = nA; cB = nB; ++ui;
;         if (wr == 1) PG8_BAR;
;     __device__ __forceinline__ void operator()(const f32x4 (&acc)[2][2][4][2], const Unit& u, int wr, int wc, int fr, int fq) const {
;     ...
;                 for (int bj = 0; bj < 2; ++bj) { float g[8]; unpack8(gw[m][bj], g); const f32x4 a0 = acc[ai][bj][m][0], a1 = acc[ai][bj][m][1]; float o[8];
; #pragma unroll
;                     for (int e = 0; e < 4; ++e) { o[e] = a0[e] * sigmoidf_(g[e]); o[4 + e] = a1[e] * sigmoidf_(g[4 + e]); }
;                     *(u32x4*)(T + (size_t)(row0 + ai * HALF + m * 16) * DM + col0 + bj * HALF) = (u32x4){cvt_pk_bf16(o[0], o[1]), cvt_pk_bf16(o[2], o[3]), cvt_pk_bf16(o[4], o[5]), cvt_pk_bf16(o[6], o[7])}; } }
	v_lshlrev_b32_e32 v14, 16, v66
	v_mul_f32_e32 v14, 0xbfb8aa3b, v14
	v_lshlrev_b32_e32 v8, 16, v64
	v_mul_f32_e32 v8, 0xbfb8aa3b, v8
	v_exp_f32_e32 v8, v8
	v_exp_f32_e32 v14, v14
	v_and_b32_e32 v9, 0xffff0000, v64
	v_mul_f32_e32 v9, 0xbfb8aa3b, v9
	v_add_f32_e32 v8, 1.0, v8
	v_div_scale_f32 v15, s[0:1], v8, v8, 1.0
	v_rcp_f32_e32 v16, v15
	v_add_f32_e32 v14, 1.0, v14
	v_exp_f32_e32 v9, v9
	v_and_b32_e32 v17, 0xffff0000, v66
	v_fma_f32 v20, -v15, v16, 1.0
	v_fmac_f32_e32 v16, v20, v16
	v_div_scale_f32 v20, vcc, 1.0, v8, 1.0
	v_mul_f32_e32 v21, v20, v16
	v_fma_f32 v22, -v15, v21, v20
	v_fmac_f32_e32 v21, v22, v16
	v_fma_f32 v15, -v15, v21, v20
	v_div_scale_f32 v20, s[0:1], v14, v14, 1.0
	v_rcp_f32_e32 v22, v20
	v_div_fmas_f32 v15, v15, v16, v21
	v_div_fixup_f32 v8, v15, v8, 1.0
	v_mul_f32_e32 v4, v4, v8
	v_fma_f32 v8, -v20, v22, 1.0
	v_fmac_f32_e32 v22, v8, v22
	v_div_scale_f32 v8, vcc, 1.0, v14, 1.0
	v_mul_f32_e32 v15, v8, v22
	v_fma_f32 v16, -v20, v15, v8
	v_add_f32_e32 v9, 1.0, v9
	v_fmac_f32_e32 v15, v16, v22
	v_div_scale_f32 v16, s[0:1], v9, v9, 1.0
	v_fma_f32 v8, -v20, v15, v8
	v_rcp_f32_e32 v20, v16
	v_div_fmas_f32 v8, v8, v22, v15
	v_div_fixup_f32 v8, v8, v14, 1.0
	v_mul_f32_e32 v15, 0xbfb8aa3b, v17
	v_mul_f32_e32 v8, v0, v8
	v_fma_f32 v0, -v16, v20, 1.0
	v_exp_f32_e32 v15, v15
	v_fmac_f32_e32 v20, v0, v20
	v_div_scale_f32 v0, vcc, 1.0, v9, 1.0
	v_mul_f32_e32 v14, v0, v20
	v_fma_f32 v17, -v16, v14, v0
	v_fmac_f32_e32 v14, v17, v20
	v_add_f32_e32 v15, 1.0, v15
	v_fma_f32 v0, -v16, v14, v0
	v_div_scale_f32 v16, s[0:1], v15, v15, 1.0
	v_rcp_f32_e32 v17, v16
	v_lshlrev_b32_e32 v10, 16, v65
	v_div_fmas_f32 v0, v0, v20, v14
	v_mul_f32_e32 v10, 0xbfb8aa3b, v10
	v_div_fixup_f32 v0, v0, v9, 1.0
	v_exp_f32_e32 v10, v10
	v_mul_f32_e32 v0, v5, v0
	v_fma_f32 v5, -v16, v17, 1.0
	v_fmac_f32_e32 v17, v5, v17
	v_div_scale_f32 v5, vcc, 1.0, v15, 1.0
	v_mul_f32_e32 v9, v5, v17
	v_fma_f32 v14, -v16, v9, v5
	v_add_f32_e32 v10, 1.0, v10
	v_fmac_f32_e32 v9, v14, v17
	v_div_scale_f32 v14, s[0:1], v10, v10, 1.0
	v_fma_f32 v5, -v16, v9, v5
	v_rcp_f32_e32 v16, v14
	v_div_fmas_f32 v5, v5, v17, v9
	v_lshlrev_b32_e32 v18, 16, v67
	v_div_fixup_f32 v5, v5, v15, 1.0
	v_mul_f32_e32 v5, v1, v5
	v_fma_f32 v1, -v14, v16, 1.0
	v_mul_f32_e32 v15, 0xbfb8aa3b, v18
	v_fmac_f32_e32 v16, v1, v16
	v_div_scale_f32 v1, vcc, 1.0, v10, 1.0
	v_exp_f32_e32 v15, v15
	v_mul_f32_e32 v9, v1, v16
	v_fma_f32 v17, -v14, v9, v1
	v_fmac_f32_e32 v9, v17, v16
	v_fma_f32 v1, -v14, v9, v1
	v_add_f32_e32 v14, 1.0, v15
	v_div_scale_f32 v15, s[0:1], v14, v14, 1.0
	v_rcp_f32_e32 v17, v15
	v_and_b32_e32 v11, 0xffff0000, v65
	v_div_fmas_f32 v1, v1, v16, v9
	v_div_fixup_f32 v1, v1, v10, 1.0
	v_mul_f32_e32 v10, 0xbfb8aa3b, v11
	v_exp_f32_e32 v10, v10
	v_mul_f32_e32 v1, v6, v1
	v_fma_f32 v6, -v15, v17, 1.0
	v_fmac_f32_e32 v17, v6, v17
	v_div_scale_f32 v6, vcc, 1.0, v14, 1.0
	v_mul_f32_e32 v9, v6, v17
	v_fma_f32 v11, -v15, v9, v6
	v_add_f32_e32 v10, 1.0, v10
	v_fmac_f32_e32 v9, v11, v17
	v_div_scale_f32 v11, s[0:1], v10, v10, 1.0
	v_fma_f32 v6, -v15, v9, v6
	v_rcp_f32_e32 v15, v11
	v_div_fmas_f32 v6, v6, v17, v9
	v_and_b32_e32 v19, 0xffff0000, v67
	v_div_fixup_f32 v6, v6, v14, 1.0
	v_mul_f32_e32 v6, v2, v6
	v_fma_f32 v2, -v11, v15, 1.0
	v_mul_f32_e32 v14, 0xbfb8aa3b, v19
	v_fmac_f32_e32 v15, v2, v15
	v_div_scale_f32 v2, vcc, 1.0, v10, 1.0
	v_exp_f32_e32 v14, v14
	v_mul_f32_e32 v9, v2, v15
	v_fma_f32 v16, -v11, v9, v2
	v_fmac_f32_e32 v9, v16, v15
	v_fma_f32 v2, -v11, v9, v2
	v_add_f32_e32 v11, 1.0, v14
	v_div_scale_f32 v14, s[0:1], v11, v11, 1.0
	v_rcp_f32_e32 v16, v14
	v_div_fmas_f32 v2, v2, v15, v9
	v_div_fixup_f32 v2, v2, v10, 1.0
	v_mul_f32_e32 v2, v7, v2
	v_fma_f32 v7, -v14, v16, 1.0
	v_fmac_f32_e32 v16, v7, v16
	v_div_scale_f32 v7, vcc, 1.0, v11, 1.0
	v_mul_f32_e32 v9, v7, v16
	v_fma_f32 v10, -v14, v9, v7
	v_fmac_f32_e32 v9, v10, v16
	v_fma_f32 v7, -v14, v9, v7
	v_div_fmas_f32 v7, v7, v16, v9
	v_div_fixup_f32 v7, v7, v11, 1.0
	v_mul_f32_e32 v3, v3, v7
	s_and_b64 vcc, exec, s[4:5]
	s_mov_b64 s[0:1], -1
	v_cvt_pk_bf16_f32 v0, v4, v0
	v_cvt_pk_bf16_f32 v1, v1, v2
	v_cvt_pk_bf16_f32 v2, v8, v5
	v_cvt_pk_bf16_f32 v3, v6, v3
	global_store_dwordx4 v[12:13], v[0:3], off offset:256 sc1
	s_cbranch_vccnz .LBB0_657
	s_andn2_b64 vcc, exec, s[14:15]
	s_cbranch_vccnz .LBB0_656
	s_barrier
	s_branch .LBB0_656

; __device__ __forceinline__ unsigned cvt_pk_bf16(float lo, float hi) { unsigned r; asm volatile("v_cvt_pk_bf16_f32 %0, %1, %2" : "=v"(r) : "v"(lo), "v"(hi)); return r; }
; __device__ __forceinline__ float sigmoidf_(float x) { return 1.f / (1.f + __expf(-x)); }
; __device__ __forceinline__ void unpack8(const u32x4& w, float (&f)[8]) { f[0] = bflo(w.x); f[1] = bfhi(w.x); f[2] = bflo(w.y); f[3] = bfhi(w.y); f[4] = bflo(w.z); f[5] = bfhi(w.z); f[6] = bflo(w.w); f[7] = bfhi(w.w); }
;     __device__ __forceinline__ void operator()(const f32x4 (&acc)[2][2][4][2], const Unit& u, int wr, int wc, int fr, int fq) const {
;     ...
;         for (int ai = 0; ai < 2; ++ai) { u32x4 gw[4][2], tw[4][2];
; #pragma unroll
;             for (int m = 0; m < 4; ++m)
; #pragma unroll
;                 for (int bj = 0; bj < 2; ++bj) { const size_t r = (size_t)(row0 + ai * HALF + m * 16); gw[m][bj] = *(const u32x4*)(gate + r * ldg + col0 + bj * HALF); tw[m][bj] = *(const u32x4*)(T + r * DM + col0 + bj * HALF); }
; #pragma unroll
;             for (int m = 0; m < 4; ++m)
; #pragma unroll
;                 for (int bj = 0; bj < 2; ++bj) { float g[8], t[8]; unpack8(gw[m][bj], g); unpack8(tw[m][bj], t); const f32x4 a0 = acc[ai][bj][m][0], a1 = acc[ai][bj][m][1]; float o[8];
; #pragma unroll
;                     for (int e = 0; e < 4; ++e) { o[e] = t[e] + a0[e] * sigmoidf_(g[e]); o[4 + e] = t[4 + e] + a1[e] * sigmoidf_(g[4 + e]); }
;                     *(u32x4*)(Y + (size_t)(row0 + ai * HALF + m * 16) * DM + col0 + bj * HALF) = (u32x4){cvt_pk_bf16(o[0], o[1]), cvt_pk_bf16(o[2], o[3]), cvt_pk_bf16(o[4], o[5]), cvt_pk_bf16(o[6], o[7])}; } }
.LBB0_700:
	v_lshl_or_b32 v88, s45, 8, v225
	v_ashrrev_i32_e32 v89, 31, v88
	v_lshl_add_u32 v208, s44, 8, v185
	v_lshlrev_b64 v[206:207], 1, v[88:89]
	v_lshl_add_u64 v[212:213], s[8:9], 0, v[206:207]
	v_ashrrev_i32_e32 v209, 31, v208
	v_lshl_add_u64 v[210:211], s[84:85], 0, v[206:207]
	v_mad_i64_i32 v[88:89], s[18:19], v208, s41, v[212:213]
	v_lshlrev_b64 v[220:221], 12, v[208:209]
	v_lshl_add_u64 v[90:91], v[210:211], 0, v[220:221]
	global_load_dwordx4 v[230:233], v[88:89], off nt
	global_load_dwordx4 v[238:241], v[90:91], off nt
	global_load_dwordx4 v[180:183], v[88:89], off offset:256 nt
	global_load_dwordx4 v[176:179], v[90:91], off offset:256 nt
	v_or_b32_e32 v88, 16, v208
	v_ashrrev_i32_e32 v89, 31, v88
	v_lshlrev_b64 v[218:219], 12, v[88:89]
	v_mad_i64_i32 v[90:91], s[18:19], v88, s41, v[212:213]
	v_lshl_add_u64 v[88:89], v[210:211], 0, v[218:219]
	global_load_dwordx4 v[172:175], v[90:91], off nt
	global_load_dwordx4 v[168:171], v[88:89], off nt
	global_load_dwordx4 v[156:159], v[90:91], off offset:256 nt
	global_load_dwordx4 v[152:155], v[88:89], off offset:256 nt
	v_or_b32_e32 v88, 32, v208
	v_ashrrev_i32_e32 v89, 31, v88
	v_lshlrev_b64 v[216:217], 12, v[88:89]
	v_mad_i64_i32 v[90:91], s[18:19], v88, s41, v[212:213]
	v_lshl_add_u64 v[88:89], v[210:211], 0, v[216:217]
	global_load_dwordx4 v[140:143], v[90:91], off nt
	global_load_dwordx4 v[136:139], v[88:89], off nt
	global_load_dwordx4 v[124:127], v[90:91], off offset:256 nt
	global_load_dwordx4 v[120:123], v[88:89], off offset:256 nt
	v_or_b32_e32 v88, 48, v208
	v_ashrrev_i32_e32 v89, 31, v88
	v_lshlrev_b64 v[214:215], 12, v[88:89]
	v_mad_i64_i32 v[90:91], s[18:19], v88, s41, v[212:213]
	v_lshl_add_u64 v[88:89], v[210:211], 0, v[214:215]
	global_load_dwordx4 v[108:111], v[90:91], off nt
	global_load_dwordx4 v[104:107], v[88:89], off nt
	global_load_dwordx4 v[92:95], v[90:91], off offset:256 nt
	s_nop 0
	global_load_dwordx4 v[88:91], v[88:89], off offset:256 nt
	s_waitcnt vmcnt(0)
	v_lshlrev_b32_e32 v237, 16, v230
	v_mul_f32_e32 v237, 0xbfb8aa3b, v237
	v_exp_f32_e32 v237, v237
	v_lshlrev_b32_e32 v209, 16, v238
	v_and_b32_e32 v229, 0xffff0000, v238
	v_and_b32_e32 v242, 0xffff0000, v230
	v_add_f32_e32 v237, 1.0, v237
	v_div_scale_f32 v238, s[18:19], v237, v237, 1.0
	v_lshlrev_b32_e32 v243, 16, v231
	v_and_b32_e32 v244, 0xffff0000, v231
	v_lshlrev_b32_e32 v230, 16, v239
	v_and_b32_e32 v231, 0xffff0000, v239
	v_rcp_f32_e32 v239, v238
	v_lshlrev_b32_e32 v245, 16, v232
	v_and_b32_e32 v246, 0xffff0000, v232
	v_lshlrev_b32_e32 v247, 16, v233
	v_and_b32_e32 v236, 0xffff0000, v233
	v_lshlrev_b32_e32 v232, 16, v240
	v_and_b32_e32 v233, 0xffff0000, v240
	v_fma_f32 v240, -v238, v239, 1.0
	v_fmac_f32_e32 v239, v240, v239
	v_div_scale_f32 v240, vcc, 1.0, v237, 1.0
	v_lshlrev_b32_e32 v234, 16, v241
	v_and_b32_e32 v235, 0xffff0000, v241
	v_mul_f32_e32 v241, v240, v239
	v_fma_f32 v248, -v238, v241, v240
	v_fmac_f32_e32 v241, v248, v239
	v_fma_f32 v238, -v238, v241, v240
	v_div_fmas_f32 v238, v238, v239, v241
	v_div_fixup_f32 v237, v238, v237, 1.0
	v_fmac_f32_e32 v209, v164, v237
	v_mul_f32_e32 v164, 0xbfb8aa3b, v245
	v_exp_f32_e32 v164, v164
	s_nop 0
	v_add_f32_e32 v164, 1.0, v164
	v_div_scale_f32 v237, s[18:19], v164, v164, 1.0
	v_rcp_f32_e32 v238, v237
	s_nop 0
	v_fma_f32 v239, -v237, v238, 1.0
	v_fmac_f32_e32 v238, v239, v238
	v_div_scale_f32 v239, vcc, 1.0, v164, 1.0
	v_mul_f32_e32 v240, v239, v238
	v_fma_f32 v241, -v237, v240, v239
	v_fmac_f32_e32 v240, v241, v238
	v_fma_f32 v237, -v237, v240, v239
	v_div_fmas_f32 v237, v237, v238, v240
	v_div_fixup_f32 v164, v237, v164, 1.0
	v_fmac_f32_e32 v232, v160, v164
	v_mul_f32_e32 v160, 0xbfb8aa3b, v242
	v_exp_f32_e32 v160, v160
	s_nop 0
	v_add_f32_e32 v160, 1.0, v160
	v_div_scale_f32 v164, s[18:19], v160, v160, 1.0
	v_rcp_f32_e32 v237, v164
	s_nop 0
	v_fma_f32 v238, -v164, v237, 1.0
	v_fmac_f32_e32 v237, v238, v237
	v_div_scale_f32 v238, vcc, 1.0, v160, 1.0
	v_mul_f32_e32 v239, v238, v237
	v_fma_f32 v240, -v164, v239, v238
	v_fmac_f32_e32 v239, v240, v237
	v_fma_f32 v164, -v164, v239, v238
	v_div_fmas_f32 v164, v164, v237, v239
	v_div_fixup_f32 v160, v164, v160, 1.0
	v_fmac_f32_e32 v229, v165, v160
	v_mul_f32_e32 v160, 0xbfb8aa3b, v246
	v_exp_f32_e32 v160, v160
	s_nop 0
	v_add_f32_e32 v160, 1.0, v160
	v_div_scale_f32 v164, s[18:19], v160, v160, 1.0
	v_rcp_f32_e32 v165, v164
	s_nop 0
	v_fma_f32 v237, -v164, v165, 1.0
	v_fmac_f32_e32 v165, v237, v165
	v_div_scale_f32 v237, vcc, 1.0, v160, 1.0
	v_mul_f32_e32 v238, v237, v165
	v_fma_f32 v239, -v164, v238, v237
	v_fmac_f32_e32 v238, v239, v165
	v_fma_f32 v164, -v164, v238, v237
	v_div_fmas_f32 v164, v164, v165, v238
	v_div_fixup_f32 v160, v164, v160, 1.0
	v_fmac_f32_e32 v233, v161, v160
	v_mul_f32_e32 v160, 0xbfb8aa3b, v243
	v_exp_f32_e32 v160, v160
	s_nop 0
	v_add_f32_e32 v160, 1.0, v160
	v_div_scale_f32 v161, s[18:19], v160, v160, 1.0
	v_rcp_f32_e32 v164, v161
	s_nop 0
	v_fma_f32 v165, -v161, v164, 1.0
	v_fmac_f32_e32 v164, v165, v164
	v_div_scale_f32 v165, vcc, 1.0, v160, 1.0
	v_mul_f32_e32 v237, v165, v164
	v_fma_f32 v238, -v161, v237, v165
	v_fmac_f32_e32 v237, v238, v164
	v_fma_f32 v161, -v161, v237, v165
	v_div_fmas_f32 v161, v161, v164, v237
	v_div_fixup_f32 v160, v161, v160, 1.0
	v_fmac_f32_e32 v230, v166, v160
	v_mul_f32_e32 v160, 0xbfb8aa3b, v247
	v_exp_f32_e32 v160, v160
	s_nop 0
	v_add_f32_e32 v160, 1.0, v160
	v_div_scale_f32 v161, s[18:19], v160, v160, 1.0
	v_rcp_f32_e32 v164, v161
	s_nop 0
	v_fma_f32 v165, -v161, v164, 1.0
	v_fmac_f32_e32 v164, v165, v164
	v_div_scale_f32 v165, vcc, 1.0, v160, 1.0
	v_mul_f32_e32 v166, v165, v164
	v_fma_f32 v237, -v161, v166, v165
	v_fmac_f32_e32 v166, v237, v164
; __device__ __forceinline__ unsigned cvt_pk_bf16(float lo, float hi) { unsigned r; asm volatile("v_cvt_pk_bf16_f32 %0, %1, %2" : "=v"(r) : "v"(lo), "v"(hi)); return r; }
; __device__ __forceinline__ float sigmoidf_(float x) { return 1.f / (1.f + __expf(-x)); }
; __device__ __forceinline__ void unpack8(const u32x4& w, float (&f)[8]) { f[0] = bflo(w.x); f[1] = bfhi(w.x); f[2] = bflo(w.y); f[3] = bfhi(w.y); f[4] = bflo(w.z); f[5] = bfhi(w.z); f[6] = bflo(w.w); f[7] = bfhi(w.w); }
;     __device__ __forceinline__ void operator()(const f32x4 (&acc)[2][2][4][2], const Unit& u, int wr, int wc, int fr, int fq) const {
;     ...
;                 for (int bj = 0; bj < 2; ++bj) { float g[8], t[8]; unpack8(gw[m][bj], g); unpack8(tw[m][bj], t); const f32x4 a0 = acc[ai][bj][m][0], a1 = acc[ai][bj][m][1]; float o[8];
; #pragma unroll
;                     for (int e = 0; e < 4; ++e) { o[e] = t[e] + a0[e] * sigmoidf_(g[e]); o[4 + e] = t[4 + e] + a1[e] * sigmoidf_(g[4 + e]); }
;                     *(u32x4*)(Y + (size_t)(row0 + ai * HALF + m * 16) * DM + col0 + bj * HALF) = (u32x4){cvt_pk_bf16(o[0], o[1]), cvt_pk_bf16(o[2], o[3]), cvt_pk_bf16(o[4], o[5]), cvt_pk_bf16(o[6], o[7])}; } }
	v_fma_f32 v161, -v161, v166, v165
	v_div_fmas_f32 v161, v161, v164, v166
	v_div_fixup_f32 v160, v161, v160, 1.0
	v_fmac_f32_e32 v234, v162, v160
	v_mul_f32_e32 v160, 0xbfb8aa3b, v244
	v_exp_f32_e32 v160, v160
	s_nop 0
	v_add_f32_e32 v160, 1.0, v160
	v_div_scale_f32 v161, s[18:19], v160, v160, 1.0
	v_rcp_f32_e32 v162, v161
	s_nop 0
	v_fma_f32 v164, -v161, v162, 1.0
	v_fmac_f32_e32 v162, v164, v162
	v_div_scale_f32 v164, vcc, 1.0, v160, 1.0
	v_mul_f32_e32 v165, v164, v162
	v_fma_f32 v166, -v161, v165, v164
	v_fmac_f32_e32 v165, v166, v162
	v_fma_f32 v161, -v161, v165, v164
	v_div_fmas_f32 v161, v161, v162, v165
	v_div_fixup_f32 v160, v161, v160, 1.0
	v_fmac_f32_e32 v231, v167, v160
	v_mul_f32_e32 v160, 0xbfb8aa3b, v236
	v_exp_f32_e32 v160, v160
	v_and_b32_e32 v167, 0xffff0000, v182
	v_add_f32_e32 v160, 1.0, v160
	v_div_scale_f32 v161, s[18:19], v160, v160, 1.0
	v_rcp_f32_e32 v162, v161
	s_nop 0
	v_fma_f32 v164, -v161, v162, 1.0
	v_fmac_f32_e32 v162, v164, v162
	v_div_scale_f32 v164, vcc, 1.0, v160, 1.0
	v_mul_f32_e32 v165, v164, v162
	v_fma_f32 v166, -v161, v165, v164
	v_fmac_f32_e32 v165, v166, v162
	v_fma_f32 v161, -v161, v165, v164
	v_div_fmas_f32 v161, v161, v162, v165
	v_div_fixup_f32 v160, v161, v160, 1.0
	v_fmac_f32_e32 v235, v163, v160
	v_lshl_add_u64 v[160:161], s[76:77], 0, v[220:221]
	v_cvt_pk_bf16_f32 v162, v209, v229
	v_lshl_add_u64 v[160:161], v[160:161], 0, v[206:207]
	v_cvt_pk_bf16_f32 v163, v230, v231
	v_cvt_pk_bf16_f32 v164, v232, v233
	v_cvt_pk_bf16_f32 v165, v234, v235
	global_store_dwordx4 v[160:161], v[162:165], off sc1
	v_lshlrev_b32_e32 v166, 16, v182
	v_lshlrev_b32_e32 v182, 16, v176
	v_lshlrev_b32_e32 v162, 16, v180
	v_mul_f32_e32 v162, 0xbfb8aa3b, v162
	v_exp_f32_e32 v162, v162
	v_and_b32_e32 v163, 0xffff0000, v180
	v_lshlrev_b32_e32 v209, 16, v178
	v_and_b32_e32 v176, 0xffff0000, v176
	v_add_f32_e32 v162, 1.0, v162
	v_div_scale_f32 v221, s[18:19], v162, v162, 1.0
	v_rcp_f32_e32 v229, v221
	v_lshlrev_b32_e32 v164, 16, v181
	v_and_b32_e32 v178, 0xffff0000, v178
	v_and_b32_e32 v165, 0xffff0000, v181
	v_fma_f32 v230, -v221, v229, 1.0
	v_fmac_f32_e32 v229, v230, v229
	v_div_scale_f32 v230, vcc, 1.0, v162, 1.0
	v_mul_f32_e32 v231, v230, v229
	v_fma_f32 v232, -v221, v231, v230
	v_fmac_f32_e32 v231, v232, v229
	v_fma_f32 v221, -v221, v231, v230
	v_div_fmas_f32 v221, v221, v229, v231
	v_div_fixup_f32 v162, v221, v162, 1.0
	v_fmac_f32_e32 v182, v148, v162
	v_mul_f32_e32 v148, 0xbfb8aa3b, v166
	v_exp_f32_e32 v148, v148
	v_lshlrev_b32_e32 v180, 16, v183
	v_and_b32_e32 v181, 0xffff0000, v183
	v_lshlrev_b32_e32 v183, 16, v177
	v_add_f32_e32 v148, 1.0, v148
	v_div_scale_f32 v162, s[18:19], v148, v148, 1.0
	v_rcp_f32_e32 v166, v162
	v_lshlrev_b32_e32 v220, 16, v179
	v_and_b32_e32 v177, 0xffff0000, v177
	v_and_b32_e32 v179, 0xffff0000, v179
	v_fma_f32 v221, -v162, v166, 1.0
	v_fmac_f32_e32 v166, v221, v166
	v_div_scale_f32 v221, vcc, 1.0, v148, 1.0
	v_mul_f32_e32 v229, v221, v166
	v_fma_f32 v230, -v162, v229, v221
	v_fmac_f32_e32 v229, v230, v166
	v_fma_f32 v162, -v162, v229, v221
	v_div_fmas_f32 v162, v162, v166, v229
	v_div_fixup_f32 v148, v162, v148, 1.0
	v_fmac_f32_e32 v209, v144, v148
	v_mul_f32_e32 v144, 0xbfb8aa3b, v163
	v_exp_f32_e32 v144, v144
	s_nop 0
	v_add_f32_e32 v144, 1.0, v144
	v_div_scale_f32 v148, s[18:19], v144, v144, 1.0
	v_rcp_f32_e32 v162, v148
	s_nop 0
	v_fma_f32 v163, -v148, v162, 1.0
	v_fmac_f32_e32 v162, v163, v162
	v_div_scale_f32 v163, vcc, 1.0, v144, 1.0
	v_mul_f32_e32 v166, v163, v162
	v_fma_f32 v221, -v148, v166, v163
	v_fmac_f32_e32 v166, v221, v162
	v_fma_f32 v148, -v148, v166, v163
	v_div_fmas_f32 v148, v148, v162, v166
	v_div_fixup_f32 v144, v148, v144, 1.0
	v_fmac_f32_e32 v176, v149, v144
	v_mul_f32_e32 v144, 0xbfb8aa3b, v167
	v_exp_f32_e32 v144, v144
	v_and_b32_e32 v167, 0xffff0000, v171
	v_add_f32_e32 v144, 1.0, v144
	v_div_scale_f32 v148, s[18:19], v144, v144, 1.0
	v_rcp_f32_e32 v149, v148
	s_nop 0
	v_fma_f32 v162, -v148, v149, 1.0
	v_fmac_f32_e32 v149, v162, v149
	v_div_scale_f32 v162, vcc, 1.0, v144, 1.0
	v_mul_f32_e32 v163, v162, v149
	v_fma_f32 v166, -v148, v163, v162
	v_fmac_f32_e32 v163, v166, v149
	v_fma_f32 v148, -v148, v163, v162
	v_div_fmas_f32 v148, v148, v149, v163
	v_div_fixup_f32 v144, v148, v144, 1.0
	v_fmac_f32_e32 v178, v145, v144
	v_mul_f32_e32 v144, 0xbfb8aa3b, v164
	v_exp_f32_e32 v144, v144
	v_lshlrev_b32_e32 v164, 16, v170
	v_lshlrev_b32_e32 v166, 16, v171
	v_add_f32_e32 v144, 1.0, v144
	v_div_scale_f32 v145, s[18:19], v144, v144, 1.0
	v_rcp_f32_e32 v148, v145
	s_nop 0
	v_fma_f32 v149, -v145, v148, 1.0
	v_fmac_f32_e32 v148, v149, v148
	v_div_scale_f32 v149, vcc, 1.0, v144, 1.0
	v_mul_f32_e32 v162, v149, v148
	v_fma_f32 v163, -v145, v162, v149
	v_fmac_f32_e32 v162, v163, v148
	v_fma_f32 v145, -v145, v162, v149
	v_div_fmas_f32 v145, v145, v148, v162
	v_div_fixup_f32 v144, v145, v144, 1.0
	v_fmac_f32_e32 v183, v150, v144
	v_mul_f32_e32 v144, 0xbfb8aa3b, v180
	v_exp_f32_e32 v144, v144
	v_and_b32_e32 v163, 0xffff0000, v169
	v_add_f32_e32 v144, 1.0, v144
	v_div_scale_f32 v145, s[18:19], v144, v144, 1.0
	v_rcp_f32_e32 v148, v145
	s_nop 0
	v_fma_f32 v149, -v145, v148, 1.0
	v_fmac_f32_e32 v148, v149, v148
	v_div_scale_f32 v149, vcc, 1.0, v144, 1.0
	v_mul_f32_e32 v150, v149, v148
	v_fma_f32 v162, -v145, v150, v149
	v_fmac_f32_e32 v150, v162, v148
	v_fma_f32 v145, -v145, v150, v149
	v_div_fmas_f32 v145, v145, v148, v150
	v_div_fixup_f32 v144, v145, v144, 1.0
	v_fmac_f32_e32 v220, v146, v144
	v_mul_f32_e32 v144, 0xbfb8aa3b, v165
	v_exp_f32_e32 v144, v144
	v_lshlrev_b32_e32 v162, 16, v169
	v_and_b32_e32 v165, 0xffff0000, v170
	v_add_f32_e32 v144, 1.0, v144
; __device__ __forceinline__ unsigned cvt_pk_bf16(float lo, float hi) { unsigned r; asm volatile("v_cvt_pk_bf16_f32 %0, %1, %2" : "=v"(r) : "v"(lo), "v"(hi)); return r; }
; __device__ __forceinline__ float sigmoidf_(float x) { return 1.f / (1.f + __expf(-x)); }
; __device__ __forceinline__ void unpack8(const u32x4& w, float (&f)[8]) { f[0] = bflo(w.x); f[1] = bfhi(w.x); f[2] = bflo(w.y); f[3] = bfhi(w.y); f[4] = bflo(w.z); f[5] = bfhi(w.z); f[6] = bflo(w.w); f[7] = bfhi(w.w); }
;     __device__ __forceinline__ void operator()(const f32x4 (&acc)[2][2][4][2], const Unit& u, int wr, int wc, int fr, int fq) const {
;     ...
;                 for (int bj = 0; bj < 2; ++bj) { float g[8], t[8]; unpack8(gw[m][bj], g); unpack8(tw[m][bj], t); const f32x4 a0 = acc[ai][bj][m][0], a1 = acc[ai][bj][m][1]; float o[8];
; #pragma unroll
;                     for (int e = 0; e < 4; ++e) { o[e] = t[e] + a0[e] * sigmoidf_(g[e]); o[4 + e] = t[4 + e] + a1[e] * sigmoidf_(g[4 + e]); }
;                     *(u32x4*)(Y + (size_t)(row0 + ai * HALF + m * 16) * DM + col0 + bj * HALF) = (u32x4){cvt_pk_bf16(o[0], o[1]), cvt_pk_bf16(o[2], o[3]), cvt_pk_bf16(o[4], o[5]), cvt_pk_bf16(o[6], o[7])}; } }
	v_div_scale_f32 v145, s[18:19], v144, v144, 1.0
	v_rcp_f32_e32 v146, v145
	s_nop 0
	v_fma_f32 v148, -v145, v146, 1.0
	v_fmac_f32_e32 v146, v148, v146
	v_div_scale_f32 v148, vcc, 1.0, v144, 1.0
	v_mul_f32_e32 v149, v148, v146
	v_fma_f32 v150, -v145, v149, v148
	v_fmac_f32_e32 v149, v150, v146
	v_fma_f32 v145, -v145, v149, v148
	v_div_fmas_f32 v145, v145, v146, v149
	v_div_fixup_f32 v144, v145, v144, 1.0
	v_fmac_f32_e32 v177, v151, v144
	v_mul_f32_e32 v144, 0xbfb8aa3b, v181
	v_exp_f32_e32 v144, v144
	v_and_b32_e32 v151, 0xffff0000, v175
	v_add_f32_e32 v144, 1.0, v144
	v_div_scale_f32 v145, s[18:19], v144, v144, 1.0
	v_rcp_f32_e32 v146, v145
	s_nop 0
	v_fma_f32 v148, -v145, v146, 1.0
	v_fmac_f32_e32 v146, v148, v146
	v_div_scale_f32 v148, vcc, 1.0, v144, 1.0
	v_mul_f32_e32 v149, v148, v146
	v_fma_f32 v150, -v145, v149, v148
	v_fmac_f32_e32 v149, v150, v146
	v_fma_f32 v145, -v145, v149, v148
	v_div_fmas_f32 v145, v145, v146, v149
	v_div_fixup_f32 v144, v145, v144, 1.0
	v_fmac_f32_e32 v179, v147, v144
	v_cvt_pk_bf16_f32 v144, v182, v176
	v_cvt_pk_bf16_f32 v145, v183, v177
	v_cvt_pk_bf16_f32 v146, v209, v178
	v_cvt_pk_bf16_f32 v147, v220, v179
	global_store_dwordx4 v[160:161], v[144:147], off offset:256 sc1
	v_lshlrev_b32_e32 v160, 16, v168
	v_and_b32_e32 v161, 0xffff0000, v168
	v_lshlrev_b32_e32 v144, 16, v172
	v_mul_f32_e32 v144, 0xbfb8aa3b, v144
	v_exp_f32_e32 v144, v144
	v_and_b32_e32 v145, 0xffff0000, v172
	v_lshlrev_b32_e32 v148, 16, v174
	v_and_b32_e32 v149, 0xffff0000, v174
	v_add_f32_e32 v144, 1.0, v144
	v_div_scale_f32 v168, s[18:19], v144, v144, 1.0
	v_rcp_f32_e32 v169, v168
	v_lshlrev_b32_e32 v146, 16, v173
	v_lshlrev_b32_e32 v150, 16, v175
	v_and_b32_e32 v147, 0xffff0000, v173
	v_fma_f32 v170, -v168, v169, 1.0
	v_fmac_f32_e32 v169, v170, v169
	v_div_scale_f32 v170, vcc, 1.0, v144, 1.0
	v_mul_f32_e32 v171, v170, v169
	v_fma_f32 v172, -v168, v171, v170
	v_fmac_f32_e32 v171, v172, v169
	v_fma_f32 v168, -v168, v171, v170
	v_div_fmas_f32 v168, v168, v169, v171
	v_div_fixup_f32 v144, v168, v144, 1.0
	v_fmac_f32_e32 v160, v132, v144
	v_mul_f32_e32 v132, 0xbfb8aa3b, v148
	v_exp_f32_e32 v132, v132
	s_nop 0
	v_add_f32_e32 v132, 1.0, v132
	v_div_scale_f32 v144, s[18:19], v132, v132, 1.0
	v_rcp_f32_e32 v148, v144
	s_nop 0
	v_fma_f32 v168, -v144, v148, 1.0
	v_fmac_f32_e32 v148, v168, v148
	v_div_scale_f32 v168, vcc, 1.0, v132, 1.0
	v_mul_f32_e32 v169, v168, v148
	v_fma_f32 v170, -v144, v169, v168
	v_fmac_f32_e32 v169, v170, v148
	v_fma_f32 v144, -v144, v169, v168
	v_div_fmas_f32 v144, v144, v148, v169
	v_div_fixup_f32 v132, v144, v132, 1.0
	v_fmac_f32_e32 v164, v128, v132
	v_mul_f32_e32 v128, 0xbfb8aa3b, v145
	v_exp_f32_e32 v128, v128
	s_nop 0
	v_add_f32_e32 v128, 1.0, v128
	v_div_scale_f32 v132, s[18:19], v128, v128, 1.0
	v_rcp_f32_e32 v144, v132
	s_nop 0
	v_fma_f32 v145, -v132, v144, 1.0
	v_fmac_f32_e32 v144, v145, v144
	v_div_scale_f32 v145, vcc, 1.0, v128, 1.0
	v_mul_f32_e32 v148, v145, v144
	v_fma_f32 v168, -v132, v148, v145
	v_fmac_f32_e32 v148, v168, v144
	v_fma_f32 v132, -v132, v148, v145
	v_div_fmas_f32 v132, v132, v144, v148
	v_div_fixup_f32 v128, v132, v128, 1.0
	v_fmac_f32_e32 v161, v133, v128
	v_mul_f32_e32 v128, 0xbfb8aa3b, v149
	v_exp_f32_e32 v128, v128
	v_and_b32_e32 v149, 0xffff0000, v153
	v_add_f32_e32 v128, 1.0, v128
	v_div_scale_f32 v132, s[18:19], v128, v128, 1.0
	v_rcp_f32_e32 v133, v132
	s_nop 0
	v_fma_f32 v144, -v132, v133, 1.0
	v_fmac_f32_e32 v133, v144, v133
	v_div_scale_f32 v144, vcc, 1.0, v128, 1.0
	v_mul_f32_e32 v145, v144, v133
	v_fma_f32 v148, -v132, v145, v144
	v_fmac_f32_e32 v145, v148, v133
	v_fma_f32 v132, -v132, v145, v144
	v_div_fmas_f32 v132, v132, v133, v145
	v_div_fixup_f32 v128, v132, v128, 1.0
	v_fmac_f32_e32 v165, v129, v128
	v_mul_f32_e32 v128, 0xbfb8aa3b, v146
	v_exp_f32_e32 v128, v128
	v_lshlrev_b32_e32 v146, 16, v152
	v_lshlrev_b32_e32 v148, 16, v153
	v_and_b32_e32 v153, 0xffff0000, v155
	v_add_f32_e32 v128, 1.0, v128
	v_div_scale_f32 v129, s[18:19], v128, v128, 1.0
	v_rcp_f32_e32 v132, v129
	s_nop 0
	v_fma_f32 v133, -v129, v132, 1.0
	v_fmac_f32_e32 v132, v133, v132
	v_div_scale_f32 v133, vcc, 1.0, v128, 1.0
	v_mul_f32_e32 v144, v133, v132
	v_fma_f32 v145, -v129, v144, v133
	v_fmac_f32_e32 v144, v145, v132
	v_fma_f32 v129, -v129, v144, v133
	v_div_fmas_f32 v129, v129, v132, v144
	v_div_fixup_f32 v128, v129, v128, 1.0
	v_fmac_f32_e32 v162, v134, v128
	v_mul_f32_e32 v128, 0xbfb8aa3b, v150
	v_exp_f32_e32 v128, v128
	v_lshlrev_b32_e32 v150, 16, v154
	v_and_b32_e32 v145, 0xffff0000, v159
	v_add_f32_e32 v128, 1.0, v128
	v_div_scale_f32 v129, s[18:19], v128, v128, 1.0
	v_rcp_f32_e32 v132, v129
	s_nop 0
	v_fma_f32 v133, -v129, v132, 1.0
	v_fmac_f32_e32 v132, v133, v132
	v_div_scale_f32 v133, vcc, 1.0, v128, 1.0
	v_mul_f32_e32 v134, v133, v132
	v_fma_f32 v144, -v129, v134, v133
	v_fmac_f32_e32 v134, v144, v132
	v_fma_f32 v129, -v129, v134, v133
	v_div_fmas_f32 v129, v129, v132, v134
	v_div_fixup_f32 v128, v129, v128, 1.0
	v_fmac_f32_e32 v166, v130, v128
	v_mul_f32_e32 v128, 0xbfb8aa3b, v147
	v_exp_f32_e32 v128, v128
	v_and_b32_e32 v147, 0xffff0000, v152
	v_lshlrev_b32_e32 v152, 16, v155
	v_lshlrev_b32_e32 v144, 16, v159
	v_add_f32_e32 v128, 1.0, v128
	v_div_scale_f32 v129, s[18:19], v128, v128, 1.0
	v_rcp_f32_e32 v130, v129
	s_nop 0
	v_fma_f32 v132, -v129, v130, 1.0
	v_fmac_f32_e32 v130, v132, v130
	v_div_scale_f32 v132, vcc, 1.0, v128, 1.0
	v_mul_f32_e32 v133, v132, v130
	v_fma_f32 v134, -v129, v133, v132
	v_fmac_f32_e32 v133, v134, v130
	v_fma_f32 v129, -v129, v133, v132
	v_div_fmas_f32 v129, v129, v130, v133
	v_div_fixup_f32 v128, v129, v128, 1.0
	v_fmac_f32_e32 v163, v135, v128
	v_mul_f32_e32 v128, 0xbfb8aa3b, v151
; __device__ __forceinline__ unsigned cvt_pk_bf16(float lo, float hi) { unsigned r; asm volatile("v_cvt_pk_bf16_f32 %0, %1, %2" : "=v"(r) : "v"(lo), "v"(hi)); return r; }
; __device__ __forceinline__ float sigmoidf_(float x) { return 1.f / (1.f + __expf(-x)); }
; __device__ __forceinline__ void unpack8(const u32x4& w, float (&f)[8]) { f[0] = bflo(w.x); f[1] = bfhi(w.x); f[2] = bflo(w.y); f[3] = bfhi(w.y); f[4] = bflo(w.z); f[5] = bfhi(w.z); f[6] = bflo(w.w); f[7] = bfhi(w.w); }
;     __device__ __forceinline__ void operator()(const f32x4 (&acc)[2][2][4][2], const Unit& u, int wr, int wc, int fr, int fq) const {
;     ...
;                 for (int bj = 0; bj < 2; ++bj) { float g[8], t[8]; unpack8(gw[m][bj], g); unpack8(tw[m][bj], t); const f32x4 a0 = acc[ai][bj][m][0], a1 = acc[ai][bj][m][1]; float o[8];
; #pragma unroll
;                     for (int e = 0; e < 4; ++e) { o[e] = t[e] + a0[e] * sigmoidf_(g[e]); o[4 + e] = t[4 + e] + a1[e] * sigmoidf_(g[4 + e]); }
;                     *(u32x4*)(Y + (size_t)(row0 + ai * HALF + m * 16) * DM + col0 + bj * HALF) = (u32x4){cvt_pk_bf16(o[0], o[1]), cvt_pk_bf16(o[2], o[3]), cvt_pk_bf16(o[4], o[5]), cvt_pk_bf16(o[6], o[7])}; } }
	v_exp_f32_e32 v128, v128
	v_and_b32_e32 v151, 0xffff0000, v154
	v_and_b32_e32 v135, 0xffff0000, v158
	v_add_f32_e32 v128, 1.0, v128
	v_div_scale_f32 v129, s[18:19], v128, v128, 1.0
	v_rcp_f32_e32 v130, v129
	s_nop 0
	v_fma_f32 v132, -v129, v130, 1.0
	v_fmac_f32_e32 v130, v132, v130
	v_div_scale_f32 v132, vcc, 1.0, v128, 1.0
	v_mul_f32_e32 v133, v132, v130
	v_fma_f32 v134, -v129, v133, v132
	v_fmac_f32_e32 v133, v134, v130
	v_fma_f32 v129, -v129, v133, v132
	v_div_fmas_f32 v129, v129, v130, v133
	v_div_fixup_f32 v128, v129, v128, 1.0
	v_fmac_f32_e32 v167, v131, v128
	v_lshl_add_u64 v[128:129], s[76:77], 0, v[218:219]
	v_cvt_pk_bf16_f32 v130, v160, v161
	v_lshl_add_u64 v[128:129], v[128:129], 0, v[206:207]
	v_cvt_pk_bf16_f32 v131, v162, v163
	v_cvt_pk_bf16_f32 v132, v164, v165
	v_cvt_pk_bf16_f32 v133, v166, v167
	global_store_dwordx4 v[128:129], v[130:133], off sc1
	v_lshlrev_b32_e32 v134, 16, v158
	s_nop 0
	v_lshlrev_b32_e32 v130, 16, v156
	v_mul_f32_e32 v130, 0xbfb8aa3b, v130
	v_exp_f32_e32 v130, v130
	v_and_b32_e32 v131, 0xffff0000, v156
	v_lshlrev_b32_e32 v132, 16, v157
	v_and_b32_e32 v133, 0xffff0000, v157
	v_add_f32_e32 v130, 1.0, v130
	v_div_scale_f32 v154, s[18:19], v130, v130, 1.0
	v_rcp_f32_e32 v155, v154
	s_nop 0
	v_fma_f32 v156, -v154, v155, 1.0
	v_fmac_f32_e32 v155, v156, v155
	v_div_scale_f32 v156, vcc, 1.0, v130, 1.0
	v_mul_f32_e32 v157, v156, v155
	v_fma_f32 v158, -v154, v157, v156
	v_fmac_f32_e32 v157, v158, v155
	v_fma_f32 v154, -v154, v157, v156
	v_div_fmas_f32 v154, v154, v155, v157
	v_div_fixup_f32 v130, v154, v130, 1.0
	v_fmac_f32_e32 v146, v116, v130
	v_mul_f32_e32 v116, 0xbfb8aa3b, v134
	v_exp_f32_e32 v116, v116
	s_nop 0
	v_add_f32_e32 v116, 1.0, v116
	v_div_scale_f32 v130, s[18:19], v116, v116, 1.0
	v_rcp_f32_e32 v134, v130
	s_nop 0
	v_fma_f32 v154, -v130, v134, 1.0
	v_fmac_f32_e32 v134, v154, v134
	v_div_scale_f32 v154, vcc, 1.0, v116, 1.0
	v_mul_f32_e32 v155, v154, v134
	v_fma_f32 v156, -v130, v155, v154
	v_fmac_f32_e32 v155, v156, v134
	v_fma_f32 v130, -v130, v155, v154
	v_div_fmas_f32 v130, v130, v134, v155
	v_div_fixup_f32 v116, v130, v116, 1.0
	v_fmac_f32_e32 v150, v112, v116
	v_mul_f32_e32 v112, 0xbfb8aa3b, v131
	v_exp_f32_e32 v112, v112
	s_nop 0
	v_add_f32_e32 v112, 1.0, v112
	v_div_scale_f32 v116, s[18:19], v112, v112, 1.0
	v_rcp_f32_e32 v130, v116
	s_nop 0
	v_fma_f32 v131, -v116, v130, 1.0
	v_fmac_f32_e32 v130, v131, v130
	v_div_scale_f32 v131, vcc, 1.0, v112, 1.0
	v_mul_f32_e32 v134, v131, v130
	v_fma_f32 v154, -v116, v134, v131
	v_fmac_f32_e32 v134, v154, v130
	v_fma_f32 v116, -v116, v134, v131
	v_div_fmas_f32 v116, v116, v130, v134
	v_div_fixup_f32 v112, v116, v112, 1.0
	v_fmac_f32_e32 v147, v117, v112
	v_mul_f32_e32 v112, 0xbfb8aa3b, v135
	v_exp_f32_e32 v112, v112
	v_and_b32_e32 v135, 0xffff0000, v139
	v_add_f32_e32 v112, 1.0, v112
	v_div_scale_f32 v116, s[18:19], v112, v112, 1.0
	v_rcp_f32_e32 v117, v116
	s_nop 0
	v_fma_f32 v130, -v116, v117, 1.0
	v_fmac_f32_e32 v117, v130, v117
	v_div_scale_f32 v130, vcc, 1.0, v112, 1.0
	v_mul_f32_e32 v131, v130, v117
	v_fma_f32 v134, -v116, v131, v130
	v_fmac_f32_e32 v131, v134, v117
	v_fma_f32 v116, -v116, v131, v130
	v_div_fmas_f32 v116, v116, v117, v131
	v_div_fixup_f32 v112, v116, v112, 1.0
	v_fmac_f32_e32 v151, v113, v112
	v_mul_f32_e32 v112, 0xbfb8aa3b, v132
	v_exp_f32_e32 v112, v112
	v_lshlrev_b32_e32 v132, 16, v138
	v_lshlrev_b32_e32 v134, 16, v139
	v_add_f32_e32 v112, 1.0, v112
	v_div_scale_f32 v113, s[18:19], v112, v112, 1.0
	v_rcp_f32_e32 v116, v113
	s_nop 0
	v_fma_f32 v117, -v113, v116, 1.0
	v_fmac_f32_e32 v116, v117, v116
	v_div_scale_f32 v117, vcc, 1.0, v112, 1.0
	v_mul_f32_e32 v130, v117, v116
	v_fma_f32 v131, -v113, v130, v117
	v_fmac_f32_e32 v130, v131, v116
	v_fma_f32 v113, -v113, v130, v117
	v_div_fmas_f32 v113, v113, v116, v130
	v_div_fixup_f32 v112, v113, v112, 1.0
	v_fmac_f32_e32 v148, v118, v112
	v_mul_f32_e32 v112, 0xbfb8aa3b, v144
	v_exp_f32_e32 v112, v112
	v_and_b32_e32 v131, 0xffff0000, v137
	v_add_f32_e32 v112, 1.0, v112
	v_div_scale_f32 v113, s[18:19], v112, v112, 1.0
	v_rcp_f32_e32 v116, v113
	s_nop 0
	v_fma_f32 v117, -v113, v116, 1.0
	v_fmac_f32_e32 v116, v117, v116
	v_div_scale_f32 v117, vcc, 1.0, v112, 1.0
	v_mul_f32_e32 v118, v117, v116
	v_fma_f32 v130, -v113, v118, v117
	v_fmac_f32_e32 v118, v130, v116
	v_fma_f32 v113, -v113, v118, v117
	v_div_fmas_f32 v113, v113, v116, v118
	v_div_fixup_f32 v112, v113, v112, 1.0
	v_fmac_f32_e32 v152, v114, v112
	v_mul_f32_e32 v112, 0xbfb8aa3b, v133
	v_exp_f32_e32 v112, v112
	v_lshlrev_b32_e32 v130, 16, v137
	v_and_b32_e32 v133, 0xffff0000, v138
	v_add_f32_e32 v112, 1.0, v112
	v_div_scale_f32 v113, s[18:19], v112, v112, 1.0
	v_rcp_f32_e32 v114, v113
	s_nop 0
	v_fma_f32 v116, -v113, v114, 1.0
	v_fmac_f32_e32 v114, v116, v114
	v_div_scale_f32 v116, vcc, 1.0, v112, 1.0
	v_mul_f32_e32 v117, v116, v114
	v_fma_f32 v118, -v113, v117, v116
	v_fmac_f32_e32 v117, v118, v114
	v_fma_f32 v113, -v113, v117, v116
	v_div_fmas_f32 v113, v113, v114, v117
	v_div_fixup_f32 v112, v113, v112, 1.0
	v_fmac_f32_e32 v149, v119, v112
	v_mul_f32_e32 v112, 0xbfb8aa3b, v145
	v_exp_f32_e32 v112, v112
	v_and_b32_e32 v119, 0xffff0000, v143
	v_add_f32_e32 v112, 1.0, v112
	v_div_scale_f32 v113, s[18:19], v112, v112, 1.0
	v_rcp_f32_e32 v114, v113
	s_nop 0
	v_fma_f32 v116, -v113, v114, 1.0
	v_fmac_f32_e32 v114, v116, v114
	v_div_scale_f32 v116, vcc, 1.0, v112, 1.0
	v_mul_f32_e32 v117, v116, v114
	v_fma_f32 v118, -v113, v117, v116
	v_fmac_f32_e32 v117, v118, v114
	v_fma_f32 v113, -v113, v117, v116
	v_div_fmas_f32 v113, v113, v114, v117
	v_div_fixup_f32 v112, v113, v112, 1.0
	v_fmac_f32_e32 v153, v115, v112
	v_cvt_pk_bf16_f32 v112, v146, v147
; __device__ __forceinline__ unsigned cvt_pk_bf16(float lo, float hi) { unsigned r; asm volatile("v_cvt_pk_bf16_f32 %0, %1, %2" : "=v"(r) : "v"(lo), "v"(hi)); return r; }
; __device__ __forceinline__ float sigmoidf_(float x) { return 1.f / (1.f + __expf(-x)); }
; __device__ __forceinline__ void unpack8(const u32x4& w, float (&f)[8]) { f[0] = bflo(w.x); f[1] = bfhi(w.x); f[2] = bflo(w.y); f[3] = bfhi(w.y); f[4] = bflo(w.z); f[5] = bfhi(w.z); f[6] = bflo(w.w); f[7] = bfhi(w.w); }
;     __device__ __forceinline__ void operator()(const f32x4 (&acc)[2][2][4][2], const Unit& u, int wr, int wc, int fr, int fq) const {
;     ...
;                 for (int bj = 0; bj < 2; ++bj) { float g[8], t[8]; unpack8(gw[m][bj], g); unpack8(tw[m][bj], t); const f32x4 a0 = acc[ai][bj][m][0], a1 = acc[ai][bj][m][1]; float o[8];
; #pragma unroll
;                     for (int e = 0; e < 4; ++e) { o[e] = t[e] + a0[e] * sigmoidf_(g[e]); o[4 + e] = t[4 + e] + a1[e] * sigmoidf_(g[4 + e]); }
;                     *(u32x4*)(Y + (size_t)(row0 + ai * HALF + m * 16) * DM + col0 + bj * HALF) = (u32x4){cvt_pk_bf16(o[0], o[1]), cvt_pk_bf16(o[2], o[3]), cvt_pk_bf16(o[4], o[5]), cvt_pk_bf16(o[6], o[7])}; } }
	v_cvt_pk_bf16_f32 v113, v148, v149
	v_cvt_pk_bf16_f32 v114, v150, v151
	v_cvt_pk_bf16_f32 v115, v152, v153
	global_store_dwordx4 v[128:129], v[112:115], off offset:256 sc1
	v_lshlrev_b32_e32 v128, 16, v136
	v_and_b32_e32 v129, 0xffff0000, v136
	v_lshlrev_b32_e32 v112, 16, v140
	v_mul_f32_e32 v112, 0xbfb8aa3b, v112
	v_exp_f32_e32 v112, v112
	v_and_b32_e32 v113, 0xffff0000, v140
	v_lshlrev_b32_e32 v116, 16, v142
	v_and_b32_e32 v117, 0xffff0000, v142
	v_add_f32_e32 v112, 1.0, v112
	v_div_scale_f32 v136, s[18:19], v112, v112, 1.0
	v_rcp_f32_e32 v137, v136
	v_lshlrev_b32_e32 v114, 16, v141
	v_lshlrev_b32_e32 v118, 16, v143
	v_and_b32_e32 v115, 0xffff0000, v141
	v_fma_f32 v138, -v136, v137, 1.0
	v_fmac_f32_e32 v137, v138, v137
	v_div_scale_f32 v138, vcc, 1.0, v112, 1.0
	v_mul_f32_e32 v139, v138, v137
	v_fma_f32 v140, -v136, v139, v138
	v_fmac_f32_e32 v139, v140, v137
	v_fma_f32 v136, -v136, v139, v138
	v_div_fmas_f32 v136, v136, v137, v139
	v_div_fixup_f32 v112, v136, v112, 1.0
	v_fmac_f32_e32 v128, v100, v112
	v_mul_f32_e32 v100, 0xbfb8aa3b, v116
	v_exp_f32_e32 v100, v100
	s_nop 0
	v_add_f32_e32 v100, 1.0, v100
	v_div_scale_f32 v112, s[18:19], v100, v100, 1.0
	v_rcp_f32_e32 v116, v112
	s_nop 0
	v_fma_f32 v136, -v112, v116, 1.0
	v_fmac_f32_e32 v116, v136, v116
	v_div_scale_f32 v136, vcc, 1.0, v100, 1.0
	v_mul_f32_e32 v137, v136, v116
	v_fma_f32 v138, -v112, v137, v136
	v_fmac_f32_e32 v137, v138, v116
	v_fma_f32 v112, -v112, v137, v136
	v_div_fmas_f32 v112, v112, v116, v137
	v_div_fixup_f32 v100, v112, v100, 1.0
	v_fmac_f32_e32 v132, v96, v100
	v_mul_f32_e32 v96, 0xbfb8aa3b, v113
	v_exp_f32_e32 v96, v96
	s_nop 0
	v_add_f32_e32 v96, 1.0, v96
	v_div_scale_f32 v100, s[18:19], v96, v96, 1.0
	v_rcp_f32_e32 v112, v100
	s_nop 0
	v_fma_f32 v113, -v100, v112, 1.0
	v_fmac_f32_e32 v112, v113, v112
	v_div_scale_f32 v113, vcc, 1.0, v96, 1.0
	v_mul_f32_e32 v116, v113, v112
	v_fma_f32 v136, -v100, v116, v113
	v_fmac_f32_e32 v116, v136, v112
	v_fma_f32 v100, -v100, v116, v113
	v_div_fmas_f32 v100, v100, v112, v116
	v_div_fixup_f32 v96, v100, v96, 1.0
	v_fmac_f32_e32 v129, v101, v96
	v_mul_f32_e32 v96, 0xbfb8aa3b, v117
	v_exp_f32_e32 v96, v96
	v_and_b32_e32 v117, 0xffff0000, v121
	v_add_f32_e32 v96, 1.0, v96
	v_div_scale_f32 v100, s[18:19], v96, v96, 1.0
	v_rcp_f32_e32 v101, v100
	s_nop 0
	v_fma_f32 v112, -v100, v101, 1.0
	v_fmac_f32_e32 v101, v112, v101
	v_div_scale_f32 v112, vcc, 1.0, v96, 1.0
	v_mul_f32_e32 v113, v112, v101
	v_fma_f32 v116, -v100, v113, v112
	v_fmac_f32_e32 v113, v116, v101
	v_fma_f32 v100, -v100, v113, v112
	v_div_fmas_f32 v100, v100, v101, v113
	v_div_fixup_f32 v96, v100, v96, 1.0
	v_fmac_f32_e32 v133, v97, v96
	v_mul_f32_e32 v96, 0xbfb8aa3b, v114
	v_exp_f32_e32 v96, v96
	v_lshlrev_b32_e32 v114, 16, v120
	v_lshlrev_b32_e32 v116, 16, v121
	v_and_b32_e32 v121, 0xffff0000, v123
	v_add_f32_e32 v96, 1.0, v96
	v_div_scale_f32 v97, s[18:19], v96, v96, 1.0
	v_rcp_f32_e32 v100, v97
	s_nop 0
	v_fma_f32 v101, -v97, v100, 1.0
	v_fmac_f32_e32 v100, v101, v100
	v_div_scale_f32 v101, vcc, 1.0, v96, 1.0
	v_mul_f32_e32 v112, v101, v100
	v_fma_f32 v113, -v97, v112, v101
	v_fmac_f32_e32 v112, v113, v100
	v_fma_f32 v97, -v97, v112, v101
	v_div_fmas_f32 v97, v97, v100, v112
	v_div_fixup_f32 v96, v97, v96, 1.0
	v_fmac_f32_e32 v130, v102, v96
	v_mul_f32_e32 v96, 0xbfb8aa3b, v118
	v_exp_f32_e32 v96, v96
	v_lshlrev_b32_e32 v118, 16, v122
	v_and_b32_e32 v113, 0xffff0000, v127
	v_add_f32_e32 v96, 1.0, v96
	v_div_scale_f32 v97, s[18:19], v96, v96, 1.0
	v_rcp_f32_e32 v100, v97
	s_nop 0
	v_fma_f32 v101, -v97, v100, 1.0
	v_fmac_f32_e32 v100, v101, v100
	v_div_scale_f32 v101, vcc, 1.0, v96, 1.0
	v_mul_f32_e32 v102, v101, v100
	v_fma_f32 v112, -v97, v102, v101
	v_fmac_f32_e32 v102, v112, v100
	v_fma_f32 v97, -v97, v102, v101
	v_div_fmas_f32 v97, v97, v100, v102
	v_div_fixup_f32 v96, v97, v96, 1.0
	v_fmac_f32_e32 v134, v98, v96
	v_mul_f32_e32 v96, 0xbfb8aa3b, v115
	v_exp_f32_e32 v96, v96
	v_and_b32_e32 v115, 0xffff0000, v120
	v_lshlrev_b32_e32 v120, 16, v123
	v_lshlrev_b32_e32 v112, 16, v127
	v_add_f32_e32 v96, 1.0, v96
	v_div_scale_f32 v97, s[18:19], v96, v96, 1.0
	v_rcp_f32_e32 v98, v97
	s_nop 0
	v_fma_f32 v100, -v97, v98, 1.0
	v_fmac_f32_e32 v98, v100, v98
	v_div_scale_f32 v100, vcc, 1.0, v96, 1.0
	v_mul_f32_e32 v101, v100, v98
	v_fma_f32 v102, -v97, v101, v100
	v_fmac_f32_e32 v101, v102, v98
	v_fma_f32 v97, -v97, v101, v100
	v_div_fmas_f32 v97, v97, v98, v101
	v_div_fixup_f32 v96, v97, v96, 1.0
	v_fmac_f32_e32 v131, v103, v96
	v_mul_f32_e32 v96, 0xbfb8aa3b, v119
	v_exp_f32_e32 v96, v96
	v_and_b32_e32 v119, 0xffff0000, v122
	v_and_b32_e32 v103, 0xffff0000, v126
	v_add_f32_e32 v96, 1.0, v96
	v_div_scale_f32 v97, s[18:19], v96, v96, 1.0
	v_rcp_f32_e32 v98, v97
	s_nop 0
	v_fma_f32 v100, -v97, v98, 1.0
	v_fmac_f32_e32 v98, v100, v98
	v_div_scale_f32 v100, vcc, 1.0, v96, 1.0
	v_mul_f32_e32 v101, v100, v98
	v_fma_f32 v102, -v97, v101, v100
	v_fmac_f32_e32 v101, v102, v98
	v_fma_f32 v97, -v97, v101, v100
	v_div_fmas_f32 v97, v97, v98, v101
	v_div_fixup_f32 v96, v97, v96, 1.0
	v_fmac_f32_e32 v135, v99, v96
	v_lshl_add_u64 v[96:97], s[76:77], 0, v[216:217]
	v_cvt_pk_bf16_f32 v98, v128, v129
	v_lshl_add_u64 v[96:97], v[96:97], 0, v[206:207]
	v_cvt_pk_bf16_f32 v99, v130, v131
	v_cvt_pk_bf16_f32 v100, v132, v133
	v_cvt_pk_bf16_f32 v101, v134, v135
	global_store_dwordx4 v[96:97], v[98:101], off sc1
	v_lshlrev_b32_e32 v102, 16, v126
	s_nop 0
	v_lshlrev_b32_e32 v98, 16, v124
	v_mul_f32_e32 v98, 0xbfb8aa3b, v98
	v_exp_f32_e32 v98, v98
	v_and_b32_e32 v99, 0xffff0000, v124
	v_lshlrev_b32_e32 v100, 16, v125
	v_and_b32_e32 v101, 0xffff0000, v125
	v_add_f32_e32 v98, 1.0, v98
; __device__ __forceinline__ unsigned cvt_pk_bf16(float lo, float hi) { unsigned r; asm volatile("v_cvt_pk_bf16_f32 %0, %1, %2" : "=v"(r) : "v"(lo), "v"(hi)); return r; }
; __device__ __forceinline__ float sigmoidf_(float x) { return 1.f / (1.f + __expf(-x)); }
; __device__ __forceinline__ void unpack8(const u32x4& w, float (&f)[8]) { f[0] = bflo(w.x); f[1] = bfhi(w.x); f[2] = bflo(w.y); f[3] = bfhi(w.y); f[4] = bflo(w.z); f[5] = bfhi(w.z); f[6] = bflo(w.w); f[7] = bfhi(w.w); }
;     __device__ __forceinline__ void operator()(const f32x4 (&acc)[2][2][4][2], const Unit& u, int wr, int wc, int fr, int fq) const {
;     ...
;                 for (int bj = 0; bj < 2; ++bj) { float g[8], t[8]; unpack8(gw[m][bj], g); unpack8(tw[m][bj], t); const f32x4 a0 = acc[ai][bj][m][0], a1 = acc[ai][bj][m][1]; float o[8];
; #pragma unroll
;                     for (int e = 0; e < 4; ++e) { o[e] = t[e] + a0[e] * sigmoidf_(g[e]); o[4 + e] = t[4 + e] + a1[e] * sigmoidf_(g[4 + e]); }
;                     *(u32x4*)(Y + (size_t)(row0 + ai * HALF + m * 16) * DM + col0 + bj * HALF) = (u32x4){cvt_pk_bf16(o[0], o[1]), cvt_pk_bf16(o[2], o[3]), cvt_pk_bf16(o[4], o[5]), cvt_pk_bf16(o[6], o[7])}; } }
	v_div_scale_f32 v122, s[18:19], v98, v98, 1.0
	v_rcp_f32_e32 v123, v122
	s_nop 0
	v_fma_f32 v124, -v122, v123, 1.0
	v_fmac_f32_e32 v123, v124, v123
	v_div_scale_f32 v124, vcc, 1.0, v98, 1.0
	v_mul_f32_e32 v125, v124, v123
	v_fma_f32 v126, -v122, v125, v124
	v_fmac_f32_e32 v125, v126, v123
	v_fma_f32 v122, -v122, v125, v124
	v_div_fmas_f32 v122, v122, v123, v125
	v_div_fixup_f32 v98, v122, v98, 1.0
	v_fmac_f32_e32 v114, v84, v98
	v_mul_f32_e32 v84, 0xbfb8aa3b, v102
	v_exp_f32_e32 v84, v84
	s_nop 0
	v_add_f32_e32 v84, 1.0, v84
	v_div_scale_f32 v98, s[18:19], v84, v84, 1.0
	v_rcp_f32_e32 v102, v98
	s_nop 0
	v_fma_f32 v122, -v98, v102, 1.0
	v_fmac_f32_e32 v102, v122, v102
	v_div_scale_f32 v122, vcc, 1.0, v84, 1.0
	v_mul_f32_e32 v123, v122, v102
	v_fma_f32 v124, -v98, v123, v122
	v_fmac_f32_e32 v123, v124, v102
	v_fma_f32 v98, -v98, v123, v122
	v_div_fmas_f32 v98, v98, v102, v123
	v_div_fixup_f32 v84, v98, v84, 1.0
	v_fmac_f32_e32 v118, v80, v84
	v_mul_f32_e32 v80, 0xbfb8aa3b, v99
	v_exp_f32_e32 v80, v80
	s_nop 0
	v_add_f32_e32 v80, 1.0, v80
	v_div_scale_f32 v84, s[18:19], v80, v80, 1.0
	v_rcp_f32_e32 v98, v84
	s_nop 0
	v_fma_f32 v99, -v84, v98, 1.0
	v_fmac_f32_e32 v98, v99, v98
	v_div_scale_f32 v99, vcc, 1.0, v80, 1.0
	v_mul_f32_e32 v102, v99, v98
	v_fma_f32 v122, -v84, v102, v99
	v_fmac_f32_e32 v102, v122, v98
	v_fma_f32 v84, -v84, v102, v99
	v_div_fmas_f32 v84, v84, v98, v102
	v_div_fixup_f32 v80, v84, v80, 1.0
	v_fmac_f32_e32 v115, v85, v80
	v_mul_f32_e32 v80, 0xbfb8aa3b, v103
	v_exp_f32_e32 v80, v80
	v_and_b32_e32 v103, 0xffff0000, v107
	v_add_f32_e32 v80, 1.0, v80
	v_div_scale_f32 v84, s[18:19], v80, v80, 1.0
	v_rcp_f32_e32 v85, v84
	s_nop 0
	v_fma_f32 v98, -v84, v85, 1.0
	v_fmac_f32_e32 v85, v98, v85
	v_div_scale_f32 v98, vcc, 1.0, v80, 1.0
	v_mul_f32_e32 v99, v98, v85
	v_fma_f32 v102, -v84, v99, v98
	v_fmac_f32_e32 v99, v102, v85
	v_fma_f32 v84, -v84, v99, v98
	v_div_fmas_f32 v84, v84, v85, v99
	v_div_fixup_f32 v80, v84, v80, 1.0
	v_fmac_f32_e32 v119, v81, v80
	v_mul_f32_e32 v80, 0xbfb8aa3b, v100
	v_exp_f32_e32 v80, v80
	v_lshlrev_b32_e32 v100, 16, v106
	v_lshlrev_b32_e32 v102, 16, v107
	v_add_f32_e32 v80, 1.0, v80
	v_div_scale_f32 v81, s[18:19], v80, v80, 1.0
	v_rcp_f32_e32 v84, v81
	s_nop 0
	v_fma_f32 v85, -v81, v84, 1.0
	v_fmac_f32_e32 v84, v85, v84
	v_div_scale_f32 v85, vcc, 1.0, v80, 1.0
	v_mul_f32_e32 v98, v85, v84
	v_fma_f32 v99, -v81, v98, v85
	v_fmac_f32_e32 v98, v99, v84
	v_fma_f32 v81, -v81, v98, v85
	v_div_fmas_f32 v81, v81, v84, v98
	v_div_fixup_f32 v80, v81, v80, 1.0
	v_fmac_f32_e32 v116, v86, v80
	v_mul_f32_e32 v80, 0xbfb8aa3b, v112
	v_exp_f32_e32 v80, v80
	v_and_b32_e32 v99, 0xffff0000, v105
	v_add_f32_e32 v80, 1.0, v80
	v_div_scale_f32 v81, s[18:19], v80, v80, 1.0
	v_rcp_f32_e32 v84, v81
	s_nop 0
	v_fma_f32 v85, -v81, v84, 1.0
	v_fmac_f32_e32 v84, v85, v84
	v_div_scale_f32 v85, vcc, 1.0, v80, 1.0
	v_mul_f32_e32 v86, v85, v84
	v_fma_f32 v98, -v81, v86, v85
	v_fmac_f32_e32 v86, v98, v84
	v_fma_f32 v81, -v81, v86, v85
	v_div_fmas_f32 v81, v81, v84, v86
	v_div_fixup_f32 v80, v81, v80, 1.0
	v_fmac_f32_e32 v120, v82, v80
	v_mul_f32_e32 v80, 0xbfb8aa3b, v101
	v_exp_f32_e32 v80, v80
	v_lshlrev_b32_e32 v98, 16, v105
	v_and_b32_e32 v101, 0xffff0000, v106
	v_add_f32_e32 v80, 1.0, v80
	v_div_scale_f32 v81, s[18:19], v80, v80, 1.0
	v_rcp_f32_e32 v82, v81
	s_nop 0
	v_fma_f32 v84, -v81, v82, 1.0
	v_fmac_f32_e32 v82, v84, v82
	v_div_scale_f32 v84, vcc, 1.0, v80, 1.0
	v_mul_f32_e32 v85, v84, v82
	v_fma_f32 v86, -v81, v85, v84
	v_fmac_f32_e32 v85, v86, v82
	v_fma_f32 v81, -v81, v85, v84
	v_div_fmas_f32 v81, v81, v82, v85
	v_div_fixup_f32 v80, v81, v80, 1.0
	v_fmac_f32_e32 v117, v87, v80
	v_mul_f32_e32 v80, 0xbfb8aa3b, v113
	v_exp_f32_e32 v80, v80
	v_and_b32_e32 v87, 0xffff0000, v111
	v_add_f32_e32 v80, 1.0, v80
	v_div_scale_f32 v81, s[18:19], v80, v80, 1.0
	v_rcp_f32_e32 v82, v81
	s_nop 0
	v_fma_f32 v84, -v81, v82, 1.0
	v_fmac_f32_e32 v82, v84, v82
	v_div_scale_f32 v84, vcc, 1.0, v80, 1.0
	v_mul_f32_e32 v85, v84, v82
	v_fma_f32 v86, -v81, v85, v84
	v_fmac_f32_e32 v85, v86, v82
	v_fma_f32 v81, -v81, v85, v84
	v_div_fmas_f32 v81, v81, v82, v85
	v_div_fixup_f32 v80, v81, v80, 1.0
	v_fmac_f32_e32 v121, v83, v80
	v_cvt_pk_bf16_f32 v80, v114, v115
	v_cvt_pk_bf16_f32 v81, v116, v117
	v_cvt_pk_bf16_f32 v82, v118, v119
	v_cvt_pk_bf16_f32 v83, v120, v121
	global_store_dwordx4 v[96:97], v[80:83], off offset:256 sc1
	v_lshlrev_b32_e32 v96, 16, v104
	v_and_b32_e32 v97, 0xffff0000, v104
	v_lshlrev_b32_e32 v80, 16, v108
	v_mul_f32_e32 v80, 0xbfb8aa3b, v80
	v_exp_f32_e32 v80, v80
	v_and_b32_e32 v81, 0xffff0000, v108
	v_lshlrev_b32_e32 v84, 16, v110
	v_and_b32_e32 v85, 0xffff0000, v110
	v_add_f32_e32 v80, 1.0, v80
	v_div_scale_f32 v104, s[18:19], v80, v80, 1.0
	v_rcp_f32_e32 v105, v104
	v_lshlrev_b32_e32 v82, 16, v109
	v_lshlrev_b32_e32 v86, 16, v111
	v_and_b32_e32 v83, 0xffff0000, v109
	v_fma_f32 v106, -v104, v105, 1.0
	v_fmac_f32_e32 v105, v106, v105
	v_div_scale_f32 v106, vcc, 1.0, v80, 1.0
	v_mul_f32_e32 v107, v106, v105
	v_fma_f32 v108, -v104, v107, v106
	v_fmac_f32_e32 v107, v108, v105
	v_fma_f32 v104, -v104, v107, v106
	v_div_fmas_f32 v104, v104, v105, v107
	v_div_fixup_f32 v80, v104, v80, 1.0
	v_fmac_f32_e32 v96, v76, v80
	v_mul_f32_e32 v76, 0xbfb8aa3b, v84
	v_exp_f32_e32 v76, v76
	s_nop 0
	v_add_f32_e32 v76, 1.0, v76
	v_div_scale_f32 v80, s[18:19], v76, v76, 1.0
	v_rcp_f32_e32 v84, v80
	s_nop 0
	v_fma_f32 v104, -v80, v84, 1.0
	v_fmac_f32_e32 v84, v104, v84
	v_div_scale_f32 v104, vcc, 1.0, v76, 1.0
	v_mul_f32_e32 v105, v104, v84
	v_fma_f32 v106, -v80, v105, v104
	v_fmac_f32_e32 v105, v106, v84
	v_fma_f32 v80, -v80, v105, v104
; __device__ __forceinline__ unsigned cvt_pk_bf16(float lo, float hi) { unsigned r; asm volatile("v_cvt_pk_bf16_f32 %0, %1, %2" : "=v"(r) : "v"(lo), "v"(hi)); return r; }
; __device__ __forceinline__ float sigmoidf_(float x) { return 1.f / (1.f + __expf(-x)); }
; __device__ __forceinline__ void unpack8(const u32x4& w, float (&f)[8]) { f[0] = bflo(w.x); f[1] = bfhi(w.x); f[2] = bflo(w.y); f[3] = bfhi(w.y); f[4] = bflo(w.z); f[5] = bfhi(w.z); f[6] = bflo(w.w); f[7] = bfhi(w.w); }
;     __device__ __forceinline__ void operator()(const f32x4 (&acc)[2][2][4][2], const Unit& u, int wr, int wc, int fr, int fq) const {
;     ...
;                 for (int bj = 0; bj < 2; ++bj) { float g[8], t[8]; unpack8(gw[m][bj], g); unpack8(tw[m][bj], t); const f32x4 a0 = acc[ai][bj][m][0], a1 = acc[ai][bj][m][1]; float o[8];
; #pragma unroll
;                     for (int e = 0; e < 4; ++e) { o[e] = t[e] + a0[e] * sigmoidf_(g[e]); o[4 + e] = t[4 + e] + a1[e] * sigmoidf_(g[4 + e]); }
;                     *(u32x4*)(Y + (size_t)(row0 + ai * HALF + m * 16) * DM + col0 + bj * HALF) = (u32x4){cvt_pk_bf16(o[0], o[1]), cvt_pk_bf16(o[2], o[3]), cvt_pk_bf16(o[4], o[5]), cvt_pk_bf16(o[6], o[7])}; } }
	v_div_fmas_f32 v80, v80, v84, v105
	v_div_fixup_f32 v76, v80, v76, 1.0
	v_fmac_f32_e32 v100, v72, v76
	v_mul_f32_e32 v72, 0xbfb8aa3b, v81
	v_exp_f32_e32 v72, v72
	s_nop 0
	v_add_f32_e32 v72, 1.0, v72
	v_div_scale_f32 v76, s[18:19], v72, v72, 1.0
	v_rcp_f32_e32 v80, v76
	s_nop 0
	v_fma_f32 v81, -v76, v80, 1.0
	v_fmac_f32_e32 v80, v81, v80
	v_div_scale_f32 v81, vcc, 1.0, v72, 1.0
	v_mul_f32_e32 v84, v81, v80
	v_fma_f32 v104, -v76, v84, v81
	v_fmac_f32_e32 v84, v104, v80
	v_fma_f32 v76, -v76, v84, v81
	v_div_fmas_f32 v76, v76, v80, v84
	v_div_fixup_f32 v72, v76, v72, 1.0
	v_fmac_f32_e32 v97, v77, v72
	v_mul_f32_e32 v72, 0xbfb8aa3b, v85
	v_exp_f32_e32 v72, v72
	v_and_b32_e32 v85, 0xffff0000, v89
	v_add_f32_e32 v72, 1.0, v72
	v_div_scale_f32 v76, s[18:19], v72, v72, 1.0
	v_rcp_f32_e32 v77, v76
	s_nop 0
	v_fma_f32 v80, -v76, v77, 1.0
	v_fmac_f32_e32 v77, v80, v77
	v_div_scale_f32 v80, vcc, 1.0, v72, 1.0
	v_mul_f32_e32 v81, v80, v77
	v_fma_f32 v84, -v76, v81, v80
	v_fmac_f32_e32 v81, v84, v77
	v_fma_f32 v76, -v76, v81, v80
	v_div_fmas_f32 v76, v76, v77, v81
	v_div_fixup_f32 v72, v76, v72, 1.0
	v_fmac_f32_e32 v101, v73, v72
	v_mul_f32_e32 v72, 0xbfb8aa3b, v82
	v_exp_f32_e32 v72, v72
	v_lshlrev_b32_e32 v82, 16, v88
	v_lshlrev_b32_e32 v84, 16, v89
	v_and_b32_e32 v89, 0xffff0000, v91
	v_add_f32_e32 v72, 1.0, v72
	v_div_scale_f32 v73, s[18:19], v72, v72, 1.0
	v_rcp_f32_e32 v76, v73
	s_nop 0
	v_fma_f32 v77, -v73, v76, 1.0
	v_fmac_f32_e32 v76, v77, v76
	v_div_scale_f32 v77, vcc, 1.0, v72, 1.0
	v_mul_f32_e32 v80, v77, v76
	v_fma_f32 v81, -v73, v80, v77
	v_fmac_f32_e32 v80, v81, v76
	v_fma_f32 v73, -v73, v80, v77
	v_div_fmas_f32 v73, v73, v76, v80
	v_div_fixup_f32 v72, v73, v72, 1.0
	v_fmac_f32_e32 v98, v78, v72
	v_mul_f32_e32 v72, 0xbfb8aa3b, v86
	v_exp_f32_e32 v72, v72
	v_lshlrev_b32_e32 v86, 16, v90
	v_and_b32_e32 v81, 0xffff0000, v95
	v_add_f32_e32 v72, 1.0, v72
	v_div_scale_f32 v73, s[18:19], v72, v72, 1.0
	v_rcp_f32_e32 v76, v73
	s_nop 0
	v_fma_f32 v77, -v73, v76, 1.0
	v_fmac_f32_e32 v76, v77, v76
	v_div_scale_f32 v77, vcc, 1.0, v72, 1.0
	v_mul_f32_e32 v78, v77, v76
	v_fma_f32 v80, -v73, v78, v77
	v_fmac_f32_e32 v78, v80, v76
	v_fma_f32 v73, -v73, v78, v77
	v_div_fmas_f32 v73, v73, v76, v78
	v_div_fixup_f32 v72, v73, v72, 1.0
	v_fmac_f32_e32 v102, v74, v72
	v_mul_f32_e32 v72, 0xbfb8aa3b, v83
	v_exp_f32_e32 v72, v72
	v_and_b32_e32 v83, 0xffff0000, v88
	v_lshlrev_b32_e32 v88, 16, v91
	v_lshlrev_b32_e32 v80, 16, v95
	v_add_f32_e32 v72, 1.0, v72
	v_div_scale_f32 v73, s[18:19], v72, v72, 1.0
	v_rcp_f32_e32 v74, v73
	s_nop 0
	v_fma_f32 v76, -v73, v74, 1.0
	v_fmac_f32_e32 v74, v76, v74
	v_div_scale_f32 v76, vcc, 1.0, v72, 1.0
	v_mul_f32_e32 v77, v76, v74
	v_fma_f32 v78, -v73, v77, v76
	v_fmac_f32_e32 v77, v78, v74
	v_fma_f32 v73, -v73, v77, v76
	v_div_fmas_f32 v73, v73, v74, v77
	v_div_fixup_f32 v72, v73, v72, 1.0
	v_fmac_f32_e32 v99, v79, v72
	v_mul_f32_e32 v72, 0xbfb8aa3b, v87
	v_exp_f32_e32 v72, v72
	v_and_b32_e32 v87, 0xffff0000, v90
	v_and_b32_e32 v79, 0xffff0000, v94
	v_add_f32_e32 v72, 1.0, v72
	v_div_scale_f32 v73, s[18:19], v72, v72, 1.0
	v_rcp_f32_e32 v74, v73
	s_nop 0
	v_fma_f32 v76, -v73, v74, 1.0
	v_fmac_f32_e32 v74, v76, v74
	v_div_scale_f32 v76, vcc, 1.0, v72, 1.0
	v_mul_f32_e32 v77, v76, v74
	v_fma_f32 v78, -v73, v77, v76
	v_fmac_f32_e32 v77, v78, v74
	v_fma_f32 v73, -v73, v77, v76
	v_div_fmas_f32 v73, v73, v74, v77
	v_div_fixup_f32 v72, v73, v72, 1.0
	v_fmac_f32_e32 v103, v75, v72
	v_lshl_add_u64 v[72:73], s[76:77], 0, v[214:215]
	v_cvt_pk_bf16_f32 v74, v96, v97
	v_lshl_add_u64 v[72:73], v[72:73], 0, v[206:207]
	v_cvt_pk_bf16_f32 v75, v98, v99
	v_cvt_pk_bf16_f32 v76, v100, v101
	v_cvt_pk_bf16_f32 v77, v102, v103
	global_store_dwordx4 v[72:73], v[74:77], off sc1
	v_lshlrev_b32_e32 v78, 16, v94
	s_nop 0
	v_lshlrev_b32_e32 v74, 16, v92
	v_mul_f32_e32 v74, 0xbfb8aa3b, v74
	v_exp_f32_e32 v74, v74
	v_and_b32_e32 v75, 0xffff0000, v92
	v_lshlrev_b32_e32 v76, 16, v93
	v_and_b32_e32 v77, 0xffff0000, v93
	v_add_f32_e32 v74, 1.0, v74
	v_div_scale_f32 v90, s[18:19], v74, v74, 1.0
	v_rcp_f32_e32 v91, v90
	s_nop 0
	v_fma_f32 v92, -v90, v91, 1.0
	v_fmac_f32_e32 v91, v92, v91
	v_div_scale_f32 v92, vcc, 1.0, v74, 1.0
	v_mul_f32_e32 v93, v92, v91
	v_fma_f32 v94, -v90, v93, v92
	v_fmac_f32_e32 v93, v94, v91
	v_fma_f32 v90, -v90, v93, v92
	v_div_fmas_f32 v90, v90, v91, v93
	v_div_fixup_f32 v74, v90, v74, 1.0
	v_fmac_f32_e32 v82, v68, v74
	v_mul_f32_e32 v68, 0xbfb8aa3b, v78
	v_exp_f32_e32 v68, v68
	s_nop 0
	v_add_f32_e32 v68, 1.0, v68
	v_div_scale_f32 v74, s[18:19], v68, v68, 1.0
	v_rcp_f32_e32 v78, v74
	s_nop 0
	v_fma_f32 v90, -v74, v78, 1.0
	v_fmac_f32_e32 v78, v90, v78
	v_div_scale_f32 v90, vcc, 1.0, v68, 1.0
	v_mul_f32_e32 v91, v90, v78
	v_fma_f32 v92, -v74, v91, v90
	v_fmac_f32_e32 v91, v92, v78
	v_fma_f32 v74, -v74, v91, v90
	v_div_fmas_f32 v74, v74, v78, v91
	v_div_fixup_f32 v68, v74, v68, 1.0
	v_fmac_f32_e32 v86, v64, v68
	v_mul_f32_e32 v64, 0xbfb8aa3b, v75
	v_exp_f32_e32 v64, v64
	s_nop 0
	v_add_f32_e32 v64, 1.0, v64
	v_div_scale_f32 v68, s[18:19], v64, v64, 1.0
	v_rcp_f32_e32 v74, v68
	s_nop 0
	v_fma_f32 v75, -v68, v74, 1.0
	v_fmac_f32_e32 v74, v75, v74
	v_div_scale_f32 v75, vcc, 1.0, v64, 1.0
	v_mul_f32_e32 v78, v75, v74
	v_fma_f32 v90, -v68, v78, v75
	v_fmac_f32_e32 v78, v90, v74
	v_fma_f32 v68, -v68, v78, v75
	v_div_fmas_f32 v68, v68, v74, v78
	v_div_fixup_f32 v64, v68, v64, 1.0
	v_fmac_f32_e32 v83, v69, v64
	v_mul_f32_e32 v64, 0xbfb8aa3b, v79
	v_exp_f32_e32 v64, v64
	s_nop 0
	v_add_f32_e32 v64, 1.0, v64
	v_div_scale_f32 v68, s[18:19], v64, v64, 1.0
	v_rcp_f32_e32 v69, v68
	s_nop 0
	v_fma_f32 v74, -v68, v69, 1.0
	v_fmac_f32_e32 v69, v74, v69
; __device__ __forceinline__ unsigned cvt_pk_bf16(float lo, float hi) { unsigned r; asm volatile("v_cvt_pk_bf16_f32 %0, %1, %2" : "=v"(r) : "v"(lo), "v"(hi)); return r; }
; __device__ __forceinline__ float sigmoidf_(float x) { return 1.f / (1.f + __expf(-x)); }
; __device__ __forceinline__ void unpack8(const u32x4& w, float (&f)[8]) { f[0] = bflo(w.x); f[1] = bfhi(w.x); f[2] = bflo(w.y); f[3] = bfhi(w.y); f[4] = bflo(w.z); f[5] = bfhi(w.z); f[6] = bflo(w.w); f[7] = bfhi(w.w); }
;     __device__ __forceinline__ void operator()(const f32x4 (&acc)[2][2][4][2], const Unit& u, int wr, int wc, int fr, int fq) const {
;     ...
;                 for (int bj = 0; bj < 2; ++bj) { const size_t r = (size_t)(row0 + ai * HALF + m * 16); gw[m][bj] = *(const u32x4*)(gate + r * ldg + col0 + bj * HALF); tw[m][bj] = *(const u32x4*)(T + r * DM + col0 + bj * HALF); }
; #pragma unroll
;             for (int m = 0; m < 4; ++m)
; #pragma unroll
;                 for (int bj = 0; bj < 2; ++bj) { float g[8], t[8]; unpack8(gw[m][bj], g); unpack8(tw[m][bj], t); const f32x4 a0 = acc[ai][bj][m][0], a1 = acc[ai][bj][m][1]; float o[8];
; #pragma unroll
;                     for (int e = 0; e < 4; ++e) { o[e] = t[e] + a0[e] * sigmoidf_(g[e]); o[4 + e] = t[4 + e] + a1[e] * sigmoidf_(g[4 + e]); }
;                     *(u32x4*)(Y + (size_t)(row0 + ai * HALF + m * 16) * DM + col0 + bj * HALF) = (u32x4){cvt_pk_bf16(o[0], o[1]), cvt_pk_bf16(o[2], o[3]), cvt_pk_bf16(o[4], o[5]), cvt_pk_bf16(o[6], o[7])}; } }
	v_div_scale_f32 v74, vcc, 1.0, v64, 1.0
	v_mul_f32_e32 v75, v74, v69
	v_fma_f32 v78, -v68, v75, v74
	v_fmac_f32_e32 v75, v78, v69
	v_fma_f32 v68, -v68, v75, v74
	v_div_fmas_f32 v68, v68, v69, v75
	v_div_fixup_f32 v64, v68, v64, 1.0
	v_fmac_f32_e32 v87, v65, v64
	v_mul_f32_e32 v64, 0xbfb8aa3b, v76
	v_exp_f32_e32 v64, v64
	s_nop 0
	v_add_f32_e32 v64, 1.0, v64
	v_div_scale_f32 v65, s[18:19], v64, v64, 1.0
	v_rcp_f32_e32 v68, v65
	s_nop 0
	v_fma_f32 v69, -v65, v68, 1.0
	v_fmac_f32_e32 v68, v69, v68
	v_div_scale_f32 v69, vcc, 1.0, v64, 1.0
	v_mul_f32_e32 v74, v69, v68
	v_fma_f32 v75, -v65, v74, v69
	v_fmac_f32_e32 v74, v75, v68
	v_fma_f32 v65, -v65, v74, v69
	v_div_fmas_f32 v65, v65, v68, v74
	v_div_fixup_f32 v64, v65, v64, 1.0
	v_fmac_f32_e32 v84, v70, v64
	v_mul_f32_e32 v64, 0xbfb8aa3b, v80
	v_exp_f32_e32 v64, v64
	s_nop 0
	v_add_f32_e32 v64, 1.0, v64
	v_div_scale_f32 v65, s[18:19], v64, v64, 1.0
	v_rcp_f32_e32 v68, v65
	s_nop 0
	v_fma_f32 v69, -v65, v68, 1.0
	v_fmac_f32_e32 v68, v69, v68
	v_div_scale_f32 v69, vcc, 1.0, v64, 1.0
	v_mul_f32_e32 v70, v69, v68
	v_fma_f32 v74, -v65, v70, v69
	v_fmac_f32_e32 v70, v74, v68
	v_fma_f32 v65, -v65, v70, v69
	v_div_fmas_f32 v65, v65, v68, v70
	v_div_fixup_f32 v64, v65, v64, 1.0
	v_fmac_f32_e32 v88, v66, v64
	v_mul_f32_e32 v64, 0xbfb8aa3b, v77
	v_exp_f32_e32 v64, v64
	s_nop 0
	v_add_f32_e32 v64, 1.0, v64
	v_div_scale_f32 v65, s[18:19], v64, v64, 1.0
	v_rcp_f32_e32 v66, v65
	s_nop 0
	v_fma_f32 v68, -v65, v66, 1.0
	v_fmac_f32_e32 v66, v68, v66
	v_div_scale_f32 v68, vcc, 1.0, v64, 1.0
	v_mul_f32_e32 v69, v68, v66
	v_fma_f32 v70, -v65, v69, v68
	v_fmac_f32_e32 v69, v70, v66
	v_fma_f32 v65, -v65, v69, v68
	v_div_fmas_f32 v65, v65, v66, v69
	v_div_fixup_f32 v64, v65, v64, 1.0
	v_fmac_f32_e32 v85, v71, v64
	v_mul_f32_e32 v64, 0xbfb8aa3b, v81
	v_exp_f32_e32 v64, v64
	s_nop 0
	v_add_f32_e32 v64, 1.0, v64
	v_div_scale_f32 v65, s[18:19], v64, v64, 1.0
	v_rcp_f32_e32 v66, v65
	s_nop 0
	v_fma_f32 v68, -v65, v66, 1.0
	v_fmac_f32_e32 v66, v68, v66
	v_div_scale_f32 v68, vcc, 1.0, v64, 1.0
	v_mul_f32_e32 v69, v68, v66
	v_fma_f32 v70, -v65, v69, v68
	v_fmac_f32_e32 v69, v70, v66
	v_fma_f32 v65, -v65, v69, v68
	v_div_fmas_f32 v65, v65, v66, v69
	v_div_fixup_f32 v64, v65, v64, 1.0
	v_fmac_f32_e32 v89, v67, v64
	v_cvt_pk_bf16_f32 v64, v82, v83
	v_cvt_pk_bf16_f32 v65, v84, v85
	v_cvt_pk_bf16_f32 v66, v86, v87
	v_cvt_pk_bf16_f32 v67, v88, v89
	global_store_dwordx4 v[72:73], v[64:67], off offset:256 sc1
	s_nop 1
	v_add_u32_e32 v64, 0x80, v208
	v_ashrrev_i32_e32 v65, 31, v64
	v_mad_i64_i32 v[66:67], s[18:19], v64, s41, v[212:213]
	v_lshlrev_b64 v[126:127], 12, v[64:65]
	v_lshl_add_u64 v[64:65], v[210:211], 0, v[126:127]
	global_load_dwordx4 v[128:131], v[66:67], off nt
	global_load_dwordx4 v[132:135], v[64:65], off nt
	global_load_dwordx4 v[116:119], v[66:67], off offset:256 nt
	global_load_dwordx4 v[112:115], v[64:65], off offset:256 nt
	v_add_u32_e32 v64, 0x90, v208
	v_ashrrev_i32_e32 v65, 31, v64
	v_lshlrev_b64 v[124:125], 12, v[64:65]
	v_mad_i64_i32 v[66:67], s[18:19], v64, s41, v[212:213]
	v_lshl_add_u64 v[64:65], v[210:211], 0, v[124:125]
	global_load_dwordx4 v[108:111], v[66:67], off nt
	global_load_dwordx4 v[104:107], v[64:65], off nt
	global_load_dwordx4 v[100:103], v[66:67], off offset:256 nt
	global_load_dwordx4 v[96:99], v[64:65], off offset:256 nt
	v_add_u32_e32 v64, 0xa0, v208
	v_ashrrev_i32_e32 v65, 31, v64
	v_lshlrev_b64 v[122:123], 12, v[64:65]
	v_mad_i64_i32 v[66:67], s[18:19], v64, s41, v[212:213]
	v_lshl_add_u64 v[64:65], v[210:211], 0, v[122:123]
	global_load_dwordx4 v[92:95], v[66:67], off nt
	global_load_dwordx4 v[88:91], v[64:65], off nt
	global_load_dwordx4 v[84:87], v[66:67], off offset:256 nt
	global_load_dwordx4 v[80:83], v[64:65], off offset:256 nt
	v_add_u32_e32 v64, 0xb0, v208
	v_ashrrev_i32_e32 v65, 31, v64
	v_lshlrev_b64 v[120:121], 12, v[64:65]
	v_mad_i64_i32 v[66:67], s[18:19], v64, s41, v[212:213]
	v_lshl_add_u64 v[64:65], v[210:211], 0, v[120:121]
	global_load_dwordx4 v[76:79], v[66:67], off nt
	global_load_dwordx4 v[72:75], v[64:65], off nt
	global_load_dwordx4 v[68:71], v[66:67], off offset:256 nt
	s_nop 0
	global_load_dwordx4 v[64:67], v[64:65], off offset:256 nt
	s_waitcnt vmcnt(15)
	v_lshlrev_b32_e32 v136, 16, v128
	v_mul_f32_e32 v136, 0xbfb8aa3b, v136
	v_exp_f32_e32 v136, v136
	v_lshlrev_b32_e32 v138, 16, v130
	s_waitcnt vmcnt(14)
; __device__ __forceinline__ unsigned cvt_pk_bf16(float lo, float hi) { unsigned r; asm volatile("v_cvt_pk_bf16_f32 %0, %1, %2" : "=v"(r) : "v"(lo), "v"(hi)); return r; }
; __device__ __forceinline__ float sigmoidf_(float x) { return 1.f / (1.f + __expf(-x)); }
; __device__ __forceinline__ void unpack8(const u32x4& w, float (&f)[8]) { f[0] = bflo(w.x); f[1] = bfhi(w.x); f[2] = bflo(w.y); f[3] = bfhi(w.y); f[4] = bflo(w.z); f[5] = bfhi(w.z); f[6] = bflo(w.w); f[7] = bfhi(w.w); }
;     __device__ __forceinline__ void operator()(const f32x4 (&acc)[2][2][4][2], const Unit& u, int wr, int wc, int fr, int fq) const {
;     ...
;                 for (int bj = 0; bj < 2; ++bj) { float g[8], t[8]; unpack8(gw[m][bj], g); unpack8(tw[m][bj], t); const f32x4 a0 = acc[ai][bj][m][0], a1 = acc[ai][bj][m][1]; float o[8];
; #pragma unroll
;                     for (int e = 0; e < 4; ++e) { o[e] = t[e] + a0[e] * sigmoidf_(g[e]); o[4 + e] = t[4 + e] + a1[e] * sigmoidf_(g[4 + e]); }
;                     *(u32x4*)(Y + (size_t)(row0 + ai * HALF + m * 16) * DM + col0 + bj * HALF) = (u32x4){cvt_pk_bf16(o[0], o[1]), cvt_pk_bf16(o[2], o[3]), cvt_pk_bf16(o[4], o[5]), cvt_pk_bf16(o[6], o[7])}; } }
	v_lshlrev_b32_e32 v140, 16, v132
	v_and_b32_e32 v128, 0xffff0000, v128
	v_add_f32_e32 v136, 1.0, v136
	v_div_scale_f32 v144, s[18:19], v136, v136, 1.0
	v_rcp_f32_e32 v145, v144
	v_lshlrev_b32_e32 v142, 16, v134
	v_and_b32_e32 v130, 0xffff0000, v130
	v_and_b32_e32 v132, 0xffff0000, v132
	v_fma_f32 v146, -v144, v145, 1.0
	v_fmac_f32_e32 v145, v146, v145
	v_div_scale_f32 v146, vcc, 1.0, v136, 1.0
	v_mul_f32_e32 v147, v146, v145
	v_fma_f32 v148, -v144, v147, v146
	v_fmac_f32_e32 v147, v148, v145
	v_fma_f32 v144, -v144, v147, v146
	v_div_fmas_f32 v144, v144, v145, v147
	v_div_fixup_f32 v136, v144, v136, 1.0
	v_fmac_f32_e32 v140, v60, v136
	v_mul_f32_e32 v60, 0xbfb8aa3b, v138
	v_exp_f32_e32 v60, v60
	v_lshlrev_b32_e32 v137, 16, v129
	v_and_b32_e32 v134, 0xffff0000, v134
	v_lshlrev_b32_e32 v139, 16, v131
	v_add_f32_e32 v60, 1.0, v60
	v_div_scale_f32 v136, s[18:19], v60, v60, 1.0
	v_rcp_f32_e32 v138, v136
	v_lshlrev_b32_e32 v141, 16, v133
	v_and_b32_e32 v129, 0xffff0000, v129
	v_lshlrev_b32_e32 v143, 16, v135
	v_fma_f32 v144, -v136, v138, 1.0
	v_fmac_f32_e32 v138, v144, v138
	v_div_scale_f32 v144, vcc, 1.0, v60, 1.0
	v_mul_f32_e32 v145, v144, v138
	v_fma_f32 v146, -v136, v145, v144
	v_fmac_f32_e32 v145, v146, v138
	v_fma_f32 v136, -v136, v145, v144
	v_div_fmas_f32 v136, v136, v138, v145
	v_div_fixup_f32 v60, v136, v60, 1.0
	v_fmac_f32_e32 v142, v56, v60
	v_mul_f32_e32 v56, 0xbfb8aa3b, v128
	v_exp_f32_e32 v56, v56
	v_and_b32_e32 v131, 0xffff0000, v131
	v_and_b32_e32 v133, 0xffff0000, v133
	v_and_b32_e32 v135, 0xffff0000, v135
	v_add_f32_e32 v56, 1.0, v56
	v_div_scale_f32 v60, s[18:19], v56, v56, 1.0
	v_rcp_f32_e32 v128, v60
	s_nop 0
	v_fma_f32 v136, -v60, v128, 1.0
	v_fmac_f32_e32 v128, v136, v128
	v_div_scale_f32 v136, vcc, 1.0, v56, 1.0
	v_mul_f32_e32 v138, v136, v128
	v_fma_f32 v144, -v60, v138, v136
	v_fmac_f32_e32 v138, v144, v128
	v_fma_f32 v60, -v60, v138, v136
	v_div_fmas_f32 v60, v60, v128, v138
	v_div_fixup_f32 v56, v60, v56, 1.0
	v_fmac_f32_e32 v132, v61, v56
	v_mul_f32_e32 v56, 0xbfb8aa3b, v130
	v_exp_f32_e32 v56, v56
	s_nop 0
	v_add_f32_e32 v56, 1.0, v56
	v_div_scale_f32 v60, s[18:19], v56, v56, 1.0
	v_rcp_f32_e32 v61, v60
	s_nop 0
	v_fma_f32 v128, -v60, v61, 1.0
	v_fmac_f32_e32 v61, v128, v61
	v_div_scale_f32 v128, vcc, 1.0, v56, 1.0
	v_mul_f32_e32 v130, v128, v61
	v_fma_f32 v136, -v60, v130, v128
	v_fmac_f32_e32 v130, v136, v61
	v_fma_f32 v60, -v60, v130, v128
	v_div_fmas_f32 v60, v60, v61, v130
	v_div_fixup_f32 v56, v60, v56, 1.0
	v_fmac_f32_e32 v134, v57, v56
	v_mul_f32_e32 v56, 0xbfb8aa3b, v137
	v_exp_f32_e32 v56, v56
	s_nop 0
	v_add_f32_e32 v56, 1.0, v56
	v_div_scale_f32 v57, s[18:19], v56, v56, 1.0
	v_rcp_f32_e32 v60, v57
	s_nop 0
	v_fma_f32 v61, -v57, v60, 1.0
	v_fmac_f32_e32 v60, v61, v60
	v_div_scale_f32 v61, vcc, 1.0, v56, 1.0
	v_mul_f32_e32 v128, v61, v60
	v_fma_f32 v130, -v57, v128, v61
	v_fmac_f32_e32 v128, v130, v60
	v_fma_f32 v57, -v57, v128, v61
	v_div_fmas_f32 v57, v57, v60, v128
	v_div_fixup_f32 v56, v57, v56, 1.0
	v_fmac_f32_e32 v141, v62, v56
	v_mul_f32_e32 v56, 0xbfb8aa3b, v139
	v_exp_f32_e32 v56, v56
	s_nop 0
	v_add_f32_e32 v56, 1.0, v56
	v_div_scale_f32 v57, s[18:19], v56, v56, 1.0
	v_rcp_f32_e32 v60, v57
	s_nop 0
	v_fma_f32 v61, -v57, v60, 1.0
	v_fmac_f32_e32 v60, v61, v60
	v_div_scale_f32 v61, vcc, 1.0, v56, 1.0
	v_mul_f32_e32 v62, v61, v60
	v_fma_f32 v128, -v57, v62, v61
	v_fmac_f32_e32 v62, v128, v60
	v_fma_f32 v57, -v57, v62, v61
	v_div_fmas_f32 v57, v57, v60, v62
	v_div_fixup_f32 v56, v57, v56, 1.0
	v_fmac_f32_e32 v143, v58, v56
	v_mul_f32_e32 v56, 0xbfb8aa3b, v129
	v_exp_f32_e32 v56, v56
	s_nop 0
	v_add_f32_e32 v56, 1.0, v56
	v_div_scale_f32 v57, s[18:19], v56, v56, 1.0
	v_rcp_f32_e32 v58, v57
	s_nop 0
	v_fma_f32 v60, -v57, v58, 1.0
	v_fmac_f32_e32 v58, v60, v58
	v_div_scale_f32 v60, vcc, 1.0, v56, 1.0
	v_mul_f32_e32 v61, v60, v58
	v_fma_f32 v62, -v57, v61, v60
	v_fmac_f32_e32 v61, v62, v58
	v_fma_f32 v57, -v57, v61, v60
	v_div_fmas_f32 v57, v57, v58, v61
	v_div_fixup_f32 v56, v57, v56, 1.0
	v_fmac_f32_e32 v133, v63, v56
	v_mul_f32_e32 v56, 0xbfb8aa3b, v131
	v_exp_f32_e32 v56, v56
	s_waitcnt vmcnt(13)
	v_and_b32_e32 v63, 0xffff0000, v118
	v_add_f32_e32 v56, 1.0, v56
	v_div_scale_f32 v57, s[18:19], v56, v56, 1.0
	v_rcp_f32_e32 v58, v57
	s_nop 0
	v_fma_f32 v60, -v57, v58, 1.0
	v_fmac_f32_e32 v58, v60, v58
	v_div_scale_f32 v60, vcc, 1.0, v56, 1.0
	v_mul_f32_e32 v61, v60, v58
	v_fma_f32 v62, -v57, v61, v60
	v_fmac_f32_e32 v61, v62, v58
	v_fma_f32 v57, -v57, v61, v60
	v_div_fmas_f32 v57, v57, v58, v61
	v_div_fixup_f32 v56, v57, v56, 1.0
	v_fmac_f32_e32 v135, v59, v56
	v_lshl_add_u64 v[56:57], s[76:77], 0, v[126:127]
	v_cvt_pk_bf16_f32 v58, v140, v132
	v_lshl_add_u64 v[56:57], v[56:57], 0, v[206:207]
	v_cvt_pk_bf16_f32 v59, v141, v133
	v_cvt_pk_bf16_f32 v60, v142, v134
	v_cvt_pk_bf16_f32 v61, v143, v135
	global_store_dwordx4 v[56:57], v[58:61], off sc1
	v_lshlrev_b32_e32 v62, 16, v118
	s_waitcnt vmcnt(13)
; __device__ __forceinline__ unsigned cvt_pk_bf16(float lo, float hi) { unsigned r; asm volatile("v_cvt_pk_bf16_f32 %0, %1, %2" : "=v"(r) : "v"(lo), "v"(hi)); return r; }
; __device__ __forceinline__ float sigmoidf_(float x) { return 1.f / (1.f + __expf(-x)); }
; __device__ __forceinline__ void unpack8(const u32x4& w, float (&f)[8]) { f[0] = bflo(w.x); f[1] = bfhi(w.x); f[2] = bflo(w.y); f[3] = bfhi(w.y); f[4] = bflo(w.z); f[5] = bfhi(w.z); f[6] = bflo(w.w); f[7] = bfhi(w.w); }
;     __device__ __forceinline__ void operator()(const f32x4 (&acc)[2][2][4][2], const Unit& u, int wr, int wc, int fr, int fq) const {
;     ...
;                 for (int bj = 0; bj < 2; ++bj) { float g[8], t[8]; unpack8(gw[m][bj], g); unpack8(tw[m][bj], t); const f32x4 a0 = acc[ai][bj][m][0], a1 = acc[ai][bj][m][1]; float o[8];
; #pragma unroll
;                     for (int e = 0; e < 4; ++e) { o[e] = t[e] + a0[e] * sigmoidf_(g[e]); o[4 + e] = t[4 + e] + a1[e] * sigmoidf_(g[4 + e]); }
;                     *(u32x4*)(Y + (size_t)(row0 + ai * HALF + m * 16) * DM + col0 + bj * HALF) = (u32x4){cvt_pk_bf16(o[0], o[1]), cvt_pk_bf16(o[2], o[3]), cvt_pk_bf16(o[4], o[5]), cvt_pk_bf16(o[6], o[7])}; } }
	v_lshlrev_b32_e32 v118, 16, v112
	v_lshlrev_b32_e32 v58, 16, v116
	v_mul_f32_e32 v58, 0xbfb8aa3b, v58
	v_exp_f32_e32 v58, v58
	v_and_b32_e32 v59, 0xffff0000, v116
	v_lshlrev_b32_e32 v126, 16, v114
	v_and_b32_e32 v112, 0xffff0000, v112
	v_add_f32_e32 v58, 1.0, v58
	v_div_scale_f32 v128, s[18:19], v58, v58, 1.0
	v_rcp_f32_e32 v129, v128
	v_lshlrev_b32_e32 v60, 16, v117
	v_and_b32_e32 v114, 0xffff0000, v114
	v_and_b32_e32 v61, 0xffff0000, v117
	v_fma_f32 v130, -v128, v129, 1.0
	v_fmac_f32_e32 v129, v130, v129
	v_div_scale_f32 v130, vcc, 1.0, v58, 1.0
	v_mul_f32_e32 v131, v130, v129
	v_fma_f32 v132, -v128, v131, v130
	v_fmac_f32_e32 v131, v132, v129
	v_fma_f32 v128, -v128, v131, v130
	v_div_fmas_f32 v128, v128, v129, v131
	v_div_fixup_f32 v58, v128, v58, 1.0
	v_fmac_f32_e32 v118, v52, v58
	v_mul_f32_e32 v52, 0xbfb8aa3b, v62
	v_exp_f32_e32 v52, v52
	v_lshlrev_b32_e32 v116, 16, v119
	v_and_b32_e32 v117, 0xffff0000, v119
	v_lshlrev_b32_e32 v119, 16, v113
	v_add_f32_e32 v52, 1.0, v52
	v_div_scale_f32 v58, s[18:19], v52, v52, 1.0
	v_rcp_f32_e32 v62, v58
	v_lshlrev_b32_e32 v127, 16, v115
	v_and_b32_e32 v113, 0xffff0000, v113
	v_and_b32_e32 v115, 0xffff0000, v115
	v_fma_f32 v128, -v58, v62, 1.0
	v_fmac_f32_e32 v62, v128, v62
	v_div_scale_f32 v128, vcc, 1.0, v52, 1.0
	v_mul_f32_e32 v129, v128, v62
	v_fma_f32 v130, -v58, v129, v128
	v_fmac_f32_e32 v129, v130, v62
	v_fma_f32 v58, -v58, v129, v128
	v_div_fmas_f32 v58, v58, v62, v129
	v_div_fixup_f32 v52, v58, v52, 1.0
	v_fmac_f32_e32 v126, v48, v52
	v_mul_f32_e32 v48, 0xbfb8aa3b, v59
	v_exp_f32_e32 v48, v48
	s_nop 0
	v_add_f32_e32 v48, 1.0, v48
	v_div_scale_f32 v52, s[18:19], v48, v48, 1.0
	v_rcp_f32_e32 v58, v52
	s_nop 0
	v_fma_f32 v59, -v52, v58, 1.0
	v_fmac_f32_e32 v58, v59, v58
	v_div_scale_f32 v59, vcc, 1.0, v48, 1.0
	v_mul_f32_e32 v62, v59, v58
	v_fma_f32 v128, -v52, v62, v59
	v_fmac_f32_e32 v62, v128, v58
	v_fma_f32 v52, -v52, v62, v59
	v_div_fmas_f32 v52, v52, v58, v62
	v_div_fixup_f32 v48, v52, v48, 1.0
	v_fmac_f32_e32 v112, v53, v48
	v_mul_f32_e32 v48, 0xbfb8aa3b, v63
	v_exp_f32_e32 v48, v48
	s_waitcnt vmcnt(11)
	v_and_b32_e32 v63, 0xffff0000, v107
	v_add_f32_e32 v48, 1.0, v48
	v_div_scale_f32 v52, s[18:19], v48, v48, 1.0
	v_rcp_f32_e32 v53, v52
	s_nop 0
	v_fma_f32 v58, -v52, v53, 1.0
	v_fmac_f32_e32 v53, v58, v53
	v_div_scale_f32 v58, vcc, 1.0, v48, 1.0
	v_mul_f32_e32 v59, v58, v53
	v_fma_f32 v62, -v52, v59, v58
	v_fmac_f32_e32 v59, v62, v53
	v_fma_f32 v52, -v52, v59, v58
	v_div_fmas_f32 v52, v52, v53, v59
	v_div_fixup_f32 v48, v52, v48, 1.0
	v_fmac_f32_e32 v114, v49, v48
	v_mul_f32_e32 v48, 0xbfb8aa3b, v60
	v_exp_f32_e32 v48, v48
	v_lshlrev_b32_e32 v60, 16, v106
	v_lshlrev_b32_e32 v62, 16, v107
	v_add_f32_e32 v48, 1.0, v48
	v_div_scale_f32 v49, s[18:19], v48, v48, 1.0
	v_rcp_f32_e32 v52, v49
	s_nop 0
	v_fma_f32 v53, -v49, v52, 1.0
	v_fmac_f32_e32 v52, v53, v52
	v_div_scale_f32 v53, vcc, 1.0, v48, 1.0
	v_mul_f32_e32 v58, v53, v52
	v_fma_f32 v59, -v49, v58, v53
	v_fmac_f32_e32 v58, v59, v52
	v_fma_f32 v49, -v49, v58, v53
	v_div_fmas_f32 v49, v49, v52, v58
	v_div_fixup_f32 v48, v49, v48, 1.0
	v_fmac_f32_e32 v119, v54, v48
	v_mul_f32_e32 v48, 0xbfb8aa3b, v116
	v_exp_f32_e32 v48, v48
	v_and_b32_e32 v59, 0xffff0000, v105
	v_add_f32_e32 v48, 1.0, v48
	v_div_scale_f32 v49, s[18:19], v48, v48, 1.0
	v_rcp_f32_e32 v52, v49
	s_nop 0
	v_fma_f32 v53, -v49, v52, 1.0
	v_fmac_f32_e32 v52, v53, v52
	v_div_scale_f32 v53, vcc, 1.0, v48, 1.0
	v_mul_f32_e32 v54, v53, v52
	v_fma_f32 v58, -v49, v54, v53
	v_fmac_f32_e32 v54, v58, v52
	v_fma_f32 v49, -v49, v54, v53
	v_div_fmas_f32 v49, v49, v52, v54
	v_div_fixup_f32 v48, v49, v48, 1.0
	v_fmac_f32_e32 v127, v50, v48
	v_mul_f32_e32 v48, 0xbfb8aa3b, v61
	v_exp_f32_e32 v48, v48
	v_lshlrev_b32_e32 v58, 16, v105
	v_and_b32_e32 v61, 0xffff0000, v106
	v_add_f32_e32 v48, 1.0, v48
	v_div_scale_f32 v49, s[18:19], v48, v48, 1.0
	v_rcp_f32_e32 v50, v49
	s_nop 0
	v_fma_f32 v52, -v49, v50, 1.0
	v_fmac_f32_e32 v50, v52, v50
	v_div_scale_f32 v52, vcc, 1.0, v48, 1.0
	v_mul_f32_e32 v53, v52, v50
	v_fma_f32 v54, -v49, v53, v52
	v_fmac_f32_e32 v53, v54, v50
	v_fma_f32 v49, -v49, v53, v52
	v_div_fmas_f32 v49, v49, v50, v53
	v_div_fixup_f32 v48, v49, v48, 1.0
	v_fmac_f32_e32 v113, v55, v48
	v_mul_f32_e32 v48, 0xbfb8aa3b, v117
	v_exp_f32_e32 v48, v48
	v_and_b32_e32 v55, 0xffff0000, v111
	v_add_f32_e32 v48, 1.0, v48
	v_div_scale_f32 v49, s[18:19], v48, v48, 1.0
	v_rcp_f32_e32 v50, v49
	s_nop 0
	v_fma_f32 v52, -v49, v50, 1.0
	v_fmac_f32_e32 v50, v52, v50
	v_div_scale_f32 v52, vcc, 1.0, v48, 1.0
	v_mul_f32_e32 v53, v52, v50
	v_fma_f32 v54, -v49, v53, v52
	v_fmac_f32_e32 v53, v54, v50
	v_fma_f32 v49, -v49, v53, v52
	v_div_fmas_f32 v49, v49, v50, v53
	v_div_fixup_f32 v48, v49, v48, 1.0
	v_fmac_f32_e32 v115, v51, v48
	v_cvt_pk_bf16_f32 v48, v118, v112
	v_cvt_pk_bf16_f32 v49, v119, v113
	v_cvt_pk_bf16_f32 v50, v126, v114
	v_cvt_pk_bf16_f32 v51, v127, v115
	global_store_dwordx4 v[56:57], v[48:51], off offset:256 sc1
	v_lshlrev_b32_e32 v56, 16, v104
	v_and_b32_e32 v57, 0xffff0000, v104
	v_lshlrev_b32_e32 v48, 16, v108
	v_mul_f32_e32 v48, 0xbfb8aa3b, v48
	v_exp_f32_e32 v48, v48
	v_and_b32_e32 v49, 0xffff0000, v108
	v_lshlrev_b32_e32 v52, 16, v110
	v_and_b32_e32 v53, 0xffff0000, v110
	v_add_f32_e32 v48, 1.0, v48
	v_div_scale_f32 v104, s[18:19], v48, v48, 1.0
	v_rcp_f32_e32 v105, v104
	v_lshlrev_b32_e32 v50, 16, v109
	v_lshlrev_b32_e32 v54, 16, v111
	v_and_b32_e32 v51, 0xffff0000, v109
	v_fma_f32 v106, -v104, v105, 1.0
	v_fmac_f32_e32 v105, v106, v105
	v_div_scale_f32 v106, vcc, 1.0, v48, 1.0
	v_mul_f32_e32 v107, v106, v105
	v_fma_f32 v108, -v104, v107, v106
	v_fmac_f32_e32 v107, v108, v105
	v_fma_f32 v104, -v104, v107, v106
	v_div_fmas_f32 v104, v104, v105, v107
	v_div_fixup_f32 v48, v104, v48, 1.0
	v_fmac_f32_e32 v56, v44, v48
	v_mul_f32_e32 v44, 0xbfb8aa3b, v52
	v_exp_f32_e32 v44, v44
	s_nop 0
	v_add_f32_e32 v44, 1.0, v44
	v_div_scale_f32 v48, s[18:19], v44, v44, 1.0
	v_rcp_f32_e32 v52, v48
	s_nop 0
	v_fma_f32 v104, -v48, v52, 1.0
	v_fmac_f32_e32 v52, v104, v52
	v_div_scale_f32 v104, vcc, 1.0, v44, 1.0
	v_mul_f32_e32 v105, v104, v52
	v_fma_f32 v106, -v48, v105, v104
	v_fmac_f32_e32 v105, v106, v52
	v_fma_f32 v48, -v48, v105, v104
	v_div_fmas_f32 v48, v48, v52, v105
	v_div_fixup_f32 v44, v48, v44, 1.0
	v_fmac_f32_e32 v60, v40, v44
	v_mul_f32_e32 v40, 0xbfb8aa3b, v49
	v_exp_f32_e32 v40, v40
	s_nop 0
	v_add_f32_e32 v40, 1.0, v40
	v_div_scale_f32 v44, s[18:19], v40, v40, 1.0
	v_rcp_f32_e32 v48, v44
	s_nop 0
	v_fma_f32 v49, -v44, v48, 1.0
	v_fmac_f32_e32 v48, v49, v48
	v_div_scale_f32 v49, vcc, 1.0, v40, 1.0
	v_mul_f32_e32 v52, v49, v48
	v_fma_f32 v104, -v44, v52, v49
	v_fmac_f32_e32 v52, v104, v48
	v_fma_f32 v44, -v44, v52, v49
	v_div_fmas_f32 v44, v44, v48, v52
	v_div_fixup_f32 v40, v44, v40, 1.0
	v_fmac_f32_e32 v57, v45, v40
	v_mul_f32_e32 v40, 0xbfb8aa3b, v53
	v_exp_f32_e32 v40, v40
	s_waitcnt vmcnt(10)
; __device__ __forceinline__ unsigned cvt_pk_bf16(float lo, float hi) { unsigned r; asm volatile("v_cvt_pk_bf16_f32 %0, %1, %2" : "=v"(r) : "v"(lo), "v"(hi)); return r; }
; __device__ __forceinline__ float sigmoidf_(float x) { return 1.f / (1.f + __expf(-x)); }
; __device__ __forceinline__ void unpack8(const u32x4& w, float (&f)[8]) { f[0] = bflo(w.x); f[1] = bfhi(w.x); f[2] = bflo(w.y); f[3] = bfhi(w.y); f[4] = bflo(w.z); f[5] = bfhi(w.z); f[6] = bflo(w.w); f[7] = bfhi(w.w); }
;     __device__ __forceinline__ void operator()(const f32x4 (&acc)[2][2][4][2], const Unit& u, int wr, int wc, int fr, int fq) const {
;     ...
;                 for (int bj = 0; bj < 2; ++bj) { float g[8], t[8]; unpack8(gw[m][bj], g); unpack8(tw[m][bj], t); const f32x4 a0 = acc[ai][bj][m][0], a1 = acc[ai][bj][m][1]; float o[8];
; #pragma unroll
;                     for (int e = 0; e < 4; ++e) { o[e] = t[e] + a0[e] * sigmoidf_(g[e]); o[4 + e] = t[4 + e] + a1[e] * sigmoidf_(g[4 + e]); }
;                     *(u32x4*)(Y + (size_t)(row0 + ai * HALF + m * 16) * DM + col0 + bj * HALF) = (u32x4){cvt_pk_bf16(o[0], o[1]), cvt_pk_bf16(o[2], o[3]), cvt_pk_bf16(o[4], o[5]), cvt_pk_bf16(o[6], o[7])}; } }
	v_and_b32_e32 v53, 0xffff0000, v97
	v_add_f32_e32 v40, 1.0, v40
	v_div_scale_f32 v44, s[18:19], v40, v40, 1.0
	v_rcp_f32_e32 v45, v44
	s_nop 0
	v_fma_f32 v48, -v44, v45, 1.0
	v_fmac_f32_e32 v45, v48, v45
	v_div_scale_f32 v48, vcc, 1.0, v40, 1.0
	v_mul_f32_e32 v49, v48, v45
	v_fma_f32 v52, -v44, v49, v48
	v_fmac_f32_e32 v49, v52, v45
	v_fma_f32 v44, -v44, v49, v48
	v_div_fmas_f32 v44, v44, v45, v49
	v_div_fixup_f32 v40, v44, v40, 1.0
	v_fmac_f32_e32 v61, v41, v40
	v_mul_f32_e32 v40, 0xbfb8aa3b, v50
	v_exp_f32_e32 v40, v40
	v_lshlrev_b32_e32 v50, 16, v96
	v_lshlrev_b32_e32 v52, 16, v97
	v_add_f32_e32 v40, 1.0, v40
	v_div_scale_f32 v41, s[18:19], v40, v40, 1.0
	v_rcp_f32_e32 v44, v41
	s_nop 0
	v_fma_f32 v45, -v41, v44, 1.0
	v_fmac_f32_e32 v44, v45, v44
	v_div_scale_f32 v45, vcc, 1.0, v40, 1.0
	v_mul_f32_e32 v48, v45, v44
	v_fma_f32 v49, -v41, v48, v45
	v_fmac_f32_e32 v48, v49, v44
	v_fma_f32 v41, -v41, v48, v45
	v_div_fmas_f32 v41, v41, v44, v48
	v_div_fixup_f32 v40, v41, v40, 1.0
	v_fmac_f32_e32 v58, v46, v40
	v_mul_f32_e32 v40, 0xbfb8aa3b, v54
	v_exp_f32_e32 v40, v40
	v_lshlrev_b32_e32 v54, 16, v98
	v_and_b32_e32 v49, 0xffff0000, v103
	v_add_f32_e32 v40, 1.0, v40
	v_div_scale_f32 v41, s[18:19], v40, v40, 1.0
	v_rcp_f32_e32 v44, v41
	s_nop 0
	v_fma_f32 v45, -v41, v44, 1.0
	v_fmac_f32_e32 v44, v45, v44
	v_div_scale_f32 v45, vcc, 1.0, v40, 1.0
	v_mul_f32_e32 v46, v45, v44
	v_fma_f32 v48, -v41, v46, v45
	v_fmac_f32_e32 v46, v48, v44
	v_fma_f32 v41, -v41, v46, v45
	v_div_fmas_f32 v41, v41, v44, v46
	v_div_fixup_f32 v40, v41, v40, 1.0
	v_fmac_f32_e32 v62, v42, v40
	v_mul_f32_e32 v40, 0xbfb8aa3b, v51
	v_exp_f32_e32 v40, v40
	v_and_b32_e32 v51, 0xffff0000, v96
	v_lshlrev_b32_e32 v48, 16, v103
	v_add_f32_e32 v40, 1.0, v40
	v_div_scale_f32 v41, s[18:19], v40, v40, 1.0
	v_rcp_f32_e32 v42, v41
	s_nop 0
	v_fma_f32 v44, -v41, v42, 1.0
	v_fmac_f32_e32 v42, v44, v42
	v_div_scale_f32 v44, vcc, 1.0, v40, 1.0
	v_mul_f32_e32 v45, v44, v42
	v_fma_f32 v46, -v41, v45, v44
	v_fmac_f32_e32 v45, v46, v42
	v_fma_f32 v41, -v41, v45, v44
	v_div_fmas_f32 v41, v41, v42, v45
	v_div_fixup_f32 v40, v41, v40, 1.0
	v_fmac_f32_e32 v59, v47, v40
	v_mul_f32_e32 v40, 0xbfb8aa3b, v55
	v_exp_f32_e32 v40, v40
	v_and_b32_e32 v47, 0xffff0000, v102
	v_and_b32_e32 v55, 0xffff0000, v98
	v_add_f32_e32 v40, 1.0, v40
	v_div_scale_f32 v41, s[18:19], v40, v40, 1.0
	v_rcp_f32_e32 v42, v41
	s_nop 0
	v_fma_f32 v44, -v41, v42, 1.0
	v_fmac_f32_e32 v42, v44, v42
	v_div_scale_f32 v44, vcc, 1.0, v40, 1.0
	v_mul_f32_e32 v45, v44, v42
	v_fma_f32 v46, -v41, v45, v44
	v_fmac_f32_e32 v45, v46, v42
	v_fma_f32 v41, -v41, v45, v44
	v_div_fmas_f32 v41, v41, v42, v45
	v_div_fixup_f32 v40, v41, v40, 1.0
	v_fmac_f32_e32 v63, v43, v40
	v_lshl_add_u64 v[40:41], s[76:77], 0, v[124:125]
	v_cvt_pk_bf16_f32 v42, v56, v57
	v_lshl_add_u64 v[40:41], v[40:41], 0, v[206:207]
	v_cvt_pk_bf16_f32 v43, v58, v59
	v_cvt_pk_bf16_f32 v44, v60, v61
	v_cvt_pk_bf16_f32 v45, v62, v63
	global_store_dwordx4 v[40:41], v[42:45], off sc1
	v_lshlrev_b32_e32 v46, 16, v102
	v_lshlrev_b32_e32 v56, 16, v99
	v_lshlrev_b32_e32 v42, 16, v100
	v_mul_f32_e32 v42, 0xbfb8aa3b, v42
	v_exp_f32_e32 v42, v42
	v_and_b32_e32 v43, 0xffff0000, v100
	v_lshlrev_b32_e32 v44, 16, v101
	v_and_b32_e32 v45, 0xffff0000, v101
	v_add_f32_e32 v42, 1.0, v42
	v_div_scale_f32 v58, s[18:19], v42, v42, 1.0
	v_rcp_f32_e32 v59, v58
	v_and_b32_e32 v57, 0xffff0000, v99
	v_fma_f32 v60, -v58, v59, 1.0
	v_fmac_f32_e32 v59, v60, v59
	v_div_scale_f32 v60, vcc, 1.0, v42, 1.0
	v_mul_f32_e32 v61, v60, v59
	v_fma_f32 v62, -v58, v61, v60
	v_fmac_f32_e32 v61, v62, v59
	v_fma_f32 v58, -v58, v61, v60
	v_div_fmas_f32 v58, v58, v59, v61
	v_div_fixup_f32 v42, v58, v42, 1.0
	v_fmac_f32_e32 v50, v36, v42
	v_mul_f32_e32 v36, 0xbfb8aa3b, v46
	v_exp_f32_e32 v36, v36
	s_nop 0
	v_add_f32_e32 v36, 1.0, v36
	v_div_scale_f32 v42, s[18:19], v36, v36, 1.0
	v_rcp_f32_e32 v46, v42
	s_nop 0
	v_fma_f32 v58, -v42, v46, 1.0
	v_fmac_f32_e32 v46, v58, v46
	v_div_scale_f32 v58, vcc, 1.0, v36, 1.0
	v_mul_f32_e32 v59, v58, v46
	v_fma_f32 v60, -v42, v59, v58
	v_fmac_f32_e32 v59, v60, v46
	v_fma_f32 v42, -v42, v59, v58
	v_div_fmas_f32 v42, v42, v46, v59
	v_div_fixup_f32 v36, v42, v36, 1.0
	v_fmac_f32_e32 v54, v32, v36
	v_mul_f32_e32 v32, 0xbfb8aa3b, v43
	v_exp_f32_e32 v32, v32
	s_nop 0
	v_add_f32_e32 v32, 1.0, v32
	v_div_scale_f32 v36, s[18:19], v32, v32, 1.0
	v_rcp_f32_e32 v42, v36
	s_nop 0
	v_fma_f32 v43, -v36, v42, 1.0
	v_fmac_f32_e32 v42, v43, v42
	v_div_scale_f32 v43, vcc, 1.0, v32, 1.0
	v_mul_f32_e32 v46, v43, v42
	v_fma_f32 v58, -v36, v46, v43
	v_fmac_f32_e32 v46, v58, v42
	v_fma_f32 v36, -v36, v46, v43
	v_div_fmas_f32 v36, v36, v42, v46
	v_div_fixup_f32 v32, v36, v32, 1.0
	v_fmac_f32_e32 v51, v37, v32
	v_mul_f32_e32 v32, 0xbfb8aa3b, v47
	v_exp_f32_e32 v32, v32
	s_waitcnt vmcnt(9)
; __device__ __forceinline__ unsigned cvt_pk_bf16(float lo, float hi) { unsigned r; asm volatile("v_cvt_pk_bf16_f32 %0, %1, %2" : "=v"(r) : "v"(lo), "v"(hi)); return r; }
; __device__ __forceinline__ float sigmoidf_(float x) { return 1.f / (1.f + __expf(-x)); }
; __device__ __forceinline__ void unpack8(const u32x4& w, float (&f)[8]) { f[0] = bflo(w.x); f[1] = bfhi(w.x); f[2] = bflo(w.y); f[3] = bfhi(w.y); f[4] = bflo(w.z); f[5] = bfhi(w.z); f[6] = bflo(w.w); f[7] = bfhi(w.w); }
;     __device__ __forceinline__ void operator()(const f32x4 (&acc)[2][2][4][2], const Unit& u, int wr, int wc, int fr, int fq) const {
;     ...
;                 for (int bj = 0; bj < 2; ++bj) { const size_t r = (size_t)(row0 + ai * HALF + m * 16); gw[m][bj] = *(const u32x4*)(gate + r * ldg + col0 + bj * HALF); tw[m][bj] = *(const u32x4*)(T + r * DM + col0 + bj * HALF); }
; #pragma unroll
;             for (int m = 0; m < 4; ++m)
; #pragma unroll
;                 for (int bj = 0; bj < 2; ++bj) { float g[8], t[8]; unpack8(gw[m][bj], g); unpack8(tw[m][bj], t); const f32x4 a0 = acc[ai][bj][m][0], a1 = acc[ai][bj][m][1]; float o[8];
; #pragma unroll
;                     for (int e = 0; e < 4; ++e) { o[e] = t[e] + a0[e] * sigmoidf_(g[e]); o[4 + e] = t[4 + e] + a1[e] * sigmoidf_(g[4 + e]); }
;                     *(u32x4*)(Y + (size_t)(row0 + ai * HALF + m * 16) * DM + col0 + bj * HALF) = (u32x4){cvt_pk_bf16(o[0], o[1]), cvt_pk_bf16(o[2], o[3]), cvt_pk_bf16(o[4], o[5]), cvt_pk_bf16(o[6], o[7])}; } }
	v_and_b32_e32 v47, 0xffff0000, v91
	v_add_f32_e32 v32, 1.0, v32
	v_div_scale_f32 v36, s[18:19], v32, v32, 1.0
	v_rcp_f32_e32 v37, v36
	s_nop 0
	v_fma_f32 v42, -v36, v37, 1.0
	v_fmac_f32_e32 v37, v42, v37
	v_div_scale_f32 v42, vcc, 1.0, v32, 1.0
	v_mul_f32_e32 v43, v42, v37
	v_fma_f32 v46, -v36, v43, v42
	v_fmac_f32_e32 v43, v46, v37
	v_fma_f32 v36, -v36, v43, v42
	v_div_fmas_f32 v36, v36, v37, v43
	v_div_fixup_f32 v32, v36, v32, 1.0
	v_fmac_f32_e32 v55, v33, v32
	v_mul_f32_e32 v32, 0xbfb8aa3b, v44
	v_exp_f32_e32 v32, v32
	v_lshlrev_b32_e32 v44, 16, v90
	v_lshlrev_b32_e32 v46, 16, v91
	v_add_f32_e32 v32, 1.0, v32
	v_div_scale_f32 v33, s[18:19], v32, v32, 1.0
	v_rcp_f32_e32 v36, v33
	s_nop 0
	v_fma_f32 v37, -v33, v36, 1.0
	v_fmac_f32_e32 v36, v37, v36
	v_div_scale_f32 v37, vcc, 1.0, v32, 1.0
	v_mul_f32_e32 v42, v37, v36
	v_fma_f32 v43, -v33, v42, v37
	v_fmac_f32_e32 v42, v43, v36
	v_fma_f32 v33, -v33, v42, v37
	v_div_fmas_f32 v33, v33, v36, v42
	v_div_fixup_f32 v32, v33, v32, 1.0
	v_fmac_f32_e32 v52, v38, v32
	v_mul_f32_e32 v32, 0xbfb8aa3b, v48
	v_exp_f32_e32 v32, v32
	v_and_b32_e32 v43, 0xffff0000, v89
	v_add_f32_e32 v32, 1.0, v32
	v_div_scale_f32 v33, s[18:19], v32, v32, 1.0
	v_rcp_f32_e32 v36, v33
	s_nop 0
	v_fma_f32 v37, -v33, v36, 1.0
	v_fmac_f32_e32 v36, v37, v36
	v_div_scale_f32 v37, vcc, 1.0, v32, 1.0
	v_mul_f32_e32 v38, v37, v36
	v_fma_f32 v42, -v33, v38, v37
	v_fmac_f32_e32 v38, v42, v36
	v_fma_f32 v33, -v33, v38, v37
	v_div_fmas_f32 v33, v33, v36, v38
	v_div_fixup_f32 v32, v33, v32, 1.0
	v_fmac_f32_e32 v56, v34, v32
	v_mul_f32_e32 v32, 0xbfb8aa3b, v45
	v_exp_f32_e32 v32, v32
	v_and_b32_e32 v45, 0xffff0000, v90
	v_lshlrev_b32_e32 v42, 16, v89
	v_add_f32_e32 v32, 1.0, v32
	v_div_scale_f32 v33, s[18:19], v32, v32, 1.0
	v_rcp_f32_e32 v34, v33
	s_nop 0
	v_fma_f32 v36, -v33, v34, 1.0
	v_fmac_f32_e32 v34, v36, v34
	v_div_scale_f32 v36, vcc, 1.0, v32, 1.0
	v_mul_f32_e32 v37, v36, v34
	v_fma_f32 v38, -v33, v37, v36
	v_fmac_f32_e32 v37, v38, v34
	v_fma_f32 v33, -v33, v37, v36
	v_div_fmas_f32 v33, v33, v34, v37
	v_div_fixup_f32 v32, v33, v32, 1.0
	v_fmac_f32_e32 v53, v39, v32
	v_mul_f32_e32 v32, 0xbfb8aa3b, v49
	v_exp_f32_e32 v32, v32
	v_and_b32_e32 v39, 0xffff0000, v95
	v_add_f32_e32 v32, 1.0, v32
	v_div_scale_f32 v33, s[18:19], v32, v32, 1.0
	v_rcp_f32_e32 v34, v33
	s_nop 0
	v_fma_f32 v36, -v33, v34, 1.0
	v_fmac_f32_e32 v34, v36, v34
	v_div_scale_f32 v36, vcc, 1.0, v32, 1.0
	v_mul_f32_e32 v37, v36, v34
	v_fma_f32 v38, -v33, v37, v36
	v_fmac_f32_e32 v37, v38, v34
	v_fma_f32 v33, -v33, v37, v36
	v_div_fmas_f32 v33, v33, v34, v37
	v_div_fixup_f32 v32, v33, v32, 1.0
	v_fmac_f32_e32 v57, v35, v32
	v_cvt_pk_bf16_f32 v32, v50, v51
	v_cvt_pk_bf16_f32 v33, v52, v53
	v_cvt_pk_bf16_f32 v34, v54, v55
	v_cvt_pk_bf16_f32 v35, v56, v57
	global_store_dwordx4 v[40:41], v[32:35], off offset:256 sc1
	v_lshlrev_b32_e32 v36, 16, v94
	v_lshlrev_b32_e32 v40, 16, v88
	v_lshlrev_b32_e32 v32, 16, v92
	v_mul_f32_e32 v32, 0xbfb8aa3b, v32
	v_exp_f32_e32 v32, v32
	v_and_b32_e32 v33, 0xffff0000, v92
	v_and_b32_e32 v37, 0xffff0000, v94
	v_and_b32_e32 v41, 0xffff0000, v88
	v_add_f32_e32 v32, 1.0, v32
	v_div_scale_f32 v48, s[18:19], v32, v32, 1.0
	v_rcp_f32_e32 v49, v48
	v_lshlrev_b32_e32 v34, 16, v93
	v_lshlrev_b32_e32 v38, 16, v95
	v_and_b32_e32 v35, 0xffff0000, v93
	v_fma_f32 v50, -v48, v49, 1.0
	v_fmac_f32_e32 v49, v50, v49
	v_div_scale_f32 v50, vcc, 1.0, v32, 1.0
	v_mul_f32_e32 v51, v50, v49
	v_fma_f32 v52, -v48, v51, v50
	v_fmac_f32_e32 v51, v52, v49
	v_fma_f32 v48, -v48, v51, v50
	v_div_fmas_f32 v48, v48, v49, v51
	v_div_fixup_f32 v32, v48, v32, 1.0
	v_fmac_f32_e32 v40, v28, v32
	v_mul_f32_e32 v28, 0xbfb8aa3b, v36
	v_exp_f32_e32 v28, v28
	s_nop 0
	v_add_f32_e32 v28, 1.0, v28
	v_div_scale_f32 v32, s[18:19], v28, v28, 1.0
	v_rcp_f32_e32 v36, v32
	s_nop 0
	v_fma_f32 v48, -v32, v36, 1.0
	v_fmac_f32_e32 v36, v48, v36
	v_div_scale_f32 v48, vcc, 1.0, v28, 1.0
	v_mul_f32_e32 v49, v48, v36
	v_fma_f32 v50, -v32, v49, v48
	v_fmac_f32_e32 v49, v50, v36
	v_fma_f32 v32, -v32, v49, v48
	v_div_fmas_f32 v32, v32, v36, v49
	v_div_fixup_f32 v28, v32, v28, 1.0
	v_fmac_f32_e32 v44, v24, v28
	v_mul_f32_e32 v24, 0xbfb8aa3b, v33
	v_exp_f32_e32 v24, v24
	s_nop 0
	v_add_f32_e32 v24, 1.0, v24
	v_div_scale_f32 v28, s[18:19], v24, v24, 1.0
	v_rcp_f32_e32 v32, v28
	s_nop 0
	v_fma_f32 v33, -v28, v32, 1.0
	v_fmac_f32_e32 v32, v33, v32
	v_div_scale_f32 v33, vcc, 1.0, v24, 1.0
	v_mul_f32_e32 v36, v33, v32
	v_fma_f32 v48, -v28, v36, v33
	v_fmac_f32_e32 v36, v48, v32
	v_fma_f32 v28, -v28, v36, v33
	v_div_fmas_f32 v28, v28, v32, v36
	v_div_fixup_f32 v24, v28, v24, 1.0
	v_fmac_f32_e32 v41, v29, v24
	v_mul_f32_e32 v24, 0xbfb8aa3b, v37
	v_exp_f32_e32 v24, v24
	s_waitcnt vmcnt(8)
; __device__ __forceinline__ unsigned cvt_pk_bf16(float lo, float hi) { unsigned r; asm volatile("v_cvt_pk_bf16_f32 %0, %1, %2" : "=v"(r) : "v"(lo), "v"(hi)); return r; }
; __device__ __forceinline__ float sigmoidf_(float x) { return 1.f / (1.f + __expf(-x)); }
; __device__ __forceinline__ void unpack8(const u32x4& w, float (&f)[8]) { f[0] = bflo(w.x); f[1] = bfhi(w.x); f[2] = bflo(w.y); f[3] = bfhi(w.y); f[4] = bflo(w.z); f[5] = bfhi(w.z); f[6] = bflo(w.w); f[7] = bfhi(w.w); }
;     __device__ __forceinline__ void operator()(const f32x4 (&acc)[2][2][4][2], const Unit& u, int wr, int wc, int fr, int fq) const {
;     ...
;                 for (int bj = 0; bj < 2; ++bj) { const size_t r = (size_t)(row0 + ai * HALF + m * 16); gw[m][bj] = *(const u32x4*)(gate + r * ldg + col0 + bj * HALF); tw[m][bj] = *(const u32x4*)(T + r * DM + col0 + bj * HALF); }
; #pragma unroll
;             for (int m = 0; m < 4; ++m)
; #pragma unroll
;                 for (int bj = 0; bj < 2; ++bj) { float g[8], t[8]; unpack8(gw[m][bj], g); unpack8(tw[m][bj], t); const f32x4 a0 = acc[ai][bj][m][0], a1 = acc[ai][bj][m][1]; float o[8];
; #pragma unroll
;                     for (int e = 0; e < 4; ++e) { o[e] = t[e] + a0[e] * sigmoidf_(g[e]); o[4 + e] = t[4 + e] + a1[e] * sigmoidf_(g[4 + e]); }
;                     *(u32x4*)(Y + (size_t)(row0 + ai * HALF + m * 16) * DM + col0 + bj * HALF) = (u32x4){cvt_pk_bf16(o[0], o[1]), cvt_pk_bf16(o[2], o[3]), cvt_pk_bf16(o[4], o[5]), cvt_pk_bf16(o[6], o[7])}; } }
	v_and_b32_e32 v37, 0xffff0000, v81
	v_add_f32_e32 v24, 1.0, v24
	v_div_scale_f32 v28, s[18:19], v24, v24, 1.0
	v_rcp_f32_e32 v29, v28
	s_nop 0
	v_fma_f32 v32, -v28, v29, 1.0
	v_fmac_f32_e32 v29, v32, v29
	v_div_scale_f32 v32, vcc, 1.0, v24, 1.0
	v_mul_f32_e32 v33, v32, v29
	v_fma_f32 v36, -v28, v33, v32
	v_fmac_f32_e32 v33, v36, v29
	v_fma_f32 v28, -v28, v33, v32
	v_div_fmas_f32 v28, v28, v29, v33
	v_div_fixup_f32 v24, v28, v24, 1.0
	v_fmac_f32_e32 v45, v25, v24
	v_mul_f32_e32 v24, 0xbfb8aa3b, v34
	v_exp_f32_e32 v24, v24
	v_lshlrev_b32_e32 v34, 16, v80
	v_lshlrev_b32_e32 v36, 16, v81
	v_add_f32_e32 v24, 1.0, v24
	v_div_scale_f32 v25, s[18:19], v24, v24, 1.0
	v_rcp_f32_e32 v28, v25
	s_nop 0
	v_fma_f32 v29, -v25, v28, 1.0
	v_fmac_f32_e32 v28, v29, v28
	v_div_scale_f32 v29, vcc, 1.0, v24, 1.0
	v_mul_f32_e32 v32, v29, v28
	v_fma_f32 v33, -v25, v32, v29
	v_fmac_f32_e32 v32, v33, v28
	v_fma_f32 v25, -v25, v32, v29
	v_div_fmas_f32 v25, v25, v28, v32
	v_div_fixup_f32 v24, v25, v24, 1.0
	v_fmac_f32_e32 v42, v30, v24
	v_mul_f32_e32 v24, 0xbfb8aa3b, v38
	v_exp_f32_e32 v24, v24
	v_lshlrev_b32_e32 v38, 16, v82
	v_and_b32_e32 v33, 0xffff0000, v87
	v_add_f32_e32 v24, 1.0, v24
	v_div_scale_f32 v25, s[18:19], v24, v24, 1.0
	v_rcp_f32_e32 v28, v25
	s_nop 0
	v_fma_f32 v29, -v25, v28, 1.0
	v_fmac_f32_e32 v28, v29, v28
	v_div_scale_f32 v29, vcc, 1.0, v24, 1.0
	v_mul_f32_e32 v30, v29, v28
	v_fma_f32 v32, -v25, v30, v29
	v_fmac_f32_e32 v30, v32, v28
	v_fma_f32 v25, -v25, v30, v29
	v_div_fmas_f32 v25, v25, v28, v30
	v_div_fixup_f32 v24, v25, v24, 1.0
	v_fmac_f32_e32 v46, v26, v24
	v_mul_f32_e32 v24, 0xbfb8aa3b, v35
	v_exp_f32_e32 v24, v24
	v_and_b32_e32 v35, 0xffff0000, v80
	v_lshlrev_b32_e32 v32, 16, v87
	v_add_f32_e32 v24, 1.0, v24
	v_div_scale_f32 v25, s[18:19], v24, v24, 1.0
	v_rcp_f32_e32 v26, v25
	s_nop 0
	v_fma_f32 v28, -v25, v26, 1.0
	v_fmac_f32_e32 v26, v28, v26
	v_div_scale_f32 v28, vcc, 1.0, v24, 1.0
	v_mul_f32_e32 v29, v28, v26
	v_fma_f32 v30, -v25, v29, v28
	v_fmac_f32_e32 v29, v30, v26
	v_fma_f32 v25, -v25, v29, v28
	v_div_fmas_f32 v25, v25, v26, v29
	v_div_fixup_f32 v24, v25, v24, 1.0
	v_fmac_f32_e32 v43, v31, v24
	v_mul_f32_e32 v24, 0xbfb8aa3b, v39
	v_exp_f32_e32 v24, v24
	v_and_b32_e32 v31, 0xffff0000, v86
	v_and_b32_e32 v39, 0xffff0000, v82
	v_add_f32_e32 v24, 1.0, v24
	v_div_scale_f32 v25, s[18:19], v24, v24, 1.0
	v_rcp_f32_e32 v26, v25
	s_nop 0
	v_fma_f32 v28, -v25, v26, 1.0
	v_fmac_f32_e32 v26, v28, v26
	v_div_scale_f32 v28, vcc, 1.0, v24, 1.0
	v_mul_f32_e32 v29, v28, v26
	v_fma_f32 v30, -v25, v29, v28
	v_fmac_f32_e32 v29, v30, v26
	v_fma_f32 v25, -v25, v29, v28
	v_div_fmas_f32 v25, v25, v26, v29
	v_div_fixup_f32 v24, v25, v24, 1.0
	v_fmac_f32_e32 v47, v27, v24
	v_lshl_add_u64 v[24:25], s[76:77], 0, v[122:123]
	v_cvt_pk_bf16_f32 v26, v40, v41
	v_lshl_add_u64 v[24:25], v[24:25], 0, v[206:207]
	v_cvt_pk_bf16_f32 v27, v42, v43
	v_cvt_pk_bf16_f32 v28, v44, v45
	v_cvt_pk_bf16_f32 v29, v46, v47
	global_store_dwordx4 v[24:25], v[26:29], off sc1
	v_lshlrev_b32_e32 v30, 16, v86
	v_lshlrev_b32_e32 v40, 16, v83
	v_lshlrev_b32_e32 v26, 16, v84
	v_mul_f32_e32 v26, 0xbfb8aa3b, v26
	v_exp_f32_e32 v26, v26
	v_and_b32_e32 v27, 0xffff0000, v84
	v_lshlrev_b32_e32 v28, 16, v85
	v_and_b32_e32 v29, 0xffff0000, v85
	v_add_f32_e32 v26, 1.0, v26
	v_div_scale_f32 v42, s[18:19], v26, v26, 1.0
	v_rcp_f32_e32 v43, v42
	v_and_b32_e32 v41, 0xffff0000, v83
	v_fma_f32 v44, -v42, v43, 1.0
	v_fmac_f32_e32 v43, v44, v43
	v_div_scale_f32 v44, vcc, 1.0, v26, 1.0
	v_mul_f32_e32 v45, v44, v43
	v_fma_f32 v46, -v42, v45, v44
	v_fmac_f32_e32 v45, v46, v43
	v_fma_f32 v42, -v42, v45, v44
	v_div_fmas_f32 v42, v42, v43, v45
	v_div_fixup_f32 v26, v42, v26, 1.0
	v_fmac_f32_e32 v34, v20, v26
	v_mul_f32_e32 v20, 0xbfb8aa3b, v30
	v_exp_f32_e32 v20, v20
	s_nop 0
	v_add_f32_e32 v20, 1.0, v20
	v_div_scale_f32 v26, s[18:19], v20, v20, 1.0
	v_rcp_f32_e32 v30, v26
	s_nop 0
	v_fma_f32 v42, -v26, v30, 1.0
	v_fmac_f32_e32 v30, v42, v30
	v_div_scale_f32 v42, vcc, 1.0, v20, 1.0
	v_mul_f32_e32 v43, v42, v30
	v_fma_f32 v44, -v26, v43, v42
	v_fmac_f32_e32 v43, v44, v30
	v_fma_f32 v26, -v26, v43, v42
	v_div_fmas_f32 v26, v26, v30, v43
	v_div_fixup_f32 v20, v26, v20, 1.0
	v_fmac_f32_e32 v38, v16, v20
	v_mul_f32_e32 v16, 0xbfb8aa3b, v27
	v_exp_f32_e32 v16, v16
	s_nop 0
	v_add_f32_e32 v16, 1.0, v16
	v_div_scale_f32 v20, s[18:19], v16, v16, 1.0
	v_rcp_f32_e32 v26, v20
	s_nop 0
	v_fma_f32 v27, -v20, v26, 1.0
	v_fmac_f32_e32 v26, v27, v26
	v_div_scale_f32 v27, vcc, 1.0, v16, 1.0
	v_mul_f32_e32 v30, v27, v26
	v_fma_f32 v42, -v20, v30, v27
	v_fmac_f32_e32 v30, v42, v26
	v_fma_f32 v20, -v20, v30, v27
	v_div_fmas_f32 v20, v20, v26, v30
	v_div_fixup_f32 v16, v20, v16, 1.0
	v_fmac_f32_e32 v35, v21, v16
	v_mul_f32_e32 v16, 0xbfb8aa3b, v31
	v_exp_f32_e32 v16, v16
	s_waitcnt vmcnt(7)
; __device__ __forceinline__ unsigned cvt_pk_bf16(float lo, float hi) { unsigned r; asm volatile("v_cvt_pk_bf16_f32 %0, %1, %2" : "=v"(r) : "v"(lo), "v"(hi)); return r; }
; __device__ __forceinline__ float sigmoidf_(float x) { return 1.f / (1.f + __expf(-x)); }
; __device__ __forceinline__ void unpack8(const u32x4& w, float (&f)[8]) { f[0] = bflo(w.x); f[1] = bfhi(w.x); f[2] = bflo(w.y); f[3] = bfhi(w.y); f[4] = bflo(w.z); f[5] = bfhi(w.z); f[6] = bflo(w.w); f[7] = bfhi(w.w); }
;     __device__ __forceinline__ void operator()(const f32x4 (&acc)[2][2][4][2], const Unit& u, int wr, int wc, int fr, int fq) const {
;     ...
;                 for (int bj = 0; bj < 2; ++bj) { const size_t r = (size_t)(row0 + ai * HALF + m * 16); gw[m][bj] = *(const u32x4*)(gate + r * ldg + col0 + bj * HALF); tw[m][bj] = *(const u32x4*)(T + r * DM + col0 + bj * HALF); }
; #pragma unroll
;             for (int m = 0; m < 4; ++m)
; #pragma unroll
;                 for (int bj = 0; bj < 2; ++bj) { float g[8], t[8]; unpack8(gw[m][bj], g); unpack8(tw[m][bj], t); const f32x4 a0 = acc[ai][bj][m][0], a1 = acc[ai][bj][m][1]; float o[8];
; #pragma unroll
;                     for (int e = 0; e < 4; ++e) { o[e] = t[e] + a0[e] * sigmoidf_(g[e]); o[4 + e] = t[4 + e] + a1[e] * sigmoidf_(g[4 + e]); }
;                     *(u32x4*)(Y + (size_t)(row0 + ai * HALF + m * 16) * DM + col0 + bj * HALF) = (u32x4){cvt_pk_bf16(o[0], o[1]), cvt_pk_bf16(o[2], o[3]), cvt_pk_bf16(o[4], o[5]), cvt_pk_bf16(o[6], o[7])}; } }
	v_and_b32_e32 v31, 0xffff0000, v75
	v_add_f32_e32 v16, 1.0, v16
	v_div_scale_f32 v20, s[18:19], v16, v16, 1.0
	v_rcp_f32_e32 v21, v20
	s_nop 0
	v_fma_f32 v26, -v20, v21, 1.0
	v_fmac_f32_e32 v21, v26, v21
	v_div_scale_f32 v26, vcc, 1.0, v16, 1.0
	v_mul_f32_e32 v27, v26, v21
	v_fma_f32 v30, -v20, v27, v26
	v_fmac_f32_e32 v27, v30, v21
	v_fma_f32 v20, -v20, v27, v26
	v_div_fmas_f32 v20, v20, v21, v27
	v_div_fixup_f32 v16, v20, v16, 1.0
	v_fmac_f32_e32 v39, v17, v16
	v_mul_f32_e32 v16, 0xbfb8aa3b, v28
	v_exp_f32_e32 v16, v16
	v_lshlrev_b32_e32 v28, 16, v74
	v_lshlrev_b32_e32 v30, 16, v75
	v_add_f32_e32 v16, 1.0, v16
	v_div_scale_f32 v17, s[18:19], v16, v16, 1.0
	v_rcp_f32_e32 v20, v17
	s_nop 0
	v_fma_f32 v21, -v17, v20, 1.0
	v_fmac_f32_e32 v20, v21, v20
	v_div_scale_f32 v21, vcc, 1.0, v16, 1.0
	v_mul_f32_e32 v26, v21, v20
	v_fma_f32 v27, -v17, v26, v21
	v_fmac_f32_e32 v26, v27, v20
	v_fma_f32 v17, -v17, v26, v21
	v_div_fmas_f32 v17, v17, v20, v26
	v_div_fixup_f32 v16, v17, v16, 1.0
	v_fmac_f32_e32 v36, v22, v16
	v_mul_f32_e32 v16, 0xbfb8aa3b, v32
	v_exp_f32_e32 v16, v16
	v_and_b32_e32 v27, 0xffff0000, v73
	v_add_f32_e32 v16, 1.0, v16
	v_div_scale_f32 v17, s[18:19], v16, v16, 1.0
	v_rcp_f32_e32 v20, v17
	s_nop 0
	v_fma_f32 v21, -v17, v20, 1.0
	v_fmac_f32_e32 v20, v21, v20
	v_div_scale_f32 v21, vcc, 1.0, v16, 1.0
	v_mul_f32_e32 v22, v21, v20
	v_fma_f32 v26, -v17, v22, v21
	v_fmac_f32_e32 v22, v26, v20
	v_fma_f32 v17, -v17, v22, v21
	v_div_fmas_f32 v17, v17, v20, v22
	v_div_fixup_f32 v16, v17, v16, 1.0
	v_fmac_f32_e32 v40, v18, v16
	v_mul_f32_e32 v16, 0xbfb8aa3b, v29
	v_exp_f32_e32 v16, v16
	v_and_b32_e32 v29, 0xffff0000, v74
	v_lshlrev_b32_e32 v26, 16, v73
	v_add_f32_e32 v16, 1.0, v16
	v_div_scale_f32 v17, s[18:19], v16, v16, 1.0
	v_rcp_f32_e32 v18, v17
	s_nop 0
	v_fma_f32 v20, -v17, v18, 1.0
	v_fmac_f32_e32 v18, v20, v18
	v_div_scale_f32 v20, vcc, 1.0, v16, 1.0
	v_mul_f32_e32 v21, v20, v18
	v_fma_f32 v22, -v17, v21, v20
	v_fmac_f32_e32 v21, v22, v18
	v_fma_f32 v17, -v17, v21, v20
	v_div_fmas_f32 v17, v17, v18, v21
	v_div_fixup_f32 v16, v17, v16, 1.0
	v_fmac_f32_e32 v37, v23, v16
	v_mul_f32_e32 v16, 0xbfb8aa3b, v33
	v_exp_f32_e32 v16, v16
	v_and_b32_e32 v23, 0xffff0000, v79
	v_add_f32_e32 v16, 1.0, v16
	v_div_scale_f32 v17, s[18:19], v16, v16, 1.0
	v_rcp_f32_e32 v18, v17
	s_nop 0
	v_fma_f32 v20, -v17, v18, 1.0
	v_fmac_f32_e32 v18, v20, v18
	v_div_scale_f32 v20, vcc, 1.0, v16, 1.0
	v_mul_f32_e32 v21, v20, v18
	v_fma_f32 v22, -v17, v21, v20
	v_fmac_f32_e32 v21, v22, v18
	v_fma_f32 v17, -v17, v21, v20
	v_div_fmas_f32 v17, v17, v18, v21
	v_div_fixup_f32 v16, v17, v16, 1.0
	v_fmac_f32_e32 v41, v19, v16
	v_cvt_pk_bf16_f32 v16, v34, v35
	v_cvt_pk_bf16_f32 v17, v36, v37
	v_cvt_pk_bf16_f32 v18, v38, v39
	v_cvt_pk_bf16_f32 v19, v40, v41
	global_store_dwordx4 v[24:25], v[16:19], off offset:256 sc1
	v_lshlrev_b32_e32 v20, 16, v78
	v_lshlrev_b32_e32 v24, 16, v72
	v_lshlrev_b32_e32 v16, 16, v76
	v_mul_f32_e32 v16, 0xbfb8aa3b, v16
	v_exp_f32_e32 v16, v16
	v_and_b32_e32 v17, 0xffff0000, v76
	v_and_b32_e32 v21, 0xffff0000, v78
	v_and_b32_e32 v25, 0xffff0000, v72
	v_add_f32_e32 v16, 1.0, v16
	v_div_scale_f32 v32, s[18:19], v16, v16, 1.0
	v_rcp_f32_e32 v33, v32
	v_lshlrev_b32_e32 v18, 16, v77
	v_lshlrev_b32_e32 v22, 16, v79
	v_and_b32_e32 v19, 0xffff0000, v77
	v_fma_f32 v34, -v32, v33, 1.0
	v_fmac_f32_e32 v33, v34, v33
	v_div_scale_f32 v34, vcc, 1.0, v16, 1.0
	v_mul_f32_e32 v35, v34, v33
	v_fma_f32 v36, -v32, v35, v34
	v_fmac_f32_e32 v35, v36, v33
	v_fma_f32 v32, -v32, v35, v34
	v_div_fmas_f32 v32, v32, v33, v35
	v_div_fixup_f32 v16, v32, v16, 1.0
	v_fmac_f32_e32 v24, v12, v16
	v_mul_f32_e32 v12, 0xbfb8aa3b, v20
	v_exp_f32_e32 v12, v12
	s_nop 0
	v_add_f32_e32 v12, 1.0, v12
	v_div_scale_f32 v16, s[18:19], v12, v12, 1.0
	v_rcp_f32_e32 v20, v16
	s_nop 0
	v_fma_f32 v32, -v16, v20, 1.0
	v_fmac_f32_e32 v20, v32, v20
	v_div_scale_f32 v32, vcc, 1.0, v12, 1.0
	v_mul_f32_e32 v33, v32, v20
	v_fma_f32 v34, -v16, v33, v32
	v_fmac_f32_e32 v33, v34, v20
	v_fma_f32 v16, -v16, v33, v32
	v_div_fmas_f32 v16, v16, v20, v33
	v_div_fixup_f32 v12, v16, v12, 1.0
	v_fmac_f32_e32 v28, v8, v12
	v_mul_f32_e32 v8, 0xbfb8aa3b, v17
	v_exp_f32_e32 v8, v8
	s_nop 0
	v_add_f32_e32 v8, 1.0, v8
	v_div_scale_f32 v12, s[18:19], v8, v8, 1.0
	v_rcp_f32_e32 v16, v12
	s_nop 0
	v_fma_f32 v17, -v12, v16, 1.0
	v_fmac_f32_e32 v16, v17, v16
	v_div_scale_f32 v17, vcc, 1.0, v8, 1.0
	v_mul_f32_e32 v20, v17, v16
	v_fma_f32 v32, -v12, v20, v17
	v_fmac_f32_e32 v20, v32, v16
	v_fma_f32 v12, -v12, v20, v17
	v_div_fmas_f32 v12, v12, v16, v20
	v_div_fixup_f32 v8, v12, v8, 1.0
	v_fmac_f32_e32 v25, v13, v8
	v_mul_f32_e32 v8, 0xbfb8aa3b, v21
	v_exp_f32_e32 v8, v8
	s_waitcnt vmcnt(6)
; __device__ __forceinline__ unsigned cvt_pk_bf16(float lo, float hi) { unsigned r; asm volatile("v_cvt_pk_bf16_f32 %0, %1, %2" : "=v"(r) : "v"(lo), "v"(hi)); return r; }
; __device__ __forceinline__ float sigmoidf_(float x) { return 1.f / (1.f + __expf(-x)); }
; __device__ __forceinline__ void unpack8(const u32x4& w, float (&f)[8]) { f[0] = bflo(w.x); f[1] = bfhi(w.x); f[2] = bflo(w.y); f[3] = bfhi(w.y); f[4] = bflo(w.z); f[5] = bfhi(w.z); f[6] = bflo(w.w); f[7] = bfhi(w.w); }
;     __device__ __forceinline__ void operator()(const f32x4 (&acc)[2][2][4][2], const Unit& u, int wr, int wc, int fr, int fq) const {
;     ...
;                 for (int bj = 0; bj < 2; ++bj) { const size_t r = (size_t)(row0 + ai * HALF + m * 16); gw[m][bj] = *(const u32x4*)(gate + r * ldg + col0 + bj * HALF); tw[m][bj] = *(const u32x4*)(T + r * DM + col0 + bj * HALF); }
; #pragma unroll
;             for (int m = 0; m < 4; ++m)
; #pragma unroll
;                 for (int bj = 0; bj < 2; ++bj) { float g[8], t[8]; unpack8(gw[m][bj], g); unpack8(tw[m][bj], t); const f32x4 a0 = acc[ai][bj][m][0], a1 = acc[ai][bj][m][1]; float o[8];
; #pragma unroll
;                     for (int e = 0; e < 4; ++e) { o[e] = t[e] + a0[e] * sigmoidf_(g[e]); o[4 + e] = t[4 + e] + a1[e] * sigmoidf_(g[4 + e]); }
;                     *(u32x4*)(Y + (size_t)(row0 + ai * HALF + m * 16) * DM + col0 + bj * HALF) = (u32x4){cvt_pk_bf16(o[0], o[1]), cvt_pk_bf16(o[2], o[3]), cvt_pk_bf16(o[4], o[5]), cvt_pk_bf16(o[6], o[7])}; } }
	v_and_b32_e32 v21, 0xffff0000, v65
	v_add_f32_e32 v8, 1.0, v8
	v_div_scale_f32 v12, s[18:19], v8, v8, 1.0
	v_rcp_f32_e32 v13, v12
	s_nop 0
	v_fma_f32 v16, -v12, v13, 1.0
	v_fmac_f32_e32 v13, v16, v13
	v_div_scale_f32 v16, vcc, 1.0, v8, 1.0
	v_mul_f32_e32 v17, v16, v13
	v_fma_f32 v20, -v12, v17, v16
	v_fmac_f32_e32 v17, v20, v13
	v_fma_f32 v12, -v12, v17, v16
	v_div_fmas_f32 v12, v12, v13, v17
	v_div_fixup_f32 v8, v12, v8, 1.0
	v_fmac_f32_e32 v29, v9, v8
	v_mul_f32_e32 v8, 0xbfb8aa3b, v18
	v_exp_f32_e32 v8, v8
	v_lshlrev_b32_e32 v18, 16, v64
	v_lshlrev_b32_e32 v20, 16, v65
	v_add_f32_e32 v8, 1.0, v8
	v_div_scale_f32 v9, s[18:19], v8, v8, 1.0
	v_rcp_f32_e32 v12, v9
	s_nop 0
	v_fma_f32 v13, -v9, v12, 1.0
	v_fmac_f32_e32 v12, v13, v12
	v_div_scale_f32 v13, vcc, 1.0, v8, 1.0
	v_mul_f32_e32 v16, v13, v12
	v_fma_f32 v17, -v9, v16, v13
	v_fmac_f32_e32 v16, v17, v12
	v_fma_f32 v9, -v9, v16, v13
	v_div_fmas_f32 v9, v9, v12, v16
	v_div_fixup_f32 v8, v9, v8, 1.0
	v_fmac_f32_e32 v26, v14, v8
	v_mul_f32_e32 v8, 0xbfb8aa3b, v22
	v_exp_f32_e32 v8, v8
	v_lshlrev_b32_e32 v22, 16, v66
	v_and_b32_e32 v17, 0xffff0000, v71
	v_add_f32_e32 v8, 1.0, v8
	v_div_scale_f32 v9, s[18:19], v8, v8, 1.0
	v_rcp_f32_e32 v12, v9
	s_nop 0
	v_fma_f32 v13, -v9, v12, 1.0
	v_fmac_f32_e32 v12, v13, v12
	v_div_scale_f32 v13, vcc, 1.0, v8, 1.0
	v_mul_f32_e32 v14, v13, v12
	v_fma_f32 v16, -v9, v14, v13
	v_fmac_f32_e32 v14, v16, v12
	v_fma_f32 v9, -v9, v14, v13
	v_div_fmas_f32 v9, v9, v12, v14
	v_div_fixup_f32 v8, v9, v8, 1.0
	v_fmac_f32_e32 v30, v10, v8
	v_mul_f32_e32 v8, 0xbfb8aa3b, v19
	v_exp_f32_e32 v8, v8
	v_and_b32_e32 v19, 0xffff0000, v64
	v_lshlrev_b32_e32 v16, 16, v71
	v_add_f32_e32 v8, 1.0, v8
	v_div_scale_f32 v9, s[18:19], v8, v8, 1.0
	v_rcp_f32_e32 v10, v9
	s_nop 0
	v_fma_f32 v12, -v9, v10, 1.0
	v_fmac_f32_e32 v10, v12, v10
	v_div_scale_f32 v12, vcc, 1.0, v8, 1.0
	v_mul_f32_e32 v13, v12, v10
	v_fma_f32 v14, -v9, v13, v12
	v_fmac_f32_e32 v13, v14, v10
	v_fma_f32 v9, -v9, v13, v12
	v_div_fmas_f32 v9, v9, v10, v13
	v_div_fixup_f32 v8, v9, v8, 1.0
	v_fmac_f32_e32 v27, v15, v8
	v_mul_f32_e32 v8, 0xbfb8aa3b, v23
	v_exp_f32_e32 v8, v8
	v_and_b32_e32 v15, 0xffff0000, v70
	v_and_b32_e32 v23, 0xffff0000, v66
	v_add_f32_e32 v8, 1.0, v8
	v_div_scale_f32 v9, s[18:19], v8, v8, 1.0
	v_rcp_f32_e32 v10, v9
	s_nop 0
	v_fma_f32 v12, -v9, v10, 1.0
	v_fmac_f32_e32 v10, v12, v10
	v_div_scale_f32 v12, vcc, 1.0, v8, 1.0
	v_mul_f32_e32 v13, v12, v10
	v_fma_f32 v14, -v9, v13, v12
	v_fmac_f32_e32 v13, v14, v10
	v_fma_f32 v9, -v9, v13, v12
	v_div_fmas_f32 v9, v9, v10, v13
	v_div_fixup_f32 v8, v9, v8, 1.0
	v_fmac_f32_e32 v31, v11, v8
	v_lshl_add_u64 v[8:9], s[76:77], 0, v[120:121]
	v_cvt_pk_bf16_f32 v10, v24, v25
	v_lshl_add_u64 v[8:9], v[8:9], 0, v[206:207]
	v_cvt_pk_bf16_f32 v11, v26, v27
	v_cvt_pk_bf16_f32 v12, v28, v29
	v_cvt_pk_bf16_f32 v13, v30, v31
	global_store_dwordx4 v[8:9], v[10:13], off sc1
	v_lshlrev_b32_e32 v14, 16, v70
	v_lshlrev_b32_e32 v24, 16, v67
	v_lshlrev_b32_e32 v10, 16, v68
	v_mul_f32_e32 v10, 0xbfb8aa3b, v10
	v_exp_f32_e32 v10, v10
	v_and_b32_e32 v11, 0xffff0000, v68
	v_lshlrev_b32_e32 v12, 16, v69
	v_and_b32_e32 v13, 0xffff0000, v69
	v_add_f32_e32 v10, 1.0, v10
	v_div_scale_f32 v26, s[18:19], v10, v10, 1.0
	v_rcp_f32_e32 v27, v26
	v_and_b32_e32 v25, 0xffff0000, v67
	v_fma_f32 v28, -v26, v27, 1.0
	v_fmac_f32_e32 v27, v28, v27
	v_div_scale_f32 v28, vcc, 1.0, v10, 1.0
	v_mul_f32_e32 v29, v28, v27
	v_fma_f32 v30, -v26, v29, v28
	v_fmac_f32_e32 v29, v30, v27
	v_fma_f32 v26, -v26, v29, v28
	v_div_fmas_f32 v26, v26, v27, v29
	v_div_fixup_f32 v10, v26, v10, 1.0
	v_fmac_f32_e32 v18, v4, v10
; __device__ __forceinline__ unsigned cvt_pk_bf16(float lo, float hi) { unsigned r; asm volatile("v_cvt_pk_bf16_f32 %0, %1, %2" : "=v"(r) : "v"(lo), "v"(hi)); return r; }
; __device__ __forceinline__ float sigmoidf_(float x) { return 1.f / (1.f + __expf(-x)); }
; #define PG8_BAR __builtin_amdgcn_s_barrier()
; __device__ __forceinline__ void unpack8(const u32x4& w, float (&f)[8]) { f[0] = bflo(w.x); f[1] = bfhi(w.x); f[2] = bflo(w.y); f[3] = bfhi(w.y); f[4] = bflo(w.z); f[5] = bfhi(w.z); f[6] = bflo(w.w); f[7] = bfhi(w.w); }
; template <class Epi, class Sched>
; __device__ __forceinline__ void gemm_phase(LAS unsigned char* lds, const Gemm g, const Sched& S, const Epi& E) {
;     ...
;         if (wr == 0) PG8_BAR;
;         E(acc, cur, wr, wc, fr, fq);
;         if (!has_next) break;
; #pragma unroll
;         for (int a = 0; a < 2; ++a)
; #pragma unroll
;             for (int b = 0; b < 2; ++b)
; #pragma unroll
;                 for (int m = 0; m < 4; ++m)
; #pragma unroll
;                     for (int n = 0; n < 2; ++n) acc[a][b][m][n] = (f32x4){0.f, 0.f, 0.f, 0.f};
;         cur = nxt; cA = nA; cB = nB; ++ui;
;         if (wr == 1) PG8_BAR;
;     __device__ __forceinline__ void operator()(const f32x4 (&acc)[2][2][4][2], const Unit& u, int wr, int wc, int fr, int fq) const {
;     ...
;                 for (int bj = 0; bj < 2; ++bj) { float g[8], t[8]; unpack8(gw[m][bj], g); unpack8(tw[m][bj], t); const f32x4 a0 = acc[ai][bj][m][0], a1 = acc[ai][bj][m][1]; float o[8];
; #pragma unroll
;                     for (int e = 0; e < 4; ++e) { o[e] = t[e] + a0[e] * sigmoidf_(g[e]); o[4 + e] = t[4 + e] + a1[e] * sigmoidf_(g[4 + e]); }
;                     *(u32x4*)(Y + (size_t)(row0 + ai * HALF + m * 16) * DM + col0 + bj * HALF) = (u32x4){cvt_pk_bf16(o[0], o[1]), cvt_pk_bf16(o[2], o[3]), cvt_pk_bf16(o[4], o[5]), cvt_pk_bf16(o[6], o[7])}; } }
	v_mul_f32_e32 v4, 0xbfb8aa3b, v14
	v_exp_f32_e32 v4, v4
	s_nop 0
	v_add_f32_e32 v4, 1.0, v4
	v_div_scale_f32 v10, s[18:19], v4, v4, 1.0
	v_rcp_f32_e32 v14, v10
	s_nop 0
	v_fma_f32 v26, -v10, v14, 1.0
	v_fmac_f32_e32 v14, v26, v14
	v_div_scale_f32 v26, vcc, 1.0, v4, 1.0
	v_mul_f32_e32 v27, v26, v14
	v_fma_f32 v28, -v10, v27, v26
	v_fmac_f32_e32 v27, v28, v14
	v_fma_f32 v10, -v10, v27, v26
	v_div_fmas_f32 v10, v10, v14, v27
	v_div_fixup_f32 v4, v10, v4, 1.0
	v_fmac_f32_e32 v22, v0, v4
	v_mul_f32_e32 v0, 0xbfb8aa3b, v11
	v_exp_f32_e32 v0, v0
	s_nop 0
	v_add_f32_e32 v0, 1.0, v0
	v_div_scale_f32 v4, s[18:19], v0, v0, 1.0
	v_rcp_f32_e32 v10, v4
	s_nop 0
	v_fma_f32 v11, -v4, v10, 1.0
	v_fmac_f32_e32 v10, v11, v10
	v_div_scale_f32 v11, vcc, 1.0, v0, 1.0
	v_mul_f32_e32 v14, v11, v10
	v_fma_f32 v26, -v4, v14, v11
	v_fmac_f32_e32 v14, v26, v10
	v_fma_f32 v4, -v4, v14, v11
	v_div_fmas_f32 v4, v4, v10, v14
	v_div_fixup_f32 v0, v4, v0, 1.0
	v_fmac_f32_e32 v19, v5, v0
	v_mul_f32_e32 v0, 0xbfb8aa3b, v15
	v_exp_f32_e32 v0, v0
	s_nop 0
	v_add_f32_e32 v0, 1.0, v0
	v_div_scale_f32 v4, s[18:19], v0, v0, 1.0
	v_rcp_f32_e32 v5, v4
	s_nop 0
	v_fma_f32 v10, -v4, v5, 1.0
	v_fmac_f32_e32 v5, v10, v5
	v_div_scale_f32 v10, vcc, 1.0, v0, 1.0
	v_mul_f32_e32 v11, v10, v5
	v_fma_f32 v14, -v4, v11, v10
	v_fmac_f32_e32 v11, v14, v5
	v_fma_f32 v4, -v4, v11, v10
	v_div_fmas_f32 v4, v4, v5, v11
	v_div_fixup_f32 v0, v4, v0, 1.0
	v_fmac_f32_e32 v23, v1, v0
	v_mul_f32_e32 v0, 0xbfb8aa3b, v12
	v_exp_f32_e32 v0, v0
	s_nop 0
	v_add_f32_e32 v0, 1.0, v0
	v_div_scale_f32 v1, s[18:19], v0, v0, 1.0
	v_rcp_f32_e32 v4, v1
	s_nop 0
	v_fma_f32 v5, -v1, v4, 1.0
	v_fmac_f32_e32 v4, v5, v4
	v_div_scale_f32 v5, vcc, 1.0, v0, 1.0
	v_mul_f32_e32 v10, v5, v4
	v_fma_f32 v11, -v1, v10, v5
	v_fmac_f32_e32 v10, v11, v4
	v_fma_f32 v1, -v1, v10, v5
	v_div_fmas_f32 v1, v1, v4, v10
	v_div_fixup_f32 v0, v1, v0, 1.0
	v_fmac_f32_e32 v20, v6, v0
	v_mul_f32_e32 v0, 0xbfb8aa3b, v16
	v_exp_f32_e32 v0, v0
	s_nop 0
	v_add_f32_e32 v0, 1.0, v0
	v_div_scale_f32 v1, s[18:19], v0, v0, 1.0
	v_rcp_f32_e32 v4, v1
	s_nop 0
	v_fma_f32 v5, -v1, v4, 1.0
	v_fmac_f32_e32 v4, v5, v4
	v_div_scale_f32 v5, vcc, 1.0, v0, 1.0
	v_mul_f32_e32 v6, v5, v4
	v_fma_f32 v10, -v1, v6, v5
	v_fmac_f32_e32 v6, v10, v4
	v_fma_f32 v1, -v1, v6, v5
	v_div_fmas_f32 v1, v1, v4, v6
	v_div_fixup_f32 v0, v1, v0, 1.0
	v_fmac_f32_e32 v24, v2, v0
	v_mul_f32_e32 v0, 0xbfb8aa3b, v13
	v_exp_f32_e32 v0, v0
	s_nop 0
	v_add_f32_e32 v0, 1.0, v0
	v_div_scale_f32 v1, s[18:19], v0, v0, 1.0
	v_rcp_f32_e32 v2, v1
	s_nop 0
	v_fma_f32 v4, -v1, v2, 1.0
	v_fmac_f32_e32 v2, v4, v2
	v_div_scale_f32 v4, vcc, 1.0, v0, 1.0
	v_mul_f32_e32 v5, v4, v2
	v_fma_f32 v6, -v1, v5, v4
	v_fmac_f32_e32 v5, v6, v2
	v_fma_f32 v1, -v1, v5, v4
	v_div_fmas_f32 v1, v1, v2, v5
	v_div_fixup_f32 v0, v1, v0, 1.0
	v_fmac_f32_e32 v21, v7, v0
	v_mul_f32_e32 v0, 0xbfb8aa3b, v17
	v_exp_f32_e32 v0, v0
	s_nop 0
	v_add_f32_e32 v0, 1.0, v0
	v_div_scale_f32 v1, s[18:19], v0, v0, 1.0
	v_rcp_f32_e32 v2, v1
	s_mov_b64 s[18:19], -1
	v_fma_f32 v4, -v1, v2, 1.0
	v_fmac_f32_e32 v2, v4, v2
	v_div_scale_f32 v4, vcc, 1.0, v0, 1.0
	v_mul_f32_e32 v5, v4, v2
	v_fma_f32 v6, -v1, v5, v4
	v_fmac_f32_e32 v5, v6, v2
	v_fma_f32 v1, -v1, v5, v4
	v_div_fmas_f32 v1, v1, v2, v5
	v_div_fixup_f32 v0, v1, v0, 1.0
	s_and_b64 vcc, exec, s[4:5]
	v_fmac_f32_e32 v25, v3, v0
	v_cvt_pk_bf16_f32 v0, v18, v19
	v_cvt_pk_bf16_f32 v1, v20, v21
	v_cvt_pk_bf16_f32 v2, v22, v23
	v_cvt_pk_bf16_f32 v3, v24, v25
	global_store_dwordx4 v[8:9], v[0:3], off offset:256 sc1
	s_cbranch_vccnz .LBB0_685
	s_andn2_b64 vcc, exec, s[0:1]
	s_cbranch_vccnz .LBB0_684
	s_barrier
	s_branch .LBB0_684

; __device__ __forceinline__ unsigned cvt_pk_bf16(float lo, float hi) { unsigned r; asm volatile("v_cvt_pk_bf16_f32 %0, %1, %2" : "=v"(r) : "v"(lo), "v"(hi)); return r; }
;     __device__ __forceinline__ void operator()(const f32x4 (&acc)[2][2][4][2], const Unit& u, int wr, int wc, int fr, int fq) const {
;     ...
;         for (int ai = 0; ai < 2; ++ai) {
;             f32x4 bf[MODE == 0 ? 4 : 1][2][2]; u32x4 bb[MODE == 1 ? 4 : 1][2];
; #pragma unroll
;             for (int m = 0; m < 4; ++m) { const int row = row0 + ai * HALF + m * 16;
;                 if (MODE == 0) { const float* br = row < MP ? basep + (size_t)row * DM : bases + (size_t)(row - MP) * DM;
; #pragma unroll
;                     for (int bj = 0; bj < 2; ++bj) { bf[MODE == 0 ? m : 0][bj][0] = *(const f32x4*)(br + col0 + bj * HALF); bf[MODE == 0 ? m : 0][bj][1] = *(const f32x4*)(br + col0 + bj * HALF + 4); } }
;                 else {
; #pragma unroll
;                     for (int bj = 0; bj < 2; ++bj) bb[MODE == 1 ? m : 0][bj] = *(const u32x4*)(baseb + (size_t)row * DM + col0 + bj * HALF); } }
; #pragma unroll
;             for (int m = 0; m < 4; ++m) { const int row = row0 + ai * HALF + m * 16; float s = 0.f;
; #pragma unroll
;                 for (int bj = 0; bj < 2; ++bj) { float o[8];
;                     if (MODE == 0) { const f32x4 b0 = bf[MODE == 0 ? m : 0][bj][0], b1 = bf[MODE == 0 ? m : 0][bj][1];
; #pragma unroll
;                         for (int e = 0; e < 4; ++e) { o[e] = b0[e] + acc[ai][bj][m][0][e]; o[4 + e] = b1[e] + acc[ai][bj][m][1][e]; } }
;                     else { float t[8]; unpack8(bb[MODE == 1 ? m : 0][bj], t);
; #pragma unroll
;                         for (int e = 0; e < 4; ++e) { o[e] = t[e] + acc[ai][bj][m][0][e]; o[4 + e] = t[4 + e] + acc[ai][bj][m][1][e]; } }
; #pragma unroll
;                     for (int e = 0; e < 8; ++e) s += o[e] * o[e];
;                     *(u32x4*)(ob + (size_t)row * DM + col0 + bj * HALF) = (u32x4){cvt_pk_bf16(o[0], o[1]), cvt_pk_bf16(o[2], o[3]), cvt_pk_bf16(o[4], o[5]), cvt_pk_bf16(o[6], o[7])}; }
;                 s += __shfl_xor(s, 16); s += __shfl_xor(s, 32);
;                 if (fq == 0) ss[(size_t)row * 32 + u.pn * 4 + wc] = s; } }
.LBB0_790:
	v_lshl_add_u32 v200, s28, 8, v185
	v_add_u32_e32 v128, 0xffffc000, v200
	v_ashrrev_i32_e32 v201, 31, v200
	v_cmp_gt_i32_e32 vcc, s43, v200
	v_lshl_or_b32 v198, s0, 8, v211
	v_mov_b32_e32 v132, s67
	v_cndmask_b32_e32 v129, 0, v201, vcc
	v_cndmask_b32_e32 v128, v128, v200, vcc
	v_mov_b32_e32 v133, s65
	v_mov_b32_e32 v134, s66
	v_mov_b32_e32 v135, s64
	v_ashrrev_i32_e32 v199, 31, v198
	v_cndmask_b32_e32 v131, v132, v133, vcc
	v_cndmask_b32_e32 v130, v134, v135, vcc
	v_lshlrev_b64 v[128:129], 13, v[128:129]
	v_lshl_add_u64 v[128:129], v[130:131], 0, v[128:129]
	v_lshlrev_b64 v[202:203], 2, v[198:199]
	v_lshl_add_u64 v[128:129], v[128:129], 0, v[202:203]
	global_load_dwordx4 v[216:219], v[128:129], off nt
	global_load_dwordx4 v[224:227], v[128:129], off offset:16 nt
	global_load_dwordx4 v[228:231], v[128:129], off offset:512 nt
	global_load_dwordx4 v[232:235], v[128:129], off offset:528 nt
	v_or_b32_e32 v208, 16, v200
	v_ashrrev_i32_e32 v209, 31, v208
	v_add_u32_e32 v128, 0xffffc010, v200
	v_cmp_gt_i32_e32 vcc, s43, v208
	v_or_b32_e32 v206, 32, v200
	v_ashrrev_i32_e32 v207, 31, v206
	v_cndmask_b32_e32 v129, 0, v209, vcc
	v_cndmask_b32_e32 v128, v128, v208, vcc
	v_cndmask_b32_e32 v131, v132, v133, vcc
	v_cndmask_b32_e32 v130, v134, v135, vcc
	v_lshlrev_b64 v[128:129], 13, v[128:129]
	v_lshl_add_u64 v[128:129], v[130:131], 0, v[128:129]
	v_lshl_add_u64 v[128:129], v[128:129], 0, v[202:203]
	global_load_dwordx4 v[168:171], v[128:129], off offset:16 nt
	global_load_dwordx4 v[172:175], v[128:129], off nt
	global_load_dwordx4 v[160:163], v[128:129], off offset:528 nt
	global_load_dwordx4 v[164:167], v[128:129], off offset:512 nt
	v_add_u32_e32 v128, 0xffffc020, v200
	v_cmp_gt_i32_e32 vcc, s43, v206
	v_or_b32_e32 v204, 48, v200
	v_ashrrev_i32_e32 v205, 31, v204
	v_cndmask_b32_e32 v129, 0, v207, vcc
	v_cndmask_b32_e32 v128, v128, v206, vcc
	v_cndmask_b32_e32 v131, v132, v133, vcc
	v_cndmask_b32_e32 v130, v134, v135, vcc
	v_lshlrev_b64 v[128:129], 13, v[128:129]
	v_lshl_add_u64 v[128:129], v[130:131], 0, v[128:129]
	v_lshl_add_u64 v[128:129], v[128:129], 0, v[202:203]
	global_load_dwordx4 v[152:155], v[128:129], off offset:16 nt
	global_load_dwordx4 v[156:159], v[128:129], off nt
	global_load_dwordx4 v[144:147], v[128:129], off offset:528 nt
	global_load_dwordx4 v[148:151], v[128:129], off offset:512 nt
	v_add_u32_e32 v128, 0xffffc030, v200
	v_cmp_gt_i32_e32 vcc, s43, v204
	v_lshlrev_b64 v[220:221], 12, v[200:201]
	s_lshl_b32 s28, s0, 2
	v_cndmask_b32_e32 v129, 0, v205, vcc
	v_cndmask_b32_e32 v128, v128, v204, vcc
	v_cndmask_b32_e32 v131, v132, v133, vcc
	v_cndmask_b32_e32 v130, v134, v135, vcc
	v_lshlrev_b64 v[128:129], 13, v[128:129]
	v_lshl_add_u64 v[128:129], v[130:131], 0, v[128:129]
	v_lshl_add_u64 v[132:133], v[128:129], 0, v[202:203]
	global_load_dwordx4 v[136:139], v[132:133], off offset:16 nt
	global_load_dwordx4 v[140:143], v[132:133], off nt
	global_load_dwordx4 v[128:131], v[132:133], off offset:528 nt
	s_nop 0
	global_load_dwordx4 v[132:135], v[132:133], off offset:512 nt
	s_ashr_i32 s29, s28, 31
	s_waitcnt vmcnt(0)
	v_add_f32_e32 v216, v124, v216
	v_add_f32_e32 v124, v125, v217
	v_add_f32_e32 v217, v122, v226
	v_mul_f32_e32 v226, v124, v124
	v_add_f32_e32 v126, v126, v218
	v_fmac_f32_e32 v226, v216, v216
	v_add_f32_e32 v127, v127, v219
	v_fmac_f32_e32 v226, v126, v126
	v_add_f32_e32 v120, v120, v224
	v_fmac_f32_e32 v226, v127, v127
	v_add_f32_e32 v121, v121, v225
	v_fmac_f32_e32 v226, v120, v120
	v_fmac_f32_e32 v226, v121, v121
	v_add_f32_e32 v218, v123, v227
	v_fmac_f32_e32 v226, v217, v217
	v_add_f32_e32 v116, v116, v228
	v_fmac_f32_e32 v226, v218, v218
	v_add_f32_e32 v117, v117, v229
	v_fmac_f32_e32 v226, v116, v116
	v_add_f32_e32 v225, v118, v230
	v_fmac_f32_e32 v226, v117, v117
	v_cvt_pk_bf16_f32 v122, v216, v124
	v_cvt_pk_bf16_f32 v123, v126, v127
	v_add_f32_e32 v127, v119, v231
	v_fmac_f32_e32 v226, v225, v225
	v_add_f32_e32 v219, v112, v232
	v_add_f32_e32 v224, v113, v233
	v_fmac_f32_e32 v226, v127, v127
	v_and_b32_e32 v113, 64, v215
	v_add_f32_e32 v216, v115, v235
	v_fmac_f32_e32 v226, v219, v219
	v_xor_b32_e32 v112, 16, v215
	v_add_u32_e32 v115, 64, v113
	v_add_f32_e32 v126, v114, v234
	v_fmac_f32_e32 v226, v224, v224
	v_cmp_lt_i32_e32 vcc, v112, v115
	v_fmac_f32_e32 v226, v126, v126
	v_cvt_pk_bf16_f32 v124, v120, v121
	v_fmac_f32_e32 v226, v216, v216
	v_cndmask_b32_e32 v112, v215, v112, vcc
	v_lshlrev_b32_e32 v120, 2, v112
	ds_bpermute_b32 v121, v120, v226
	v_lshl_add_u64 v[112:113], s[12:13], 0, v[220:221]
	v_lshl_add_u64 v[118:119], v[198:199], 1, v[112:113]
	v_xor_b32_e32 v113, 32, v215
	v_cmp_lt_i32_e32 vcc, v113, v115
	s_waitcnt lgkmcnt(0)
	v_add_f32_e32 v112, v226, v121
	v_cvt_pk_bf16_f32 v125, v217, v218
	global_store_dwordx4 v[118:119], v[122:125], off sc1
	v_cndmask_b32_e32 v113, v215, v113, vcc
	v_lshlrev_b32_e32 v121, 2, v113
	ds_bpermute_b32 v113, v121, v112
	v_cvt_pk_bf16_f32 v114, v116, v117
	v_cvt_pk_bf16_f32 v115, v225, v127
	v_cvt_pk_bf16_f32 v116, v219, v224
	v_cvt_pk_bf16_f32 v117, v126, v216
	global_store_dwordx4 v[118:119], v[114:117], off offset:256 sc1
	s_and_saveexec_b64 s[30:31], s[4:5]
	s_cbranch_execz .LBB0_792
	v_lshlrev_b64 v[114:115], 7, v[200:201]
	v_lshl_add_u64 v[114:115], s[16:17], 0, v[114:115]
	v_lshl_add_u64 v[114:115], s[28:29], 2, v[114:115]
	s_lshl_b32 s0, s44, 2
	v_lshl_add_u64 v[114:115], v[114:115], 0, s[0:1]
	s_waitcnt lgkmcnt(0)
	v_add_f32_e32 v112, v112, v113
	global_store_dword v[114:115], v112, off
; __device__ __forceinline__ unsigned cvt_pk_bf16(float lo, float hi) { unsigned r; asm volatile("v_cvt_pk_bf16_f32 %0, %1, %2" : "=v"(r) : "v"(lo), "v"(hi)); return r; }
; __device__ __forceinline__ void unpack8(const u32x4& w, float (&f)[8]) { f[0] = bflo(w.x); f[1] = bfhi(w.x); f[2] = bflo(w.y); f[3] = bfhi(w.y); f[4] = bflo(w.z); f[5] = bfhi(w.z); f[6] = bflo(w.w); f[7] = bfhi(w.w); }
;     __device__ __forceinline__ void operator()(const f32x4 (&acc)[2][2][4][2], const Unit& u, int wr, int wc, int fr, int fq) const {
;     ...
;             for (int m = 0; m < 4; ++m) { const int row = row0 + ai * HALF + m * 16; float s = 0.f;
; #pragma unroll
;                 for (int bj = 0; bj < 2; ++bj) { float o[8];
;                     if (MODE == 0) { const f32x4 b0 = bf[MODE == 0 ? m : 0][bj][0], b1 = bf[MODE == 0 ? m : 0][bj][1];
; #pragma unroll
;                         for (int e = 0; e < 4; ++e) { o[e] = b0[e] + acc[ai][bj][m][0][e]; o[4 + e] = b1[e] + acc[ai][bj][m][1][e]; } }
;                     else { float t[8]; unpack8(bb[MODE == 1 ? m : 0][bj], t);
; #pragma unroll
;                         for (int e = 0; e < 4; ++e) { o[e] = t[e] + acc[ai][bj][m][0][e]; o[4 + e] = t[4 + e] + acc[ai][bj][m][1][e]; } }
; #pragma unroll
;                     for (int e = 0; e < 8; ++e) s += o[e] * o[e];
;                     *(u32x4*)(ob + (size_t)row * DM + col0 + bj * HALF) = (u32x4){cvt_pk_bf16(o[0], o[1]), cvt_pk_bf16(o[2], o[3]), cvt_pk_bf16(o[4], o[5]), cvt_pk_bf16(o[6], o[7])}; }
;                 s += __shfl_xor(s, 16); s += __shfl_xor(s, 32);
;                 if (fq == 0) ss[(size_t)row * 32 + u.pn * 4 + wc] = s; } }
.LBB0_792:
	s_or_b64 exec, exec, s[30:31]
	v_add_f32_e32 v114, v104, v168
	v_add_f32_e32 v104, v109, v173
	v_add_f32_e32 v108, v108, v172
	v_add_f32_e32 v109, v105, v169
	v_add_f32_e32 v105, v110, v174
	v_add_f32_e32 v110, v106, v170
	v_add_f32_e32 v106, v111, v175
	v_mul_f32_e32 v111, v104, v104
	v_fmac_f32_e32 v111, v108, v108
	v_fmac_f32_e32 v111, v105, v105
	v_fmac_f32_e32 v111, v106, v106
	v_fmac_f32_e32 v111, v114, v114
	v_fmac_f32_e32 v111, v109, v109
	v_add_f32_e32 v107, v107, v171
	v_fmac_f32_e32 v111, v110, v110
	v_fmac_f32_e32 v111, v107, v107
	v_add_f32_e32 v100, v100, v164
	v_add_f32_e32 v101, v101, v165
	v_fmac_f32_e32 v111, v100, v100
	v_cvt_pk_bf16_f32 v104, v108, v104
	v_cvt_pk_bf16_f32 v105, v105, v106
	v_cvt_pk_bf16_f32 v106, v114, v109
	v_cvt_pk_bf16_f32 v107, v110, v107
	v_add_f32_e32 v110, v102, v166
	v_fmac_f32_e32 v111, v101, v101
	v_add_f32_e32 v115, v103, v167
	v_fmac_f32_e32 v111, v110, v110
	v_add_f32_e32 v108, v96, v160
	v_fmac_f32_e32 v111, v115, v115
	v_add_f32_e32 v109, v97, v161
	v_fmac_f32_e32 v111, v108, v108
	v_add_f32_e32 v114, v98, v162
	v_fmac_f32_e32 v111, v109, v109
	v_add_f32_e32 v116, v99, v163
	v_fmac_f32_e32 v111, v114, v114
	v_fmac_f32_e32 v111, v116, v116
	ds_bpermute_b32 v99, v120, v111
	s_waitcnt lgkmcnt(1)
	v_lshlrev_b64 v[112:113], 12, v[208:209]
	v_lshl_add_u64 v[96:97], s[12:13], 0, v[112:113]
	v_lshl_add_u64 v[102:103], v[198:199], 1, v[96:97]
	global_store_dwordx4 v[102:103], v[104:107], off sc1
	s_waitcnt lgkmcnt(0)
	v_add_f32_e32 v96, v111, v99
	ds_bpermute_b32 v97, v121, v96
	v_cvt_pk_bf16_f32 v98, v100, v101
	v_cvt_pk_bf16_f32 v99, v110, v115
	v_cvt_pk_bf16_f32 v100, v108, v109
	v_cvt_pk_bf16_f32 v101, v114, v116
	global_store_dwordx4 v[102:103], v[98:101], off offset:256 sc1
	s_and_saveexec_b64 s[30:31], s[4:5]
	s_cbranch_execz .LBB0_794
	v_lshlrev_b64 v[98:99], 7, v[208:209]
	v_lshl_add_u64 v[98:99], s[16:17], 0, v[98:99]
	v_lshl_add_u64 v[98:99], s[28:29], 2, v[98:99]
	s_lshl_b32 s0, s44, 2
	v_lshl_add_u64 v[98:99], v[98:99], 0, s[0:1]
	s_waitcnt lgkmcnt(0)
	v_add_f32_e32 v96, v96, v97
	global_store_dword v[98:99], v96, off
.LBB0_794:
	s_or_b64 exec, exec, s[30:31]
	v_add_f32_e32 v98, v88, v152
	v_add_f32_e32 v88, v93, v157
	v_add_f32_e32 v92, v92, v156
	v_add_f32_e32 v93, v89, v153
	v_add_f32_e32 v89, v94, v158
	v_add_f32_e32 v94, v90, v154
	v_add_f32_e32 v90, v95, v159
	v_mul_f32_e32 v95, v88, v88
	v_fmac_f32_e32 v95, v92, v92
	v_fmac_f32_e32 v95, v89, v89
	v_fmac_f32_e32 v95, v90, v90
	v_fmac_f32_e32 v95, v98, v98
	v_fmac_f32_e32 v95, v93, v93
	v_add_f32_e32 v91, v91, v155
	v_fmac_f32_e32 v95, v94, v94
	v_fmac_f32_e32 v95, v91, v91
	v_add_f32_e32 v84, v84, v148
	v_add_f32_e32 v85, v85, v149
	v_fmac_f32_e32 v95, v84, v84
	v_cvt_pk_bf16_f32 v88, v92, v88
	v_cvt_pk_bf16_f32 v89, v89, v90
	v_cvt_pk_bf16_f32 v90, v98, v93
	v_cvt_pk_bf16_f32 v91, v94, v91
	v_add_f32_e32 v94, v86, v150
	v_fmac_f32_e32 v95, v85, v85
	v_add_f32_e32 v99, v87, v151
	v_fmac_f32_e32 v95, v94, v94
	v_add_f32_e32 v92, v80, v144
	v_fmac_f32_e32 v95, v99, v99
	v_add_f32_e32 v93, v81, v145
	v_fmac_f32_e32 v95, v92, v92
	v_add_f32_e32 v98, v82, v146
	v_fmac_f32_e32 v95, v93, v93
	v_add_f32_e32 v100, v83, v147
	v_fmac_f32_e32 v95, v98, v98
	v_fmac_f32_e32 v95, v100, v100
	ds_bpermute_b32 v83, v120, v95
	s_waitcnt lgkmcnt(1)
	v_lshlrev_b64 v[96:97], 12, v[206:207]
	v_lshl_add_u64 v[80:81], s[12:13], 0, v[96:97]
	v_lshl_add_u64 v[86:87], v[198:199], 1, v[80:81]
	global_store_dwordx4 v[86:87], v[88:91], off sc1
	s_waitcnt lgkmcnt(0)
	v_add_f32_e32 v80, v95, v83
	ds_bpermute_b32 v81, v121, v80
	v_cvt_pk_bf16_f32 v82, v84, v85
	v_cvt_pk_bf16_f32 v83, v94, v99
	v_cvt_pk_bf16_f32 v84, v92, v93
	v_cvt_pk_bf16_f32 v85, v98, v100
	global_store_dwordx4 v[86:87], v[82:85], off offset:256 sc1
	s_and_saveexec_b64 s[30:31], s[4:5]
	s_cbranch_execz .LBB0_796
	v_lshlrev_b64 v[82:83], 7, v[206:207]
	v_lshl_add_u64 v[82:83], s[16:17], 0, v[82:83]
	v_lshl_add_u64 v[82:83], s[28:29], 2, v[82:83]
	s_lshl_b32 s0, s44, 2
	v_lshl_add_u64 v[82:83], v[82:83], 0, s[0:1]
	s_waitcnt lgkmcnt(0)
	v_add_f32_e32 v80, v80, v81
	global_store_dword v[82:83], v80, off
.LBB0_796:
	s_or_b64 exec, exec, s[30:31]
	v_add_f32_e32 v82, v72, v136
	v_add_f32_e32 v72, v77, v141
	v_add_f32_e32 v76, v76, v140
	v_add_f32_e32 v77, v73, v137
	v_add_f32_e32 v73, v78, v142
	v_add_f32_e32 v78, v74, v138
	v_add_f32_e32 v74, v79, v143
	v_mul_f32_e32 v79, v72, v72
	v_fmac_f32_e32 v79, v76, v76
	v_fmac_f32_e32 v79, v73, v73
	v_fmac_f32_e32 v79, v74, v74
	v_fmac_f32_e32 v79, v82, v82
	v_fmac_f32_e32 v79, v77, v77
	v_add_f32_e32 v75, v75, v139
	v_fmac_f32_e32 v79, v78, v78
	v_fmac_f32_e32 v79, v75, v75
	v_add_f32_e32 v68, v68, v132
	v_add_f32_e32 v69, v69, v133
	v_fmac_f32_e32 v79, v68, v68
	v_cvt_pk_bf16_f32 v72, v76, v72
	v_cvt_pk_bf16_f32 v73, v73, v74
	v_cvt_pk_bf16_f32 v74, v82, v77
	v_cvt_pk_bf16_f32 v75, v78, v75
	v_add_f32_e32 v78, v70, v134
	v_fmac_f32_e32 v79, v69, v69
	v_add_f32_e32 v83, v71, v135
	v_fmac_f32_e32 v79, v78, v78
	v_add_f32_e32 v76, v64, v128
	v_fmac_f32_e32 v79, v83, v83
	v_add_f32_e32 v77, v65, v129
	v_fmac_f32_e32 v79, v76, v76
	v_add_f32_e32 v82, v66, v130
	v_fmac_f32_e32 v79, v77, v77
	v_add_f32_e32 v84, v67, v131
	v_fmac_f32_e32 v79, v82, v82
	v_fmac_f32_e32 v79, v84, v84
	ds_bpermute_b32 v67, v120, v79
	s_waitcnt lgkmcnt(1)
	v_lshlrev_b64 v[80:81], 12, v[204:205]
	v_lshl_add_u64 v[64:65], s[12:13], 0, v[80:81]
	v_lshl_add_u64 v[70:71], v[198:199], 1, v[64:65]
	global_store_dwordx4 v[70:71], v[72:75], off sc1
	s_waitcnt lgkmcnt(0)
	v_add_f32_e32 v64, v79, v67
	ds_bpermute_b32 v65, v121, v64
	v_cvt_pk_bf16_f32 v66, v68, v69
	v_cvt_pk_bf16_f32 v67, v78, v83
	v_cvt_pk_bf16_f32 v68, v76, v77
	v_cvt_pk_bf16_f32 v69, v82, v84
	global_store_dwordx4 v[70:71], v[66:69], off offset:256 sc1
	s_and_saveexec_b64 s[30:31], s[4:5]
	s_cbranch_execz .LBB0_798
	v_lshlrev_b64 v[66:67], 7, v[204:205]
	v_lshl_add_u64 v[66:67], s[16:17], 0, v[66:67]
	v_lshl_add_u64 v[66:67], s[28:29], 2, v[66:67]
	s_lshl_b32 s0, s44, 2
	v_lshl_add_u64 v[66:67], v[66:67], 0, s[0:1]
	s_waitcnt lgkmcnt(0)
	v_add_f32_e32 v64, v64, v65
	global_store_dword v[66:67], v64, off
; __device__ __forceinline__ unsigned cvt_pk_bf16(float lo, float hi) { unsigned r; asm volatile("v_cvt_pk_bf16_f32 %0, %1, %2" : "=v"(r) : "v"(lo), "v"(hi)); return r; }
;     __device__ __forceinline__ void operator()(const f32x4 (&acc)[2][2][4][2], const Unit& u, int wr, int wc, int fr, int fq) const {
;     ...
;         for (int ai = 0; ai < 2; ++ai) {
;             f32x4 bf[MODE == 0 ? 4 : 1][2][2]; u32x4 bb[MODE == 1 ? 4 : 1][2];
; #pragma unroll
;             for (int m = 0; m < 4; ++m) { const int row = row0 + ai * HALF + m * 16;
;                 if (MODE == 0) { const float* br = row < MP ? basep + (size_t)row * DM : bases + (size_t)(row - MP) * DM;
; #pragma unroll
;                     for (int bj = 0; bj < 2; ++bj) { bf[MODE == 0 ? m : 0][bj][0] = *(const f32x4*)(br + col0 + bj * HALF); bf[MODE == 0 ? m : 0][bj][1] = *(const f32x4*)(br + col0 + bj * HALF + 4); } }
;                 else {
; #pragma unroll
;                     for (int bj = 0; bj < 2; ++bj) bb[MODE == 1 ? m : 0][bj] = *(const u32x4*)(baseb + (size_t)row * DM + col0 + bj * HALF); } }
; #pragma unroll
;             for (int m = 0; m < 4; ++m) { const int row = row0 + ai * HALF + m * 16; float s = 0.f;
; #pragma unroll
;                 for (int bj = 0; bj < 2; ++bj) { float o[8];
;                     if (MODE == 0) { const f32x4 b0 = bf[MODE == 0 ? m : 0][bj][0], b1 = bf[MODE == 0 ? m : 0][bj][1];
; #pragma unroll
;                         for (int e = 0; e < 4; ++e) { o[e] = b0[e] + acc[ai][bj][m][0][e]; o[4 + e] = b1[e] + acc[ai][bj][m][1][e]; } }
;                     else { float t[8]; unpack8(bb[MODE == 1 ? m : 0][bj], t);
; #pragma unroll
;                         for (int e = 0; e < 4; ++e) { o[e] = t[e] + acc[ai][bj][m][0][e]; o[4 + e] = t[4 + e] + acc[ai][bj][m][1][e]; } }
; #pragma unroll
;                     for (int e = 0; e < 8; ++e) s += o[e] * o[e];
;                     *(u32x4*)(ob + (size_t)row * DM + col0 + bj * HALF) = (u32x4){cvt_pk_bf16(o[0], o[1]), cvt_pk_bf16(o[2], o[3]), cvt_pk_bf16(o[4], o[5]), cvt_pk_bf16(o[6], o[7])}; }
;                 s += __shfl_xor(s, 16); s += __shfl_xor(s, 32);
;                 if (fq == 0) ss[(size_t)row * 32 + u.pn * 4 + wc] = s; } }
.LBB0_798:
	s_or_b64 exec, exec, s[30:31]
	v_add_u32_e32 v118, 0x80, v200
	v_ashrrev_i32_e32 v119, 31, v118
	v_add_u32_e32 v64, 0xffffc080, v200
	v_cmp_gt_i32_e32 vcc, s52, v200
	v_mov_b32_e32 v68, s67
	v_mov_b32_e32 v69, s65
	s_waitcnt lgkmcnt(0)
	v_cndmask_b32_e32 v65, 0, v119, vcc
	v_cndmask_b32_e32 v64, v64, v118, vcc
	v_mov_b32_e32 v70, s66
	v_mov_b32_e32 v71, s64
	v_cndmask_b32_e32 v67, v68, v69, vcc
	v_cndmask_b32_e32 v66, v70, v71, vcc
	v_lshlrev_b64 v[64:65], 13, v[64:65]
	v_lshl_add_u64 v[64:65], v[66:67], 0, v[64:65]
	v_lshl_add_u64 v[64:65], v[64:65], 0, v[202:203]
	global_load_dwordx4 v[122:125], v[64:65], off offset:16 nt
	global_load_dwordx4 v[126:129], v[64:65], off nt
	global_load_dwordx4 v[130:133], v[64:65], off offset:528 nt
	global_load_dwordx4 v[134:137], v[64:65], off offset:512 nt
	v_add_u32_e32 v116, 0x90, v200
	v_ashrrev_i32_e32 v117, 31, v116
	v_add_u32_e32 v64, 0xffffc090, v200
	v_cmp_gt_i32_e32 vcc, s53, v200
	v_add_u32_e32 v114, 0xa0, v200
	v_ashrrev_i32_e32 v115, 31, v114
	v_cndmask_b32_e32 v65, 0, v117, vcc
	v_cndmask_b32_e32 v64, v64, v116, vcc
	v_cndmask_b32_e32 v67, v68, v69, vcc
	v_cndmask_b32_e32 v66, v70, v71, vcc
	v_lshlrev_b64 v[64:65], 13, v[64:65]
	v_lshl_add_u64 v[64:65], v[66:67], 0, v[64:65]
	v_lshl_add_u64 v[64:65], v[64:65], 0, v[202:203]
	global_load_dwordx4 v[104:107], v[64:65], off offset:16 nt
	global_load_dwordx4 v[108:111], v[64:65], off nt
	global_load_dwordx4 v[96:99], v[64:65], off offset:528 nt
	global_load_dwordx4 v[100:103], v[64:65], off offset:512 nt
	v_add_u32_e32 v64, 0xffffc0a0, v200
	v_cmp_gt_i32_e32 vcc, s54, v200
	v_add_u32_e32 v112, 0xb0, v200
	v_ashrrev_i32_e32 v113, 31, v112
	v_cndmask_b32_e32 v65, 0, v115, vcc
	v_cndmask_b32_e32 v64, v64, v114, vcc
	v_cndmask_b32_e32 v67, v68, v69, vcc
	v_cndmask_b32_e32 v66, v70, v71, vcc
	v_lshlrev_b64 v[64:65], 13, v[64:65]
	v_lshl_add_u64 v[64:65], v[66:67], 0, v[64:65]
	v_lshl_add_u64 v[64:65], v[64:65], 0, v[202:203]
	global_load_dwordx4 v[88:91], v[64:65], off offset:16 nt
	global_load_dwordx4 v[92:95], v[64:65], off nt
	global_load_dwordx4 v[80:83], v[64:65], off offset:528 nt
	global_load_dwordx4 v[84:87], v[64:65], off offset:512 nt
	v_add_u32_e32 v64, 0xffffc0b0, v200
	v_cmp_gt_i32_e32 vcc, s55, v200
	v_lshlrev_b64 v[138:139], 12, v[118:119]
	s_waitcnt vmcnt(11)
	v_add_f32_e32 v56, v56, v122
	v_cndmask_b32_e32 v65, 0, v113, vcc
	v_cndmask_b32_e32 v64, v64, v112, vcc
	v_cndmask_b32_e32 v67, v68, v69, vcc
	v_cndmask_b32_e32 v66, v70, v71, vcc
	v_lshlrev_b64 v[64:65], 13, v[64:65]
	v_lshl_add_u64 v[64:65], v[66:67], 0, v[64:65]
	v_lshl_add_u64 v[68:69], v[64:65], 0, v[202:203]
	global_load_dwordx4 v[72:75], v[68:69], off offset:16 nt
	global_load_dwordx4 v[76:79], v[68:69], off nt
	global_load_dwordx4 v[64:67], v[68:69], off offset:528 nt
	s_nop 0
	global_load_dwordx4 v[68:71], v[68:69], off offset:512 nt
	s_waitcnt vmcnt(14)
	v_add_f32_e32 v61, v61, v127
	v_add_f32_e32 v60, v60, v126
	v_add_f32_e32 v63, v63, v129
	v_mul_f32_e32 v129, v61, v61
	v_add_f32_e32 v62, v62, v128
	v_fmac_f32_e32 v129, v60, v60
	v_fmac_f32_e32 v129, v62, v62
	v_fmac_f32_e32 v129, v63, v63
	v_add_f32_e32 v57, v57, v123
	v_fmac_f32_e32 v129, v56, v56
	v_add_f32_e32 v58, v58, v124
	v_fmac_f32_e32 v129, v57, v57
	v_add_f32_e32 v59, v59, v125
	v_fmac_f32_e32 v129, v58, v58
	s_waitcnt vmcnt(12)
	v_add_f32_e32 v122, v52, v134
	v_fmac_f32_e32 v129, v59, v59
	v_add_f32_e32 v124, v53, v135
	v_fmac_f32_e32 v129, v122, v122
	v_add_f32_e32 v126, v54, v136
	v_fmac_f32_e32 v129, v124, v124
	v_add_f32_e32 v128, v55, v137
	v_fmac_f32_e32 v129, v126, v126
	v_add_f32_e32 v123, v48, v130
	v_fmac_f32_e32 v129, v128, v128
	v_add_f32_e32 v125, v49, v131
	v_fmac_f32_e32 v129, v123, v123
	v_add_f32_e32 v127, v50, v132
	v_fmac_f32_e32 v129, v125, v125
	v_cvt_pk_bf16_f32 v52, v60, v61
	v_cvt_pk_bf16_f32 v53, v62, v63
	v_cvt_pk_bf16_f32 v54, v56, v57
	v_cvt_pk_bf16_f32 v55, v58, v59
	v_add_f32_e32 v58, v51, v133
	v_fmac_f32_e32 v129, v127, v127
	v_fmac_f32_e32 v129, v58, v58
	ds_bpermute_b32 v51, v120, v129
	v_lshl_add_u64 v[48:49], s[12:13], 0, v[138:139]
	v_lshl_add_u64 v[56:57], v[198:199], 1, v[48:49]
	global_store_dwordx4 v[56:57], v[52:55], off sc1
	v_cvt_pk_bf16_f32 v50, v122, v124
	s_waitcnt lgkmcnt(0)
	v_add_f32_e32 v48, v129, v51
	ds_bpermute_b32 v49, v121, v48
	v_cvt_pk_bf16_f32 v51, v126, v128
	v_cvt_pk_bf16_f32 v52, v123, v125
	v_cvt_pk_bf16_f32 v53, v127, v58
	global_store_dwordx4 v[56:57], v[50:53], off offset:256 sc1
	s_and_saveexec_b64 s[30:31], s[4:5]
	s_cbranch_execz .LBB0_800
	v_lshlrev_b64 v[50:51], 7, v[118:119]
	v_lshl_add_u64 v[50:51], s[16:17], 0, v[50:51]
	v_lshl_add_u64 v[50:51], s[28:29], 2, v[50:51]
	s_lshl_b32 s0, s44, 2
	v_lshl_add_u64 v[50:51], v[50:51], 0, s[0:1]
	s_waitcnt lgkmcnt(0)
	v_add_f32_e32 v48, v48, v49
	global_store_dword v[50:51], v48, off
; __device__ __forceinline__ unsigned cvt_pk_bf16(float lo, float hi) { unsigned r; asm volatile("v_cvt_pk_bf16_f32 %0, %1, %2" : "=v"(r) : "v"(lo), "v"(hi)); return r; }
; __device__ __forceinline__ void unpack8(const u32x4& w, float (&f)[8]) { f[0] = bflo(w.x); f[1] = bfhi(w.x); f[2] = bflo(w.y); f[3] = bfhi(w.y); f[4] = bflo(w.z); f[5] = bfhi(w.z); f[6] = bflo(w.w); f[7] = bfhi(w.w); }
;     __device__ __forceinline__ void operator()(const f32x4 (&acc)[2][2][4][2], const Unit& u, int wr, int wc, int fr, int fq) const {
;     ...
;             for (int m = 0; m < 4; ++m) { const int row = row0 + ai * HALF + m * 16; float s = 0.f;
; #pragma unroll
;                 for (int bj = 0; bj < 2; ++bj) { float o[8];
;                     if (MODE == 0) { const f32x4 b0 = bf[MODE == 0 ? m : 0][bj][0], b1 = bf[MODE == 0 ? m : 0][bj][1];
; #pragma unroll
;                         for (int e = 0; e < 4; ++e) { o[e] = b0[e] + acc[ai][bj][m][0][e]; o[4 + e] = b1[e] + acc[ai][bj][m][1][e]; } }
;                     else { float t[8]; unpack8(bb[MODE == 1 ? m : 0][bj], t);
; #pragma unroll
;                         for (int e = 0; e < 4; ++e) { o[e] = t[e] + acc[ai][bj][m][0][e]; o[4 + e] = t[4 + e] + acc[ai][bj][m][1][e]; } }
; #pragma unroll
;                     for (int e = 0; e < 8; ++e) s += o[e] * o[e];
;                     *(u32x4*)(ob + (size_t)row * DM + col0 + bj * HALF) = (u32x4){cvt_pk_bf16(o[0], o[1]), cvt_pk_bf16(o[2], o[3]), cvt_pk_bf16(o[4], o[5]), cvt_pk_bf16(o[6], o[7])}; }
;                 s += __shfl_xor(s, 16); s += __shfl_xor(s, 32);
;                 if (fq == 0) ss[(size_t)row * 32 + u.pn * 4 + wc] = s; } }
.LBB0_800:
	s_or_b64 exec, exec, s[30:31]
	s_waitcnt vmcnt(13)
	v_add_f32_e32 v50, v40, v104
	s_waitcnt vmcnt(12)
	v_add_f32_e32 v40, v45, v109
	v_add_f32_e32 v44, v44, v108
	v_add_f32_e32 v45, v41, v105
	v_add_f32_e32 v41, v46, v110
	v_add_f32_e32 v46, v42, v106
	v_add_f32_e32 v42, v47, v111
	v_mul_f32_e32 v47, v40, v40
	v_fmac_f32_e32 v47, v44, v44
	v_fmac_f32_e32 v47, v41, v41
	v_fmac_f32_e32 v47, v42, v42
	v_fmac_f32_e32 v47, v50, v50
	v_fmac_f32_e32 v47, v45, v45
	v_add_f32_e32 v43, v43, v107
	v_fmac_f32_e32 v47, v46, v46
	v_fmac_f32_e32 v47, v43, v43
	s_waitcnt vmcnt(10)
	v_add_f32_e32 v36, v36, v100
	v_add_f32_e32 v37, v37, v101
	v_fmac_f32_e32 v47, v36, v36
	v_cvt_pk_bf16_f32 v40, v44, v40
	v_cvt_pk_bf16_f32 v41, v41, v42
	v_cvt_pk_bf16_f32 v42, v50, v45
	v_cvt_pk_bf16_f32 v43, v46, v43
	v_add_f32_e32 v46, v38, v102
	v_fmac_f32_e32 v47, v37, v37
	v_add_f32_e32 v51, v39, v103
	v_fmac_f32_e32 v47, v46, v46
	v_add_f32_e32 v44, v32, v96
	v_fmac_f32_e32 v47, v51, v51
	v_add_f32_e32 v45, v33, v97
	v_fmac_f32_e32 v47, v44, v44
	v_add_f32_e32 v50, v34, v98
	v_fmac_f32_e32 v47, v45, v45
	v_add_f32_e32 v52, v35, v99
	v_fmac_f32_e32 v47, v50, v50
	v_fmac_f32_e32 v47, v52, v52
	ds_bpermute_b32 v35, v120, v47
	s_waitcnt lgkmcnt(1)
	v_lshlrev_b64 v[48:49], 12, v[116:117]
	v_lshl_add_u64 v[32:33], s[12:13], 0, v[48:49]
	v_lshl_add_u64 v[38:39], v[198:199], 1, v[32:33]
	global_store_dwordx4 v[38:39], v[40:43], off sc1
	s_waitcnt lgkmcnt(0)
	v_add_f32_e32 v32, v47, v35
	ds_bpermute_b32 v33, v121, v32
	v_cvt_pk_bf16_f32 v34, v36, v37
	v_cvt_pk_bf16_f32 v35, v46, v51
	v_cvt_pk_bf16_f32 v36, v44, v45
	v_cvt_pk_bf16_f32 v37, v50, v52
	global_store_dwordx4 v[38:39], v[34:37], off offset:256 sc1
	s_and_saveexec_b64 s[30:31], s[4:5]
	s_cbranch_execz .LBB0_802
	v_lshlrev_b64 v[34:35], 7, v[116:117]
	v_lshl_add_u64 v[34:35], s[16:17], 0, v[34:35]
	v_lshl_add_u64 v[34:35], s[28:29], 2, v[34:35]
	s_lshl_b32 s0, s44, 2
	v_lshl_add_u64 v[34:35], v[34:35], 0, s[0:1]
	s_waitcnt lgkmcnt(0)
	v_add_f32_e32 v32, v32, v33
	global_store_dword v[34:35], v32, off
.LBB0_802:
	s_or_b64 exec, exec, s[30:31]
	s_waitcnt vmcnt(11)
	v_add_f32_e32 v34, v24, v88
	s_waitcnt vmcnt(10)
	v_add_f32_e32 v24, v29, v93
	v_add_f32_e32 v28, v28, v92
	v_add_f32_e32 v29, v25, v89
	v_add_f32_e32 v25, v30, v94
	v_add_f32_e32 v30, v26, v90
	v_add_f32_e32 v26, v31, v95
	v_mul_f32_e32 v31, v24, v24
	v_fmac_f32_e32 v31, v28, v28
	v_fmac_f32_e32 v31, v25, v25
	v_fmac_f32_e32 v31, v26, v26
	v_fmac_f32_e32 v31, v34, v34
	v_fmac_f32_e32 v31, v29, v29
	v_add_f32_e32 v27, v27, v91
	v_fmac_f32_e32 v31, v30, v30
	v_fmac_f32_e32 v31, v27, v27
	s_waitcnt vmcnt(8)
	v_add_f32_e32 v20, v20, v84
	v_add_f32_e32 v21, v21, v85
	v_fmac_f32_e32 v31, v20, v20
	v_cvt_pk_bf16_f32 v24, v28, v24
	v_cvt_pk_bf16_f32 v25, v25, v26
	v_cvt_pk_bf16_f32 v26, v34, v29
	v_cvt_pk_bf16_f32 v27, v30, v27
	v_add_f32_e32 v30, v22, v86
	v_fmac_f32_e32 v31, v21, v21
	v_add_f32_e32 v35, v23, v87
	v_fmac_f32_e32 v31, v30, v30
	v_add_f32_e32 v28, v16, v80
	v_fmac_f32_e32 v31, v35, v35
	v_add_f32_e32 v29, v17, v81
	v_fmac_f32_e32 v31, v28, v28
	v_add_f32_e32 v34, v18, v82
	v_fmac_f32_e32 v31, v29, v29
	v_add_f32_e32 v36, v19, v83
	v_fmac_f32_e32 v31, v34, v34
	v_fmac_f32_e32 v31, v36, v36
	ds_bpermute_b32 v19, v120, v31
	s_waitcnt lgkmcnt(1)
	v_lshlrev_b64 v[32:33], 12, v[114:115]
	v_lshl_add_u64 v[16:17], s[12:13], 0, v[32:33]
	v_lshl_add_u64 v[22:23], v[198:199], 1, v[16:17]
	global_store_dwordx4 v[22:23], v[24:27], off sc1
	s_waitcnt lgkmcnt(0)
	v_add_f32_e32 v16, v31, v19
	ds_bpermute_b32 v17, v121, v16
	v_cvt_pk_bf16_f32 v18, v20, v21
	v_cvt_pk_bf16_f32 v19, v30, v35
	v_cvt_pk_bf16_f32 v20, v28, v29
	v_cvt_pk_bf16_f32 v21, v34, v36
	global_store_dwordx4 v[22:23], v[18:21], off offset:256 sc1
	s_and_saveexec_b64 s[30:31], s[4:5]
	s_cbranch_execz .LBB0_804
	v_lshlrev_b64 v[18:19], 7, v[114:115]
	v_lshl_add_u64 v[18:19], s[16:17], 0, v[18:19]
	v_lshl_add_u64 v[18:19], s[28:29], 2, v[18:19]
	s_lshl_b32 s0, s44, 2
	v_lshl_add_u64 v[18:19], v[18:19], 0, s[0:1]
	s_waitcnt lgkmcnt(0)
	v_add_f32_e32 v16, v16, v17
	global_store_dword v[18:19], v16, off
.LBB0_804:
	s_or_b64 exec, exec, s[30:31]
	s_waitcnt vmcnt(9)
	v_add_f32_e32 v18, v8, v72
	s_waitcnt vmcnt(8)
	v_add_f32_e32 v8, v13, v77
	v_add_f32_e32 v12, v12, v76
	v_add_f32_e32 v13, v9, v73
	v_add_f32_e32 v9, v14, v78
	v_add_f32_e32 v14, v10, v74
	v_add_f32_e32 v10, v15, v79
	v_mul_f32_e32 v15, v8, v8
	v_fmac_f32_e32 v15, v12, v12
	v_fmac_f32_e32 v15, v9, v9
	v_fmac_f32_e32 v15, v10, v10
	v_fmac_f32_e32 v15, v18, v18
	v_fmac_f32_e32 v15, v13, v13
	v_add_f32_e32 v11, v11, v75
	v_fmac_f32_e32 v15, v14, v14
	v_fmac_f32_e32 v15, v11, v11
	s_waitcnt vmcnt(6)
	v_add_f32_e32 v4, v4, v68
	v_add_f32_e32 v5, v5, v69
	v_fmac_f32_e32 v15, v4, v4
	v_cvt_pk_bf16_f32 v8, v12, v8
	v_cvt_pk_bf16_f32 v9, v9, v10
	v_cvt_pk_bf16_f32 v10, v18, v13
	v_cvt_pk_bf16_f32 v11, v14, v11
	v_add_f32_e32 v14, v6, v70
	v_fmac_f32_e32 v15, v5, v5
	v_add_f32_e32 v19, v7, v71
	v_fmac_f32_e32 v15, v14, v14
	v_add_f32_e32 v12, v0, v64
	v_fmac_f32_e32 v15, v19, v19
	v_add_f32_e32 v13, v1, v65
	v_fmac_f32_e32 v15, v12, v12
	v_add_f32_e32 v18, v2, v66
	v_fmac_f32_e32 v15, v13, v13
	v_add_f32_e32 v20, v3, v67
	v_fmac_f32_e32 v15, v18, v18
	v_fmac_f32_e32 v15, v20, v20
	ds_bpermute_b32 v3, v120, v15
	s_waitcnt lgkmcnt(1)
	v_lshlrev_b64 v[16:17], 12, v[112:113]
	v_lshl_add_u64 v[0:1], s[12:13], 0, v[16:17]
	v_lshl_add_u64 v[6:7], v[198:199], 1, v[0:1]
	global_store_dwordx4 v[6:7], v[8:11], off sc1
	s_waitcnt lgkmcnt(0)
	v_add_f32_e32 v0, v15, v3
	ds_bpermute_b32 v1, v121, v0
	v_cvt_pk_bf16_f32 v2, v4, v5
	v_cvt_pk_bf16_f32 v3, v14, v19
	v_cvt_pk_bf16_f32 v4, v12, v13
	v_cvt_pk_bf16_f32 v5, v18, v20
	global_store_dwordx4 v[6:7], v[2:5], off offset:256 sc1
	s_and_saveexec_b64 s[30:31], s[4:5]
	s_cbranch_execz .LBB0_806
	v_lshlrev_b64 v[2:3], 7, v[112:113]
	v_lshl_add_u64 v[2:3], s[16:17], 0, v[2:3]
	v_lshl_add_u64 v[2:3], s[28:29], 2, v[2:3]
	s_lshl_b32 s0, s44, 2
	v_lshl_add_u64 v[2:3], v[2:3], 0, s[0:1]
	s_waitcnt lgkmcnt(0)
	v_add_f32_e32 v0, v0, v1
	global_store_dword v[2:3], v0, off

; __device__ __forceinline__ unsigned cvt_pk_bf16(float lo, float hi) { unsigned r; asm volatile("v_cvt_pk_bf16_f32 %0, %1, %2" : "=v"(r) : "v"(lo), "v"(hi)); return r; }
;     __device__ __forceinline__ void operator()(const f32x4 (&acc)[2][2][4][2], const Unit& u, int wr, int wc, int fr, int fq) const {
;         const int row0 = u.pm * BM + wr * 64 + fr, col0 = u.pn * BM + wc * 32 + 8 * fq;
; #pragma unroll
;         for (int ai = 0; ai < 2; ++ai)
; #pragma unroll
;             for (int m = 0; m < 4; ++m) { const int row = row0 + ai * HALF + m * 16; const float rs = ACT == 1 ? ss[row] : 1.0f;
;                 bf16_t* rowp = O + (size_t)row * ldc + col0;
; #pragma unroll
;                 for (int bj = 0; bj < 2; ++bj) { f32x4 v0 = acc[ai][bj][m][0] * rs, v1 = acc[ai][bj][m][1] * rs;
;                     if (ACT == 1) {
; #pragma unroll
;                         for (int e = 0; e < 4; ++e) { const float a0 = fmaxf(v0[e], 0.f), a1 = fmaxf(v1[e], 0.f); v0[e] = a0 * a0; v1[e] = a1 * a1; } }
;                     u32x4 w; w.x = cvt_pk_bf16(v0[0], v0[1]); w.y = cvt_pk_bf16(v0[2], v0[3]); w.z = cvt_pk_bf16(v1[0], v1[1]); w.w = cvt_pk_bf16(v1[2], v1[3]);
;                     *(u32x4*)(rowp + bj * HALF) = w; } }
.LBB0_936:
	v_lshl_add_u32 v148, s0, 8, v152
	v_ashrrev_i32_e32 v149, 31, v148
	v_lshl_add_u64 v[146:147], v[148:149], 2, s[86:87]
	global_load_dword v158, v[146:147], off
	v_lshl_or_b32 v144, s1, 8, v154
	v_ashrrev_i32_e32 v145, 31, v144
	v_lshlrev_b64 v[160:161], 14, v[148:149]
	v_lshlrev_b64 v[150:151], 1, v[144:145]
	v_lshl_add_u64 v[144:145], s[74:75], 0, v[160:161]
	v_lshl_add_u64 v[144:145], v[144:145], 0, v[150:151]
	s_waitcnt vmcnt(0)
	v_pk_mul_f32 v[126:127], v[126:127], v[158:159] op_sel_hi:[1,0]
	v_pk_mul_f32 v[124:125], v[124:125], v[158:159] op_sel_hi:[1,0]
	v_pk_mul_f32 v[122:123], v[122:123], v[158:159] op_sel_hi:[1,0]
	v_pk_mul_f32 v[120:121], v[120:121], v[158:159] op_sel_hi:[1,0]
	v_pk_mul_f32 v[114:115], v[114:115], v[158:159] op_sel_hi:[1,0]
	v_pk_mul_f32 v[112:113], v[112:113], v[158:159] op_sel_hi:[1,0]
	v_pk_mul_f32 v[118:119], v[118:119], v[158:159] op_sel_hi:[1,0]
	v_pk_mul_f32 v[116:117], v[116:117], v[158:159] op_sel_hi:[1,0]
	v_max_f32_e32 v124, 0, v124
	v_max_f32_e32 v120, 0, v120
	v_max_f32_e32 v125, 0, v125
	v_max_f32_e32 v121, 0, v121
	v_max_f32_e32 v126, 0, v126
	v_max_f32_e32 v122, 0, v122
	v_max_f32_e32 v127, 0, v127
	v_max_f32_e32 v123, 0, v123
	v_max_f32_e32 v112, 0, v112
	v_max_f32_e32 v113, 0, v113
	v_max_f32_e32 v114, 0, v114
	v_max_f32_e32 v115, 0, v115
	v_max_f32_e32 v116, 0, v116
	v_max_f32_e32 v117, 0, v117
	v_max_f32_e32 v118, 0, v118
	v_max_f32_e32 v119, 0, v119
	v_mul_f32_e32 v124, v124, v124
	v_mul_f32_e32 v120, v120, v120
	v_mul_f32_e32 v125, v125, v125
	v_mul_f32_e32 v121, v121, v121
	v_mul_f32_e32 v126, v126, v126
	v_mul_f32_e32 v122, v122, v122
	v_mul_f32_e32 v127, v127, v127
	v_mul_f32_e32 v123, v123, v123
	v_mul_f32_e32 v149, v112, v112
	v_mul_f32_e32 v158, v113, v113
	v_mul_f32_e32 v159, v114, v114
	v_mul_f32_e32 v160, v115, v115
	v_cvt_pk_bf16_f32 v112, v124, v125
	v_cvt_pk_bf16_f32 v113, v126, v127
	v_cvt_pk_bf16_f32 v114, v120, v121
	v_cvt_pk_bf16_f32 v115, v122, v123
	v_mul_f32_e32 v116, v116, v116
	v_mul_f32_e32 v117, v117, v117
	v_mul_f32_e32 v118, v118, v118
	v_mul_f32_e32 v119, v119, v119
	global_store_dwordx4 v[144:145], v[112:115], off sc1
	s_nop 1
	v_cvt_pk_bf16_f32 v112, v116, v117
	v_cvt_pk_bf16_f32 v113, v118, v119
	v_cvt_pk_bf16_f32 v114, v149, v158
	v_cvt_pk_bf16_f32 v115, v159, v160
	global_store_dwordx4 v[144:145], v[112:115], off offset:256 sc1
	global_load_dword v112, v[146:147], off offset:64
	s_waitcnt vmcnt(0)
	v_pk_mul_f32 v[110:111], v[110:111], v[112:113] op_sel_hi:[1,0]
	v_or_b32_e32 v114, 16, v148
	v_ashrrev_i32_e32 v115, 31, v114
	v_lshlrev_b64 v[114:115], 14, v[114:115]
	v_pk_mul_f32 v[108:109], v[108:109], v[112:113] op_sel_hi:[1,0]
	v_pk_mul_f32 v[106:107], v[106:107], v[112:113] op_sel_hi:[1,0]
	v_pk_mul_f32 v[104:105], v[104:105], v[112:113] op_sel_hi:[1,0]
	v_pk_mul_f32 v[98:99], v[98:99], v[112:113] op_sel_hi:[1,0]
	v_pk_mul_f32 v[96:97], v[96:97], v[112:113] op_sel_hi:[1,0]
	v_lshl_add_u64 v[114:115], s[74:75], 0, v[114:115]
	v_pk_mul_f32 v[102:103], v[102:103], v[112:113] op_sel_hi:[1,0]
	v_pk_mul_f32 v[100:101], v[100:101], v[112:113] op_sel_hi:[1,0]
	v_max_f32_e32 v108, 0, v108
	v_max_f32_e32 v104, 0, v104
	v_max_f32_e32 v109, 0, v109
	v_max_f32_e32 v105, 0, v105
	v_max_f32_e32 v110, 0, v110
	v_max_f32_e32 v106, 0, v106
	v_max_f32_e32 v111, 0, v111
	v_max_f32_e32 v107, 0, v107
	v_max_f32_e32 v96, 0, v96
	v_max_f32_e32 v97, 0, v97
	v_max_f32_e32 v98, 0, v98
	v_max_f32_e32 v99, 0, v99
	v_lshl_add_u64 v[114:115], v[114:115], 0, v[150:151]
	v_max_f32_e32 v100, 0, v100
	v_max_f32_e32 v101, 0, v101
	v_max_f32_e32 v102, 0, v102
	v_max_f32_e32 v103, 0, v103
	v_mul_f32_e32 v108, v108, v108
	v_mul_f32_e32 v104, v104, v104
	v_mul_f32_e32 v109, v109, v109
	v_mul_f32_e32 v105, v105, v105
	v_mul_f32_e32 v110, v110, v110
	v_mul_f32_e32 v106, v106, v106
	v_mul_f32_e32 v111, v111, v111
	v_mul_f32_e32 v107, v107, v107
	v_mul_f32_e32 v112, v96, v96
	v_mul_f32_e32 v113, v97, v97
	v_mul_f32_e32 v116, v98, v98
	v_mul_f32_e32 v117, v99, v99
	v_cvt_pk_bf16_f32 v96, v108, v109
	v_cvt_pk_bf16_f32 v97, v110, v111
	v_cvt_pk_bf16_f32 v98, v104, v105
	v_cvt_pk_bf16_f32 v99, v106, v107
	v_mul_f32_e32 v100, v100, v100
	v_mul_f32_e32 v101, v101, v101
	v_mul_f32_e32 v102, v102, v102
	v_mul_f32_e32 v103, v103, v103
	global_store_dwordx4 v[114:115], v[96:99], off sc1
	s_nop 1
	v_cvt_pk_bf16_f32 v96, v100, v101
	v_cvt_pk_bf16_f32 v97, v102, v103
	v_cvt_pk_bf16_f32 v98, v112, v113
	v_cvt_pk_bf16_f32 v99, v116, v117
	global_store_dwordx4 v[114:115], v[96:99], off offset:256 sc1
	global_load_dword v96, v[146:147], off offset:128
	s_waitcnt vmcnt(0)
	v_pk_mul_f32 v[94:95], v[94:95], v[96:97] op_sel_hi:[1,0]
	v_or_b32_e32 v98, 32, v148
	v_ashrrev_i32_e32 v99, 31, v98
	v_lshlrev_b64 v[98:99], 14, v[98:99]
	v_pk_mul_f32 v[92:93], v[92:93], v[96:97] op_sel_hi:[1,0]
	v_pk_mul_f32 v[90:91], v[90:91], v[96:97] op_sel_hi:[1,0]
	v_pk_mul_f32 v[88:89], v[88:89], v[96:97] op_sel_hi:[1,0]
	v_pk_mul_f32 v[82:83], v[82:83], v[96:97] op_sel_hi:[1,0]
	v_pk_mul_f32 v[80:81], v[80:81], v[96:97] op_sel_hi:[1,0]
	v_lshl_add_u64 v[98:99], s[74:75], 0, v[98:99]
	v_pk_mul_f32 v[86:87], v[86:87], v[96:97] op_sel_hi:[1,0]
	v_pk_mul_f32 v[84:85], v[84:85], v[96:97] op_sel_hi:[1,0]
	v_max_f32_e32 v92, 0, v92
	v_max_f32_e32 v88, 0, v88
	v_max_f32_e32 v93, 0, v93
	v_max_f32_e32 v89, 0, v89
	v_max_f32_e32 v94, 0, v94
	v_max_f32_e32 v90, 0, v90
	v_max_f32_e32 v95, 0, v95
	v_max_f32_e32 v91, 0, v91
	v_max_f32_e32 v80, 0, v80
	v_max_f32_e32 v81, 0, v81
	v_max_f32_e32 v82, 0, v82
	v_max_f32_e32 v83, 0, v83
	v_lshl_add_u64 v[98:99], v[98:99], 0, v[150:151]
	v_max_f32_e32 v84, 0, v84
	v_max_f32_e32 v85, 0, v85
	v_max_f32_e32 v86, 0, v86
	v_max_f32_e32 v87, 0, v87
	v_mul_f32_e32 v92, v92, v92
	v_mul_f32_e32 v88, v88, v88
	v_mul_f32_e32 v93, v93, v93
	v_mul_f32_e32 v89, v89, v89
	v_mul_f32_e32 v94, v94, v94
	v_mul_f32_e32 v90, v90, v90
	v_mul_f32_e32 v95, v95, v95
	v_mul_f32_e32 v91, v91, v91
	v_mul_f32_e32 v96, v80, v80
	v_mul_f32_e32 v97, v81, v81
	v_mul_f32_e32 v100, v82, v82
	v_mul_f32_e32 v101, v83, v83
	v_cvt_pk_bf16_f32 v80, v92, v93
	v_cvt_pk_bf16_f32 v81, v94, v95
	v_cvt_pk_bf16_f32 v82, v88, v89
	v_cvt_pk_bf16_f32 v83, v90, v91
	v_mul_f32_e32 v84, v84, v84
	v_mul_f32_e32 v85, v85, v85
	v_mul_f32_e32 v86, v86, v86
	v_mul_f32_e32 v87, v87, v87
	global_store_dwordx4 v[98:99], v[80:83], off sc1
	s_nop 1
	v_cvt_pk_bf16_f32 v80, v84, v85
	v_cvt_pk_bf16_f32 v81, v86, v87
	v_cvt_pk_bf16_f32 v82, v96, v97
	v_cvt_pk_bf16_f32 v83, v100, v101
	global_store_dwordx4 v[98:99], v[80:83], off offset:256 sc1
	global_load_dword v80, v[146:147], off offset:192
	s_waitcnt vmcnt(0)
; __device__ __forceinline__ unsigned cvt_pk_bf16(float lo, float hi) { unsigned r; asm volatile("v_cvt_pk_bf16_f32 %0, %1, %2" : "=v"(r) : "v"(lo), "v"(hi)); return r; }
;     __device__ __forceinline__ void operator()(const f32x4 (&acc)[2][2][4][2], const Unit& u, int wr, int wc, int fr, int fq) const {
;         const int row0 = u.pm * BM + wr * 64 + fr, col0 = u.pn * BM + wc * 32 + 8 * fq;
; #pragma unroll
;         for (int ai = 0; ai < 2; ++ai)
; #pragma unroll
;             for (int m = 0; m < 4; ++m) { const int row = row0 + ai * HALF + m * 16; const float rs = ACT == 1 ? ss[row] : 1.0f;
;                 bf16_t* rowp = O + (size_t)row * ldc + col0;
; #pragma unroll
;                 for (int bj = 0; bj < 2; ++bj) { f32x4 v0 = acc[ai][bj][m][0] * rs, v1 = acc[ai][bj][m][1] * rs;
;                     if (ACT == 1) {
; #pragma unroll
;                         for (int e = 0; e < 4; ++e) { const float a0 = fmaxf(v0[e], 0.f), a1 = fmaxf(v1[e], 0.f); v0[e] = a0 * a0; v1[e] = a1 * a1; } }
;                     u32x4 w; w.x = cvt_pk_bf16(v0[0], v0[1]); w.y = cvt_pk_bf16(v0[2], v0[3]); w.z = cvt_pk_bf16(v1[0], v1[1]); w.w = cvt_pk_bf16(v1[2], v1[3]);
;                     *(u32x4*)(rowp + bj * HALF) = w; } }
	v_pk_mul_f32 v[78:79], v[78:79], v[80:81] op_sel_hi:[1,0]
	v_or_b32_e32 v82, 48, v148
	v_ashrrev_i32_e32 v83, 31, v82
	v_lshlrev_b64 v[82:83], 14, v[82:83]
	v_pk_mul_f32 v[76:77], v[76:77], v[80:81] op_sel_hi:[1,0]
	v_pk_mul_f32 v[74:75], v[74:75], v[80:81] op_sel_hi:[1,0]
	v_pk_mul_f32 v[72:73], v[72:73], v[80:81] op_sel_hi:[1,0]
	v_pk_mul_f32 v[66:67], v[66:67], v[80:81] op_sel_hi:[1,0]
	v_pk_mul_f32 v[64:65], v[64:65], v[80:81] op_sel_hi:[1,0]
	v_lshl_add_u64 v[82:83], s[74:75], 0, v[82:83]
	v_pk_mul_f32 v[70:71], v[70:71], v[80:81] op_sel_hi:[1,0]
	v_pk_mul_f32 v[68:69], v[68:69], v[80:81] op_sel_hi:[1,0]
	v_max_f32_e32 v76, 0, v76
	v_max_f32_e32 v72, 0, v72
	v_max_f32_e32 v77, 0, v77
	v_max_f32_e32 v73, 0, v73
	v_max_f32_e32 v78, 0, v78
	v_max_f32_e32 v74, 0, v74
	v_max_f32_e32 v79, 0, v79
	v_max_f32_e32 v75, 0, v75
	v_max_f32_e32 v64, 0, v64
	v_max_f32_e32 v65, 0, v65
	v_max_f32_e32 v66, 0, v66
	v_max_f32_e32 v67, 0, v67
	v_lshl_add_u64 v[82:83], v[82:83], 0, v[150:151]
	v_max_f32_e32 v68, 0, v68
	v_max_f32_e32 v69, 0, v69
	v_max_f32_e32 v70, 0, v70
	v_max_f32_e32 v71, 0, v71
	v_mul_f32_e32 v76, v76, v76
	v_mul_f32_e32 v72, v72, v72
	v_mul_f32_e32 v77, v77, v77
	v_mul_f32_e32 v73, v73, v73
	v_mul_f32_e32 v78, v78, v78
	v_mul_f32_e32 v74, v74, v74
	v_mul_f32_e32 v79, v79, v79
	v_mul_f32_e32 v75, v75, v75
	v_mul_f32_e32 v80, v64, v64
	v_mul_f32_e32 v81, v65, v65
	v_mul_f32_e32 v84, v66, v66
	v_mul_f32_e32 v85, v67, v67
	v_cvt_pk_bf16_f32 v64, v76, v77
	v_cvt_pk_bf16_f32 v65, v78, v79
	v_cvt_pk_bf16_f32 v66, v72, v73
	v_cvt_pk_bf16_f32 v67, v74, v75
	v_mul_f32_e32 v68, v68, v68
	v_mul_f32_e32 v69, v69, v69
	v_mul_f32_e32 v70, v70, v70
	v_mul_f32_e32 v71, v71, v71
	global_store_dwordx4 v[82:83], v[64:67], off sc1
	s_nop 1
	v_cvt_pk_bf16_f32 v64, v68, v69
	v_cvt_pk_bf16_f32 v65, v70, v71
	v_cvt_pk_bf16_f32 v66, v80, v81
	v_cvt_pk_bf16_f32 v67, v84, v85
	global_store_dwordx4 v[82:83], v[64:67], off offset:256 sc1
	global_load_dword v64, v[146:147], off offset:512
	v_add_co_u32_e32 v68, vcc, s52, v144
	v_lshl_add_u64 v[66:67], v[144:145], 0, s[16:17]
	s_nop 0
	v_addc_co_u32_e32 v69, vcc, 0, v145, vcc
	s_waitcnt vmcnt(0)
	v_pk_mul_f32 v[62:63], v[62:63], v[64:65] op_sel_hi:[1,0]
	v_pk_mul_f32 v[60:61], v[60:61], v[64:65] op_sel_hi:[1,0]
	v_pk_mul_f32 v[58:59], v[58:59], v[64:65] op_sel_hi:[1,0]
	v_pk_mul_f32 v[56:57], v[56:57], v[64:65] op_sel_hi:[1,0]
	v_pk_mul_f32 v[50:51], v[50:51], v[64:65] op_sel_hi:[1,0]
	v_pk_mul_f32 v[48:49], v[48:49], v[64:65] op_sel_hi:[1,0]
	v_pk_mul_f32 v[54:55], v[54:55], v[64:65] op_sel_hi:[1,0]
	v_pk_mul_f32 v[52:53], v[52:53], v[64:65] op_sel_hi:[1,0]
	v_max_f32_e32 v60, 0, v60
	v_max_f32_e32 v56, 0, v56
	v_max_f32_e32 v61, 0, v61
	v_max_f32_e32 v57, 0, v57
	v_max_f32_e32 v62, 0, v62
	v_max_f32_e32 v58, 0, v58
	v_max_f32_e32 v63, 0, v63
	v_max_f32_e32 v59, 0, v59
	v_max_f32_e32 v48, 0, v48
	v_max_f32_e32 v49, 0, v49
	v_max_f32_e32 v50, 0, v50
	v_max_f32_e32 v51, 0, v51
	v_max_f32_e32 v52, 0, v52
	v_max_f32_e32 v53, 0, v53
	v_max_f32_e32 v54, 0, v54
	v_max_f32_e32 v55, 0, v55
	v_mul_f32_e32 v60, v60, v60
	v_mul_f32_e32 v56, v56, v56
	v_mul_f32_e32 v61, v61, v61
	v_mul_f32_e32 v57, v57, v57
	v_mul_f32_e32 v62, v62, v62
	v_mul_f32_e32 v58, v58, v58
	v_mul_f32_e32 v63, v63, v63
	v_mul_f32_e32 v59, v59, v59
	v_mul_f32_e32 v64, v48, v48
	v_mul_f32_e32 v65, v49, v49
	v_mul_f32_e32 v70, v50, v50
	v_mul_f32_e32 v71, v51, v51
	v_cvt_pk_bf16_f32 v48, v60, v61
	v_cvt_pk_bf16_f32 v49, v62, v63
	v_cvt_pk_bf16_f32 v50, v56, v57
	v_cvt_pk_bf16_f32 v51, v58, v59
	v_mul_f32_e32 v52, v52, v52
	v_mul_f32_e32 v53, v53, v53
	v_mul_f32_e32 v54, v54, v54
	v_mul_f32_e32 v55, v55, v55
	global_store_dwordx4 v[68:69], v[48:51], off sc1
	s_nop 1
	v_cvt_pk_bf16_f32 v48, v52, v53
	v_cvt_pk_bf16_f32 v49, v54, v55
	v_cvt_pk_bf16_f32 v50, v64, v65
	v_cvt_pk_bf16_f32 v51, v70, v71
	global_store_dwordx4 v[66:67], v[48:51], off offset:256 sc1
	global_load_dword v48, v[146:147], off offset:576
	v_add_co_u32_e32 v52, vcc, s53, v144
	v_lshl_add_u64 v[50:51], v[144:145], 0, s[18:19]
	s_nop 0
	v_addc_co_u32_e32 v53, vcc, 0, v145, vcc
	s_waitcnt vmcnt(0)
; __device__ __forceinline__ unsigned cvt_pk_bf16(float lo, float hi) { unsigned r; asm volatile("v_cvt_pk_bf16_f32 %0, %1, %2" : "=v"(r) : "v"(lo), "v"(hi)); return r; }
; #define PG8_BAR __builtin_amdgcn_s_barrier()
; template <class Epi, class Sched>
; __device__ __forceinline__ void gemm_phase(LAS unsigned char* lds, const Gemm g, const Sched& S, const Epi& E) {
;     ...
;         if (wr == 0) PG8_BAR;
;         E(acc, cur, wr, wc, fr, fq);
;         if (!has_next) break;
; #pragma unroll
;         for (int a = 0; a < 2; ++a)
; #pragma unroll
;             for (int b = 0; b < 2; ++b)
; #pragma unroll
;                 for (int m = 0; m < 4; ++m)
; #pragma unroll
;                     for (int n = 0; n < 2; ++n) acc[a][b][m][n] = (f32x4){0.f, 0.f, 0.f, 0.f};
;         cur = nxt; cA = nA; cB = nB; ++ui;
;         if (wr == 1) PG8_BAR;
;     __device__ __forceinline__ void operator()(const f32x4 (&acc)[2][2][4][2], const Unit& u, int wr, int wc, int fr, int fq) const {
;         const int row0 = u.pm * BM + wr * 64 + fr, col0 = u.pn * BM + wc * 32 + 8 * fq;
; #pragma unroll
;         for (int ai = 0; ai < 2; ++ai)
; #pragma unroll
;             for (int m = 0; m < 4; ++m) { const int row = row0 + ai * HALF + m * 16; const float rs = ACT == 1 ? ss[row] : 1.0f;
;                 bf16_t* rowp = O + (size_t)row * ldc + col0;
; #pragma unroll
;                 for (int bj = 0; bj < 2; ++bj) { f32x4 v0 = acc[ai][bj][m][0] * rs, v1 = acc[ai][bj][m][1] * rs;
;                     if (ACT == 1) {
; #pragma unroll
;                         for (int e = 0; e < 4; ++e) { const float a0 = fmaxf(v0[e], 0.f), a1 = fmaxf(v1[e], 0.f); v0[e] = a0 * a0; v1[e] = a1 * a1; } }
;                     u32x4 w; w.x = cvt_pk_bf16(v0[0], v0[1]); w.y = cvt_pk_bf16(v0[2], v0[3]); w.z = cvt_pk_bf16(v1[0], v1[1]); w.w = cvt_pk_bf16(v1[2], v1[3]);
;                     *(u32x4*)(rowp + bj * HALF) = w; } }
	v_pk_mul_f32 v[46:47], v[46:47], v[48:49] op_sel_hi:[1,0]
	v_pk_mul_f32 v[44:45], v[44:45], v[48:49] op_sel_hi:[1,0]
	v_pk_mul_f32 v[42:43], v[42:43], v[48:49] op_sel_hi:[1,0]
	v_pk_mul_f32 v[40:41], v[40:41], v[48:49] op_sel_hi:[1,0]
	v_pk_mul_f32 v[34:35], v[34:35], v[48:49] op_sel_hi:[1,0]
	v_pk_mul_f32 v[32:33], v[32:33], v[48:49] op_sel_hi:[1,0]
	v_pk_mul_f32 v[38:39], v[38:39], v[48:49] op_sel_hi:[1,0]
	v_pk_mul_f32 v[36:37], v[36:37], v[48:49] op_sel_hi:[1,0]
	v_max_f32_e32 v44, 0, v44
	v_max_f32_e32 v40, 0, v40
	v_max_f32_e32 v45, 0, v45
	v_max_f32_e32 v41, 0, v41
	v_max_f32_e32 v46, 0, v46
	v_max_f32_e32 v42, 0, v42
	v_max_f32_e32 v47, 0, v47
	v_max_f32_e32 v43, 0, v43
	v_max_f32_e32 v32, 0, v32
	v_max_f32_e32 v33, 0, v33
	v_max_f32_e32 v34, 0, v34
	v_max_f32_e32 v35, 0, v35
	v_max_f32_e32 v36, 0, v36
	v_max_f32_e32 v37, 0, v37
	v_max_f32_e32 v38, 0, v38
	v_max_f32_e32 v39, 0, v39
	v_mul_f32_e32 v44, v44, v44
	v_mul_f32_e32 v40, v40, v40
	v_mul_f32_e32 v45, v45, v45
	v_mul_f32_e32 v41, v41, v41
	v_mul_f32_e32 v46, v46, v46
	v_mul_f32_e32 v42, v42, v42
	v_mul_f32_e32 v47, v47, v47
	v_mul_f32_e32 v43, v43, v43
	v_mul_f32_e32 v48, v32, v32
	v_mul_f32_e32 v49, v33, v33
	v_mul_f32_e32 v54, v34, v34
	v_mul_f32_e32 v55, v35, v35
	v_cvt_pk_bf16_f32 v32, v44, v45
	v_cvt_pk_bf16_f32 v33, v46, v47
	v_cvt_pk_bf16_f32 v34, v40, v41
	v_cvt_pk_bf16_f32 v35, v42, v43
	v_mul_f32_e32 v36, v36, v36
	v_mul_f32_e32 v37, v37, v37
	v_mul_f32_e32 v38, v38, v38
	v_mul_f32_e32 v39, v39, v39
	global_store_dwordx4 v[52:53], v[32:35], off sc1
	s_nop 1
	v_cvt_pk_bf16_f32 v32, v36, v37
	v_cvt_pk_bf16_f32 v33, v38, v39
	v_cvt_pk_bf16_f32 v34, v48, v49
	v_cvt_pk_bf16_f32 v35, v54, v55
	global_store_dwordx4 v[50:51], v[32:35], off offset:256 sc1
	global_load_dword v32, v[146:147], off offset:640
	v_add_co_u32_e32 v36, vcc, s54, v144
	v_lshl_add_u64 v[34:35], v[144:145], 0, s[20:21]
	s_nop 0
	v_addc_co_u32_e32 v37, vcc, 0, v145, vcc
	s_andn2_b64 vcc, exec, s[4:5]
	s_waitcnt vmcnt(0)
	v_pk_mul_f32 v[30:31], v[30:31], v[32:33] op_sel_hi:[1,0]
	v_pk_mul_f32 v[28:29], v[28:29], v[32:33] op_sel_hi:[1,0]
	v_pk_mul_f32 v[26:27], v[26:27], v[32:33] op_sel_hi:[1,0]
	v_pk_mul_f32 v[24:25], v[24:25], v[32:33] op_sel_hi:[1,0]
	v_pk_mul_f32 v[18:19], v[18:19], v[32:33] op_sel_hi:[1,0]
	v_pk_mul_f32 v[16:17], v[16:17], v[32:33] op_sel_hi:[1,0]
	v_pk_mul_f32 v[22:23], v[22:23], v[32:33] op_sel_hi:[1,0]
	v_pk_mul_f32 v[20:21], v[20:21], v[32:33] op_sel_hi:[1,0]
	v_max_f32_e32 v28, 0, v28
	v_max_f32_e32 v24, 0, v24
	v_max_f32_e32 v29, 0, v29
	v_max_f32_e32 v25, 0, v25
	v_max_f32_e32 v30, 0, v30
	v_max_f32_e32 v26, 0, v26
	v_max_f32_e32 v31, 0, v31
	v_max_f32_e32 v27, 0, v27
	v_max_f32_e32 v16, 0, v16
	v_max_f32_e32 v17, 0, v17
	v_max_f32_e32 v18, 0, v18
	v_max_f32_e32 v19, 0, v19
	v_max_f32_e32 v20, 0, v20
	v_max_f32_e32 v21, 0, v21
	v_max_f32_e32 v22, 0, v22
	v_max_f32_e32 v23, 0, v23
	v_mul_f32_e32 v28, v28, v28
	v_mul_f32_e32 v24, v24, v24
	v_mul_f32_e32 v29, v29, v29
	v_mul_f32_e32 v25, v25, v25
	v_mul_f32_e32 v30, v30, v30
	v_mul_f32_e32 v26, v26, v26
	v_mul_f32_e32 v31, v31, v31
	v_mul_f32_e32 v27, v27, v27
	v_mul_f32_e32 v32, v16, v16
	v_mul_f32_e32 v33, v17, v17
	v_mul_f32_e32 v38, v18, v18
	v_mul_f32_e32 v39, v19, v19
	v_cvt_pk_bf16_f32 v16, v28, v29
	v_cvt_pk_bf16_f32 v17, v30, v31
	v_cvt_pk_bf16_f32 v18, v24, v25
	v_cvt_pk_bf16_f32 v19, v26, v27
	v_mul_f32_e32 v20, v20, v20
	v_mul_f32_e32 v21, v21, v21
	v_mul_f32_e32 v22, v22, v22
	v_mul_f32_e32 v23, v23, v23
	global_store_dwordx4 v[36:37], v[16:19], off sc1
	s_nop 1
	v_cvt_pk_bf16_f32 v16, v20, v21
	v_cvt_pk_bf16_f32 v17, v22, v23
	v_cvt_pk_bf16_f32 v18, v32, v33
	v_cvt_pk_bf16_f32 v19, v38, v39
	global_store_dwordx4 v[34:35], v[16:19], off offset:256 sc1
	global_load_dword v16, v[146:147], off offset:704
	v_add_co_u32_e64 v20, s[0:1], s55, v144
	v_lshl_add_u64 v[18:19], v[144:145], 0, s[22:23]
	s_nop 0
	v_addc_co_u32_e64 v21, s[0:1], 0, v145, s[0:1]
	s_mov_b64 s[0:1], -1
	s_waitcnt vmcnt(0)
	v_pk_mul_f32 v[14:15], v[14:15], v[16:17] op_sel_hi:[1,0]
	v_pk_mul_f32 v[12:13], v[12:13], v[16:17] op_sel_hi:[1,0]
	v_pk_mul_f32 v[10:11], v[10:11], v[16:17] op_sel_hi:[1,0]
	v_pk_mul_f32 v[8:9], v[8:9], v[16:17] op_sel_hi:[1,0]
	v_pk_mul_f32 v[2:3], v[2:3], v[16:17] op_sel_hi:[1,0]
	v_pk_mul_f32 v[0:1], v[0:1], v[16:17] op_sel_hi:[1,0]
	v_pk_mul_f32 v[6:7], v[6:7], v[16:17] op_sel_hi:[1,0]
	v_pk_mul_f32 v[4:5], v[4:5], v[16:17] op_sel_hi:[1,0]
	v_max_f32_e32 v12, 0, v12
	v_max_f32_e32 v8, 0, v8
	v_max_f32_e32 v13, 0, v13
	v_max_f32_e32 v9, 0, v9
	v_max_f32_e32 v14, 0, v14
	v_max_f32_e32 v10, 0, v10
	v_max_f32_e32 v15, 0, v15
	v_max_f32_e32 v11, 0, v11
	v_max_f32_e32 v0, 0, v0
	v_max_f32_e32 v1, 0, v1
	v_max_f32_e32 v2, 0, v2
	v_max_f32_e32 v3, 0, v3
	v_max_f32_e32 v4, 0, v4
	v_max_f32_e32 v5, 0, v5
	v_max_f32_e32 v6, 0, v6
	v_max_f32_e32 v7, 0, v7
	v_mul_f32_e32 v12, v12, v12
	v_mul_f32_e32 v8, v8, v8
	v_mul_f32_e32 v13, v13, v13
	v_mul_f32_e32 v9, v9, v9
	v_mul_f32_e32 v14, v14, v14
	v_mul_f32_e32 v10, v10, v10
	v_mul_f32_e32 v15, v15, v15
	v_mul_f32_e32 v11, v11, v11
	v_mul_f32_e32 v16, v0, v0
	v_mul_f32_e32 v17, v1, v1
	v_mul_f32_e32 v22, v2, v2
	v_mul_f32_e32 v23, v3, v3
	v_cvt_pk_bf16_f32 v0, v12, v13
	v_cvt_pk_bf16_f32 v1, v14, v15
	v_cvt_pk_bf16_f32 v2, v8, v9
	v_cvt_pk_bf16_f32 v3, v10, v11
	v_mul_f32_e32 v4, v4, v4
	v_mul_f32_e32 v5, v5, v5
	v_mul_f32_e32 v6, v6, v6
	v_mul_f32_e32 v7, v7, v7
	global_store_dwordx4 v[20:21], v[0:3], off sc1
	s_nop 1
	v_cvt_pk_bf16_f32 v0, v4, v5
	v_cvt_pk_bf16_f32 v1, v6, v7
	v_cvt_pk_bf16_f32 v2, v16, v17
	v_cvt_pk_bf16_f32 v3, v22, v23
	global_store_dwordx4 v[18:19], v[0:3], off offset:256 sc1
	s_cbranch_vccnz .LBB0_929
	s_andn2_b64 vcc, exec, s[8:9]
	s_cbranch_vccnz .LBB0_928
	s_barrier
	s_branch .LBB0_928

; __device__ __forceinline__ unsigned cvt_pk_bf16(float lo, float hi) { unsigned r; asm volatile("v_cvt_pk_bf16_f32 %0, %1, %2" : "=v"(r) : "v"(lo), "v"(hi)); return r; }
;     __device__ __forceinline__ void operator()(const f32x4 (&acc)[2][2][4][2], const Unit& u, int wr, int wc, int fr, int fq) const {
;     ...
;         for (int ai = 0; ai < 2; ++ai) {
;             f32x4 bf[MODE == 0 ? 4 : 1][2][2]; u32x4 bb[MODE == 1 ? 4 : 1][2];
; #pragma unroll
;             for (int m = 0; m < 4; ++m) { const int row = row0 + ai * HALF + m * 16;
;                 if (MODE == 0) { const float* br = row < MP ? basep + (size_t)row * DM : bases + (size_t)(row - MP) * DM;
; #pragma unroll
;                     for (int bj = 0; bj < 2; ++bj) { bf[MODE == 0 ? m : 0][bj][0] = *(const f32x4*)(br + col0 + bj * HALF); bf[MODE == 0 ? m : 0][bj][1] = *(const f32x4*)(br + col0 + bj * HALF + 4); } }
;                 else {
; #pragma unroll
;                     for (int bj = 0; bj < 2; ++bj) bb[MODE == 1 ? m : 0][bj] = *(const u32x4*)(baseb + (size_t)row * DM + col0 + bj * HALF); } }
; #pragma unroll
;             for (int m = 0; m < 4; ++m) { const int row = row0 + ai * HALF + m * 16; float s = 0.f;
; #pragma unroll
;                 for (int bj = 0; bj < 2; ++bj) { float o[8];
;                     if (MODE == 0) { const f32x4 b0 = bf[MODE == 0 ? m : 0][bj][0], b1 = bf[MODE == 0 ? m : 0][bj][1];
; #pragma unroll
;                         for (int e = 0; e < 4; ++e) { o[e] = b0[e] + acc[ai][bj][m][0][e]; o[4 + e] = b1[e] + acc[ai][bj][m][1][e]; } }
;                     else { float t[8]; unpack8(bb[MODE == 1 ? m : 0][bj], t);
; #pragma unroll
;                         for (int e = 0; e < 4; ++e) { o[e] = t[e] + acc[ai][bj][m][0][e]; o[4 + e] = t[4 + e] + acc[ai][bj][m][1][e]; } }
; #pragma unroll
;                     for (int e = 0; e < 8; ++e) s += o[e] * o[e];
;                     *(u32x4*)(ob + (size_t)row * DM + col0 + bj * HALF) = (u32x4){cvt_pk_bf16(o[0], o[1]), cvt_pk_bf16(o[2], o[3]), cvt_pk_bf16(o[4], o[5]), cvt_pk_bf16(o[6], o[7])}; }
;                 s += __shfl_xor(s, 16); s += __shfl_xor(s, 32);
;                 if (fq == 0) ss[(size_t)row * 32 + u.pn * 4 + wc] = s; } }
.LBB0_1031:
	v_lshl_or_b32 v168, s8, 8, v190
	v_lshl_add_u32 v172, s28, 8, v185
	v_ashrrev_i32_e32 v169, 31, v168
	v_lshlrev_b64 v[204:205], 1, v[168:169]
	v_ashrrev_i32_e32 v173, 31, v172
	v_lshl_add_u64 v[170:171], s[12:13], 0, v[204:205]
	v_lshlrev_b64 v[206:207], 12, v[172:173]
	v_lshl_add_u64 v[128:129], v[170:171], 0, v[206:207]
	global_load_dwordx4 v[196:199], v[128:129], off nt
	global_load_dwordx4 v[200:203], v[128:129], off offset:256 nt
	v_or_b32_e32 v182, 16, v172
	v_or_b32_e32 v178, 32, v172
	v_or_b32_e32 v174, 48, v172
	v_ashrrev_i32_e32 v183, 31, v182
	v_ashrrev_i32_e32 v179, 31, v178
	v_ashrrev_i32_e32 v175, 31, v174
	v_lshlrev_b64 v[188:189], 12, v[182:183]
	v_lshlrev_b64 v[180:181], 12, v[178:179]
	v_lshlrev_b64 v[176:177], 12, v[174:175]
	v_lshl_add_u64 v[128:129], v[170:171], 0, v[188:189]
	v_lshl_add_u64 v[130:131], v[170:171], 0, v[180:181]
	v_lshl_add_u64 v[208:209], v[170:171], 0, v[176:177]
	global_load_dwordx4 v[148:151], v[128:129], off nt
	global_load_dwordx4 v[144:147], v[128:129], off offset:256 nt
	global_load_dwordx4 v[140:143], v[130:131], off nt
	global_load_dwordx4 v[136:139], v[130:131], off offset:256 nt
	global_load_dwordx4 v[132:135], v[208:209], off nt
	s_nop 0
	global_load_dwordx4 v[128:131], v[208:209], off offset:256 nt
	v_lshl_add_u64 v[206:207], s[76:77], 0, v[206:207]
	v_and_b32_e32 v208, 64, v194
	v_lshl_add_u64 v[204:205], v[206:207], 0, v[204:205]
	v_xor_b32_e32 v195, 16, v194
	v_add_u32_e32 v208, 64, v208
	v_xor_b32_e32 v209, 32, v194
	v_cmp_lt_i32_e32 vcc, v195, v208
	s_lshl_b32 s28, s8, 2
	s_ashr_i32 s29, s28, 31
	v_cndmask_b32_e32 v195, v194, v195, vcc
	v_cmp_lt_i32_e32 vcc, v209, v208
	v_lshlrev_b32_e32 v195, 2, v195
	s_waitcnt vmcnt(0)
	v_lshlrev_b32_e32 v206, 16, v196
	v_and_b32_e32 v196, 0xffff0000, v196
	v_lshlrev_b32_e32 v211, 16, v200
	v_and_b32_e32 v200, 0xffff0000, v200
	v_add_f32_e32 v125, v125, v196
	v_lshlrev_b32_e32 v207, 16, v197
	v_add_f32_e32 v124, v124, v206
	v_add_f32_e32 v117, v117, v200
	v_mul_f32_e32 v200, v125, v125
	v_and_b32_e32 v197, 0xffff0000, v197
	v_add_f32_e32 v126, v126, v207
	v_fmac_f32_e32 v200, v124, v124
	v_cndmask_b32_e32 v208, v194, v209, vcc
	v_lshlrev_b32_e32 v209, 16, v198
	v_add_f32_e32 v127, v127, v197
	v_fmac_f32_e32 v200, v126, v126
	v_and_b32_e32 v198, 0xffff0000, v198
	v_add_f32_e32 v120, v120, v209
	v_fmac_f32_e32 v200, v127, v127
	v_lshlrev_b32_e32 v210, 16, v199
	v_add_f32_e32 v121, v121, v198
	v_fmac_f32_e32 v200, v120, v120
	v_and_b32_e32 v199, 0xffff0000, v199
	v_add_f32_e32 v122, v122, v210
	v_fmac_f32_e32 v200, v121, v121
	v_add_f32_e32 v123, v123, v199
	v_fmac_f32_e32 v200, v122, v122
	v_add_f32_e32 v116, v116, v211
	v_fmac_f32_e32 v200, v123, v123
	v_lshlrev_b32_e32 v212, 16, v201
	v_fmac_f32_e32 v200, v116, v116
	v_and_b32_e32 v201, 0xffff0000, v201
	v_add_f32_e32 v118, v118, v212
	v_fmac_f32_e32 v200, v117, v117
	v_lshlrev_b32_e32 v213, 16, v202
	v_add_f32_e32 v119, v119, v201
	v_fmac_f32_e32 v200, v118, v118
	v_and_b32_e32 v202, 0xffff0000, v202
	v_add_f32_e32 v196, v112, v213
	v_fmac_f32_e32 v200, v119, v119
	v_lshlrev_b32_e32 v214, 16, v203
	v_add_f32_e32 v197, v113, v202
	v_fmac_f32_e32 v200, v196, v196
	v_and_b32_e32 v203, 0xffff0000, v203
	v_add_f32_e32 v198, v114, v214
	v_fmac_f32_e32 v200, v197, v197
	v_add_f32_e32 v199, v115, v203
	v_fmac_f32_e32 v200, v198, v198
	v_fmac_f32_e32 v200, v199, v199
	v_cvt_pk_bf16_f32 v112, v124, v125
	ds_bpermute_b32 v124, v195, v200
	v_cvt_pk_bf16_f32 v113, v126, v127
	v_cvt_pk_bf16_f32 v114, v120, v121
	v_cvt_pk_bf16_f32 v115, v122, v123
	global_store_dwordx4 v[204:205], v[112:115], off sc1
	v_cvt_pk_bf16_f32 v116, v116, v117
	v_cvt_pk_bf16_f32 v117, v118, v119
	v_cvt_pk_bf16_f32 v118, v196, v197
	v_cvt_pk_bf16_f32 v119, v198, v199
	global_store_dwordx4 v[204:205], v[116:119], off offset:256 sc1
	s_waitcnt lgkmcnt(0)
	v_add_f32_e32 v113, v200, v124
	v_lshlrev_b32_e32 v112, 2, v208
	ds_bpermute_b32 v114, v112, v113
	s_and_saveexec_b64 s[30:31], s[4:5]
	s_cbranch_execz .LBB0_1033
	v_lshlrev_b64 v[116:117], 7, v[172:173]
	v_lshl_add_u64 v[116:117], s[14:15], 0, v[116:117]
	v_lshl_add_u64 v[116:117], s[28:29], 2, v[116:117]
	s_lshl_b32 s8, s43, 2
	v_lshl_add_u64 v[116:117], v[116:117], 0, s[8:9]
	s_waitcnt lgkmcnt(0)
	v_add_f32_e32 v113, v113, v114
	global_store_dword v[116:117], v113, off
; __device__ __forceinline__ unsigned cvt_pk_bf16(float lo, float hi) { unsigned r; asm volatile("v_cvt_pk_bf16_f32 %0, %1, %2" : "=v"(r) : "v"(lo), "v"(hi)); return r; }
; __device__ __forceinline__ void unpack8(const u32x4& w, float (&f)[8]) { f[0] = bflo(w.x); f[1] = bfhi(w.x); f[2] = bflo(w.y); f[3] = bfhi(w.y); f[4] = bflo(w.z); f[5] = bfhi(w.z); f[6] = bflo(w.w); f[7] = bfhi(w.w); }
;     __device__ __forceinline__ void operator()(const f32x4 (&acc)[2][2][4][2], const Unit& u, int wr, int wc, int fr, int fq) const {
;     ...
;             for (int m = 0; m < 4; ++m) { const int row = row0 + ai * HALF + m * 16; float s = 0.f;
; #pragma unroll
;                 for (int bj = 0; bj < 2; ++bj) { float o[8];
;                     if (MODE == 0) { const f32x4 b0 = bf[MODE == 0 ? m : 0][bj][0], b1 = bf[MODE == 0 ? m : 0][bj][1];
; #pragma unroll
;                         for (int e = 0; e < 4; ++e) { o[e] = b0[e] + acc[ai][bj][m][0][e]; o[4 + e] = b1[e] + acc[ai][bj][m][1][e]; } }
;                     else { float t[8]; unpack8(bb[MODE == 1 ? m : 0][bj], t);
; #pragma unroll
;                         for (int e = 0; e < 4; ++e) { o[e] = t[e] + acc[ai][bj][m][0][e]; o[4 + e] = t[4 + e] + acc[ai][bj][m][1][e]; } }
; #pragma unroll
;                     for (int e = 0; e < 8; ++e) s += o[e] * o[e];
;                     *(u32x4*)(ob + (size_t)row * DM + col0 + bj * HALF) = (u32x4){cvt_pk_bf16(o[0], o[1]), cvt_pk_bf16(o[2], o[3]), cvt_pk_bf16(o[4], o[5]), cvt_pk_bf16(o[6], o[7])}; }
;                 s += __shfl_xor(s, 16); s += __shfl_xor(s, 32);
;                 if (fq == 0) ss[(size_t)row * 32 + u.pn * 4 + wc] = s; } }
.LBB0_1033:
	s_or_b64 exec, exec, s[30:31]
	v_lshlrev_b32_e32 v113, 16, v148
	s_waitcnt lgkmcnt(0)
	v_and_b32_e32 v114, 0xffff0000, v148
	v_lshlrev_b32_e32 v117, 16, v150
	v_lshlrev_b32_e32 v115, 16, v149
	v_and_b32_e32 v116, 0xffff0000, v149
	v_and_b32_e32 v118, 0xffff0000, v150
	v_lshlrev_b32_e32 v119, 16, v151
	v_add_f32_e32 v108, v108, v113
	v_add_f32_e32 v113, v104, v117
	v_add_f32_e32 v104, v109, v114
	v_add_f32_e32 v109, v105, v118
	v_add_f32_e32 v105, v110, v115
	v_add_f32_e32 v110, v106, v119
	v_add_f32_e32 v106, v111, v116
	v_mul_f32_e32 v111, v104, v104
	v_fmac_f32_e32 v111, v108, v108
	v_fmac_f32_e32 v111, v105, v105
	v_fmac_f32_e32 v111, v106, v106
	v_fmac_f32_e32 v111, v113, v113
	v_and_b32_e32 v120, 0xffff0000, v151
	v_fmac_f32_e32 v111, v109, v109
	v_add_f32_e32 v107, v107, v120
	v_fmac_f32_e32 v111, v110, v110
	v_cvt_pk_bf16_f32 v104, v108, v104
	v_lshlrev_b32_e32 v108, 16, v144
	v_fmac_f32_e32 v111, v107, v107
	v_cvt_pk_bf16_f32 v105, v105, v106
	v_cvt_pk_bf16_f32 v106, v113, v109
	v_and_b32_e32 v109, 0xffff0000, v144
	v_add_f32_e32 v100, v100, v108
	v_cvt_pk_bf16_f32 v107, v110, v107
	v_lshlrev_b32_e32 v110, 16, v145
	v_add_f32_e32 v101, v101, v109
	v_fmac_f32_e32 v111, v100, v100
	v_and_b32_e32 v113, 0xffff0000, v145
	v_add_f32_e32 v110, v102, v110
	v_fmac_f32_e32 v111, v101, v101
	v_lshlrev_b32_e32 v114, 16, v146
	v_add_f32_e32 v113, v103, v113
	v_fmac_f32_e32 v111, v110, v110
	v_and_b32_e32 v115, 0xffff0000, v146
	v_add_f32_e32 v108, v96, v114
	v_fmac_f32_e32 v111, v113, v113
	v_lshlrev_b32_e32 v116, 16, v147
	v_add_f32_e32 v109, v97, v115
	v_fmac_f32_e32 v111, v108, v108
	v_and_b32_e32 v117, 0xffff0000, v147
	v_add_f32_e32 v114, v98, v116
	v_fmac_f32_e32 v111, v109, v109
	v_add_f32_e32 v115, v99, v117
	v_fmac_f32_e32 v111, v114, v114
	v_fmac_f32_e32 v111, v115, v115
	ds_bpermute_b32 v99, v195, v111
	v_lshl_add_u64 v[96:97], s[76:77], 0, v[188:189]
	v_lshl_add_u64 v[102:103], v[168:169], 1, v[96:97]
	global_store_dwordx4 v[102:103], v[104:107], off sc1
	v_cvt_pk_bf16_f32 v98, v100, v101
	s_waitcnt lgkmcnt(0)
	v_add_f32_e32 v96, v111, v99
	ds_bpermute_b32 v97, v112, v96
	v_cvt_pk_bf16_f32 v99, v110, v113
	v_cvt_pk_bf16_f32 v100, v108, v109
	v_cvt_pk_bf16_f32 v101, v114, v115
	global_store_dwordx4 v[102:103], v[98:101], off offset:256 sc1
	s_and_saveexec_b64 s[30:31], s[4:5]
	s_cbranch_execz .LBB0_1035
	v_lshlrev_b64 v[98:99], 7, v[182:183]
	v_lshl_add_u64 v[98:99], s[14:15], 0, v[98:99]
	v_lshl_add_u64 v[98:99], s[28:29], 2, v[98:99]
	s_lshl_b32 s8, s43, 2
	v_lshl_add_u64 v[98:99], v[98:99], 0, s[8:9]
	s_waitcnt lgkmcnt(0)
	v_add_f32_e32 v96, v96, v97
	global_store_dword v[98:99], v96, off
.LBB0_1035:
	s_or_b64 exec, exec, s[30:31]
	v_lshlrev_b32_e32 v96, 16, v140
	s_waitcnt lgkmcnt(0)
	v_and_b32_e32 v97, 0xffff0000, v140
	v_lshlrev_b32_e32 v100, 16, v142
	v_lshlrev_b32_e32 v98, 16, v141
	v_and_b32_e32 v99, 0xffff0000, v141
	v_and_b32_e32 v101, 0xffff0000, v142
	v_lshlrev_b32_e32 v102, 16, v143
	v_add_f32_e32 v92, v92, v96
	v_add_f32_e32 v96, v88, v100
	v_add_f32_e32 v88, v93, v97
	v_add_f32_e32 v93, v89, v101
	v_add_f32_e32 v89, v94, v98
	v_add_f32_e32 v94, v90, v102
	v_add_f32_e32 v90, v95, v99
	v_mul_f32_e32 v95, v88, v88
	v_fmac_f32_e32 v95, v92, v92
	v_fmac_f32_e32 v95, v89, v89
	v_fmac_f32_e32 v95, v90, v90
	v_fmac_f32_e32 v95, v96, v96
	v_and_b32_e32 v103, 0xffff0000, v143
	v_fmac_f32_e32 v95, v93, v93
	v_add_f32_e32 v91, v91, v103
	v_fmac_f32_e32 v95, v94, v94
	v_cvt_pk_bf16_f32 v88, v92, v88
	v_lshlrev_b32_e32 v92, 16, v136
	v_fmac_f32_e32 v95, v91, v91
	v_cvt_pk_bf16_f32 v89, v89, v90
	v_cvt_pk_bf16_f32 v90, v96, v93
	v_and_b32_e32 v93, 0xffff0000, v136
	v_add_f32_e32 v84, v84, v92
	v_cvt_pk_bf16_f32 v91, v94, v91
	v_lshlrev_b32_e32 v94, 16, v137
	v_add_f32_e32 v85, v85, v93
	v_fmac_f32_e32 v95, v84, v84
	v_and_b32_e32 v96, 0xffff0000, v137
	v_add_f32_e32 v94, v86, v94
	v_fmac_f32_e32 v95, v85, v85
	v_lshlrev_b32_e32 v97, 16, v138
	v_add_f32_e32 v96, v87, v96
	v_fmac_f32_e32 v95, v94, v94
	v_and_b32_e32 v98, 0xffff0000, v138
	v_add_f32_e32 v92, v80, v97
	v_fmac_f32_e32 v95, v96, v96
	v_lshlrev_b32_e32 v99, 16, v139
	v_add_f32_e32 v93, v81, v98
	v_fmac_f32_e32 v95, v92, v92
	v_and_b32_e32 v100, 0xffff0000, v139
	v_add_f32_e32 v97, v82, v99
	v_fmac_f32_e32 v95, v93, v93
	v_add_f32_e32 v98, v83, v100
	v_fmac_f32_e32 v95, v97, v97
	v_fmac_f32_e32 v95, v98, v98
	ds_bpermute_b32 v83, v195, v95
	v_lshl_add_u64 v[80:81], s[76:77], 0, v[180:181]
	v_lshl_add_u64 v[86:87], v[168:169], 1, v[80:81]
	global_store_dwordx4 v[86:87], v[88:91], off sc1
	v_cvt_pk_bf16_f32 v82, v84, v85
	s_waitcnt lgkmcnt(0)
	v_add_f32_e32 v80, v95, v83
	ds_bpermute_b32 v81, v112, v80
	v_cvt_pk_bf16_f32 v83, v94, v96
	v_cvt_pk_bf16_f32 v84, v92, v93
	v_cvt_pk_bf16_f32 v85, v97, v98
	global_store_dwordx4 v[86:87], v[82:85], off offset:256 sc1
	s_and_saveexec_b64 s[30:31], s[4:5]
	s_cbranch_execz .LBB0_1037
	v_lshlrev_b64 v[82:83], 7, v[178:179]
	v_lshl_add_u64 v[82:83], s[14:15], 0, v[82:83]
	v_lshl_add_u64 v[82:83], s[28:29], 2, v[82:83]
	s_lshl_b32 s8, s43, 2
	v_lshl_add_u64 v[82:83], v[82:83], 0, s[8:9]
	s_waitcnt lgkmcnt(0)
	v_add_f32_e32 v80, v80, v81
	global_store_dword v[82:83], v80, off
; __device__ __forceinline__ unsigned cvt_pk_bf16(float lo, float hi) { unsigned r; asm volatile("v_cvt_pk_bf16_f32 %0, %1, %2" : "=v"(r) : "v"(lo), "v"(hi)); return r; }
;     __device__ __forceinline__ void operator()(const f32x4 (&acc)[2][2][4][2], const Unit& u, int wr, int wc, int fr, int fq) const {
;     ...
;         for (int ai = 0; ai < 2; ++ai) {
;             f32x4 bf[MODE == 0 ? 4 : 1][2][2]; u32x4 bb[MODE == 1 ? 4 : 1][2];
; #pragma unroll
;             for (int m = 0; m < 4; ++m) { const int row = row0 + ai * HALF + m * 16;
;                 if (MODE == 0) { const float* br = row < MP ? basep + (size_t)row * DM : bases + (size_t)(row - MP) * DM;
; #pragma unroll
;                     for (int bj = 0; bj < 2; ++bj) { bf[MODE == 0 ? m : 0][bj][0] = *(const f32x4*)(br + col0 + bj * HALF); bf[MODE == 0 ? m : 0][bj][1] = *(const f32x4*)(br + col0 + bj * HALF + 4); } }
;                 else {
; #pragma unroll
;                     for (int bj = 0; bj < 2; ++bj) bb[MODE == 1 ? m : 0][bj] = *(const u32x4*)(baseb + (size_t)row * DM + col0 + bj * HALF); } }
; #pragma unroll
;             for (int m = 0; m < 4; ++m) { const int row = row0 + ai * HALF + m * 16; float s = 0.f;
; #pragma unroll
;                 for (int bj = 0; bj < 2; ++bj) { float o[8];
;                     if (MODE == 0) { const f32x4 b0 = bf[MODE == 0 ? m : 0][bj][0], b1 = bf[MODE == 0 ? m : 0][bj][1];
; #pragma unroll
;                         for (int e = 0; e < 4; ++e) { o[e] = b0[e] + acc[ai][bj][m][0][e]; o[4 + e] = b1[e] + acc[ai][bj][m][1][e]; } }
;                     else { float t[8]; unpack8(bb[MODE == 1 ? m : 0][bj], t);
; #pragma unroll
;                         for (int e = 0; e < 4; ++e) { o[e] = t[e] + acc[ai][bj][m][0][e]; o[4 + e] = t[4 + e] + acc[ai][bj][m][1][e]; } }
; #pragma unroll
;                     for (int e = 0; e < 8; ++e) s += o[e] * o[e];
;                     *(u32x4*)(ob + (size_t)row * DM + col0 + bj * HALF) = (u32x4){cvt_pk_bf16(o[0], o[1]), cvt_pk_bf16(o[2], o[3]), cvt_pk_bf16(o[4], o[5]), cvt_pk_bf16(o[6], o[7])}; }
;                 s += __shfl_xor(s, 16); s += __shfl_xor(s, 32);
;                 if (fq == 0) ss[(size_t)row * 32 + u.pn * 4 + wc] = s; } }
.LBB0_1037:
	s_or_b64 exec, exec, s[30:31]
	v_lshlrev_b32_e32 v80, 16, v132
	s_waitcnt lgkmcnt(0)
	v_and_b32_e32 v81, 0xffff0000, v132
	v_lshlrev_b32_e32 v84, 16, v134
	v_lshlrev_b32_e32 v82, 16, v133
	v_and_b32_e32 v83, 0xffff0000, v133
	v_and_b32_e32 v85, 0xffff0000, v134
	v_lshlrev_b32_e32 v86, 16, v135
	v_add_f32_e32 v76, v76, v80
	v_add_f32_e32 v80, v72, v84
	v_add_f32_e32 v72, v77, v81
	v_add_f32_e32 v77, v73, v85
	v_add_f32_e32 v73, v78, v82
	v_add_f32_e32 v78, v74, v86
	v_add_f32_e32 v74, v79, v83
	v_mul_f32_e32 v79, v72, v72
	v_fmac_f32_e32 v79, v76, v76
	v_fmac_f32_e32 v79, v73, v73
	v_fmac_f32_e32 v79, v74, v74
	v_fmac_f32_e32 v79, v80, v80
	v_and_b32_e32 v87, 0xffff0000, v135
	v_fmac_f32_e32 v79, v77, v77
	v_add_f32_e32 v75, v75, v87
	v_fmac_f32_e32 v79, v78, v78
	v_cvt_pk_bf16_f32 v72, v76, v72
	v_lshlrev_b32_e32 v76, 16, v128
	v_fmac_f32_e32 v79, v75, v75
	v_cvt_pk_bf16_f32 v73, v73, v74
	v_cvt_pk_bf16_f32 v74, v80, v77
	v_and_b32_e32 v77, 0xffff0000, v128
	v_add_f32_e32 v68, v68, v76
	v_cvt_pk_bf16_f32 v75, v78, v75
	v_lshlrev_b32_e32 v78, 16, v129
	v_add_f32_e32 v69, v69, v77
	v_fmac_f32_e32 v79, v68, v68
	v_and_b32_e32 v80, 0xffff0000, v129
	v_add_f32_e32 v78, v70, v78
	v_fmac_f32_e32 v79, v69, v69
	v_lshlrev_b32_e32 v81, 16, v130
	v_add_f32_e32 v80, v71, v80
	v_fmac_f32_e32 v79, v78, v78
	v_and_b32_e32 v82, 0xffff0000, v130
	v_add_f32_e32 v76, v64, v81
	v_fmac_f32_e32 v79, v80, v80
	v_lshlrev_b32_e32 v83, 16, v131
	v_add_f32_e32 v77, v65, v82
	v_fmac_f32_e32 v79, v76, v76
	v_and_b32_e32 v84, 0xffff0000, v131
	v_add_f32_e32 v81, v66, v83
	v_fmac_f32_e32 v79, v77, v77
	v_add_f32_e32 v82, v67, v84
	v_fmac_f32_e32 v79, v81, v81
	v_fmac_f32_e32 v79, v82, v82
	ds_bpermute_b32 v67, v195, v79
	v_lshl_add_u64 v[64:65], s[76:77], 0, v[176:177]
	v_lshl_add_u64 v[70:71], v[168:169], 1, v[64:65]
	global_store_dwordx4 v[70:71], v[72:75], off sc1
	v_cvt_pk_bf16_f32 v66, v68, v69
	s_waitcnt lgkmcnt(0)
	v_add_f32_e32 v64, v79, v67
	ds_bpermute_b32 v65, v112, v64
	v_cvt_pk_bf16_f32 v67, v78, v80
	v_cvt_pk_bf16_f32 v68, v76, v77
	v_cvt_pk_bf16_f32 v69, v81, v82
	global_store_dwordx4 v[70:71], v[66:69], off offset:256 sc1
	s_and_saveexec_b64 s[30:31], s[4:5]
	s_cbranch_execz .LBB0_1039
	v_lshlrev_b64 v[66:67], 7, v[174:175]
	v_lshl_add_u64 v[66:67], s[14:15], 0, v[66:67]
	v_lshl_add_u64 v[66:67], s[28:29], 2, v[66:67]
	s_lshl_b32 s8, s43, 2
	v_lshl_add_u64 v[66:67], v[66:67], 0, s[8:9]
	s_waitcnt lgkmcnt(0)
	v_add_f32_e32 v64, v64, v65
	global_store_dword v[66:67], v64, off
.LBB0_1039:
	s_or_b64 exec, exec, s[30:31]
	v_add_u32_e32 v100, 0x80, v172
	v_ashrrev_i32_e32 v101, 31, v100
	v_lshlrev_b64 v[110:111], 12, v[100:101]
	s_waitcnt lgkmcnt(0)
	v_lshl_add_u64 v[64:65], v[170:171], 0, v[110:111]
	global_load_dwordx4 v[102:105], v[64:65], off nt
	global_load_dwordx4 v[106:109], v[64:65], off offset:256 nt
	v_add_u32_e32 v96, 0x90, v172
	v_add_u32_e32 v92, 0xa0, v172
	v_add_u32_e32 v88, 0xb0, v172
	v_ashrrev_i32_e32 v97, 31, v96
	v_ashrrev_i32_e32 v93, 31, v92
	v_ashrrev_i32_e32 v89, 31, v88
	v_lshlrev_b64 v[98:99], 12, v[96:97]
	v_lshlrev_b64 v[94:95], 12, v[92:93]
	v_lshlrev_b64 v[90:91], 12, v[88:89]
	v_lshl_add_u64 v[64:65], v[170:171], 0, v[98:99]
	v_lshl_add_u64 v[66:67], v[170:171], 0, v[94:95]
	v_lshl_add_u64 v[114:115], v[170:171], 0, v[90:91]
	global_load_dwordx4 v[84:87], v[64:65], off nt
	global_load_dwordx4 v[80:83], v[64:65], off offset:256 nt
	global_load_dwordx4 v[76:79], v[66:67], off nt
	global_load_dwordx4 v[72:75], v[66:67], off offset:256 nt
	global_load_dwordx4 v[68:71], v[114:115], off nt
	s_nop 0
	global_load_dwordx4 v[64:67], v[114:115], off offset:256 nt
	s_waitcnt vmcnt(7)
	v_lshlrev_b32_e32 v113, 16, v102
	v_and_b32_e32 v102, 0xffff0000, v102
	v_add_f32_e32 v61, v61, v102
	v_lshlrev_b32_e32 v114, 16, v103
	v_add_f32_e32 v60, v60, v113
	v_mul_f32_e32 v113, v61, v61
	v_and_b32_e32 v103, 0xffff0000, v103
	v_add_f32_e32 v62, v62, v114
	v_fmac_f32_e32 v113, v60, v60
	v_lshlrev_b32_e32 v115, 16, v104
	v_add_f32_e32 v63, v63, v103
	v_fmac_f32_e32 v113, v62, v62
	v_and_b32_e32 v104, 0xffff0000, v104
	v_add_f32_e32 v56, v56, v115
	v_fmac_f32_e32 v113, v63, v63
	v_lshlrev_b32_e32 v116, 16, v105
	v_add_f32_e32 v57, v57, v104
	v_fmac_f32_e32 v113, v56, v56
	v_and_b32_e32 v105, 0xffff0000, v105
	v_add_f32_e32 v58, v58, v116
	v_fmac_f32_e32 v113, v57, v57
	s_waitcnt vmcnt(6)
	v_lshlrev_b32_e32 v117, 16, v106
	v_add_f32_e32 v59, v59, v105
	v_fmac_f32_e32 v113, v58, v58
	v_and_b32_e32 v106, 0xffff0000, v106
	v_add_f32_e32 v102, v52, v117
	v_fmac_f32_e32 v113, v59, v59
	v_lshlrev_b32_e32 v118, 16, v107
	v_add_f32_e32 v104, v53, v106
	v_fmac_f32_e32 v113, v102, v102
	v_and_b32_e32 v107, 0xffff0000, v107
	v_add_f32_e32 v106, v54, v118
	v_fmac_f32_e32 v113, v104, v104
	v_lshlrev_b32_e32 v119, 16, v108
	v_add_f32_e32 v107, v55, v107
	v_fmac_f32_e32 v113, v106, v106
	v_and_b32_e32 v108, 0xffff0000, v108
	v_add_f32_e32 v103, v48, v119
	v_fmac_f32_e32 v113, v107, v107
	v_lshlrev_b32_e32 v120, 16, v109
	v_add_f32_e32 v105, v49, v108
	v_fmac_f32_e32 v113, v103, v103
	v_and_b32_e32 v109, 0xffff0000, v109
	v_add_f32_e32 v108, v50, v120
	v_fmac_f32_e32 v113, v105, v105
	v_cvt_pk_bf16_f32 v52, v60, v61
	v_cvt_pk_bf16_f32 v53, v62, v63
	v_cvt_pk_bf16_f32 v54, v56, v57
	v_cvt_pk_bf16_f32 v55, v58, v59
	v_add_f32_e32 v58, v51, v109
	v_fmac_f32_e32 v113, v108, v108
	v_fmac_f32_e32 v113, v58, v58
	ds_bpermute_b32 v51, v195, v113
	v_lshl_add_u64 v[48:49], s[76:77], 0, v[110:111]
	v_lshl_add_u64 v[56:57], v[168:169], 1, v[48:49]
	global_store_dwordx4 v[56:57], v[52:55], off sc1
	v_cvt_pk_bf16_f32 v50, v102, v104
	s_waitcnt lgkmcnt(0)
	v_add_f32_e32 v48, v113, v51
	ds_bpermute_b32 v49, v112, v48
	v_cvt_pk_bf16_f32 v51, v106, v107
	v_cvt_pk_bf16_f32 v52, v103, v105
	v_cvt_pk_bf16_f32 v53, v108, v58
	global_store_dwordx4 v[56:57], v[50:53], off offset:256 sc1
	s_and_saveexec_b64 s[30:31], s[4:5]
	s_cbranch_execz .LBB0_1041
	v_lshlrev_b64 v[50:51], 7, v[100:101]
	v_lshl_add_u64 v[50:51], s[14:15], 0, v[50:51]
	v_lshl_add_u64 v[50:51], s[28:29], 2, v[50:51]
	s_lshl_b32 s8, s43, 2
	v_lshl_add_u64 v[50:51], v[50:51], 0, s[8:9]
	s_waitcnt lgkmcnt(0)
	v_add_f32_e32 v48, v48, v49
	global_store_dword v[50:51], v48, off
; __device__ __forceinline__ unsigned cvt_pk_bf16(float lo, float hi) { unsigned r; asm volatile("v_cvt_pk_bf16_f32 %0, %1, %2" : "=v"(r) : "v"(lo), "v"(hi)); return r; }
; __device__ __forceinline__ void unpack8(const u32x4& w, float (&f)[8]) { f[0] = bflo(w.x); f[1] = bfhi(w.x); f[2] = bflo(w.y); f[3] = bfhi(w.y); f[4] = bflo(w.z); f[5] = bfhi(w.z); f[6] = bflo(w.w); f[7] = bfhi(w.w); }
;     __device__ __forceinline__ void operator()(const f32x4 (&acc)[2][2][4][2], const Unit& u, int wr, int wc, int fr, int fq) const {
;     ...
;             for (int m = 0; m < 4; ++m) { const int row = row0 + ai * HALF + m * 16; float s = 0.f;
; #pragma unroll
;                 for (int bj = 0; bj < 2; ++bj) { float o[8];
;                     if (MODE == 0) { const f32x4 b0 = bf[MODE == 0 ? m : 0][bj][0], b1 = bf[MODE == 0 ? m : 0][bj][1];
; #pragma unroll
;                         for (int e = 0; e < 4; ++e) { o[e] = b0[e] + acc[ai][bj][m][0][e]; o[4 + e] = b1[e] + acc[ai][bj][m][1][e]; } }
;                     else { float t[8]; unpack8(bb[MODE == 1 ? m : 0][bj], t);
; #pragma unroll
;                         for (int e = 0; e < 4; ++e) { o[e] = t[e] + acc[ai][bj][m][0][e]; o[4 + e] = t[4 + e] + acc[ai][bj][m][1][e]; } }
; #pragma unroll
;                     for (int e = 0; e < 8; ++e) s += o[e] * o[e];
;                     *(u32x4*)(ob + (size_t)row * DM + col0 + bj * HALF) = (u32x4){cvt_pk_bf16(o[0], o[1]), cvt_pk_bf16(o[2], o[3]), cvt_pk_bf16(o[4], o[5]), cvt_pk_bf16(o[6], o[7])}; }
;                 s += __shfl_xor(s, 16); s += __shfl_xor(s, 32);
;                 if (fq == 0) ss[(size_t)row * 32 + u.pn * 4 + wc] = s; } }
.LBB0_1041:
	s_or_b64 exec, exec, s[30:31]
	s_waitcnt vmcnt(7)
	v_lshlrev_b32_e32 v48, 16, v84
	s_waitcnt lgkmcnt(0)
	v_and_b32_e32 v49, 0xffff0000, v84
	v_lshlrev_b32_e32 v52, 16, v86
	v_lshlrev_b32_e32 v50, 16, v85
	v_and_b32_e32 v51, 0xffff0000, v85
	v_and_b32_e32 v53, 0xffff0000, v86
	v_lshlrev_b32_e32 v54, 16, v87
	v_add_f32_e32 v44, v44, v48
	v_add_f32_e32 v48, v40, v52
	v_add_f32_e32 v40, v45, v49
	v_add_f32_e32 v45, v41, v53
	v_add_f32_e32 v41, v46, v50
	v_add_f32_e32 v46, v42, v54
	v_add_f32_e32 v42, v47, v51
	v_mul_f32_e32 v47, v40, v40
	v_fmac_f32_e32 v47, v44, v44
	v_fmac_f32_e32 v47, v41, v41
	v_fmac_f32_e32 v47, v42, v42
	v_fmac_f32_e32 v47, v48, v48
	v_and_b32_e32 v55, 0xffff0000, v87
	v_fmac_f32_e32 v47, v45, v45
	v_add_f32_e32 v43, v43, v55
	v_fmac_f32_e32 v47, v46, v46
	v_cvt_pk_bf16_f32 v40, v44, v40
	s_waitcnt vmcnt(6)
	v_lshlrev_b32_e32 v44, 16, v80
	v_fmac_f32_e32 v47, v43, v43
	v_cvt_pk_bf16_f32 v41, v41, v42
	v_cvt_pk_bf16_f32 v42, v48, v45
	v_and_b32_e32 v45, 0xffff0000, v80
	v_add_f32_e32 v36, v36, v44
	v_cvt_pk_bf16_f32 v43, v46, v43
	v_lshlrev_b32_e32 v46, 16, v81
	v_add_f32_e32 v37, v37, v45
	v_fmac_f32_e32 v47, v36, v36
	v_and_b32_e32 v48, 0xffff0000, v81
	v_add_f32_e32 v46, v38, v46
	v_fmac_f32_e32 v47, v37, v37
	v_lshlrev_b32_e32 v49, 16, v82
	v_add_f32_e32 v48, v39, v48
	v_fmac_f32_e32 v47, v46, v46
	v_and_b32_e32 v50, 0xffff0000, v82
	v_add_f32_e32 v44, v32, v49
	v_fmac_f32_e32 v47, v48, v48
	v_lshlrev_b32_e32 v51, 16, v83
	v_add_f32_e32 v45, v33, v50
	v_fmac_f32_e32 v47, v44, v44
	v_and_b32_e32 v52, 0xffff0000, v83
	v_add_f32_e32 v49, v34, v51
	v_fmac_f32_e32 v47, v45, v45
	v_add_f32_e32 v50, v35, v52
	v_fmac_f32_e32 v47, v49, v49
	v_fmac_f32_e32 v47, v50, v50
	ds_bpermute_b32 v35, v195, v47
	v_lshl_add_u64 v[32:33], s[76:77], 0, v[98:99]
	v_lshl_add_u64 v[38:39], v[168:169], 1, v[32:33]
	global_store_dwordx4 v[38:39], v[40:43], off sc1
	v_cvt_pk_bf16_f32 v34, v36, v37
	s_waitcnt lgkmcnt(0)
	v_add_f32_e32 v32, v47, v35
	ds_bpermute_b32 v33, v112, v32
	v_cvt_pk_bf16_f32 v35, v46, v48
	v_cvt_pk_bf16_f32 v36, v44, v45
	v_cvt_pk_bf16_f32 v37, v49, v50
	global_store_dwordx4 v[38:39], v[34:37], off offset:256 sc1
	s_and_saveexec_b64 s[30:31], s[4:5]
	s_cbranch_execz .LBB0_1043
	v_lshlrev_b64 v[34:35], 7, v[96:97]
	v_lshl_add_u64 v[34:35], s[14:15], 0, v[34:35]
	v_lshl_add_u64 v[34:35], s[28:29], 2, v[34:35]
	s_lshl_b32 s8, s43, 2
	v_lshl_add_u64 v[34:35], v[34:35], 0, s[8:9]
	s_waitcnt lgkmcnt(0)
	v_add_f32_e32 v32, v32, v33
	global_store_dword v[34:35], v32, off
; __device__ __forceinline__ unsigned cvt_pk_bf16(float lo, float hi) { unsigned r; asm volatile("v_cvt_pk_bf16_f32 %0, %1, %2" : "=v"(r) : "v"(lo), "v"(hi)); return r; }
; __device__ __forceinline__ void unpack8(const u32x4& w, float (&f)[8]) { f[0] = bflo(w.x); f[1] = bfhi(w.x); f[2] = bflo(w.y); f[3] = bfhi(w.y); f[4] = bflo(w.z); f[5] = bfhi(w.z); f[6] = bflo(w.w); f[7] = bfhi(w.w); }
;     __device__ __forceinline__ void operator()(const f32x4 (&acc)[2][2][4][2], const Unit& u, int wr, int wc, int fr, int fq) const {
;     ...
;             for (int m = 0; m < 4; ++m) { const int row = row0 + ai * HALF + m * 16; float s = 0.f;
; #pragma unroll
;                 for (int bj = 0; bj < 2; ++bj) { float o[8];
;                     if (MODE == 0) { const f32x4 b0 = bf[MODE == 0 ? m : 0][bj][0], b1 = bf[MODE == 0 ? m : 0][bj][1];
; #pragma unroll
;                         for (int e = 0; e < 4; ++e) { o[e] = b0[e] + acc[ai][bj][m][0][e]; o[4 + e] = b1[e] + acc[ai][bj][m][1][e]; } }
;                     else { float t[8]; unpack8(bb[MODE == 1 ? m : 0][bj], t);
; #pragma unroll
;                         for (int e = 0; e < 4; ++e) { o[e] = t[e] + acc[ai][bj][m][0][e]; o[4 + e] = t[4 + e] + acc[ai][bj][m][1][e]; } }
; #pragma unroll
;                     for (int e = 0; e < 8; ++e) s += o[e] * o[e];
;                     *(u32x4*)(ob + (size_t)row * DM + col0 + bj * HALF) = (u32x4){cvt_pk_bf16(o[0], o[1]), cvt_pk_bf16(o[2], o[3]), cvt_pk_bf16(o[4], o[5]), cvt_pk_bf16(o[6], o[7])}; }
;                 s += __shfl_xor(s, 16); s += __shfl_xor(s, 32);
;                 if (fq == 0) ss[(size_t)row * 32 + u.pn * 4 + wc] = s; } }
.LBB0_1043:
	s_or_b64 exec, exec, s[30:31]
	s_waitcnt vmcnt(7)
	v_lshlrev_b32_e32 v32, 16, v76
	s_waitcnt lgkmcnt(0)
	v_and_b32_e32 v33, 0xffff0000, v76
	v_lshlrev_b32_e32 v36, 16, v78
	v_lshlrev_b32_e32 v34, 16, v77
	v_and_b32_e32 v35, 0xffff0000, v77
	v_and_b32_e32 v37, 0xffff0000, v78
	v_lshlrev_b32_e32 v38, 16, v79
	v_add_f32_e32 v28, v28, v32
	v_add_f32_e32 v32, v24, v36
	v_add_f32_e32 v24, v29, v33
	v_add_f32_e32 v29, v25, v37
	v_add_f32_e32 v25, v30, v34
	v_add_f32_e32 v30, v26, v38
	v_add_f32_e32 v26, v31, v35
	v_mul_f32_e32 v31, v24, v24
	v_fmac_f32_e32 v31, v28, v28
	v_fmac_f32_e32 v31, v25, v25
	v_fmac_f32_e32 v31, v26, v26
	v_fmac_f32_e32 v31, v32, v32
	v_and_b32_e32 v39, 0xffff0000, v79
	v_fmac_f32_e32 v31, v29, v29
	v_add_f32_e32 v27, v27, v39
	v_fmac_f32_e32 v31, v30, v30
	v_cvt_pk_bf16_f32 v24, v28, v24
	s_waitcnt vmcnt(6)
	v_lshlrev_b32_e32 v28, 16, v72
	v_fmac_f32_e32 v31, v27, v27
	v_cvt_pk_bf16_f32 v25, v25, v26
	v_cvt_pk_bf16_f32 v26, v32, v29
	v_and_b32_e32 v29, 0xffff0000, v72
	v_add_f32_e32 v20, v20, v28
	v_cvt_pk_bf16_f32 v27, v30, v27
	v_lshlrev_b32_e32 v30, 16, v73
	v_add_f32_e32 v21, v21, v29
	v_fmac_f32_e32 v31, v20, v20
	v_and_b32_e32 v32, 0xffff0000, v73
	v_add_f32_e32 v30, v22, v30
	v_fmac_f32_e32 v31, v21, v21
	v_lshlrev_b32_e32 v33, 16, v74
	v_add_f32_e32 v32, v23, v32
	v_fmac_f32_e32 v31, v30, v30
	v_and_b32_e32 v34, 0xffff0000, v74
	v_add_f32_e32 v28, v16, v33
	v_fmac_f32_e32 v31, v32, v32
	v_lshlrev_b32_e32 v35, 16, v75
	v_add_f32_e32 v29, v17, v34
	v_fmac_f32_e32 v31, v28, v28
	v_and_b32_e32 v36, 0xffff0000, v75
	v_add_f32_e32 v33, v18, v35
	v_fmac_f32_e32 v31, v29, v29
	v_add_f32_e32 v34, v19, v36
	v_fmac_f32_e32 v31, v33, v33
	v_fmac_f32_e32 v31, v34, v34
	ds_bpermute_b32 v19, v195, v31
	v_lshl_add_u64 v[16:17], s[76:77], 0, v[94:95]
	v_lshl_add_u64 v[22:23], v[168:169], 1, v[16:17]
	global_store_dwordx4 v[22:23], v[24:27], off sc1
	v_cvt_pk_bf16_f32 v18, v20, v21
	s_waitcnt lgkmcnt(0)
	v_add_f32_e32 v16, v31, v19
	ds_bpermute_b32 v17, v112, v16
	v_cvt_pk_bf16_f32 v19, v30, v32
	v_cvt_pk_bf16_f32 v20, v28, v29
	v_cvt_pk_bf16_f32 v21, v33, v34
	global_store_dwordx4 v[22:23], v[18:21], off offset:256 sc1
	s_and_saveexec_b64 s[30:31], s[4:5]
	s_cbranch_execz .LBB0_1045
	v_lshlrev_b64 v[18:19], 7, v[92:93]
	v_lshl_add_u64 v[18:19], s[14:15], 0, v[18:19]
	v_lshl_add_u64 v[18:19], s[28:29], 2, v[18:19]
	s_lshl_b32 s8, s43, 2
	v_lshl_add_u64 v[18:19], v[18:19], 0, s[8:9]
	s_waitcnt lgkmcnt(0)
	v_add_f32_e32 v16, v16, v17
	global_store_dword v[18:19], v16, off
.LBB0_1045:
	s_or_b64 exec, exec, s[30:31]
	s_waitcnt vmcnt(7)
	v_lshlrev_b32_e32 v16, 16, v68
	s_waitcnt lgkmcnt(0)
	v_and_b32_e32 v17, 0xffff0000, v68
	v_lshlrev_b32_e32 v20, 16, v70
	v_lshlrev_b32_e32 v18, 16, v69
	v_and_b32_e32 v19, 0xffff0000, v69
	v_and_b32_e32 v21, 0xffff0000, v70
	v_lshlrev_b32_e32 v22, 16, v71
	v_add_f32_e32 v12, v12, v16
	v_add_f32_e32 v16, v8, v20
	v_add_f32_e32 v8, v13, v17
	v_add_f32_e32 v13, v9, v21
	v_add_f32_e32 v9, v14, v18
	v_add_f32_e32 v14, v10, v22
	v_add_f32_e32 v10, v15, v19
	v_mul_f32_e32 v15, v8, v8
	v_fmac_f32_e32 v15, v12, v12
	v_fmac_f32_e32 v15, v9, v9
	v_fmac_f32_e32 v15, v10, v10
	v_fmac_f32_e32 v15, v16, v16
	v_and_b32_e32 v23, 0xffff0000, v71
	v_fmac_f32_e32 v15, v13, v13
	v_add_f32_e32 v11, v11, v23
	v_fmac_f32_e32 v15, v14, v14
	v_cvt_pk_bf16_f32 v8, v12, v8
	s_waitcnt vmcnt(6)
	v_lshlrev_b32_e32 v12, 16, v64
	v_fmac_f32_e32 v15, v11, v11
	v_cvt_pk_bf16_f32 v9, v9, v10
	v_cvt_pk_bf16_f32 v10, v16, v13
	v_and_b32_e32 v13, 0xffff0000, v64
	v_add_f32_e32 v4, v4, v12
	v_cvt_pk_bf16_f32 v11, v14, v11
	v_lshlrev_b32_e32 v14, 16, v65
	v_add_f32_e32 v5, v5, v13
	v_fmac_f32_e32 v15, v4, v4
	v_and_b32_e32 v16, 0xffff0000, v65
	v_add_f32_e32 v14, v6, v14
	v_fmac_f32_e32 v15, v5, v5
	v_lshlrev_b32_e32 v17, 16, v66
	v_add_f32_e32 v16, v7, v16
	v_fmac_f32_e32 v15, v14, v14
	v_and_b32_e32 v18, 0xffff0000, v66
	v_add_f32_e32 v12, v0, v17
	v_fmac_f32_e32 v15, v16, v16
	v_lshlrev_b32_e32 v19, 16, v67
	v_add_f32_e32 v13, v1, v18
	v_fmac_f32_e32 v15, v12, v12
	v_and_b32_e32 v20, 0xffff0000, v67
	v_add_f32_e32 v17, v2, v19
	v_fmac_f32_e32 v15, v13, v13
	v_add_f32_e32 v18, v3, v20
	v_fmac_f32_e32 v15, v17, v17
	v_fmac_f32_e32 v15, v18, v18
	ds_bpermute_b32 v3, v195, v15
	v_lshl_add_u64 v[0:1], s[76:77], 0, v[90:91]
	v_lshl_add_u64 v[6:7], v[168:169], 1, v[0:1]
	global_store_dwordx4 v[6:7], v[8:11], off sc1
	v_cvt_pk_bf16_f32 v2, v4, v5
	s_waitcnt lgkmcnt(0)
	v_add_f32_e32 v0, v15, v3
	ds_bpermute_b32 v1, v112, v0
	v_cvt_pk_bf16_f32 v3, v14, v16
	v_cvt_pk_bf16_f32 v4, v12, v13
	v_cvt_pk_bf16_f32 v5, v17, v18
	global_store_dwordx4 v[6:7], v[2:5], off offset:256 sc1
	s_and_saveexec_b64 s[30:31], s[4:5]
	s_cbranch_execz .LBB0_1047
	v_lshlrev_b64 v[2:3], 7, v[88:89]
	v_lshl_add_u64 v[2:3], s[14:15], 0, v[2:3]
	v_lshl_add_u64 v[2:3], s[28:29], 2, v[2:3]
	s_lshl_b32 s8, s43, 2
	v_lshl_add_u64 v[2:3], v[2:3], 0, s[8:9]
	s_waitcnt lgkmcnt(0)
	v_add_f32_e32 v0, v0, v1
	global_store_dword v[2:3], v0, off
